# G1 epilogue + layer-1 adaLN units: packed f32 VALU ops split into scalar pairs (bit-identical)
# baseline (speedup 1.0000x reference)
; __device__ __forceinline__ f32x2 silu_pk(f32x2 x) { const f32x2 t = x * -1.4426950408889634f; f32x2 e; e.x = __builtin_amdgcn_exp2f(t.x); e.y = __builtin_amdgcn_exp2f(t.y); e = e + 1.0f; f32x2 r; r.x = __builtin_amdgcn_rcpf(e.x); r.y = __builtin_amdgcn_rcpf(e.y); return x * r; }
;     __device__ __forceinline__ void operator()(const pg8::f32x4 (&acc)[2][2][4][2], const pg8::Unit& u, int wr, int wc, int fr, int fq) const {
;     ...
;                     } else if (pn < 44) {
; #pragma unroll
;                         for (int e = 0; e < 8; e += 2) { const f32x2 g2 = silu_pk((f32x2){v[e], v[e + 1]}); v[e] = g2.x; v[e + 1] = g2.y; }
;                         st_bf16((bf16*)(ws + WS_ZB) + (size_t)r * 2048 + (pn - 36) * 256 + cl, v);
;                     } else if (pn < 48) {
;                         st_bf16((bf16*)(ws + WS_QC) + (size_t)r * 1024 + (pn - 44) * 256 + cl, v);
;                     } else if (pn < 50) {
;                         const bool isv = pn == 49;
;                         st_bf16((bf16*)(ws + (isv ? WS_VC : WS_KC)) + (size_t)r * 256 + cl, v);
;                         if (r < PT) st_f32(out + (isv ? O_PV : O_PK) + ((size_t)l * PT + r) * 256 + cl, v);
;                         else st_f32(out + (isv ? O_SV : O_SK) + ((size_t)l * ST + (r - PT)) * 256 + cl, v);
;                     } else if (pn < 54) {
; #pragma unroll
;                         for (int e = 0; e < 8; e += 2) { const f32x2 g2 = silu_pk((f32x2){v[e], v[e + 1]}); v[e] = g2.x; v[e + 1] = g2.y; }
;                         st_bf16((bf16*)(ws + WS_ZC) + (size_t)r * 1024 + (pn - 50) * 256 + cl, v);
.LBB0_249:
	s_andn2_b64 vcc, exec, s[6:7]
	s_cbranch_vccnz .LBB0_251
	v_mul_f32_e64 v172, v124, s48
	v_mul_f32_e64 v173, v125, s48
	v_mul_f32_e64 v174, v126, s48
	v_mul_f32_e64 v175, v127, s48
	v_exp_f32_e32 v172, v172
	v_exp_f32_e32 v173, v173
	v_exp_f32_e32 v174, v174
	v_exp_f32_e32 v175, v175
	v_mul_f32_e64 v176, v120, s48
	v_mul_f32_e64 v177, v121, s48
	v_mul_f32_e64 v178, v122, s48
	v_mul_f32_e64 v179, v123, s48
	v_exp_f32_e32 v176, v176
	v_exp_f32_e32 v177, v177
	v_exp_f32_e32 v178, v178
	v_exp_f32_e32 v179, v179
	v_add_f32_e64 v172, v172, 1.0
	v_add_f32_e64 v173, v173, 1.0
	v_add_f32_e64 v174, v174, 1.0
	v_add_f32_e64 v175, v175, 1.0
	v_rcp_f32_e32 v172, v172
	v_rcp_f32_e32 v173, v173
	v_rcp_f32_e32 v174, v174
	v_rcp_f32_e32 v175, v175
	v_add_f32_e64 v176, v176, 1.0
	v_add_f32_e64 v177, v177, 1.0
	v_add_f32_e64 v178, v178, 1.0
	v_add_f32_e64 v179, v179, 1.0
	v_rcp_f32_e32 v176, v176
	v_rcp_f32_e32 v177, v177
	v_rcp_f32_e32 v178, v178
	v_rcp_f32_e32 v179, v179
	v_lshlrev_b32_e32 v136, 1, v140
	v_mul_f32_e64 v172, v124, v172
	v_mul_f32_e64 v173, v125, v173
	v_mul_f32_e64 v174, v126, v174
	v_mul_f32_e64 v175, v127, v175
	v_lshl_add_u64 v[186:187], v[166:167], 0, v[136:137]
	v_mul_f32_e64 v176, v120, v176
	v_mul_f32_e64 v177, v121, v177
	v_mul_f32_e64 v178, v122, v178
	v_mul_f32_e64 v179, v123, v179
	v_cvt_pk_bf16_f32 v172, v172, v173
	v_cvt_pk_bf16_f32 v173, v174, v175
	v_cvt_pk_bf16_f32 v174, v176, v177
	s_nop 0
	v_cvt_pk_bf16_f32 v175, v178, v179
	global_store_dwordx4 v[186:187], v[172:175], off

; __device__ __forceinline__ f32x2 silu_pk(f32x2 x) { const f32x2 t = x * -1.4426950408889634f; f32x2 e; e.x = __builtin_amdgcn_exp2f(t.x); e.y = __builtin_amdgcn_exp2f(t.y); e = e + 1.0f; f32x2 r; r.x = __builtin_amdgcn_rcpf(e.x); r.y = __builtin_amdgcn_rcpf(e.y); return x * r; }
;     __device__ __forceinline__ void operator()(const pg8::f32x4 (&acc)[2][2][4][2], const pg8::Unit& u, int wr, int wc, int fr, int fq) const {
;     ...
;                     } else if (pn < 44) {
; #pragma unroll
;                         for (int e = 0; e < 8; e += 2) { const f32x2 g2 = silu_pk((f32x2){v[e], v[e + 1]}); v[e] = g2.x; v[e + 1] = g2.y; }
;                         st_bf16((bf16*)(ws + WS_ZB) + (size_t)r * 2048 + (pn - 36) * 256 + cl, v);
;                     } else if (pn < 48) {
;                         st_bf16((bf16*)(ws + WS_QC) + (size_t)r * 1024 + (pn - 44) * 256 + cl, v);
;                     } else if (pn < 50) {
;                         const bool isv = pn == 49;
;                         st_bf16((bf16*)(ws + (isv ? WS_VC : WS_KC)) + (size_t)r * 256 + cl, v);
;                         if (r < PT) st_f32(out + (isv ? O_PV : O_PK) + ((size_t)l * PT + r) * 256 + cl, v);
;                         else st_f32(out + (isv ? O_SV : O_SK) + ((size_t)l * ST + (r - PT)) * 256 + cl, v);
;                     } else if (pn < 54) {
; #pragma unroll
;                         for (int e = 0; e < 8; e += 2) { const f32x2 g2 = silu_pk((f32x2){v[e], v[e + 1]}); v[e] = g2.x; v[e + 1] = g2.y; }
;                         st_bf16((bf16*)(ws + WS_ZC) + (size_t)r * 1024 + (pn - 50) * 256 + cl, v);
.LBB0_262:
	s_andn2_b64 vcc, exec, s[6:7]
	s_cbranch_vccnz .LBB0_264
	v_mul_f32_e64 v172, v124, s48
	v_mul_f32_e64 v173, v125, s48
	v_mul_f32_e64 v174, v126, s48
	v_mul_f32_e64 v175, v127, s48
	v_exp_f32_e32 v172, v172
	v_exp_f32_e32 v173, v173
	v_exp_f32_e32 v174, v174
	v_exp_f32_e32 v175, v175
	v_mul_f32_e64 v176, v120, s48
	v_mul_f32_e64 v177, v121, s48
	v_mul_f32_e64 v178, v122, s48
	v_mul_f32_e64 v179, v123, s48
	v_exp_f32_e32 v176, v176
	v_exp_f32_e32 v177, v177
	v_exp_f32_e32 v178, v178
	v_exp_f32_e32 v179, v179
	v_add_f32_e64 v172, v172, 1.0
	v_add_f32_e64 v173, v173, 1.0
	v_add_f32_e64 v174, v174, 1.0
	v_add_f32_e64 v175, v175, 1.0
	v_rcp_f32_e32 v172, v172
	v_rcp_f32_e32 v173, v173
	v_rcp_f32_e32 v174, v174
	v_rcp_f32_e32 v175, v175
	v_add_f32_e64 v176, v176, 1.0
	v_add_f32_e64 v177, v177, 1.0
	v_add_f32_e64 v178, v178, 1.0
	v_add_f32_e64 v179, v179, 1.0
	v_rcp_f32_e32 v176, v176
	v_rcp_f32_e32 v177, v177
	v_rcp_f32_e32 v178, v178
	v_rcp_f32_e32 v179, v179
	v_lshlrev_b32_e32 v136, 1, v140
	v_mul_f32_e64 v172, v124, v172
	v_mul_f32_e64 v173, v125, v173
	v_mul_f32_e64 v174, v126, v174
	v_mul_f32_e64 v175, v127, v175
	v_lshl_add_u64 v[186:187], v[156:157], 0, v[136:137]
	v_mul_f32_e64 v176, v120, v176
	v_mul_f32_e64 v177, v121, v177
	v_mul_f32_e64 v178, v122, v178
	v_mul_f32_e64 v179, v123, v179
	v_cvt_pk_bf16_f32 v172, v172, v173
	v_cvt_pk_bf16_f32 v173, v174, v175
	v_cvt_pk_bf16_f32 v174, v176, v177
	s_nop 0
	v_cvt_pk_bf16_f32 v175, v178, v179
	global_store_dwordx4 v[186:187], v[172:175], off

; __device__ __forceinline__ f32x2 silu_pk(f32x2 x) { const f32x2 t = x * -1.4426950408889634f; f32x2 e; e.x = __builtin_amdgcn_exp2f(t.x); e.y = __builtin_amdgcn_exp2f(t.y); e = e + 1.0f; f32x2 r; r.x = __builtin_amdgcn_rcpf(e.x); r.y = __builtin_amdgcn_rcpf(e.y); return x * r; }
;     __device__ __forceinline__ void operator()(const pg8::f32x4 (&acc)[2][2][4][2], const pg8::Unit& u, int wr, int wc, int fr, int fq) const {
;     ...
;                     } else if (pn < 44) {
; #pragma unroll
;                         for (int e = 0; e < 8; e += 2) { const f32x2 g2 = silu_pk((f32x2){v[e], v[e + 1]}); v[e] = g2.x; v[e + 1] = g2.y; }
;                         st_bf16((bf16*)(ws + WS_ZB) + (size_t)r * 2048 + (pn - 36) * 256 + cl, v);
;                     } else if (pn < 48) {
;                         st_bf16((bf16*)(ws + WS_QC) + (size_t)r * 1024 + (pn - 44) * 256 + cl, v);
;                     } else if (pn < 50) {
;                         const bool isv = pn == 49;
;                         st_bf16((bf16*)(ws + (isv ? WS_VC : WS_KC)) + (size_t)r * 256 + cl, v);
;                         if (r < PT) st_f32(out + (isv ? O_PV : O_PK) + ((size_t)l * PT + r) * 256 + cl, v);
;                         else st_f32(out + (isv ? O_SV : O_SK) + ((size_t)l * ST + (r - PT)) * 256 + cl, v);
;                     } else if (pn < 54) {
; #pragma unroll
;                         for (int e = 0; e < 8; e += 2) { const f32x2 g2 = silu_pk((f32x2){v[e], v[e + 1]}); v[e] = g2.x; v[e + 1] = g2.y; }
;                         st_bf16((bf16*)(ws + WS_ZC) + (size_t)r * 1024 + (pn - 50) * 256 + cl, v);
.LBB0_279:
	s_andn2_b64 vcc, exec, s[6:7]
	s_cbranch_vccnz .LBB0_281
	v_mul_f32_e64 v120, v116, s48
	v_mul_f32_e64 v121, v117, s48
	v_mul_f32_e64 v122, v118, s48
	v_mul_f32_e64 v123, v119, s48
	v_exp_f32_e32 v120, v120
	v_exp_f32_e32 v121, v121
	v_exp_f32_e32 v122, v122
	v_exp_f32_e32 v123, v123
	v_mul_f32_e64 v124, v112, s48
	v_mul_f32_e64 v125, v113, s48
	v_mul_f32_e64 v126, v114, s48
	v_mul_f32_e64 v127, v115, s48
	v_exp_f32_e32 v124, v124
	v_exp_f32_e32 v125, v125
	v_exp_f32_e32 v126, v126
	v_exp_f32_e32 v127, v127
	v_add_f32_e64 v120, v120, 1.0
	v_add_f32_e64 v121, v121, 1.0
	v_add_f32_e64 v122, v122, 1.0
	v_add_f32_e64 v123, v123, 1.0
	v_rcp_f32_e32 v120, v120
	v_rcp_f32_e32 v121, v121
	v_rcp_f32_e32 v122, v122
	v_rcp_f32_e32 v123, v123
	v_add_f32_e64 v124, v124, 1.0
	v_add_f32_e64 v125, v125, 1.0
	v_add_f32_e64 v126, v126, 1.0
	v_add_f32_e64 v127, v127, 1.0
	v_rcp_f32_e32 v124, v124
	v_rcp_f32_e32 v125, v125
	v_rcp_f32_e32 v126, v126
	v_rcp_f32_e32 v127, v127
	v_lshlrev_b32_e32 v136, 1, v142
	v_mul_f32_e64 v120, v116, v120
	v_mul_f32_e64 v121, v117, v121
	v_mul_f32_e64 v122, v118, v122
	v_mul_f32_e64 v123, v119, v123
	v_lshl_add_u64 v[166:167], v[166:167], 0, v[136:137]
	v_mul_f32_e64 v124, v112, v124
	v_mul_f32_e64 v125, v113, v125
	v_mul_f32_e64 v126, v114, v126
	v_mul_f32_e64 v127, v115, v127
	v_cvt_pk_bf16_f32 v120, v120, v121
	v_cvt_pk_bf16_f32 v121, v122, v123
	v_cvt_pk_bf16_f32 v122, v124, v125
	s_nop 0
	v_cvt_pk_bf16_f32 v123, v126, v127
	global_store_dwordx4 v[166:167], v[120:123], off

; __device__ __forceinline__ f32x2 silu_pk(f32x2 x) { const f32x2 t = x * -1.4426950408889634f; f32x2 e; e.x = __builtin_amdgcn_exp2f(t.x); e.y = __builtin_amdgcn_exp2f(t.y); e = e + 1.0f; f32x2 r; r.x = __builtin_amdgcn_rcpf(e.x); r.y = __builtin_amdgcn_rcpf(e.y); return x * r; }
;     __device__ __forceinline__ void operator()(const pg8::f32x4 (&acc)[2][2][4][2], const pg8::Unit& u, int wr, int wc, int fr, int fq) const {
;     ...
;                     } else if (pn < 44) {
; #pragma unroll
;                         for (int e = 0; e < 8; e += 2) { const f32x2 g2 = silu_pk((f32x2){v[e], v[e + 1]}); v[e] = g2.x; v[e + 1] = g2.y; }
;                         st_bf16((bf16*)(ws + WS_ZB) + (size_t)r * 2048 + (pn - 36) * 256 + cl, v);
;                     } else if (pn < 48) {
;                         st_bf16((bf16*)(ws + WS_QC) + (size_t)r * 1024 + (pn - 44) * 256 + cl, v);
;                     } else if (pn < 50) {
;                         const bool isv = pn == 49;
;                         st_bf16((bf16*)(ws + (isv ? WS_VC : WS_KC)) + (size_t)r * 256 + cl, v);
;                         if (r < PT) st_f32(out + (isv ? O_PV : O_PK) + ((size_t)l * PT + r) * 256 + cl, v);
;                         else st_f32(out + (isv ? O_SV : O_SK) + ((size_t)l * ST + (r - PT)) * 256 + cl, v);
;                     } else if (pn < 54) {
; #pragma unroll
;                         for (int e = 0; e < 8; e += 2) { const f32x2 g2 = silu_pk((f32x2){v[e], v[e + 1]}); v[e] = g2.x; v[e + 1] = g2.y; }
;                         st_bf16((bf16*)(ws + WS_ZC) + (size_t)r * 1024 + (pn - 50) * 256 + cl, v);
.LBB0_292:
	s_andn2_b64 vcc, exec, s[6:7]
	s_cbranch_vccnz .LBB0_294
	v_mul_f32_e64 v120, v116, s48
	v_mul_f32_e64 v121, v117, s48
	v_mul_f32_e64 v122, v118, s48
	v_mul_f32_e64 v123, v119, s48
	v_exp_f32_e32 v120, v120
	v_exp_f32_e32 v121, v121
	v_exp_f32_e32 v122, v122
	v_exp_f32_e32 v123, v123
	v_mul_f32_e64 v124, v112, s48
	v_mul_f32_e64 v125, v113, s48
	v_mul_f32_e64 v126, v114, s48
	v_mul_f32_e64 v127, v115, s48
	v_exp_f32_e32 v124, v124
	v_exp_f32_e32 v125, v125
	v_exp_f32_e32 v126, v126
	v_exp_f32_e32 v127, v127
	v_add_f32_e64 v120, v120, 1.0
	v_add_f32_e64 v121, v121, 1.0
	v_add_f32_e64 v122, v122, 1.0
	v_add_f32_e64 v123, v123, 1.0
	v_rcp_f32_e32 v120, v120
	v_rcp_f32_e32 v121, v121
	v_rcp_f32_e32 v122, v122
	v_rcp_f32_e32 v123, v123
	v_add_f32_e64 v124, v124, 1.0
	v_add_f32_e64 v125, v125, 1.0
	v_add_f32_e64 v126, v126, 1.0
	v_add_f32_e64 v127, v127, 1.0
	v_rcp_f32_e32 v124, v124
	v_rcp_f32_e32 v125, v125
	v_rcp_f32_e32 v126, v126
	v_rcp_f32_e32 v127, v127
	v_lshlrev_b32_e32 v136, 1, v142
	v_mul_f32_e64 v120, v116, v120
	v_mul_f32_e64 v121, v117, v121
	v_mul_f32_e64 v122, v118, v122
	v_mul_f32_e64 v123, v119, v123
	v_lshl_add_u64 v[156:157], v[156:157], 0, v[136:137]
	v_mul_f32_e64 v124, v112, v124
	v_mul_f32_e64 v125, v113, v125
	v_mul_f32_e64 v126, v114, v126
	v_mul_f32_e64 v127, v115, v127
	v_cvt_pk_bf16_f32 v120, v120, v121
	v_cvt_pk_bf16_f32 v121, v122, v123
	v_cvt_pk_bf16_f32 v122, v124, v125
	s_nop 0
	v_cvt_pk_bf16_f32 v123, v126, v127
	global_store_dwordx4 v[156:157], v[120:123], off

; __device__ __forceinline__ f32x2 silu_pk(f32x2 x) { const f32x2 t = x * -1.4426950408889634f; f32x2 e; e.x = __builtin_amdgcn_exp2f(t.x); e.y = __builtin_amdgcn_exp2f(t.y); e = e + 1.0f; f32x2 r; r.x = __builtin_amdgcn_rcpf(e.x); r.y = __builtin_amdgcn_rcpf(e.y); return x * r; }
; __device__ __forceinline__ f32x2 gelu_pk(f32x2 x) { const f32x2 x2 = x * x; const f32x2 t = (x2 * 0.044715f + 1.0f) * (x * -2.302208198144325f); f32x2 e; e.x = __builtin_amdgcn_exp2f(t.x); e.y = __builtin_amdgcn_exp2f(t.y); e = e + 1.0f; f32x2 r; r.x = __builtin_amdgcn_rcpf(e.x); r.y = __builtin_amd ...
;     __device__ __forceinline__ void operator()(const pg8::f32x4 (&acc)[2][2][4][2], const pg8::Unit& u, int wr, int wc, int fr, int fq) const {
;     ...
;                     if (pn < 12) {
;                         const int seg = pn >> 2, cc = (pn & 3) * 256 + cl;
;                         if (seg < 2) {
; #pragma unroll
;                             for (int e = 0; e < 8; e += 2) { const f32x2 g2 = gelu_pk((f32x2){v[e], v[e + 1]}); v[e] = g2.x; v[e + 1] = g2.y; }
;                         } else {
; #pragma unroll
;                             for (int e = 0; e < 8; e += 2) { const f32x2 g2 = silu_pk((f32x2){v[e], v[e + 1]}); v[e] = g2.x; v[e + 1] = g2.y; }
;                         }
;                         bf16* base = (bf16*)(ws + (seg == 0 ? WS_UA : seg == 1 ? WS_VA : WS_ZA));
;                         st_bf16(base + (size_t)r * 1024 + cc, v);
.LBB0_301:
	s_andn2_b64 vcc, exec, s[16:17]
	s_mov_b64 s[96:97], -1
	s_cbranch_vccnz .LBB0_303
	v_mul_f32_e64 v174, v126, s48
	v_mul_f32_e64 v175, v127, s48
	v_mul_f32_e64 v172, v124, s48
	v_mul_f32_e64 v173, v125, s48
	v_exp_f32_e32 v174, v174
	v_exp_f32_e32 v175, v175
	v_mul_f32_e64 v176, v120, s48
	v_mul_f32_e64 v177, v121, s48
	v_exp_f32_e32 v172, v172
	v_exp_f32_e32 v173, v173
	v_exp_f32_e32 v176, v176
	v_exp_f32_e32 v177, v177
	v_add_f32_e64 v174, v174, 1.0
	v_add_f32_e64 v175, v175, 1.0
	v_add_f32_e64 v172, v172, 1.0
	v_add_f32_e64 v173, v173, 1.0
	v_rcp_f32_e32 v178, v174
	v_rcp_f32_e32 v179, v175
	v_add_f32_e64 v174, v176, 1.0
	v_add_f32_e64 v175, v177, 1.0
	v_rcp_f32_e32 v172, v172
	v_rcp_f32_e32 v173, v173
	v_rcp_f32_e32 v176, v174
	v_rcp_f32_e32 v177, v175
	s_mov_b64 s[96:97], 0
	v_mul_f32_e64 v174, v124, v172
	v_mul_f32_e64 v175, v125, v173
	v_mul_f32_e64 v172, v126, v178
	v_mul_f32_e64 v173, v127, v179
	v_mul_f32_e64 v176, v120, v176
	v_mul_f32_e64 v177, v121, v177
	v_mul_f32_e64 v178, v122, s48
	v_mul_f32_e64 v179, v123, s48
.LBB0_303:
	s_andn2_b64 vcc, exec, s[96:97]
	s_cbranch_vccnz .LBB0_305
	v_mul_f32_e64 v174, v124, v124
	v_mul_f32_e64 v175, v125, v125
	v_mul_f32_e64 v176, v124, s52
	v_mul_f32_e64 v177, v125, s52
	v_fma_f32 v174, v174, s50, 1.0
	v_fma_f32 v175, v175, s50, 1.0
	v_mul_f32_e64 v172, v126, v126
	v_mul_f32_e64 v173, v127, v127
	v_mul_f32_e64 v174, v176, v174
	v_mul_f32_e64 v175, v177, v175
	v_mul_f32_e64 v176, v120, s52
	v_mul_f32_e64 v177, v121, s52
	v_exp_f32_e32 v174, v174
	v_exp_f32_e32 v175, v175
	s_nop 0
	v_add_f32_e64 v174, v174, 1.0
	v_add_f32_e64 v175, v175, 1.0
	s_nop 0
	v_rcp_f32_e32 v174, v174
	v_rcp_f32_e32 v175, v175
	s_nop 0
	v_mul_f32_e64 v174, v124, v174
	v_mul_f32_e64 v175, v125, v175
	v_fma_f32 v124, v172, s50, 1.0
	v_fma_f32 v125, v173, s50, 1.0
	v_mul_f32_e64 v172, v126, s52
	v_mul_f32_e64 v173, v127, s52
	s_nop 0
	v_mul_f32_e64 v124, v172, v124
	v_mul_f32_e64 v125, v173, v125
	s_nop 0
	v_exp_f32_e32 v124, v124
	v_exp_f32_e32 v125, v125
	s_nop 0
	v_add_f32_e64 v124, v124, 1.0
	v_add_f32_e64 v125, v125, 1.0
	s_nop 0
	v_rcp_f32_e32 v124, v124
	v_rcp_f32_e32 v125, v125
	s_nop 0
	v_mul_f32_e64 v172, v126, v124
	v_mul_f32_e64 v173, v127, v125
	v_mul_f32_e64 v126, v120, v120
	v_mul_f32_e64 v127, v121, v121
	v_mul_f32_e64 v124, v122, v122
	v_mul_f32_e64 v125, v123, v123
	v_fma_f32 v126, v126, s50, 1.0
	v_fma_f32 v127, v127, s50, 1.0
	s_nop 0
	v_mul_f32_e64 v126, v176, v126
	v_mul_f32_e64 v127, v177, v127
	s_nop 0
	v_exp_f32_e32 v126, v126
	v_exp_f32_e32 v127, v127
	s_nop 0
	v_add_f32_e64 v126, v126, 1.0
	v_add_f32_e64 v127, v127, 1.0
	s_nop 0
	v_rcp_f32_e32 v126, v126
	v_rcp_f32_e32 v127, v127
	s_nop 0
	v_mul_f32_e64 v176, v120, v126
	v_mul_f32_e64 v177, v121, v127
	v_fma_f32 v120, v124, s50, 1.0
	v_fma_f32 v121, v125, s50, 1.0
	v_mul_f32_e64 v124, v122, s52
	v_mul_f32_e64 v125, v123, s52
	s_nop 0
	v_mul_f32_e64 v178, v124, v120
	v_mul_f32_e64 v179, v125, v121
.LBB0_305:
	s_nop 0
	v_exp_f32_e32 v120, v178
	v_exp_f32_e32 v121, v179
	v_or_b32_e32 v126, s26, v140
	v_lshlrev_b32_e32 v136, 1, v126
	v_lshl_add_u64 v[126:127], v[168:169], 0, v[136:137]
	v_add_f32_e64 v120, v120, 1.0
	v_add_f32_e64 v121, v121, 1.0
	s_nop 0
	v_rcp_f32_e32 v120, v120
	v_rcp_f32_e32 v121, v121
	s_nop 0
	v_mul_f32_e64 v124, v122, v120
	v_mul_f32_e64 v125, v123, v121
	v_cvt_pk_bf16_f32 v120, v174, v175
	v_cvt_pk_bf16_f32 v121, v172, v173
	v_cvt_pk_bf16_f32 v122, v176, v177
	s_nop 0
	v_cvt_pk_bf16_f32 v123, v124, v125
	global_store_dwordx4 v[126:127], v[120:123], off
	s_andn2_b64 vcc, exec, s[12:13]
	s_mov_b64 s[6:7], -1
	s_cbranch_vccz .LBB0_271

; __device__ __forceinline__ f32x2 silu_pk(f32x2 x) { const f32x2 t = x * -1.4426950408889634f; f32x2 e; e.x = __builtin_amdgcn_exp2f(t.x); e.y = __builtin_amdgcn_exp2f(t.y); e = e + 1.0f; f32x2 r; r.x = __builtin_amdgcn_rcpf(e.x); r.y = __builtin_amdgcn_rcpf(e.y); return x * r; }
; __device__ __forceinline__ f32x2 gelu_pk(f32x2 x) { const f32x2 x2 = x * x; const f32x2 t = (x2 * 0.044715f + 1.0f) * (x * -2.302208198144325f); f32x2 e; e.x = __builtin_amdgcn_exp2f(t.x); e.y = __builtin_amdgcn_exp2f(t.y); e = e + 1.0f; f32x2 r; r.x = __builtin_amdgcn_rcpf(e.x); r.y = __builtin_amd ...
;     __device__ __forceinline__ void operator()(const pg8::f32x4 (&acc)[2][2][4][2], const pg8::Unit& u, int wr, int wc, int fr, int fq) const {
;     ...
;                     if (pn < 12) {
;                         const int seg = pn >> 2, cc = (pn & 3) * 256 + cl;
;                         if (seg < 2) {
; #pragma unroll
;                             for (int e = 0; e < 8; e += 2) { const f32x2 g2 = gelu_pk((f32x2){v[e], v[e + 1]}); v[e] = g2.x; v[e + 1] = g2.y; }
;                         } else {
; #pragma unroll
;                             for (int e = 0; e < 8; e += 2) { const f32x2 g2 = silu_pk((f32x2){v[e], v[e + 1]}); v[e] = g2.x; v[e + 1] = g2.y; }
;                         }
;                         bf16* base = (bf16*)(ws + (seg == 0 ? WS_UA : seg == 1 ? WS_VA : WS_ZA));
;                         st_bf16(base + (size_t)r * 1024 + cc, v);
.LBB0_307:
	s_andn2_b64 vcc, exec, s[16:17]
	s_mov_b64 s[0:1], -1
	s_cbranch_vccnz .LBB0_309
	v_mul_f32_e64 v120, v116, s48
	v_mul_f32_e64 v121, v117, s48
	v_mul_f32_e64 v122, v118, s48
	v_mul_f32_e64 v123, v119, s48
	v_mul_f32_e64 v124, v112, s48
	v_mul_f32_e64 v125, v113, s48
	v_exp_f32_e32 v120, v120
	v_exp_f32_e32 v121, v121
	v_exp_f32_e32 v122, v122
	v_exp_f32_e32 v123, v123
	v_exp_f32_e32 v124, v124
	v_exp_f32_e32 v125, v125
	v_add_f32_e64 v120, v120, 1.0
	v_add_f32_e64 v121, v121, 1.0
	v_add_f32_e64 v122, v122, 1.0
	v_add_f32_e64 v123, v123, 1.0
	v_rcp_f32_e32 v120, v120
	v_add_f32_e64 v124, v124, 1.0
	v_add_f32_e64 v125, v125, 1.0
	v_rcp_f32_e32 v121, v121
	v_rcp_f32_e32 v122, v122
	v_rcp_f32_e32 v123, v123
	v_rcp_f32_e32 v124, v124
	v_rcp_f32_e32 v125, v125
	v_mul_f32_e64 v120, v116, v120
	v_mul_f32_e64 v121, v117, v121
	v_mul_f32_e64 v122, v118, v122
	v_mul_f32_e64 v123, v119, v123
	v_mul_f32_e64 v126, v114, s48
	v_mul_f32_e64 v127, v115, s48
	v_mul_f32_e64 v124, v112, v124
	v_mul_f32_e64 v125, v113, v125
	s_mov_b64 s[0:1], 0
.LBB0_309:
	s_andn2_b64 vcc, exec, s[0:1]
	s_cbranch_vccnz .LBB0_311
	v_mul_f32_e64 v120, v116, v116
	v_mul_f32_e64 v121, v117, v117
	v_mul_f32_e64 v124, v116, s52
	v_mul_f32_e64 v125, v117, s52
	v_fma_f32 v120, v120, s50, 1.0
	v_fma_f32 v121, v121, s50, 1.0
	v_mul_f32_e64 v122, v118, v118
	v_mul_f32_e64 v123, v119, v119
	v_mul_f32_e64 v120, v124, v120
	v_mul_f32_e64 v121, v125, v121
	v_mul_f32_e64 v124, v112, s52
	v_mul_f32_e64 v125, v113, s52
	v_exp_f32_e32 v120, v120
	v_exp_f32_e32 v121, v121
	s_nop 0
	v_add_f32_e64 v120, v120, 1.0
	v_add_f32_e64 v121, v121, 1.0
	s_nop 0
	v_rcp_f32_e32 v120, v120
	v_rcp_f32_e32 v121, v121
	s_nop 0
	v_mul_f32_e64 v120, v116, v120
	v_mul_f32_e64 v121, v117, v121
	v_fma_f32 v116, v122, s50, 1.0
	v_fma_f32 v117, v123, s50, 1.0
	v_mul_f32_e64 v122, v118, s52
	v_mul_f32_e64 v123, v119, s52
	s_nop 0
	v_mul_f32_e64 v116, v122, v116
	v_mul_f32_e64 v117, v123, v117
	s_nop 0
	v_exp_f32_e32 v116, v116
	v_exp_f32_e32 v117, v117
	s_nop 0
	v_add_f32_e64 v116, v116, 1.0
	v_add_f32_e64 v117, v117, 1.0
	s_nop 0
	v_rcp_f32_e32 v116, v116
	v_rcp_f32_e32 v117, v117
	s_nop 0
	v_mul_f32_e64 v122, v118, v116
	v_mul_f32_e64 v123, v119, v117
	v_mul_f32_e64 v118, v112, v112
	v_mul_f32_e64 v119, v113, v113
	v_mul_f32_e64 v116, v114, v114
	v_mul_f32_e64 v117, v115, v115
	v_fma_f32 v118, v118, s50, 1.0
	v_fma_f32 v119, v119, s50, 1.0
	s_nop 0
	v_mul_f32_e64 v118, v124, v118
	v_mul_f32_e64 v119, v125, v119
	s_nop 0
	v_exp_f32_e32 v118, v118
	v_exp_f32_e32 v119, v119
	s_nop 0
	v_add_f32_e64 v118, v118, 1.0
	v_add_f32_e64 v119, v119, 1.0
	s_nop 0
	v_rcp_f32_e32 v118, v118
	v_rcp_f32_e32 v119, v119
	s_nop 0
	v_mul_f32_e64 v124, v112, v118
	v_mul_f32_e64 v125, v113, v119
	v_fma_f32 v112, v116, s50, 1.0
	v_fma_f32 v113, v117, s50, 1.0
	v_mul_f32_e64 v116, v114, s52
	v_mul_f32_e64 v117, v115, s52
	s_nop 0
	v_mul_f32_e64 v126, v116, v112
	v_mul_f32_e64 v127, v117, v113
.LBB0_311:
	s_nop 0
	v_exp_f32_e32 v112, v126
	v_exp_f32_e32 v113, v127
	v_add_lshl_u32 v136, s26, v140, 1
	v_lshl_add_u64 v[118:119], v[168:169], 0, v[136:137]
	v_add_f32_e64 v112, v112, 1.0
	v_add_f32_e64 v113, v113, 1.0
	s_nop 0
	v_rcp_f32_e32 v112, v112
	v_rcp_f32_e32 v113, v113
	s_nop 0
	v_mul_f32_e64 v116, v114, v112
	v_mul_f32_e64 v117, v115, v113
	v_cvt_pk_bf16_f32 v112, v120, v121
	v_cvt_pk_bf16_f32 v113, v122, v123
	v_cvt_pk_bf16_f32 v114, v124, v125
	s_nop 0
	v_cvt_pk_bf16_f32 v115, v116, v117
	global_store_dwordx4 v[118:119], v[112:115], off offset:256

; __device__ __forceinline__ f32x2 silu_pk(f32x2 x) { const f32x2 t = x * -1.4426950408889634f; f32x2 e; e.x = __builtin_amdgcn_exp2f(t.x); e.y = __builtin_amdgcn_exp2f(t.y); e = e + 1.0f; f32x2 r; r.x = __builtin_amdgcn_rcpf(e.x); r.y = __builtin_amdgcn_rcpf(e.y); return x * r; }
;     __device__ __forceinline__ void operator()(const pg8::f32x4 (&acc)[2][2][4][2], const pg8::Unit& u, int wr, int wc, int fr, int fq) const {
;     ...
;                     } else if (pn < 44) {
; #pragma unroll
;                         for (int e = 0; e < 8; e += 2) { const f32x2 g2 = silu_pk((f32x2){v[e], v[e + 1]}); v[e] = g2.x; v[e + 1] = g2.y; }
;                         st_bf16((bf16*)(ws + WS_ZB) + (size_t)r * 2048 + (pn - 36) * 256 + cl, v);
;                     } else if (pn < 48) {
;                         st_bf16((bf16*)(ws + WS_QC) + (size_t)r * 1024 + (pn - 44) * 256 + cl, v);
;                     } else if (pn < 50) {
;                         const bool isv = pn == 49;
;                         st_bf16((bf16*)(ws + (isv ? WS_VC : WS_KC)) + (size_t)r * 256 + cl, v);
;                         if (r < PT) st_f32(out + (isv ? O_PV : O_PK) + ((size_t)l * PT + r) * 256 + cl, v);
;                         else st_f32(out + (isv ? O_SV : O_SK) + ((size_t)l * ST + (r - PT)) * 256 + cl, v);
;                     } else if (pn < 54) {
; #pragma unroll
;                         for (int e = 0; e < 8; e += 2) { const f32x2 g2 = silu_pk((f32x2){v[e], v[e + 1]}); v[e] = g2.x; v[e + 1] = g2.y; }
;                         st_bf16((bf16*)(ws + WS_ZC) + (size_t)r * 1024 + (pn - 50) * 256 + cl, v);
.LBB0_338:
	s_andn2_b64 vcc, exec, s[6:7]
	s_cbranch_vccnz .LBB0_340
	v_mul_f32_e64 v156, v108, s48
	v_mul_f32_e64 v157, v109, s48
	v_mul_f32_e64 v158, v110, s48
	v_mul_f32_e64 v159, v111, s48
	v_exp_f32_e32 v156, v156
	v_exp_f32_e32 v157, v157
	v_exp_f32_e32 v158, v158
	v_exp_f32_e32 v159, v159
	v_mul_f32_e64 v160, v104, s48
	v_mul_f32_e64 v161, v105, s48
	v_mul_f32_e64 v162, v106, s48
	v_mul_f32_e64 v163, v107, s48
	v_exp_f32_e32 v160, v160
	v_exp_f32_e32 v161, v161
	v_exp_f32_e32 v162, v162
	v_exp_f32_e32 v163, v163
	v_add_f32_e64 v156, v156, 1.0
	v_add_f32_e64 v157, v157, 1.0
	v_add_f32_e64 v158, v158, 1.0
	v_add_f32_e64 v159, v159, 1.0
	v_rcp_f32_e32 v156, v156
	v_rcp_f32_e32 v157, v157
	v_rcp_f32_e32 v158, v158
	v_rcp_f32_e32 v159, v159
	v_add_f32_e64 v160, v160, 1.0
	v_add_f32_e64 v161, v161, 1.0
	v_add_f32_e64 v162, v162, 1.0
	v_add_f32_e64 v163, v163, 1.0
	v_rcp_f32_e32 v160, v160
	v_rcp_f32_e32 v161, v161
	v_rcp_f32_e32 v162, v162
	v_rcp_f32_e32 v163, v163
	v_lshlrev_b32_e32 v136, 1, v140
	v_mul_f32_e64 v156, v108, v156
	v_mul_f32_e64 v157, v109, v157
	v_mul_f32_e64 v158, v110, v158
	v_mul_f32_e64 v159, v111, v159
	v_lshl_add_u64 v[164:165], v[124:125], 0, v[136:137]
	v_mul_f32_e64 v160, v104, v160
	v_mul_f32_e64 v161, v105, v161
	v_mul_f32_e64 v162, v106, v162
	v_mul_f32_e64 v163, v107, v163
	v_cvt_pk_bf16_f32 v156, v156, v157
	v_cvt_pk_bf16_f32 v157, v158, v159
	v_cvt_pk_bf16_f32 v158, v160, v161
	s_nop 0
	v_cvt_pk_bf16_f32 v159, v162, v163
	global_store_dwordx4 v[164:165], v[156:159], off

; __device__ __forceinline__ f32x2 silu_pk(f32x2 x) { const f32x2 t = x * -1.4426950408889634f; f32x2 e; e.x = __builtin_amdgcn_exp2f(t.x); e.y = __builtin_amdgcn_exp2f(t.y); e = e + 1.0f; f32x2 r; r.x = __builtin_amdgcn_rcpf(e.x); r.y = __builtin_amdgcn_rcpf(e.y); return x * r; }
;     __device__ __forceinline__ void operator()(const pg8::f32x4 (&acc)[2][2][4][2], const pg8::Unit& u, int wr, int wc, int fr, int fq) const {
;     ...
;                     } else if (pn < 44) {
; #pragma unroll
;                         for (int e = 0; e < 8; e += 2) { const f32x2 g2 = silu_pk((f32x2){v[e], v[e + 1]}); v[e] = g2.x; v[e + 1] = g2.y; }
;                         st_bf16((bf16*)(ws + WS_ZB) + (size_t)r * 2048 + (pn - 36) * 256 + cl, v);
;                     } else if (pn < 48) {
;                         st_bf16((bf16*)(ws + WS_QC) + (size_t)r * 1024 + (pn - 44) * 256 + cl, v);
;                     } else if (pn < 50) {
;                         const bool isv = pn == 49;
;                         st_bf16((bf16*)(ws + (isv ? WS_VC : WS_KC)) + (size_t)r * 256 + cl, v);
;                         if (r < PT) st_f32(out + (isv ? O_PV : O_PK) + ((size_t)l * PT + r) * 256 + cl, v);
;                         else st_f32(out + (isv ? O_SV : O_SK) + ((size_t)l * ST + (r - PT)) * 256 + cl, v);
;                     } else if (pn < 54) {
; #pragma unroll
;                         for (int e = 0; e < 8; e += 2) { const f32x2 g2 = silu_pk((f32x2){v[e], v[e + 1]}); v[e] = g2.x; v[e + 1] = g2.y; }
;                         st_bf16((bf16*)(ws + WS_ZC) + (size_t)r * 1024 + (pn - 50) * 256 + cl, v);
.LBB0_351:
	s_andn2_b64 vcc, exec, s[6:7]
	s_cbranch_vccnz .LBB0_353
	v_mul_f32_e64 v156, v108, s48
	v_mul_f32_e64 v157, v109, s48
	v_mul_f32_e64 v158, v110, s48
	v_mul_f32_e64 v159, v111, s48
	v_exp_f32_e32 v156, v156
	v_exp_f32_e32 v157, v157
	v_exp_f32_e32 v158, v158
	v_exp_f32_e32 v159, v159
	v_mul_f32_e64 v160, v104, s48
	v_mul_f32_e64 v161, v105, s48
	v_mul_f32_e64 v162, v106, s48
	v_mul_f32_e64 v163, v107, s48
	v_exp_f32_e32 v160, v160
	v_exp_f32_e32 v161, v161
	v_exp_f32_e32 v162, v162
	v_exp_f32_e32 v163, v163
	v_add_f32_e64 v156, v156, 1.0
	v_add_f32_e64 v157, v157, 1.0
	v_add_f32_e64 v158, v158, 1.0
	v_add_f32_e64 v159, v159, 1.0
	v_rcp_f32_e32 v156, v156
	v_rcp_f32_e32 v157, v157
	v_rcp_f32_e32 v158, v158
	v_rcp_f32_e32 v159, v159
	v_add_f32_e64 v160, v160, 1.0
	v_add_f32_e64 v161, v161, 1.0
	v_add_f32_e64 v162, v162, 1.0
	v_add_f32_e64 v163, v163, 1.0
	v_rcp_f32_e32 v160, v160
	v_rcp_f32_e32 v161, v161
	v_rcp_f32_e32 v162, v162
	v_rcp_f32_e32 v163, v163
	v_lshlrev_b32_e32 v136, 1, v140
	v_mul_f32_e64 v156, v108, v156
	v_mul_f32_e64 v157, v109, v157
	v_mul_f32_e64 v158, v110, v158
	v_mul_f32_e64 v159, v111, v159
	v_lshl_add_u64 v[164:165], v[114:115], 0, v[136:137]
	v_mul_f32_e64 v160, v104, v160
	v_mul_f32_e64 v161, v105, v161
	v_mul_f32_e64 v162, v106, v162
	v_mul_f32_e64 v163, v107, v163
	v_cvt_pk_bf16_f32 v156, v156, v157
	v_cvt_pk_bf16_f32 v157, v158, v159
	v_cvt_pk_bf16_f32 v158, v160, v161
	s_nop 0
	v_cvt_pk_bf16_f32 v159, v162, v163
	global_store_dwordx4 v[164:165], v[156:159], off

; __device__ __forceinline__ f32x2 silu_pk(f32x2 x) { const f32x2 t = x * -1.4426950408889634f; f32x2 e; e.x = __builtin_amdgcn_exp2f(t.x); e.y = __builtin_amdgcn_exp2f(t.y); e = e + 1.0f; f32x2 r; r.x = __builtin_amdgcn_rcpf(e.x); r.y = __builtin_amdgcn_rcpf(e.y); return x * r; }
;     __device__ __forceinline__ void operator()(const pg8::f32x4 (&acc)[2][2][4][2], const pg8::Unit& u, int wr, int wc, int fr, int fq) const {
;     ...
;                     } else if (pn < 44) {
; #pragma unroll
;                         for (int e = 0; e < 8; e += 2) { const f32x2 g2 = silu_pk((f32x2){v[e], v[e + 1]}); v[e] = g2.x; v[e + 1] = g2.y; }
;                         st_bf16((bf16*)(ws + WS_ZB) + (size_t)r * 2048 + (pn - 36) * 256 + cl, v);
;                     } else if (pn < 48) {
;                         st_bf16((bf16*)(ws + WS_QC) + (size_t)r * 1024 + (pn - 44) * 256 + cl, v);
;                     } else if (pn < 50) {
;                         const bool isv = pn == 49;
;                         st_bf16((bf16*)(ws + (isv ? WS_VC : WS_KC)) + (size_t)r * 256 + cl, v);
;                         if (r < PT) st_f32(out + (isv ? O_PV : O_PK) + ((size_t)l * PT + r) * 256 + cl, v);
;                         else st_f32(out + (isv ? O_SV : O_SK) + ((size_t)l * ST + (r - PT)) * 256 + cl, v);
;                     } else if (pn < 54) {
; #pragma unroll
;                         for (int e = 0; e < 8; e += 2) { const f32x2 g2 = silu_pk((f32x2){v[e], v[e + 1]}); v[e] = g2.x; v[e + 1] = g2.y; }
;                         st_bf16((bf16*)(ws + WS_ZC) + (size_t)r * 1024 + (pn - 50) * 256 + cl, v);
.LBB0_368:
	s_andn2_b64 vcc, exec, s[6:7]
	s_cbranch_vccnz .LBB0_370
	v_mul_f32_e64 v104, v100, s48
	v_mul_f32_e64 v105, v101, s48
	v_mul_f32_e64 v106, v102, s48
	v_mul_f32_e64 v107, v103, s48
	v_exp_f32_e32 v104, v104
	v_exp_f32_e32 v105, v105
	v_exp_f32_e32 v106, v106
	v_exp_f32_e32 v107, v107
	v_mul_f32_e64 v108, v96, s48
	v_mul_f32_e64 v109, v97, s48
	v_mul_f32_e64 v110, v98, s48
	v_mul_f32_e64 v111, v99, s48
	v_exp_f32_e32 v108, v108
	v_exp_f32_e32 v109, v109
	v_exp_f32_e32 v110, v110
	v_exp_f32_e32 v111, v111
	v_add_f32_e64 v104, v104, 1.0
	v_add_f32_e64 v105, v105, 1.0
	v_add_f32_e64 v106, v106, 1.0
	v_add_f32_e64 v107, v107, 1.0
	v_rcp_f32_e32 v104, v104
	v_rcp_f32_e32 v105, v105
	v_rcp_f32_e32 v106, v106
	v_rcp_f32_e32 v107, v107
	v_add_f32_e64 v108, v108, 1.0
	v_add_f32_e64 v109, v109, 1.0
	v_add_f32_e64 v110, v110, 1.0
	v_add_f32_e64 v111, v111, 1.0
	v_rcp_f32_e32 v108, v108
	v_rcp_f32_e32 v109, v109
	v_rcp_f32_e32 v110, v110
	v_rcp_f32_e32 v111, v111
	v_lshlrev_b32_e32 v136, 1, v142
	v_mul_f32_e64 v104, v100, v104
	v_mul_f32_e64 v105, v101, v105
	v_mul_f32_e64 v106, v102, v106
	v_mul_f32_e64 v107, v103, v107
	v_lshl_add_u64 v[124:125], v[124:125], 0, v[136:137]
	v_mul_f32_e64 v108, v96, v108
	v_mul_f32_e64 v109, v97, v109
	v_mul_f32_e64 v110, v98, v110
	v_mul_f32_e64 v111, v99, v111
	v_cvt_pk_bf16_f32 v104, v104, v105
	v_cvt_pk_bf16_f32 v105, v106, v107
	v_cvt_pk_bf16_f32 v106, v108, v109
	s_nop 0
	v_cvt_pk_bf16_f32 v107, v110, v111
	global_store_dwordx4 v[124:125], v[104:107], off

; __device__ __forceinline__ f32x2 silu_pk(f32x2 x) { const f32x2 t = x * -1.4426950408889634f; f32x2 e; e.x = __builtin_amdgcn_exp2f(t.x); e.y = __builtin_amdgcn_exp2f(t.y); e = e + 1.0f; f32x2 r; r.x = __builtin_amdgcn_rcpf(e.x); r.y = __builtin_amdgcn_rcpf(e.y); return x * r; }
;     __device__ __forceinline__ void operator()(const pg8::f32x4 (&acc)[2][2][4][2], const pg8::Unit& u, int wr, int wc, int fr, int fq) const {
;     ...
;                     } else if (pn < 44) {
; #pragma unroll
;                         for (int e = 0; e < 8; e += 2) { const f32x2 g2 = silu_pk((f32x2){v[e], v[e + 1]}); v[e] = g2.x; v[e + 1] = g2.y; }
;                         st_bf16((bf16*)(ws + WS_ZB) + (size_t)r * 2048 + (pn - 36) * 256 + cl, v);
;                     } else if (pn < 48) {
;                         st_bf16((bf16*)(ws + WS_QC) + (size_t)r * 1024 + (pn - 44) * 256 + cl, v);
;                     } else if (pn < 50) {
;                         const bool isv = pn == 49;
;                         st_bf16((bf16*)(ws + (isv ? WS_VC : WS_KC)) + (size_t)r * 256 + cl, v);
;                         if (r < PT) st_f32(out + (isv ? O_PV : O_PK) + ((size_t)l * PT + r) * 256 + cl, v);
;                         else st_f32(out + (isv ? O_SV : O_SK) + ((size_t)l * ST + (r - PT)) * 256 + cl, v);
;                     } else if (pn < 54) {
; #pragma unroll
;                         for (int e = 0; e < 8; e += 2) { const f32x2 g2 = silu_pk((f32x2){v[e], v[e + 1]}); v[e] = g2.x; v[e + 1] = g2.y; }
;                         st_bf16((bf16*)(ws + WS_ZC) + (size_t)r * 1024 + (pn - 50) * 256 + cl, v);
.LBB0_381:
	s_andn2_b64 vcc, exec, s[6:7]
	s_cbranch_vccnz .LBB0_383
	v_mul_f32_e64 v104, v100, s48
	v_mul_f32_e64 v105, v101, s48
	v_mul_f32_e64 v106, v102, s48
	v_mul_f32_e64 v107, v103, s48
	v_exp_f32_e32 v104, v104
	v_exp_f32_e32 v105, v105
	v_exp_f32_e32 v106, v106
	v_exp_f32_e32 v107, v107
	v_mul_f32_e64 v108, v96, s48
	v_mul_f32_e64 v109, v97, s48
	v_mul_f32_e64 v110, v98, s48
	v_mul_f32_e64 v111, v99, s48
	v_exp_f32_e32 v108, v108
	v_exp_f32_e32 v109, v109
	v_exp_f32_e32 v110, v110
	v_exp_f32_e32 v111, v111
	v_add_f32_e64 v104, v104, 1.0
	v_add_f32_e64 v105, v105, 1.0
	v_add_f32_e64 v106, v106, 1.0
	v_add_f32_e64 v107, v107, 1.0
	v_rcp_f32_e32 v104, v104
	v_rcp_f32_e32 v105, v105
	v_rcp_f32_e32 v106, v106
	v_rcp_f32_e32 v107, v107
	v_add_f32_e64 v108, v108, 1.0
	v_add_f32_e64 v109, v109, 1.0
	v_add_f32_e64 v110, v110, 1.0
	v_add_f32_e64 v111, v111, 1.0
	v_rcp_f32_e32 v108, v108
	v_rcp_f32_e32 v109, v109
	v_rcp_f32_e32 v110, v110
	v_rcp_f32_e32 v111, v111
	v_lshlrev_b32_e32 v136, 1, v142
	v_mul_f32_e64 v104, v100, v104
	v_mul_f32_e64 v105, v101, v105
	v_mul_f32_e64 v106, v102, v106
	v_mul_f32_e64 v107, v103, v107
	v_lshl_add_u64 v[114:115], v[114:115], 0, v[136:137]
	v_mul_f32_e64 v108, v96, v108
	v_mul_f32_e64 v109, v97, v109
	v_mul_f32_e64 v110, v98, v110
	v_mul_f32_e64 v111, v99, v111
	v_cvt_pk_bf16_f32 v104, v104, v105
	v_cvt_pk_bf16_f32 v105, v106, v107
	v_cvt_pk_bf16_f32 v106, v108, v109
	s_nop 0
	v_cvt_pk_bf16_f32 v107, v110, v111
	global_store_dwordx4 v[114:115], v[104:107], off

; __device__ __forceinline__ f32x2 silu_pk(f32x2 x) { const f32x2 t = x * -1.4426950408889634f; f32x2 e; e.x = __builtin_amdgcn_exp2f(t.x); e.y = __builtin_amdgcn_exp2f(t.y); e = e + 1.0f; f32x2 r; r.x = __builtin_amdgcn_rcpf(e.x); r.y = __builtin_amdgcn_rcpf(e.y); return x * r; }
; __device__ __forceinline__ f32x2 gelu_pk(f32x2 x) { const f32x2 x2 = x * x; const f32x2 t = (x2 * 0.044715f + 1.0f) * (x * -2.302208198144325f); f32x2 e; e.x = __builtin_amdgcn_exp2f(t.x); e.y = __builtin_amdgcn_exp2f(t.y); e = e + 1.0f; f32x2 r; r.x = __builtin_amdgcn_rcpf(e.x); r.y = __builtin_amd ...
;     __device__ __forceinline__ void operator()(const pg8::f32x4 (&acc)[2][2][4][2], const pg8::Unit& u, int wr, int wc, int fr, int fq) const {
;     ...
;                     if (pn < 12) {
;                         const int seg = pn >> 2, cc = (pn & 3) * 256 + cl;
;                         if (seg < 2) {
; #pragma unroll
;                             for (int e = 0; e < 8; e += 2) { const f32x2 g2 = gelu_pk((f32x2){v[e], v[e + 1]}); v[e] = g2.x; v[e + 1] = g2.y; }
;                         } else {
; #pragma unroll
;                             for (int e = 0; e < 8; e += 2) { const f32x2 g2 = silu_pk((f32x2){v[e], v[e + 1]}); v[e] = g2.x; v[e + 1] = g2.y; }
;                         }
;                         bf16* base = (bf16*)(ws + (seg == 0 ? WS_UA : seg == 1 ? WS_VA : WS_ZA));
;                         st_bf16(base + (size_t)r * 1024 + cc, v);
.LBB0_390:
	s_andn2_b64 vcc, exec, s[16:17]
	s_mov_b64 s[96:97], -1
	s_cbranch_vccnz .LBB0_392
	v_mul_f32_e64 v158, v110, s48
	v_mul_f32_e64 v159, v111, s48
	v_mul_f32_e64 v156, v108, s48
	v_mul_f32_e64 v157, v109, s48
	v_exp_f32_e32 v158, v158
	v_exp_f32_e32 v159, v159
	v_mul_f32_e64 v160, v104, s48
	v_mul_f32_e64 v161, v105, s48
	v_exp_f32_e32 v156, v156
	v_exp_f32_e32 v157, v157
	v_exp_f32_e32 v160, v160
	v_exp_f32_e32 v161, v161
	v_add_f32_e64 v158, v158, 1.0
	v_add_f32_e64 v159, v159, 1.0
	v_add_f32_e64 v156, v156, 1.0
	v_add_f32_e64 v157, v157, 1.0
	v_rcp_f32_e32 v162, v158
	v_rcp_f32_e32 v163, v159
	v_add_f32_e64 v158, v160, 1.0
	v_add_f32_e64 v159, v161, 1.0
	v_rcp_f32_e32 v156, v156
	v_rcp_f32_e32 v157, v157
	v_rcp_f32_e32 v160, v158
	v_rcp_f32_e32 v161, v159
	s_mov_b64 s[96:97], 0
	v_mul_f32_e64 v158, v108, v156
	v_mul_f32_e64 v159, v109, v157
	v_mul_f32_e64 v156, v110, v162
	v_mul_f32_e64 v157, v111, v163
	v_mul_f32_e64 v160, v104, v160
	v_mul_f32_e64 v161, v105, v161
	v_mul_f32_e64 v162, v106, s48
	v_mul_f32_e64 v163, v107, s48
.LBB0_392:
	s_andn2_b64 vcc, exec, s[96:97]
	s_cbranch_vccnz .LBB0_394
	v_mul_f32_e64 v158, v108, v108
	v_mul_f32_e64 v159, v109, v109
	v_mul_f32_e64 v160, v108, s52
	v_mul_f32_e64 v161, v109, s52
	v_fma_f32 v158, v158, s50, 1.0
	v_fma_f32 v159, v159, s50, 1.0
	v_mul_f32_e64 v156, v110, v110
	v_mul_f32_e64 v157, v111, v111
	v_mul_f32_e64 v158, v160, v158
	v_mul_f32_e64 v159, v161, v159
	v_mul_f32_e64 v160, v104, s52
	v_mul_f32_e64 v161, v105, s52
	v_exp_f32_e32 v158, v158
	v_exp_f32_e32 v159, v159
	s_nop 0
	v_add_f32_e64 v158, v158, 1.0
	v_add_f32_e64 v159, v159, 1.0
	s_nop 0
	v_rcp_f32_e32 v158, v158
	v_rcp_f32_e32 v159, v159
	s_nop 0
	v_mul_f32_e64 v158, v108, v158
	v_mul_f32_e64 v159, v109, v159
	v_fma_f32 v108, v156, s50, 1.0
	v_fma_f32 v109, v157, s50, 1.0
	v_mul_f32_e64 v156, v110, s52
	v_mul_f32_e64 v157, v111, s52
	s_nop 0
	v_mul_f32_e64 v108, v156, v108
	v_mul_f32_e64 v109, v157, v109
	s_nop 0
	v_exp_f32_e32 v108, v108
	v_exp_f32_e32 v109, v109
	s_nop 0
	v_add_f32_e64 v108, v108, 1.0
	v_add_f32_e64 v109, v109, 1.0
	s_nop 0
	v_rcp_f32_e32 v108, v108
	v_rcp_f32_e32 v109, v109
	s_nop 0
	v_mul_f32_e64 v156, v110, v108
	v_mul_f32_e64 v157, v111, v109
	v_mul_f32_e64 v110, v104, v104
	v_mul_f32_e64 v111, v105, v105
	v_mul_f32_e64 v108, v106, v106
	v_mul_f32_e64 v109, v107, v107
	v_fma_f32 v110, v110, s50, 1.0
	v_fma_f32 v111, v111, s50, 1.0
	s_nop 0
	v_mul_f32_e64 v110, v160, v110
	v_mul_f32_e64 v111, v161, v111
	s_nop 0
	v_exp_f32_e32 v110, v110
	v_exp_f32_e32 v111, v111
	s_nop 0
	v_add_f32_e64 v110, v110, 1.0
	v_add_f32_e64 v111, v111, 1.0
	s_nop 0
	v_rcp_f32_e32 v110, v110
	v_rcp_f32_e32 v111, v111
	s_nop 0
	v_mul_f32_e64 v160, v104, v110
	v_mul_f32_e64 v161, v105, v111
	v_fma_f32 v104, v108, s50, 1.0
	v_fma_f32 v105, v109, s50, 1.0
	v_mul_f32_e64 v108, v106, s52
	v_mul_f32_e64 v109, v107, s52
	s_nop 0
	v_mul_f32_e64 v162, v108, v104
	v_mul_f32_e64 v163, v109, v105
.LBB0_394:
	s_nop 0
	v_exp_f32_e32 v104, v162
	v_exp_f32_e32 v105, v163
	v_or_b32_e32 v110, s26, v140
	v_lshlrev_b32_e32 v136, 1, v110
	v_lshl_add_u64 v[110:111], v[126:127], 0, v[136:137]
	v_add_f32_e64 v104, v104, 1.0
	v_add_f32_e64 v105, v105, 1.0
	s_nop 0
	v_rcp_f32_e32 v104, v104
	v_rcp_f32_e32 v105, v105
	s_nop 0
	v_mul_f32_e64 v108, v106, v104
	v_mul_f32_e64 v109, v107, v105
	v_cvt_pk_bf16_f32 v104, v158, v159
	v_cvt_pk_bf16_f32 v105, v156, v157
	v_cvt_pk_bf16_f32 v106, v160, v161
	s_nop 0
	v_cvt_pk_bf16_f32 v107, v108, v109
	global_store_dwordx4 v[110:111], v[104:107], off
	s_and_b64 vcc, exec, s[10:11]
	s_mov_b64 s[6:7], -1
	s_cbranch_vccz .LBB0_360

; __device__ __forceinline__ f32x2 silu_pk(f32x2 x) { const f32x2 t = x * -1.4426950408889634f; f32x2 e; e.x = __builtin_amdgcn_exp2f(t.x); e.y = __builtin_amdgcn_exp2f(t.y); e = e + 1.0f; f32x2 r; r.x = __builtin_amdgcn_rcpf(e.x); r.y = __builtin_amdgcn_rcpf(e.y); return x * r; }
; __device__ __forceinline__ f32x2 gelu_pk(f32x2 x) { const f32x2 x2 = x * x; const f32x2 t = (x2 * 0.044715f + 1.0f) * (x * -2.302208198144325f); f32x2 e; e.x = __builtin_amdgcn_exp2f(t.x); e.y = __builtin_amdgcn_exp2f(t.y); e = e + 1.0f; f32x2 r; r.x = __builtin_amdgcn_rcpf(e.x); r.y = __builtin_amd ...
;     __device__ __forceinline__ void operator()(const pg8::f32x4 (&acc)[2][2][4][2], const pg8::Unit& u, int wr, int wc, int fr, int fq) const {
;     ...
;                     if (pn < 12) {
;                         const int seg = pn >> 2, cc = (pn & 3) * 256 + cl;
;                         if (seg < 2) {
; #pragma unroll
;                             for (int e = 0; e < 8; e += 2) { const f32x2 g2 = gelu_pk((f32x2){v[e], v[e + 1]}); v[e] = g2.x; v[e + 1] = g2.y; }
;                         } else {
; #pragma unroll
;                             for (int e = 0; e < 8; e += 2) { const f32x2 g2 = silu_pk((f32x2){v[e], v[e + 1]}); v[e] = g2.x; v[e + 1] = g2.y; }
;                         }
;                         bf16* base = (bf16*)(ws + (seg == 0 ? WS_UA : seg == 1 ? WS_VA : WS_ZA));
;                         st_bf16(base + (size_t)r * 1024 + cc, v);
.LBB0_396:
	s_andn2_b64 vcc, exec, s[16:17]
	s_mov_b64 s[0:1], -1
	s_cbranch_vccnz .LBB0_398
	v_mul_f32_e64 v104, v100, s48
	v_mul_f32_e64 v105, v101, s48
	v_mul_f32_e64 v106, v102, s48
	v_mul_f32_e64 v107, v103, s48
	v_mul_f32_e64 v108, v96, s48
	v_mul_f32_e64 v109, v97, s48
	v_exp_f32_e32 v104, v104
	v_exp_f32_e32 v105, v105
	v_exp_f32_e32 v106, v106
	v_exp_f32_e32 v107, v107
	v_exp_f32_e32 v108, v108
	v_exp_f32_e32 v109, v109
	v_add_f32_e64 v104, v104, 1.0
	v_add_f32_e64 v105, v105, 1.0
	v_add_f32_e64 v106, v106, 1.0
	v_add_f32_e64 v107, v107, 1.0
	v_rcp_f32_e32 v104, v104
	v_add_f32_e64 v108, v108, 1.0
	v_add_f32_e64 v109, v109, 1.0
	v_rcp_f32_e32 v105, v105
	v_rcp_f32_e32 v106, v106
	v_rcp_f32_e32 v107, v107
	v_rcp_f32_e32 v108, v108
	v_rcp_f32_e32 v109, v109
	v_mul_f32_e64 v104, v100, v104
	v_mul_f32_e64 v105, v101, v105
	v_mul_f32_e64 v106, v102, v106
	v_mul_f32_e64 v107, v103, v107
	v_mul_f32_e64 v110, v98, s48
	v_mul_f32_e64 v111, v99, s48
	v_mul_f32_e64 v108, v96, v108
	v_mul_f32_e64 v109, v97, v109
	s_mov_b64 s[0:1], 0
.LBB0_398:
	s_andn2_b64 vcc, exec, s[0:1]
	s_cbranch_vccnz .LBB0_400
	v_mul_f32_e64 v104, v100, v100
	v_mul_f32_e64 v105, v101, v101
	v_mul_f32_e64 v108, v100, s52
	v_mul_f32_e64 v109, v101, s52
	v_fma_f32 v104, v104, s50, 1.0
	v_fma_f32 v105, v105, s50, 1.0
	v_mul_f32_e64 v106, v102, v102
	v_mul_f32_e64 v107, v103, v103
	v_mul_f32_e64 v104, v108, v104
	v_mul_f32_e64 v105, v109, v105
	v_mul_f32_e64 v108, v96, s52
	v_mul_f32_e64 v109, v97, s52
	v_exp_f32_e32 v104, v104
	v_exp_f32_e32 v105, v105
	s_nop 0
	v_add_f32_e64 v104, v104, 1.0
	v_add_f32_e64 v105, v105, 1.0
	s_nop 0
	v_rcp_f32_e32 v104, v104
	v_rcp_f32_e32 v105, v105
	s_nop 0
	v_mul_f32_e64 v104, v100, v104
	v_mul_f32_e64 v105, v101, v105
	v_fma_f32 v100, v106, s50, 1.0
	v_fma_f32 v101, v107, s50, 1.0
	v_mul_f32_e64 v106, v102, s52
	v_mul_f32_e64 v107, v103, s52
	s_nop 0
	v_mul_f32_e64 v100, v106, v100
	v_mul_f32_e64 v101, v107, v101
	s_nop 0
	v_exp_f32_e32 v100, v100
	v_exp_f32_e32 v101, v101
	s_nop 0
	v_add_f32_e64 v100, v100, 1.0
	v_add_f32_e64 v101, v101, 1.0
	s_nop 0
	v_rcp_f32_e32 v100, v100
	v_rcp_f32_e32 v101, v101
	s_nop 0
	v_mul_f32_e64 v106, v102, v100
	v_mul_f32_e64 v107, v103, v101
	v_mul_f32_e64 v102, v96, v96
	v_mul_f32_e64 v103, v97, v97
	v_mul_f32_e64 v100, v98, v98
	v_mul_f32_e64 v101, v99, v99
	v_fma_f32 v102, v102, s50, 1.0
	v_fma_f32 v103, v103, s50, 1.0
	s_nop 0
	v_mul_f32_e64 v102, v108, v102
	v_mul_f32_e64 v103, v109, v103
	s_nop 0
	v_exp_f32_e32 v102, v102
	v_exp_f32_e32 v103, v103
	s_nop 0
	v_add_f32_e64 v102, v102, 1.0
	v_add_f32_e64 v103, v103, 1.0
	s_nop 0
	v_rcp_f32_e32 v102, v102
	v_rcp_f32_e32 v103, v103
	s_nop 0
	v_mul_f32_e64 v108, v96, v102
	v_mul_f32_e64 v109, v97, v103
	v_fma_f32 v96, v100, s50, 1.0
	v_fma_f32 v97, v101, s50, 1.0
	v_mul_f32_e64 v100, v98, s52
	v_mul_f32_e64 v101, v99, s52
	s_nop 0
	v_mul_f32_e64 v110, v100, v96
	v_mul_f32_e64 v111, v101, v97
.LBB0_400:
	s_nop 0
	v_exp_f32_e32 v96, v110
	v_exp_f32_e32 v97, v111
	v_add_lshl_u32 v136, s26, v140, 1
	v_lshl_add_u64 v[102:103], v[126:127], 0, v[136:137]
	v_add_f32_e64 v96, v96, 1.0
	v_add_f32_e64 v97, v97, 1.0
	s_nop 0
	v_rcp_f32_e32 v96, v96
	v_rcp_f32_e32 v97, v97
	s_nop 0
	v_mul_f32_e64 v100, v98, v96
	v_mul_f32_e64 v101, v99, v97
	v_cvt_pk_bf16_f32 v96, v104, v105
	v_cvt_pk_bf16_f32 v97, v106, v107
	v_cvt_pk_bf16_f32 v98, v108, v109
	s_nop 0
	v_cvt_pk_bf16_f32 v99, v100, v101
	global_store_dwordx4 v[102:103], v[96:99], off offset:256

; __device__ __forceinline__ f32x2 silu_pk(f32x2 x) { const f32x2 t = x * -1.4426950408889634f; f32x2 e; e.x = __builtin_amdgcn_exp2f(t.x); e.y = __builtin_amdgcn_exp2f(t.y); e = e + 1.0f; f32x2 r; r.x = __builtin_amdgcn_rcpf(e.x); r.y = __builtin_amdgcn_rcpf(e.y); return x * r; }
;     __device__ __forceinline__ void operator()(const pg8::f32x4 (&acc)[2][2][4][2], const pg8::Unit& u, int wr, int wc, int fr, int fq) const {
;     ...
;                     } else if (pn < 44) {
; #pragma unroll
;                         for (int e = 0; e < 8; e += 2) { const f32x2 g2 = silu_pk((f32x2){v[e], v[e + 1]}); v[e] = g2.x; v[e + 1] = g2.y; }
;                         st_bf16((bf16*)(ws + WS_ZB) + (size_t)r * 2048 + (pn - 36) * 256 + cl, v);
;                     } else if (pn < 48) {
;                         st_bf16((bf16*)(ws + WS_QC) + (size_t)r * 1024 + (pn - 44) * 256 + cl, v);
;                     } else if (pn < 50) {
;                         const bool isv = pn == 49;
;                         st_bf16((bf16*)(ws + (isv ? WS_VC : WS_KC)) + (size_t)r * 256 + cl, v);
;                         if (r < PT) st_f32(out + (isv ? O_PV : O_PK) + ((size_t)l * PT + r) * 256 + cl, v);
;                         else st_f32(out + (isv ? O_SV : O_SK) + ((size_t)l * ST + (r - PT)) * 256 + cl, v);
;                     } else if (pn < 54) {
; #pragma unroll
;                         for (int e = 0; e < 8; e += 2) { const f32x2 g2 = silu_pk((f32x2){v[e], v[e + 1]}); v[e] = g2.x; v[e + 1] = g2.y; }
;                         st_bf16((bf16*)(ws + WS_ZC) + (size_t)r * 1024 + (pn - 50) * 256 + cl, v);
.LBB0_427:
	s_andn2_b64 vcc, exec, s[6:7]
	s_cbranch_vccnz .LBB0_429
	v_mul_f32_e64 v114, v92, s48
	v_mul_f32_e64 v115, v93, s48
	v_mul_f32_e64 v116, v94, s48
	v_mul_f32_e64 v117, v95, s48
	v_exp_f32_e32 v114, v114
	v_exp_f32_e32 v115, v115
	v_exp_f32_e32 v116, v116
	v_exp_f32_e32 v117, v117
	v_mul_f32_e64 v118, v88, s48
	v_mul_f32_e64 v119, v89, s48
	v_mul_f32_e64 v120, v90, s48
	v_mul_f32_e64 v121, v91, s48
	v_exp_f32_e32 v118, v118
	v_exp_f32_e32 v119, v119
	v_exp_f32_e32 v120, v120
	v_exp_f32_e32 v121, v121
	v_add_f32_e64 v114, v114, 1.0
	v_add_f32_e64 v115, v115, 1.0
	v_add_f32_e64 v116, v116, 1.0
	v_add_f32_e64 v117, v117, 1.0
	v_rcp_f32_e32 v114, v114
	v_rcp_f32_e32 v115, v115
	v_rcp_f32_e32 v116, v116
	v_rcp_f32_e32 v117, v117
	v_add_f32_e64 v118, v118, 1.0
	v_add_f32_e64 v119, v119, 1.0
	v_add_f32_e64 v120, v120, 1.0
	v_add_f32_e64 v121, v121, 1.0
	v_rcp_f32_e32 v118, v118
	v_rcp_f32_e32 v119, v119
	v_rcp_f32_e32 v120, v120
	v_rcp_f32_e32 v121, v121
	v_lshlrev_b32_e32 v136, 1, v140
	v_mul_f32_e64 v114, v92, v114
	v_mul_f32_e64 v115, v93, v115
	v_mul_f32_e64 v116, v94, v116
	v_mul_f32_e64 v117, v95, v117
	v_lshl_add_u64 v[124:125], v[108:109], 0, v[136:137]
	v_mul_f32_e64 v118, v88, v118
	v_mul_f32_e64 v119, v89, v119
	v_mul_f32_e64 v120, v90, v120
	v_mul_f32_e64 v121, v91, v121
	v_cvt_pk_bf16_f32 v114, v114, v115
	v_cvt_pk_bf16_f32 v115, v116, v117
	v_cvt_pk_bf16_f32 v116, v118, v119
	s_nop 0
	v_cvt_pk_bf16_f32 v117, v120, v121
	global_store_dwordx4 v[124:125], v[114:117], off

; __device__ __forceinline__ f32x2 silu_pk(f32x2 x) { const f32x2 t = x * -1.4426950408889634f; f32x2 e; e.x = __builtin_amdgcn_exp2f(t.x); e.y = __builtin_amdgcn_exp2f(t.y); e = e + 1.0f; f32x2 r; r.x = __builtin_amdgcn_rcpf(e.x); r.y = __builtin_amdgcn_rcpf(e.y); return x * r; }
;     __device__ __forceinline__ void operator()(const pg8::f32x4 (&acc)[2][2][4][2], const pg8::Unit& u, int wr, int wc, int fr, int fq) const {
;     ...
;                     } else if (pn < 44) {
; #pragma unroll
;                         for (int e = 0; e < 8; e += 2) { const f32x2 g2 = silu_pk((f32x2){v[e], v[e + 1]}); v[e] = g2.x; v[e + 1] = g2.y; }
;                         st_bf16((bf16*)(ws + WS_ZB) + (size_t)r * 2048 + (pn - 36) * 256 + cl, v);
;                     } else if (pn < 48) {
;                         st_bf16((bf16*)(ws + WS_QC) + (size_t)r * 1024 + (pn - 44) * 256 + cl, v);
;                     } else if (pn < 50) {
;                         const bool isv = pn == 49;
;                         st_bf16((bf16*)(ws + (isv ? WS_VC : WS_KC)) + (size_t)r * 256 + cl, v);
;                         if (r < PT) st_f32(out + (isv ? O_PV : O_PK) + ((size_t)l * PT + r) * 256 + cl, v);
;                         else st_f32(out + (isv ? O_SV : O_SK) + ((size_t)l * ST + (r - PT)) * 256 + cl, v);
;                     } else if (pn < 54) {
; #pragma unroll
;                         for (int e = 0; e < 8; e += 2) { const f32x2 g2 = silu_pk((f32x2){v[e], v[e + 1]}); v[e] = g2.x; v[e + 1] = g2.y; }
;                         st_bf16((bf16*)(ws + WS_ZC) + (size_t)r * 1024 + (pn - 50) * 256 + cl, v);
.LBB0_440:
	s_andn2_b64 vcc, exec, s[6:7]
	s_cbranch_vccnz .LBB0_442
	v_mul_f32_e64 v114, v92, s48
	v_mul_f32_e64 v115, v93, s48
	v_mul_f32_e64 v116, v94, s48
	v_mul_f32_e64 v117, v95, s48
	v_exp_f32_e32 v114, v114
	v_exp_f32_e32 v115, v115
	v_exp_f32_e32 v116, v116
	v_exp_f32_e32 v117, v117
	v_mul_f32_e64 v118, v88, s48
	v_mul_f32_e64 v119, v89, s48
	v_mul_f32_e64 v120, v90, s48
	v_mul_f32_e64 v121, v91, s48
	v_exp_f32_e32 v118, v118
	v_exp_f32_e32 v119, v119
	v_exp_f32_e32 v120, v120
	v_exp_f32_e32 v121, v121
	v_add_f32_e64 v114, v114, 1.0
	v_add_f32_e64 v115, v115, 1.0
	v_add_f32_e64 v116, v116, 1.0
	v_add_f32_e64 v117, v117, 1.0
	v_rcp_f32_e32 v114, v114
	v_rcp_f32_e32 v115, v115
	v_rcp_f32_e32 v116, v116
	v_rcp_f32_e32 v117, v117
	v_add_f32_e64 v118, v118, 1.0
	v_add_f32_e64 v119, v119, 1.0
	v_add_f32_e64 v120, v120, 1.0
	v_add_f32_e64 v121, v121, 1.0
	v_rcp_f32_e32 v118, v118
	v_rcp_f32_e32 v119, v119
	v_rcp_f32_e32 v120, v120
	v_rcp_f32_e32 v121, v121
	v_lshlrev_b32_e32 v136, 1, v140
	v_mul_f32_e64 v114, v92, v114
	v_mul_f32_e64 v115, v93, v115
	v_mul_f32_e64 v116, v94, v116
	v_mul_f32_e64 v117, v95, v117
	v_lshl_add_u64 v[124:125], v[98:99], 0, v[136:137]
	v_mul_f32_e64 v118, v88, v118
	v_mul_f32_e64 v119, v89, v119
	v_mul_f32_e64 v120, v90, v120
	v_mul_f32_e64 v121, v91, v121
	v_cvt_pk_bf16_f32 v114, v114, v115
	v_cvt_pk_bf16_f32 v115, v116, v117
	v_cvt_pk_bf16_f32 v116, v118, v119
	s_nop 0
	v_cvt_pk_bf16_f32 v117, v120, v121
	global_store_dwordx4 v[124:125], v[114:117], off

; __device__ __forceinline__ f32x2 silu_pk(f32x2 x) { const f32x2 t = x * -1.4426950408889634f; f32x2 e; e.x = __builtin_amdgcn_exp2f(t.x); e.y = __builtin_amdgcn_exp2f(t.y); e = e + 1.0f; f32x2 r; r.x = __builtin_amdgcn_rcpf(e.x); r.y = __builtin_amdgcn_rcpf(e.y); return x * r; }
;     __device__ __forceinline__ void operator()(const pg8::f32x4 (&acc)[2][2][4][2], const pg8::Unit& u, int wr, int wc, int fr, int fq) const {
;     ...
;                     } else if (pn < 44) {
; #pragma unroll
;                         for (int e = 0; e < 8; e += 2) { const f32x2 g2 = silu_pk((f32x2){v[e], v[e + 1]}); v[e] = g2.x; v[e + 1] = g2.y; }
;                         st_bf16((bf16*)(ws + WS_ZB) + (size_t)r * 2048 + (pn - 36) * 256 + cl, v);
;                     } else if (pn < 48) {
;                         st_bf16((bf16*)(ws + WS_QC) + (size_t)r * 1024 + (pn - 44) * 256 + cl, v);
;                     } else if (pn < 50) {
;                         const bool isv = pn == 49;
;                         st_bf16((bf16*)(ws + (isv ? WS_VC : WS_KC)) + (size_t)r * 256 + cl, v);
;                         if (r < PT) st_f32(out + (isv ? O_PV : O_PK) + ((size_t)l * PT + r) * 256 + cl, v);
;                         else st_f32(out + (isv ? O_SV : O_SK) + ((size_t)l * ST + (r - PT)) * 256 + cl, v);
;                     } else if (pn < 54) {
; #pragma unroll
;                         for (int e = 0; e < 8; e += 2) { const f32x2 g2 = silu_pk((f32x2){v[e], v[e + 1]}); v[e] = g2.x; v[e + 1] = g2.y; }
;                         st_bf16((bf16*)(ws + WS_ZC) + (size_t)r * 1024 + (pn - 50) * 256 + cl, v);
.LBB0_457:
	s_andn2_b64 vcc, exec, s[6:7]
	s_cbranch_vccnz .LBB0_459
	v_mul_f32_e64 v88, v84, s48
	v_mul_f32_e64 v89, v85, s48
	v_mul_f32_e64 v90, v86, s48
	v_mul_f32_e64 v91, v87, s48
	v_exp_f32_e32 v88, v88
	v_exp_f32_e32 v89, v89
	v_exp_f32_e32 v90, v90
	v_exp_f32_e32 v91, v91
	v_mul_f32_e64 v92, v80, s48
	v_mul_f32_e64 v93, v81, s48
	v_mul_f32_e64 v94, v82, s48
	v_mul_f32_e64 v95, v83, s48
	v_exp_f32_e32 v92, v92
	v_exp_f32_e32 v93, v93
	v_exp_f32_e32 v94, v94
	v_exp_f32_e32 v95, v95
	v_add_f32_e64 v88, v88, 1.0
	v_add_f32_e64 v89, v89, 1.0
	v_add_f32_e64 v90, v90, 1.0
	v_add_f32_e64 v91, v91, 1.0
	v_rcp_f32_e32 v88, v88
	v_rcp_f32_e32 v89, v89
	v_rcp_f32_e32 v90, v90
	v_rcp_f32_e32 v91, v91
	v_add_f32_e64 v92, v92, 1.0
	v_add_f32_e64 v93, v93, 1.0
	v_add_f32_e64 v94, v94, 1.0
	v_add_f32_e64 v95, v95, 1.0
	v_rcp_f32_e32 v92, v92
	v_rcp_f32_e32 v93, v93
	v_rcp_f32_e32 v94, v94
	v_rcp_f32_e32 v95, v95
	v_lshlrev_b32_e32 v136, 1, v142
	v_mul_f32_e64 v88, v84, v88
	v_mul_f32_e64 v89, v85, v89
	v_mul_f32_e64 v90, v86, v90
	v_mul_f32_e64 v91, v87, v91
	v_lshl_add_u64 v[108:109], v[108:109], 0, v[136:137]
	v_mul_f32_e64 v92, v80, v92
	v_mul_f32_e64 v93, v81, v93
	v_mul_f32_e64 v94, v82, v94
	v_mul_f32_e64 v95, v83, v95
	v_cvt_pk_bf16_f32 v88, v88, v89
	v_cvt_pk_bf16_f32 v89, v90, v91
	v_cvt_pk_bf16_f32 v90, v92, v93
	s_nop 0
	v_cvt_pk_bf16_f32 v91, v94, v95
	global_store_dwordx4 v[108:109], v[88:91], off

; __device__ __forceinline__ f32x2 silu_pk(f32x2 x) { const f32x2 t = x * -1.4426950408889634f; f32x2 e; e.x = __builtin_amdgcn_exp2f(t.x); e.y = __builtin_amdgcn_exp2f(t.y); e = e + 1.0f; f32x2 r; r.x = __builtin_amdgcn_rcpf(e.x); r.y = __builtin_amdgcn_rcpf(e.y); return x * r; }
;     __device__ __forceinline__ void operator()(const pg8::f32x4 (&acc)[2][2][4][2], const pg8::Unit& u, int wr, int wc, int fr, int fq) const {
;     ...
;                     } else if (pn < 44) {
; #pragma unroll
;                         for (int e = 0; e < 8; e += 2) { const f32x2 g2 = silu_pk((f32x2){v[e], v[e + 1]}); v[e] = g2.x; v[e + 1] = g2.y; }
;                         st_bf16((bf16*)(ws + WS_ZB) + (size_t)r * 2048 + (pn - 36) * 256 + cl, v);
;                     } else if (pn < 48) {
;                         st_bf16((bf16*)(ws + WS_QC) + (size_t)r * 1024 + (pn - 44) * 256 + cl, v);
;                     } else if (pn < 50) {
;                         const bool isv = pn == 49;
;                         st_bf16((bf16*)(ws + (isv ? WS_VC : WS_KC)) + (size_t)r * 256 + cl, v);
;                         if (r < PT) st_f32(out + (isv ? O_PV : O_PK) + ((size_t)l * PT + r) * 256 + cl, v);
;                         else st_f32(out + (isv ? O_SV : O_SK) + ((size_t)l * ST + (r - PT)) * 256 + cl, v);
;                     } else if (pn < 54) {
; #pragma unroll
;                         for (int e = 0; e < 8; e += 2) { const f32x2 g2 = silu_pk((f32x2){v[e], v[e + 1]}); v[e] = g2.x; v[e + 1] = g2.y; }
;                         st_bf16((bf16*)(ws + WS_ZC) + (size_t)r * 1024 + (pn - 50) * 256 + cl, v);
.LBB0_470:
	s_andn2_b64 vcc, exec, s[6:7]
	s_cbranch_vccnz .LBB0_472
	v_mul_f32_e64 v88, v84, s48
	v_mul_f32_e64 v89, v85, s48
	v_mul_f32_e64 v90, v86, s48
	v_mul_f32_e64 v91, v87, s48
	v_exp_f32_e32 v88, v88
	v_exp_f32_e32 v89, v89
	v_exp_f32_e32 v90, v90
	v_exp_f32_e32 v91, v91
	v_mul_f32_e64 v92, v80, s48
	v_mul_f32_e64 v93, v81, s48
	v_mul_f32_e64 v94, v82, s48
	v_mul_f32_e64 v95, v83, s48
	v_exp_f32_e32 v92, v92
	v_exp_f32_e32 v93, v93
	v_exp_f32_e32 v94, v94
	v_exp_f32_e32 v95, v95
	v_add_f32_e64 v88, v88, 1.0
	v_add_f32_e64 v89, v89, 1.0
	v_add_f32_e64 v90, v90, 1.0
	v_add_f32_e64 v91, v91, 1.0
	v_rcp_f32_e32 v88, v88
	v_rcp_f32_e32 v89, v89
	v_rcp_f32_e32 v90, v90
	v_rcp_f32_e32 v91, v91
	v_add_f32_e64 v92, v92, 1.0
	v_add_f32_e64 v93, v93, 1.0
	v_add_f32_e64 v94, v94, 1.0
	v_add_f32_e64 v95, v95, 1.0
	v_rcp_f32_e32 v92, v92
	v_rcp_f32_e32 v93, v93
	v_rcp_f32_e32 v94, v94
	v_rcp_f32_e32 v95, v95
	v_lshlrev_b32_e32 v136, 1, v142
	v_mul_f32_e64 v88, v84, v88
	v_mul_f32_e64 v89, v85, v89
	v_mul_f32_e64 v90, v86, v90
	v_mul_f32_e64 v91, v87, v91
	v_lshl_add_u64 v[98:99], v[98:99], 0, v[136:137]
	v_mul_f32_e64 v92, v80, v92
	v_mul_f32_e64 v93, v81, v93
	v_mul_f32_e64 v94, v82, v94
	v_mul_f32_e64 v95, v83, v95
	v_cvt_pk_bf16_f32 v88, v88, v89
	v_cvt_pk_bf16_f32 v89, v90, v91
	v_cvt_pk_bf16_f32 v90, v92, v93
	s_nop 0
	v_cvt_pk_bf16_f32 v91, v94, v95
	global_store_dwordx4 v[98:99], v[88:91], off

; __device__ __forceinline__ f32x2 silu_pk(f32x2 x) { const f32x2 t = x * -1.4426950408889634f; f32x2 e; e.x = __builtin_amdgcn_exp2f(t.x); e.y = __builtin_amdgcn_exp2f(t.y); e = e + 1.0f; f32x2 r; r.x = __builtin_amdgcn_rcpf(e.x); r.y = __builtin_amdgcn_rcpf(e.y); return x * r; }
; __device__ __forceinline__ f32x2 gelu_pk(f32x2 x) { const f32x2 x2 = x * x; const f32x2 t = (x2 * 0.044715f + 1.0f) * (x * -2.302208198144325f); f32x2 e; e.x = __builtin_amdgcn_exp2f(t.x); e.y = __builtin_amdgcn_exp2f(t.y); e = e + 1.0f; f32x2 r; r.x = __builtin_amdgcn_rcpf(e.x); r.y = __builtin_amd ...
;     __device__ __forceinline__ void operator()(const pg8::f32x4 (&acc)[2][2][4][2], const pg8::Unit& u, int wr, int wc, int fr, int fq) const {
;     ...
;                     if (pn < 12) {
;                         const int seg = pn >> 2, cc = (pn & 3) * 256 + cl;
;                         if (seg < 2) {
; #pragma unroll
;                             for (int e = 0; e < 8; e += 2) { const f32x2 g2 = gelu_pk((f32x2){v[e], v[e + 1]}); v[e] = g2.x; v[e + 1] = g2.y; }
;                         } else {
; #pragma unroll
;                             for (int e = 0; e < 8; e += 2) { const f32x2 g2 = silu_pk((f32x2){v[e], v[e + 1]}); v[e] = g2.x; v[e + 1] = g2.y; }
;                         }
;                         bf16* base = (bf16*)(ws + (seg == 0 ? WS_UA : seg == 1 ? WS_VA : WS_ZA));
;                         st_bf16(base + (size_t)r * 1024 + cc, v);
.LBB0_479:
	s_andn2_b64 vcc, exec, s[16:17]
	s_mov_b64 s[96:97], -1
	s_cbranch_vccnz .LBB0_481
	v_mul_f32_e64 v116, v94, s48
	v_mul_f32_e64 v117, v95, s48
	v_mul_f32_e64 v114, v92, s48
	v_mul_f32_e64 v115, v93, s48
	v_exp_f32_e32 v116, v116
	v_exp_f32_e32 v117, v117
	v_mul_f32_e64 v118, v88, s48
	v_mul_f32_e64 v119, v89, s48
	v_exp_f32_e32 v114, v114
	v_exp_f32_e32 v115, v115
	v_exp_f32_e32 v118, v118
	v_exp_f32_e32 v119, v119
	v_add_f32_e64 v116, v116, 1.0
	v_add_f32_e64 v117, v117, 1.0
	v_add_f32_e64 v114, v114, 1.0
	v_add_f32_e64 v115, v115, 1.0
	v_rcp_f32_e32 v120, v116
	v_rcp_f32_e32 v121, v117
	v_add_f32_e64 v116, v118, 1.0
	v_add_f32_e64 v117, v119, 1.0
	v_rcp_f32_e32 v114, v114
	v_rcp_f32_e32 v115, v115
	v_rcp_f32_e32 v118, v116
	v_rcp_f32_e32 v119, v117
	s_mov_b64 s[96:97], 0
	v_mul_f32_e64 v116, v92, v114
	v_mul_f32_e64 v117, v93, v115
	v_mul_f32_e64 v114, v94, v120
	v_mul_f32_e64 v115, v95, v121
	v_mul_f32_e64 v118, v88, v118
	v_mul_f32_e64 v119, v89, v119
	v_mul_f32_e64 v120, v90, s48
	v_mul_f32_e64 v121, v91, s48
.LBB0_481:
	s_andn2_b64 vcc, exec, s[96:97]
	s_cbranch_vccnz .LBB0_483
	v_mul_f32_e64 v116, v92, v92
	v_mul_f32_e64 v117, v93, v93
	v_mul_f32_e64 v118, v92, s52
	v_mul_f32_e64 v119, v93, s52
	v_fma_f32 v116, v116, s50, 1.0
	v_fma_f32 v117, v117, s50, 1.0
	v_mul_f32_e64 v114, v94, v94
	v_mul_f32_e64 v115, v95, v95
	v_mul_f32_e64 v116, v118, v116
	v_mul_f32_e64 v117, v119, v117
	v_mul_f32_e64 v118, v88, s52
	v_mul_f32_e64 v119, v89, s52
	v_exp_f32_e32 v116, v116
	v_exp_f32_e32 v117, v117
	s_nop 0
	v_add_f32_e64 v116, v116, 1.0
	v_add_f32_e64 v117, v117, 1.0
	s_nop 0
	v_rcp_f32_e32 v116, v116
	v_rcp_f32_e32 v117, v117
	s_nop 0
	v_mul_f32_e64 v116, v92, v116
	v_mul_f32_e64 v117, v93, v117
	v_fma_f32 v92, v114, s50, 1.0
	v_fma_f32 v93, v115, s50, 1.0
	v_mul_f32_e64 v114, v94, s52
	v_mul_f32_e64 v115, v95, s52
	s_nop 0
	v_mul_f32_e64 v92, v114, v92
	v_mul_f32_e64 v93, v115, v93
	s_nop 0
	v_exp_f32_e32 v92, v92
	v_exp_f32_e32 v93, v93
	s_nop 0
	v_add_f32_e64 v92, v92, 1.0
	v_add_f32_e64 v93, v93, 1.0
	s_nop 0
	v_rcp_f32_e32 v92, v92
	v_rcp_f32_e32 v93, v93
	s_nop 0
	v_mul_f32_e64 v114, v94, v92
	v_mul_f32_e64 v115, v95, v93
	v_mul_f32_e64 v94, v88, v88
	v_mul_f32_e64 v95, v89, v89
	v_mul_f32_e64 v92, v90, v90
	v_mul_f32_e64 v93, v91, v91
	v_fma_f32 v94, v94, s50, 1.0
	v_fma_f32 v95, v95, s50, 1.0
	s_nop 0
	v_mul_f32_e64 v94, v118, v94
	v_mul_f32_e64 v95, v119, v95
	s_nop 0
	v_exp_f32_e32 v94, v94
	v_exp_f32_e32 v95, v95
	s_nop 0
	v_add_f32_e64 v94, v94, 1.0
	v_add_f32_e64 v95, v95, 1.0
	s_nop 0
	v_rcp_f32_e32 v94, v94
	v_rcp_f32_e32 v95, v95
	s_nop 0
	v_mul_f32_e64 v118, v88, v94
	v_mul_f32_e64 v119, v89, v95
	v_fma_f32 v88, v92, s50, 1.0
	v_fma_f32 v89, v93, s50, 1.0
	v_mul_f32_e64 v92, v90, s52
	v_mul_f32_e64 v93, v91, s52
	s_nop 0
	v_mul_f32_e64 v120, v92, v88
	v_mul_f32_e64 v121, v93, v89
.LBB0_483:
	s_nop 0
	v_exp_f32_e32 v88, v120
	v_exp_f32_e32 v89, v121
	v_or_b32_e32 v94, s26, v140
	v_lshlrev_b32_e32 v136, 1, v94
	v_lshl_add_u64 v[94:95], v[110:111], 0, v[136:137]
	v_add_f32_e64 v88, v88, 1.0
	v_add_f32_e64 v89, v89, 1.0
	s_nop 0
	v_rcp_f32_e32 v88, v88
	v_rcp_f32_e32 v89, v89
	s_nop 0
	v_mul_f32_e64 v92, v90, v88
	v_mul_f32_e64 v93, v91, v89
	v_cvt_pk_bf16_f32 v88, v116, v117
	v_cvt_pk_bf16_f32 v89, v114, v115
	v_cvt_pk_bf16_f32 v90, v118, v119
	s_nop 0
	v_cvt_pk_bf16_f32 v91, v92, v93
	global_store_dwordx4 v[94:95], v[88:91], off
	s_and_b64 vcc, exec, s[10:11]
	s_mov_b64 s[6:7], -1
	s_cbranch_vccz .LBB0_449

; __device__ __forceinline__ f32x2 silu_pk(f32x2 x) { const f32x2 t = x * -1.4426950408889634f; f32x2 e; e.x = __builtin_amdgcn_exp2f(t.x); e.y = __builtin_amdgcn_exp2f(t.y); e = e + 1.0f; f32x2 r; r.x = __builtin_amdgcn_rcpf(e.x); r.y = __builtin_amdgcn_rcpf(e.y); return x * r; }
; __device__ __forceinline__ f32x2 gelu_pk(f32x2 x) { const f32x2 x2 = x * x; const f32x2 t = (x2 * 0.044715f + 1.0f) * (x * -2.302208198144325f); f32x2 e; e.x = __builtin_amdgcn_exp2f(t.x); e.y = __builtin_amdgcn_exp2f(t.y); e = e + 1.0f; f32x2 r; r.x = __builtin_amdgcn_rcpf(e.x); r.y = __builtin_amd ...
;     __device__ __forceinline__ void operator()(const pg8::f32x4 (&acc)[2][2][4][2], const pg8::Unit& u, int wr, int wc, int fr, int fq) const {
;     ...
;                     if (pn < 12) {
;                         const int seg = pn >> 2, cc = (pn & 3) * 256 + cl;
;                         if (seg < 2) {
; #pragma unroll
;                             for (int e = 0; e < 8; e += 2) { const f32x2 g2 = gelu_pk((f32x2){v[e], v[e + 1]}); v[e] = g2.x; v[e + 1] = g2.y; }
;                         } else {
; #pragma unroll
;                             for (int e = 0; e < 8; e += 2) { const f32x2 g2 = silu_pk((f32x2){v[e], v[e + 1]}); v[e] = g2.x; v[e + 1] = g2.y; }
;                         }
;                         bf16* base = (bf16*)(ws + (seg == 0 ? WS_UA : seg == 1 ? WS_VA : WS_ZA));
;                         st_bf16(base + (size_t)r * 1024 + cc, v);
.LBB0_485:
	s_andn2_b64 vcc, exec, s[16:17]
	s_mov_b64 s[0:1], -1
	s_cbranch_vccnz .LBB0_487
	v_mul_f32_e64 v88, v84, s48
	v_mul_f32_e64 v89, v85, s48
	v_mul_f32_e64 v90, v86, s48
	v_mul_f32_e64 v91, v87, s48
	v_mul_f32_e64 v92, v80, s48
	v_mul_f32_e64 v93, v81, s48
	v_exp_f32_e32 v88, v88
	v_exp_f32_e32 v89, v89
	v_exp_f32_e32 v90, v90
	v_exp_f32_e32 v91, v91
	v_exp_f32_e32 v92, v92
	v_exp_f32_e32 v93, v93
	v_add_f32_e64 v88, v88, 1.0
	v_add_f32_e64 v89, v89, 1.0
	v_add_f32_e64 v90, v90, 1.0
	v_add_f32_e64 v91, v91, 1.0
	v_rcp_f32_e32 v88, v88
	v_add_f32_e64 v92, v92, 1.0
	v_add_f32_e64 v93, v93, 1.0
	v_rcp_f32_e32 v89, v89
	v_rcp_f32_e32 v90, v90
	v_rcp_f32_e32 v91, v91
	v_rcp_f32_e32 v92, v92
	v_rcp_f32_e32 v93, v93
	v_mul_f32_e64 v88, v84, v88
	v_mul_f32_e64 v89, v85, v89
	v_mul_f32_e64 v90, v86, v90
	v_mul_f32_e64 v91, v87, v91
	v_mul_f32_e64 v94, v82, s48
	v_mul_f32_e64 v95, v83, s48
	v_mul_f32_e64 v92, v80, v92
	v_mul_f32_e64 v93, v81, v93
	s_mov_b64 s[0:1], 0
.LBB0_487:
	s_andn2_b64 vcc, exec, s[0:1]
	s_cbranch_vccnz .LBB0_489
	v_mul_f32_e64 v88, v84, v84
	v_mul_f32_e64 v89, v85, v85
	v_mul_f32_e64 v92, v84, s52
	v_mul_f32_e64 v93, v85, s52
	v_fma_f32 v88, v88, s50, 1.0
	v_fma_f32 v89, v89, s50, 1.0
	v_mul_f32_e64 v90, v86, v86
	v_mul_f32_e64 v91, v87, v87
	v_mul_f32_e64 v88, v92, v88
	v_mul_f32_e64 v89, v93, v89
	v_mul_f32_e64 v92, v80, s52
	v_mul_f32_e64 v93, v81, s52
	v_exp_f32_e32 v88, v88
	v_exp_f32_e32 v89, v89
	s_nop 0
	v_add_f32_e64 v88, v88, 1.0
	v_add_f32_e64 v89, v89, 1.0
	s_nop 0
	v_rcp_f32_e32 v88, v88
	v_rcp_f32_e32 v89, v89
	s_nop 0
	v_mul_f32_e64 v88, v84, v88
	v_mul_f32_e64 v89, v85, v89
	v_fma_f32 v84, v90, s50, 1.0
	v_fma_f32 v85, v91, s50, 1.0
	v_mul_f32_e64 v90, v86, s52
	v_mul_f32_e64 v91, v87, s52
	s_nop 0
	v_mul_f32_e64 v84, v90, v84
	v_mul_f32_e64 v85, v91, v85
	s_nop 0
	v_exp_f32_e32 v84, v84
	v_exp_f32_e32 v85, v85
	s_nop 0
	v_add_f32_e64 v84, v84, 1.0
	v_add_f32_e64 v85, v85, 1.0
	s_nop 0
	v_rcp_f32_e32 v84, v84
	v_rcp_f32_e32 v85, v85
	s_nop 0
	v_mul_f32_e64 v90, v86, v84
	v_mul_f32_e64 v91, v87, v85
	v_mul_f32_e64 v86, v80, v80
	v_mul_f32_e64 v87, v81, v81
	v_mul_f32_e64 v84, v82, v82
	v_mul_f32_e64 v85, v83, v83
	v_fma_f32 v86, v86, s50, 1.0
	v_fma_f32 v87, v87, s50, 1.0
	s_nop 0
	v_mul_f32_e64 v86, v92, v86
	v_mul_f32_e64 v87, v93, v87
	s_nop 0
	v_exp_f32_e32 v86, v86
	v_exp_f32_e32 v87, v87
	s_nop 0
	v_add_f32_e64 v86, v86, 1.0
	v_add_f32_e64 v87, v87, 1.0
	s_nop 0
	v_rcp_f32_e32 v86, v86
	v_rcp_f32_e32 v87, v87
	s_nop 0
	v_mul_f32_e64 v92, v80, v86
	v_mul_f32_e64 v93, v81, v87
	v_fma_f32 v80, v84, s50, 1.0
	v_fma_f32 v81, v85, s50, 1.0
	v_mul_f32_e64 v84, v82, s52
	v_mul_f32_e64 v85, v83, s52
	s_nop 0
	v_mul_f32_e64 v94, v84, v80
	v_mul_f32_e64 v95, v85, v81
.LBB0_489:
	s_nop 0
	v_exp_f32_e32 v80, v94
	v_exp_f32_e32 v81, v95
	v_add_lshl_u32 v136, s26, v140, 1
	v_lshl_add_u64 v[86:87], v[110:111], 0, v[136:137]
	v_add_f32_e64 v80, v80, 1.0
	v_add_f32_e64 v81, v81, 1.0
	s_nop 0
	v_rcp_f32_e32 v80, v80
	v_rcp_f32_e32 v81, v81
	s_nop 0
	v_mul_f32_e64 v84, v82, v80
	v_mul_f32_e64 v85, v83, v81
	v_cvt_pk_bf16_f32 v80, v88, v89
	v_cvt_pk_bf16_f32 v81, v90, v91
	v_cvt_pk_bf16_f32 v82, v92, v93
	s_nop 0
	v_cvt_pk_bf16_f32 v83, v84, v85
	global_store_dwordx4 v[86:87], v[80:83], off offset:256

; __device__ __forceinline__ f32x2 silu_pk(f32x2 x) { const f32x2 t = x * -1.4426950408889634f; f32x2 e; e.x = __builtin_amdgcn_exp2f(t.x); e.y = __builtin_amdgcn_exp2f(t.y); e = e + 1.0f; f32x2 r; r.x = __builtin_amdgcn_rcpf(e.x); r.y = __builtin_amdgcn_rcpf(e.y); return x * r; }
;     __device__ __forceinline__ void operator()(const pg8::f32x4 (&acc)[2][2][4][2], const pg8::Unit& u, int wr, int wc, int fr, int fq) const {
;     ...
;                     } else if (pn < 44) {
; #pragma unroll
;                         for (int e = 0; e < 8; e += 2) { const f32x2 g2 = silu_pk((f32x2){v[e], v[e + 1]}); v[e] = g2.x; v[e + 1] = g2.y; }
;                         st_bf16((bf16*)(ws + WS_ZB) + (size_t)r * 2048 + (pn - 36) * 256 + cl, v);
;                     } else if (pn < 48) {
;                         st_bf16((bf16*)(ws + WS_QC) + (size_t)r * 1024 + (pn - 44) * 256 + cl, v);
;                     } else if (pn < 50) {
;                         const bool isv = pn == 49;
;                         st_bf16((bf16*)(ws + (isv ? WS_VC : WS_KC)) + (size_t)r * 256 + cl, v);
;                         if (r < PT) st_f32(out + (isv ? O_PV : O_PK) + ((size_t)l * PT + r) * 256 + cl, v);
;                         else st_f32(out + (isv ? O_SV : O_SK) + ((size_t)l * ST + (r - PT)) * 256 + cl, v);
;                     } else if (pn < 54) {
; #pragma unroll
;                         for (int e = 0; e < 8; e += 2) { const f32x2 g2 = silu_pk((f32x2){v[e], v[e + 1]}); v[e] = g2.x; v[e + 1] = g2.y; }
;                         st_bf16((bf16*)(ws + WS_ZC) + (size_t)r * 1024 + (pn - 50) * 256 + cl, v);
.LBB0_516:
	s_andn2_b64 vcc, exec, s[6:7]
	s_cbranch_vccnz .LBB0_518
	v_mul_f32_e64 v100, v76, s48
	v_mul_f32_e64 v101, v77, s48
	v_mul_f32_e64 v102, v78, s48
	v_mul_f32_e64 v103, v79, s48
	v_exp_f32_e32 v100, v100
	v_exp_f32_e32 v101, v101
	v_exp_f32_e32 v102, v102
	v_exp_f32_e32 v103, v103
	v_mul_f32_e64 v104, v72, s48
	v_mul_f32_e64 v105, v73, s48
	v_mul_f32_e64 v106, v74, s48
	v_mul_f32_e64 v107, v75, s48
	v_exp_f32_e32 v104, v104
	v_exp_f32_e32 v105, v105
	v_exp_f32_e32 v106, v106
	v_exp_f32_e32 v107, v107
	v_add_f32_e64 v100, v100, 1.0
	v_add_f32_e64 v101, v101, 1.0
	v_add_f32_e64 v102, v102, 1.0
	v_add_f32_e64 v103, v103, 1.0
	v_rcp_f32_e32 v100, v100
	v_rcp_f32_e32 v101, v101
	v_rcp_f32_e32 v102, v102
	v_rcp_f32_e32 v103, v103
	v_add_f32_e64 v104, v104, 1.0
	v_add_f32_e64 v105, v105, 1.0
	v_add_f32_e64 v106, v106, 1.0
	v_add_f32_e64 v107, v107, 1.0
	v_rcp_f32_e32 v104, v104
	v_rcp_f32_e32 v105, v105
	v_rcp_f32_e32 v106, v106
	v_rcp_f32_e32 v107, v107
	v_lshlrev_b32_e32 v136, 1, v140
	v_mul_f32_e64 v100, v76, v100
	v_mul_f32_e64 v101, v77, v101
	v_mul_f32_e64 v102, v78, v102
	v_mul_f32_e64 v103, v79, v103
	v_lshl_add_u64 v[110:111], v[94:95], 0, v[136:137]
	v_mul_f32_e64 v104, v72, v104
	v_mul_f32_e64 v105, v73, v105
	v_mul_f32_e64 v106, v74, v106
	v_mul_f32_e64 v107, v75, v107
	v_cvt_pk_bf16_f32 v100, v100, v101
	v_cvt_pk_bf16_f32 v101, v102, v103
	v_cvt_pk_bf16_f32 v102, v104, v105
	s_nop 0
	v_cvt_pk_bf16_f32 v103, v106, v107
	global_store_dwordx4 v[110:111], v[100:103], off

; __device__ __forceinline__ f32x2 silu_pk(f32x2 x) { const f32x2 t = x * -1.4426950408889634f; f32x2 e; e.x = __builtin_amdgcn_exp2f(t.x); e.y = __builtin_amdgcn_exp2f(t.y); e = e + 1.0f; f32x2 r; r.x = __builtin_amdgcn_rcpf(e.x); r.y = __builtin_amdgcn_rcpf(e.y); return x * r; }
;     __device__ __forceinline__ void operator()(const pg8::f32x4 (&acc)[2][2][4][2], const pg8::Unit& u, int wr, int wc, int fr, int fq) const {
;     ...
;                     } else if (pn < 44) {
; #pragma unroll
;                         for (int e = 0; e < 8; e += 2) { const f32x2 g2 = silu_pk((f32x2){v[e], v[e + 1]}); v[e] = g2.x; v[e + 1] = g2.y; }
;                         st_bf16((bf16*)(ws + WS_ZB) + (size_t)r * 2048 + (pn - 36) * 256 + cl, v);
;                     } else if (pn < 48) {
;                         st_bf16((bf16*)(ws + WS_QC) + (size_t)r * 1024 + (pn - 44) * 256 + cl, v);
;                     } else if (pn < 50) {
;                         const bool isv = pn == 49;
;                         st_bf16((bf16*)(ws + (isv ? WS_VC : WS_KC)) + (size_t)r * 256 + cl, v);
;                         if (r < PT) st_f32(out + (isv ? O_PV : O_PK) + ((size_t)l * PT + r) * 256 + cl, v);
;                         else st_f32(out + (isv ? O_SV : O_SK) + ((size_t)l * ST + (r - PT)) * 256 + cl, v);
;                     } else if (pn < 54) {
; #pragma unroll
;                         for (int e = 0; e < 8; e += 2) { const f32x2 g2 = silu_pk((f32x2){v[e], v[e + 1]}); v[e] = g2.x; v[e + 1] = g2.y; }
;                         st_bf16((bf16*)(ws + WS_ZC) + (size_t)r * 1024 + (pn - 50) * 256 + cl, v);
.LBB0_529:
	s_andn2_b64 vcc, exec, s[6:7]
	s_cbranch_vccnz .LBB0_531
	v_mul_f32_e64 v100, v76, s48
	v_mul_f32_e64 v101, v77, s48
	v_mul_f32_e64 v102, v78, s48
	v_mul_f32_e64 v103, v79, s48
	v_exp_f32_e32 v100, v100
	v_exp_f32_e32 v101, v101
	v_exp_f32_e32 v102, v102
	v_exp_f32_e32 v103, v103
	v_mul_f32_e64 v104, v72, s48
	v_mul_f32_e64 v105, v73, s48
	v_mul_f32_e64 v106, v74, s48
	v_mul_f32_e64 v107, v75, s48
	v_exp_f32_e32 v104, v104
	v_exp_f32_e32 v105, v105
	v_exp_f32_e32 v106, v106
	v_exp_f32_e32 v107, v107
	v_add_f32_e64 v100, v100, 1.0
	v_add_f32_e64 v101, v101, 1.0
	v_add_f32_e64 v102, v102, 1.0
	v_add_f32_e64 v103, v103, 1.0
	v_rcp_f32_e32 v100, v100
	v_rcp_f32_e32 v101, v101
	v_rcp_f32_e32 v102, v102
	v_rcp_f32_e32 v103, v103
	v_add_f32_e64 v104, v104, 1.0
	v_add_f32_e64 v105, v105, 1.0
	v_add_f32_e64 v106, v106, 1.0
	v_add_f32_e64 v107, v107, 1.0
	v_rcp_f32_e32 v104, v104
	v_rcp_f32_e32 v105, v105
	v_rcp_f32_e32 v106, v106
	v_rcp_f32_e32 v107, v107
	v_lshlrev_b32_e32 v136, 1, v140
	v_mul_f32_e64 v100, v76, v100
	v_mul_f32_e64 v101, v77, v101
	v_mul_f32_e64 v102, v78, v102
	v_mul_f32_e64 v103, v79, v103
	v_lshl_add_u64 v[110:111], v[84:85], 0, v[136:137]
	v_mul_f32_e64 v104, v72, v104
	v_mul_f32_e64 v105, v73, v105
	v_mul_f32_e64 v106, v74, v106
	v_mul_f32_e64 v107, v75, v107
	v_cvt_pk_bf16_f32 v100, v100, v101
	v_cvt_pk_bf16_f32 v101, v102, v103
	v_cvt_pk_bf16_f32 v102, v104, v105
	s_nop 0
	v_cvt_pk_bf16_f32 v103, v106, v107
	global_store_dwordx4 v[110:111], v[100:103], off

; __device__ __forceinline__ f32x2 silu_pk(f32x2 x) { const f32x2 t = x * -1.4426950408889634f; f32x2 e; e.x = __builtin_amdgcn_exp2f(t.x); e.y = __builtin_amdgcn_exp2f(t.y); e = e + 1.0f; f32x2 r; r.x = __builtin_amdgcn_rcpf(e.x); r.y = __builtin_amdgcn_rcpf(e.y); return x * r; }
;     __device__ __forceinline__ void operator()(const pg8::f32x4 (&acc)[2][2][4][2], const pg8::Unit& u, int wr, int wc, int fr, int fq) const {
;     ...
;                     } else if (pn < 44) {
; #pragma unroll
;                         for (int e = 0; e < 8; e += 2) { const f32x2 g2 = silu_pk((f32x2){v[e], v[e + 1]}); v[e] = g2.x; v[e + 1] = g2.y; }
;                         st_bf16((bf16*)(ws + WS_ZB) + (size_t)r * 2048 + (pn - 36) * 256 + cl, v);
;                     } else if (pn < 48) {
;                         st_bf16((bf16*)(ws + WS_QC) + (size_t)r * 1024 + (pn - 44) * 256 + cl, v);
;                     } else if (pn < 50) {
;                         const bool isv = pn == 49;
;                         st_bf16((bf16*)(ws + (isv ? WS_VC : WS_KC)) + (size_t)r * 256 + cl, v);
;                         if (r < PT) st_f32(out + (isv ? O_PV : O_PK) + ((size_t)l * PT + r) * 256 + cl, v);
;                         else st_f32(out + (isv ? O_SV : O_SK) + ((size_t)l * ST + (r - PT)) * 256 + cl, v);
;                     } else if (pn < 54) {
; #pragma unroll
;                         for (int e = 0; e < 8; e += 2) { const f32x2 g2 = silu_pk((f32x2){v[e], v[e + 1]}); v[e] = g2.x; v[e + 1] = g2.y; }
;                         st_bf16((bf16*)(ws + WS_ZC) + (size_t)r * 1024 + (pn - 50) * 256 + cl, v);
.LBB0_552:
	s_andn2_b64 vcc, exec, s[6:7]
	s_cbranch_vccnz .LBB0_554
	v_mul_f32_e64 v72, v68, s48
	v_mul_f32_e64 v73, v69, s48
	v_mul_f32_e64 v74, v70, s48
	v_mul_f32_e64 v75, v71, s48
	v_exp_f32_e32 v72, v72
	v_exp_f32_e32 v73, v73
	v_exp_f32_e32 v74, v74
	v_exp_f32_e32 v75, v75
	v_mul_f32_e64 v76, v64, s48
	v_mul_f32_e64 v77, v65, s48
	v_mul_f32_e64 v78, v66, s48
	v_mul_f32_e64 v79, v67, s48
	v_exp_f32_e32 v76, v76
	v_exp_f32_e32 v77, v77
	v_exp_f32_e32 v78, v78
	v_exp_f32_e32 v79, v79
	v_add_f32_e64 v72, v72, 1.0
	v_add_f32_e64 v73, v73, 1.0
	v_add_f32_e64 v74, v74, 1.0
	v_add_f32_e64 v75, v75, 1.0
	v_rcp_f32_e32 v72, v72
	v_rcp_f32_e32 v73, v73
	v_rcp_f32_e32 v74, v74
	v_rcp_f32_e32 v75, v75
	v_add_f32_e64 v76, v76, 1.0
	v_add_f32_e64 v77, v77, 1.0
	v_add_f32_e64 v78, v78, 1.0
	v_add_f32_e64 v79, v79, 1.0
	v_rcp_f32_e32 v76, v76
	v_rcp_f32_e32 v77, v77
	v_rcp_f32_e32 v78, v78
	v_rcp_f32_e32 v79, v79
	v_lshlrev_b32_e32 v136, 1, v142
	v_mul_f32_e64 v72, v68, v72
	v_mul_f32_e64 v73, v69, v73
	v_mul_f32_e64 v74, v70, v74
	v_mul_f32_e64 v75, v71, v75
	v_lshl_add_u64 v[94:95], v[94:95], 0, v[136:137]
	v_mul_f32_e64 v76, v64, v76
	v_mul_f32_e64 v77, v65, v77
	v_mul_f32_e64 v78, v66, v78
	v_mul_f32_e64 v79, v67, v79
	v_cvt_pk_bf16_f32 v72, v72, v73
	v_cvt_pk_bf16_f32 v73, v74, v75
	v_cvt_pk_bf16_f32 v74, v76, v77
	s_nop 0
	v_cvt_pk_bf16_f32 v75, v78, v79
	global_store_dwordx4 v[94:95], v[72:75], off

; __device__ __forceinline__ f32x2 silu_pk(f32x2 x) { const f32x2 t = x * -1.4426950408889634f; f32x2 e; e.x = __builtin_amdgcn_exp2f(t.x); e.y = __builtin_amdgcn_exp2f(t.y); e = e + 1.0f; f32x2 r; r.x = __builtin_amdgcn_rcpf(e.x); r.y = __builtin_amdgcn_rcpf(e.y); return x * r; }
;     __device__ __forceinline__ void operator()(const pg8::f32x4 (&acc)[2][2][4][2], const pg8::Unit& u, int wr, int wc, int fr, int fq) const {
;     ...
;                     } else if (pn < 44) {
; #pragma unroll
;                         for (int e = 0; e < 8; e += 2) { const f32x2 g2 = silu_pk((f32x2){v[e], v[e + 1]}); v[e] = g2.x; v[e + 1] = g2.y; }
;                         st_bf16((bf16*)(ws + WS_ZB) + (size_t)r * 2048 + (pn - 36) * 256 + cl, v);
;                     } else if (pn < 48) {
;                         st_bf16((bf16*)(ws + WS_QC) + (size_t)r * 1024 + (pn - 44) * 256 + cl, v);
;                     } else if (pn < 50) {
;                         const bool isv = pn == 49;
;                         st_bf16((bf16*)(ws + (isv ? WS_VC : WS_KC)) + (size_t)r * 256 + cl, v);
;                         if (r < PT) st_f32(out + (isv ? O_PV : O_PK) + ((size_t)l * PT + r) * 256 + cl, v);
;                         else st_f32(out + (isv ? O_SV : O_SK) + ((size_t)l * ST + (r - PT)) * 256 + cl, v);
;                     } else if (pn < 54) {
; #pragma unroll
;                         for (int e = 0; e < 8; e += 2) { const f32x2 g2 = silu_pk((f32x2){v[e], v[e + 1]}); v[e] = g2.x; v[e + 1] = g2.y; }
;                         st_bf16((bf16*)(ws + WS_ZC) + (size_t)r * 1024 + (pn - 50) * 256 + cl, v);
.LBB0_565:
	s_andn2_b64 vcc, exec, s[6:7]
	s_cbranch_vccnz .LBB0_567
	v_mul_f32_e64 v72, v68, s48
	v_mul_f32_e64 v73, v69, s48
	v_mul_f32_e64 v74, v70, s48
	v_mul_f32_e64 v75, v71, s48
	v_exp_f32_e32 v72, v72
	v_exp_f32_e32 v73, v73
	v_exp_f32_e32 v74, v74
	v_exp_f32_e32 v75, v75
	v_mul_f32_e64 v76, v64, s48
	v_mul_f32_e64 v77, v65, s48
	v_mul_f32_e64 v78, v66, s48
	v_mul_f32_e64 v79, v67, s48
	v_exp_f32_e32 v76, v76
	v_exp_f32_e32 v77, v77
	v_exp_f32_e32 v78, v78
	v_exp_f32_e32 v79, v79
	v_add_f32_e64 v72, v72, 1.0
	v_add_f32_e64 v73, v73, 1.0
	v_add_f32_e64 v74, v74, 1.0
	v_add_f32_e64 v75, v75, 1.0
	v_rcp_f32_e32 v72, v72
	v_rcp_f32_e32 v73, v73
	v_rcp_f32_e32 v74, v74
	v_rcp_f32_e32 v75, v75
	v_add_f32_e64 v76, v76, 1.0
	v_add_f32_e64 v77, v77, 1.0
	v_add_f32_e64 v78, v78, 1.0
	v_add_f32_e64 v79, v79, 1.0
	v_rcp_f32_e32 v76, v76
	v_rcp_f32_e32 v77, v77
	v_rcp_f32_e32 v78, v78
	v_rcp_f32_e32 v79, v79
	v_lshlrev_b32_e32 v136, 1, v142
	v_mul_f32_e64 v72, v68, v72
	v_mul_f32_e64 v73, v69, v73
	v_mul_f32_e64 v74, v70, v74
	v_mul_f32_e64 v75, v71, v75
	v_lshl_add_u64 v[84:85], v[84:85], 0, v[136:137]
	v_mul_f32_e64 v76, v64, v76
	v_mul_f32_e64 v77, v65, v77
	v_mul_f32_e64 v78, v66, v78
	v_mul_f32_e64 v79, v67, v79
	v_cvt_pk_bf16_f32 v72, v72, v73
	v_cvt_pk_bf16_f32 v73, v74, v75
	v_cvt_pk_bf16_f32 v74, v76, v77
	s_nop 0
	v_cvt_pk_bf16_f32 v75, v78, v79
	global_store_dwordx4 v[84:85], v[72:75], off

; __device__ __forceinline__ f32x2 silu_pk(f32x2 x) { const f32x2 t = x * -1.4426950408889634f; f32x2 e; e.x = __builtin_amdgcn_exp2f(t.x); e.y = __builtin_amdgcn_exp2f(t.y); e = e + 1.0f; f32x2 r; r.x = __builtin_amdgcn_rcpf(e.x); r.y = __builtin_amdgcn_rcpf(e.y); return x * r; }
; __device__ __forceinline__ f32x2 gelu_pk(f32x2 x) { const f32x2 x2 = x * x; const f32x2 t = (x2 * 0.044715f + 1.0f) * (x * -2.302208198144325f); f32x2 e; e.x = __builtin_amdgcn_exp2f(t.x); e.y = __builtin_amdgcn_exp2f(t.y); e = e + 1.0f; f32x2 r; r.x = __builtin_amdgcn_rcpf(e.x); r.y = __builtin_amd ...
;     __device__ __forceinline__ void operator()(const pg8::f32x4 (&acc)[2][2][4][2], const pg8::Unit& u, int wr, int wc, int fr, int fq) const {
;     ...
;                     if (pn < 12) {
;                         const int seg = pn >> 2, cc = (pn & 3) * 256 + cl;
;                         if (seg < 2) {
; #pragma unroll
;                             for (int e = 0; e < 8; e += 2) { const f32x2 g2 = gelu_pk((f32x2){v[e], v[e + 1]}); v[e] = g2.x; v[e + 1] = g2.y; }
;                         } else {
; #pragma unroll
;                             for (int e = 0; e < 8; e += 2) { const f32x2 g2 = silu_pk((f32x2){v[e], v[e + 1]}); v[e] = g2.x; v[e + 1] = g2.y; }
;                         }
;                         bf16* base = (bf16*)(ws + (seg == 0 ? WS_UA : seg == 1 ? WS_VA : WS_ZA));
;                         st_bf16(base + (size_t)r * 1024 + cc, v);
.LBB0_580:
	s_andn2_b64 vcc, exec, s[16:17]
	s_mov_b64 s[96:97], -1
	s_cbranch_vccnz .LBB0_582
	v_mul_f32_e64 v102, v78, s48
	v_mul_f32_e64 v103, v79, s48
	v_mul_f32_e64 v100, v76, s48
	v_mul_f32_e64 v101, v77, s48
	v_exp_f32_e32 v102, v102
	v_exp_f32_e32 v103, v103
	v_mul_f32_e64 v104, v72, s48
	v_mul_f32_e64 v105, v73, s48
	v_exp_f32_e32 v100, v100
	v_exp_f32_e32 v101, v101
	v_exp_f32_e32 v104, v104
	v_exp_f32_e32 v105, v105
	v_add_f32_e64 v102, v102, 1.0
	v_add_f32_e64 v103, v103, 1.0
	v_add_f32_e64 v100, v100, 1.0
	v_add_f32_e64 v101, v101, 1.0
	v_rcp_f32_e32 v106, v102
	v_rcp_f32_e32 v107, v103
	v_add_f32_e64 v102, v104, 1.0
	v_add_f32_e64 v103, v105, 1.0
	v_rcp_f32_e32 v100, v100
	v_rcp_f32_e32 v101, v101
	v_rcp_f32_e32 v104, v102
	v_rcp_f32_e32 v105, v103
	s_mov_b64 s[96:97], 0
	v_mul_f32_e64 v102, v76, v100
	v_mul_f32_e64 v103, v77, v101
	v_mul_f32_e64 v100, v78, v106
	v_mul_f32_e64 v101, v79, v107
	v_mul_f32_e64 v104, v72, v104
	v_mul_f32_e64 v105, v73, v105
	v_mul_f32_e64 v106, v74, s48
	v_mul_f32_e64 v107, v75, s48
.LBB0_582:
	s_andn2_b64 vcc, exec, s[96:97]
	s_cbranch_vccnz .LBB0_584
	v_mul_f32_e64 v102, v76, v76
	v_mul_f32_e64 v103, v77, v77
	v_mul_f32_e64 v104, v76, s52
	v_mul_f32_e64 v105, v77, s52
	v_fma_f32 v102, v102, s50, 1.0
	v_fma_f32 v103, v103, s50, 1.0
	v_mul_f32_e64 v100, v78, v78
	v_mul_f32_e64 v101, v79, v79
	v_mul_f32_e64 v102, v104, v102
	v_mul_f32_e64 v103, v105, v103
	v_mul_f32_e64 v104, v72, s52
	v_mul_f32_e64 v105, v73, s52
	v_exp_f32_e32 v102, v102
	v_exp_f32_e32 v103, v103
	s_nop 0
	v_add_f32_e64 v102, v102, 1.0
	v_add_f32_e64 v103, v103, 1.0
	s_nop 0
	v_rcp_f32_e32 v102, v102
	v_rcp_f32_e32 v103, v103
	s_nop 0
	v_mul_f32_e64 v102, v76, v102
	v_mul_f32_e64 v103, v77, v103
	v_fma_f32 v76, v100, s50, 1.0
	v_fma_f32 v77, v101, s50, 1.0
	v_mul_f32_e64 v100, v78, s52
	v_mul_f32_e64 v101, v79, s52
	s_nop 0
	v_mul_f32_e64 v76, v100, v76
	v_mul_f32_e64 v77, v101, v77
	s_nop 0
	v_exp_f32_e32 v76, v76
	v_exp_f32_e32 v77, v77
	s_nop 0
	v_add_f32_e64 v76, v76, 1.0
	v_add_f32_e64 v77, v77, 1.0
	s_nop 0
	v_rcp_f32_e32 v76, v76
	v_rcp_f32_e32 v77, v77
	s_nop 0
	v_mul_f32_e64 v100, v78, v76
	v_mul_f32_e64 v101, v79, v77
	v_mul_f32_e64 v78, v72, v72
	v_mul_f32_e64 v79, v73, v73
	v_mul_f32_e64 v76, v74, v74
	v_mul_f32_e64 v77, v75, v75
	v_fma_f32 v78, v78, s50, 1.0
	v_fma_f32 v79, v79, s50, 1.0
	s_nop 0
	v_mul_f32_e64 v78, v104, v78
	v_mul_f32_e64 v79, v105, v79
	s_nop 0
	v_exp_f32_e32 v78, v78
	v_exp_f32_e32 v79, v79
	s_nop 0
	v_add_f32_e64 v78, v78, 1.0
	v_add_f32_e64 v79, v79, 1.0
	s_nop 0
	v_rcp_f32_e32 v78, v78
	v_rcp_f32_e32 v79, v79
	s_nop 0
	v_mul_f32_e64 v104, v72, v78
	v_mul_f32_e64 v105, v73, v79
	v_fma_f32 v72, v76, s50, 1.0
	v_fma_f32 v73, v77, s50, 1.0
	v_mul_f32_e64 v76, v74, s52
	v_mul_f32_e64 v77, v75, s52
	s_nop 0
	v_mul_f32_e64 v106, v76, v72
	v_mul_f32_e64 v107, v77, v73
.LBB0_584:
	s_nop 0
	v_exp_f32_e32 v72, v106
	v_exp_f32_e32 v73, v107
	v_or_b32_e32 v78, s26, v140
	v_lshlrev_b32_e32 v136, 1, v78
	v_lshl_add_u64 v[78:79], v[96:97], 0, v[136:137]
	v_add_f32_e64 v72, v72, 1.0
	v_add_f32_e64 v73, v73, 1.0
	s_nop 0
	v_rcp_f32_e32 v72, v72
	v_rcp_f32_e32 v73, v73
	s_nop 0
	v_mul_f32_e64 v76, v74, v72
	v_mul_f32_e64 v77, v75, v73
	v_cvt_pk_bf16_f32 v72, v102, v103
	v_cvt_pk_bf16_f32 v73, v100, v101
	v_cvt_pk_bf16_f32 v74, v104, v105
	s_nop 0
	v_cvt_pk_bf16_f32 v75, v76, v77
	global_store_dwordx4 v[78:79], v[72:75], off
	s_and_b64 vcc, exec, s[10:11]
	s_mov_b64 s[6:7], -1
	s_cbranch_vccz .LBB0_544

; __device__ __forceinline__ f32x2 silu_pk(f32x2 x) { const f32x2 t = x * -1.4426950408889634f; f32x2 e; e.x = __builtin_amdgcn_exp2f(t.x); e.y = __builtin_amdgcn_exp2f(t.y); e = e + 1.0f; f32x2 r; r.x = __builtin_amdgcn_rcpf(e.x); r.y = __builtin_amdgcn_rcpf(e.y); return x * r; }
; __device__ __forceinline__ f32x2 gelu_pk(f32x2 x) { const f32x2 x2 = x * x; const f32x2 t = (x2 * 0.044715f + 1.0f) * (x * -2.302208198144325f); f32x2 e; e.x = __builtin_amdgcn_exp2f(t.x); e.y = __builtin_amdgcn_exp2f(t.y); e = e + 1.0f; f32x2 r; r.x = __builtin_amdgcn_rcpf(e.x); r.y = __builtin_amd ...
;     __device__ __forceinline__ void operator()(const pg8::f32x4 (&acc)[2][2][4][2], const pg8::Unit& u, int wr, int wc, int fr, int fq) const {
;     ...
;                     if (pn < 12) {
;                         const int seg = pn >> 2, cc = (pn & 3) * 256 + cl;
;                         if (seg < 2) {
; #pragma unroll
;                             for (int e = 0; e < 8; e += 2) { const f32x2 g2 = gelu_pk((f32x2){v[e], v[e + 1]}); v[e] = g2.x; v[e + 1] = g2.y; }
;                         } else {
; #pragma unroll
;                             for (int e = 0; e < 8; e += 2) { const f32x2 g2 = silu_pk((f32x2){v[e], v[e + 1]}); v[e] = g2.x; v[e + 1] = g2.y; }
;                         }
;                         bf16* base = (bf16*)(ws + (seg == 0 ? WS_UA : seg == 1 ? WS_VA : WS_ZA));
;                         st_bf16(base + (size_t)r * 1024 + cc, v);
.LBB0_586:
	s_andn2_b64 vcc, exec, s[16:17]
	s_mov_b64 s[0:1], -1
	s_cbranch_vccnz .LBB0_588
	v_mul_f32_e64 v72, v68, s48
	v_mul_f32_e64 v73, v69, s48
	v_mul_f32_e64 v74, v70, s48
	v_mul_f32_e64 v75, v71, s48
	v_mul_f32_e64 v76, v64, s48
	v_mul_f32_e64 v77, v65, s48
	v_exp_f32_e32 v72, v72
	v_exp_f32_e32 v73, v73
	v_exp_f32_e32 v74, v74
	v_exp_f32_e32 v75, v75
	v_exp_f32_e32 v76, v76
	v_exp_f32_e32 v77, v77
	v_add_f32_e64 v72, v72, 1.0
	v_add_f32_e64 v73, v73, 1.0
	v_add_f32_e64 v74, v74, 1.0
	v_add_f32_e64 v75, v75, 1.0
	v_rcp_f32_e32 v72, v72
	v_add_f32_e64 v76, v76, 1.0
	v_add_f32_e64 v77, v77, 1.0
	v_rcp_f32_e32 v73, v73
	v_rcp_f32_e32 v74, v74
	v_rcp_f32_e32 v75, v75
	v_rcp_f32_e32 v76, v76
	v_rcp_f32_e32 v77, v77
	v_mul_f32_e64 v72, v68, v72
	v_mul_f32_e64 v73, v69, v73
	v_mul_f32_e64 v74, v70, v74
	v_mul_f32_e64 v75, v71, v75
	v_mul_f32_e64 v78, v66, s48
	v_mul_f32_e64 v79, v67, s48
	v_mul_f32_e64 v76, v64, v76
	v_mul_f32_e64 v77, v65, v77
	s_mov_b64 s[0:1], 0
.LBB0_588:
	s_andn2_b64 vcc, exec, s[0:1]
	s_cbranch_vccnz .LBB0_590
	v_mul_f32_e64 v72, v68, v68
	v_mul_f32_e64 v73, v69, v69
	v_mul_f32_e64 v76, v68, s52
	v_mul_f32_e64 v77, v69, s52
	v_fma_f32 v72, v72, s50, 1.0
	v_fma_f32 v73, v73, s50, 1.0
	v_mul_f32_e64 v74, v70, v70
	v_mul_f32_e64 v75, v71, v71
	v_mul_f32_e64 v72, v76, v72
	v_mul_f32_e64 v73, v77, v73
	v_mul_f32_e64 v76, v64, s52
	v_mul_f32_e64 v77, v65, s52
	v_exp_f32_e32 v72, v72
	v_exp_f32_e32 v73, v73
	s_nop 0
	v_add_f32_e64 v72, v72, 1.0
	v_add_f32_e64 v73, v73, 1.0
	s_nop 0
	v_rcp_f32_e32 v72, v72
	v_rcp_f32_e32 v73, v73
	s_nop 0
	v_mul_f32_e64 v72, v68, v72
	v_mul_f32_e64 v73, v69, v73
	v_fma_f32 v68, v74, s50, 1.0
	v_fma_f32 v69, v75, s50, 1.0
	v_mul_f32_e64 v74, v70, s52
	v_mul_f32_e64 v75, v71, s52
	s_nop 0
	v_mul_f32_e64 v68, v74, v68
	v_mul_f32_e64 v69, v75, v69
	s_nop 0
	v_exp_f32_e32 v68, v68
	v_exp_f32_e32 v69, v69
	s_nop 0
	v_add_f32_e64 v68, v68, 1.0
	v_add_f32_e64 v69, v69, 1.0
	s_nop 0
	v_rcp_f32_e32 v68, v68
	v_rcp_f32_e32 v69, v69
	s_nop 0
	v_mul_f32_e64 v74, v70, v68
	v_mul_f32_e64 v75, v71, v69
	v_mul_f32_e64 v70, v64, v64
	v_mul_f32_e64 v71, v65, v65
	v_mul_f32_e64 v68, v66, v66
	v_mul_f32_e64 v69, v67, v67
	v_fma_f32 v70, v70, s50, 1.0
	v_fma_f32 v71, v71, s50, 1.0
	s_nop 0
	v_mul_f32_e64 v70, v76, v70
	v_mul_f32_e64 v71, v77, v71
	s_nop 0
	v_exp_f32_e32 v70, v70
	v_exp_f32_e32 v71, v71
	s_nop 0
	v_add_f32_e64 v70, v70, 1.0
	v_add_f32_e64 v71, v71, 1.0
	s_nop 0
	v_rcp_f32_e32 v70, v70
	v_rcp_f32_e32 v71, v71
	s_nop 0
	v_mul_f32_e64 v76, v64, v70
	v_mul_f32_e64 v77, v65, v71
	v_fma_f32 v64, v68, s50, 1.0
	v_fma_f32 v65, v69, s50, 1.0
	v_mul_f32_e64 v68, v66, s52
	v_mul_f32_e64 v69, v67, s52
	s_nop 0
	v_mul_f32_e64 v78, v68, v64
	v_mul_f32_e64 v79, v69, v65
.LBB0_590:
	s_nop 0
	v_exp_f32_e32 v64, v78
	v_exp_f32_e32 v65, v79
	v_add_lshl_u32 v136, s26, v140, 1
	v_lshl_add_u64 v[70:71], v[96:97], 0, v[136:137]
	v_add_f32_e64 v64, v64, 1.0
	v_add_f32_e64 v65, v65, 1.0
	s_nop 0
	v_rcp_f32_e32 v64, v64
	v_rcp_f32_e32 v65, v65
	s_nop 0
	v_mul_f32_e64 v68, v66, v64
	v_mul_f32_e64 v69, v67, v65
	v_cvt_pk_bf16_f32 v64, v72, v73
	v_cvt_pk_bf16_f32 v65, v74, v75
	v_cvt_pk_bf16_f32 v66, v76, v77
	s_nop 0
	v_cvt_pk_bf16_f32 v67, v68, v69
	global_store_dwordx4 v[70:71], v[64:67], off offset:256

; __device__ __forceinline__ f32x2 silu_pk(f32x2 x) { const f32x2 t = x * -1.4426950408889634f; f32x2 e; e.x = __builtin_amdgcn_exp2f(t.x); e.y = __builtin_amdgcn_exp2f(t.y); e = e + 1.0f; f32x2 r; r.x = __builtin_amdgcn_rcpf(e.x); r.y = __builtin_amdgcn_rcpf(e.y); return x * r; }
;     __device__ __forceinline__ void operator()(const pg8::f32x4 (&acc)[2][2][4][2], const pg8::Unit& u, int wr, int wc, int fr, int fq) const {
;     ...
;                     } else if (pn < 44) {
; #pragma unroll
;                         for (int e = 0; e < 8; e += 2) { const f32x2 g2 = silu_pk((f32x2){v[e], v[e + 1]}); v[e] = g2.x; v[e + 1] = g2.y; }
;                         st_bf16((bf16*)(ws + WS_ZB) + (size_t)r * 2048 + (pn - 36) * 256 + cl, v);
;                     } else if (pn < 48) {
;                         st_bf16((bf16*)(ws + WS_QC) + (size_t)r * 1024 + (pn - 44) * 256 + cl, v);
;                     } else if (pn < 50) {
;                         const bool isv = pn == 49;
;                         st_bf16((bf16*)(ws + (isv ? WS_VC : WS_KC)) + (size_t)r * 256 + cl, v);
;                         if (r < PT) st_f32(out + (isv ? O_PV : O_PK) + ((size_t)l * PT + r) * 256 + cl, v);
;                         else st_f32(out + (isv ? O_SV : O_SK) + ((size_t)l * ST + (r - PT)) * 256 + cl, v);
;                     } else if (pn < 54) {
; #pragma unroll
;                         for (int e = 0; e < 8; e += 2) { const f32x2 g2 = silu_pk((f32x2){v[e], v[e + 1]}); v[e] = g2.x; v[e + 1] = g2.y; }
;                         st_bf16((bf16*)(ws + WS_ZC) + (size_t)r * 1024 + (pn - 50) * 256 + cl, v);
.LBB0_617:
	s_andn2_b64 vcc, exec, s[6:7]
	s_cbranch_vccnz .LBB0_619
	v_mul_f32_e64 v84, v60, s48
	v_mul_f32_e64 v85, v61, s48
	v_mul_f32_e64 v86, v62, s48
	v_mul_f32_e64 v87, v63, s48
	v_exp_f32_e32 v84, v84
	v_exp_f32_e32 v85, v85
	v_exp_f32_e32 v86, v86
	v_exp_f32_e32 v87, v87
	v_mul_f32_e64 v88, v56, s48
	v_mul_f32_e64 v89, v57, s48
	v_mul_f32_e64 v90, v58, s48
	v_mul_f32_e64 v91, v59, s48
	v_exp_f32_e32 v88, v88
	v_exp_f32_e32 v89, v89
	v_exp_f32_e32 v90, v90
	v_exp_f32_e32 v91, v91
	v_add_f32_e64 v84, v84, 1.0
	v_add_f32_e64 v85, v85, 1.0
	v_add_f32_e64 v86, v86, 1.0
	v_add_f32_e64 v87, v87, 1.0
	v_rcp_f32_e32 v84, v84
	v_rcp_f32_e32 v85, v85
	v_rcp_f32_e32 v86, v86
	v_rcp_f32_e32 v87, v87
	v_add_f32_e64 v88, v88, 1.0
	v_add_f32_e64 v89, v89, 1.0
	v_add_f32_e64 v90, v90, 1.0
	v_add_f32_e64 v91, v91, 1.0
	v_rcp_f32_e32 v88, v88
	v_rcp_f32_e32 v89, v89
	v_rcp_f32_e32 v90, v90
	v_rcp_f32_e32 v91, v91
	v_lshlrev_b32_e32 v136, 1, v140
	v_mul_f32_e64 v84, v60, v84
	v_mul_f32_e64 v85, v61, v85
	v_mul_f32_e64 v86, v62, v86
	v_mul_f32_e64 v87, v63, v87
	v_lshl_add_u64 v[94:95], v[78:79], 0, v[136:137]
	v_mul_f32_e64 v88, v56, v88
	v_mul_f32_e64 v89, v57, v89
	v_mul_f32_e64 v90, v58, v90
	v_mul_f32_e64 v91, v59, v91
	v_cvt_pk_bf16_f32 v84, v84, v85
	v_cvt_pk_bf16_f32 v85, v86, v87
	v_cvt_pk_bf16_f32 v86, v88, v89
	s_nop 0
	v_cvt_pk_bf16_f32 v87, v90, v91
	global_store_dwordx4 v[94:95], v[84:87], off

; __device__ __forceinline__ f32x2 silu_pk(f32x2 x) { const f32x2 t = x * -1.4426950408889634f; f32x2 e; e.x = __builtin_amdgcn_exp2f(t.x); e.y = __builtin_amdgcn_exp2f(t.y); e = e + 1.0f; f32x2 r; r.x = __builtin_amdgcn_rcpf(e.x); r.y = __builtin_amdgcn_rcpf(e.y); return x * r; }
;     __device__ __forceinline__ void operator()(const pg8::f32x4 (&acc)[2][2][4][2], const pg8::Unit& u, int wr, int wc, int fr, int fq) const {
;     ...
;                     } else if (pn < 44) {
; #pragma unroll
;                         for (int e = 0; e < 8; e += 2) { const f32x2 g2 = silu_pk((f32x2){v[e], v[e + 1]}); v[e] = g2.x; v[e + 1] = g2.y; }
;                         st_bf16((bf16*)(ws + WS_ZB) + (size_t)r * 2048 + (pn - 36) * 256 + cl, v);
;                     } else if (pn < 48) {
;                         st_bf16((bf16*)(ws + WS_QC) + (size_t)r * 1024 + (pn - 44) * 256 + cl, v);
;                     } else if (pn < 50) {
;                         const bool isv = pn == 49;
;                         st_bf16((bf16*)(ws + (isv ? WS_VC : WS_KC)) + (size_t)r * 256 + cl, v);
;                         if (r < PT) st_f32(out + (isv ? O_PV : O_PK) + ((size_t)l * PT + r) * 256 + cl, v);
;                         else st_f32(out + (isv ? O_SV : O_SK) + ((size_t)l * ST + (r - PT)) * 256 + cl, v);
;                     } else if (pn < 54) {
; #pragma unroll
;                         for (int e = 0; e < 8; e += 2) { const f32x2 g2 = silu_pk((f32x2){v[e], v[e + 1]}); v[e] = g2.x; v[e + 1] = g2.y; }
;                         st_bf16((bf16*)(ws + WS_ZC) + (size_t)r * 1024 + (pn - 50) * 256 + cl, v);
.LBB0_630:
	s_andn2_b64 vcc, exec, s[6:7]
	s_cbranch_vccnz .LBB0_632
	v_mul_f32_e64 v84, v60, s48
	v_mul_f32_e64 v85, v61, s48
	v_mul_f32_e64 v86, v62, s48
	v_mul_f32_e64 v87, v63, s48
	v_exp_f32_e32 v84, v84
	v_exp_f32_e32 v85, v85
	v_exp_f32_e32 v86, v86
	v_exp_f32_e32 v87, v87
	v_mul_f32_e64 v88, v56, s48
	v_mul_f32_e64 v89, v57, s48
	v_mul_f32_e64 v90, v58, s48
	v_mul_f32_e64 v91, v59, s48
	v_exp_f32_e32 v88, v88
	v_exp_f32_e32 v89, v89
	v_exp_f32_e32 v90, v90
	v_exp_f32_e32 v91, v91
	v_add_f32_e64 v84, v84, 1.0
	v_add_f32_e64 v85, v85, 1.0
	v_add_f32_e64 v86, v86, 1.0
	v_add_f32_e64 v87, v87, 1.0
	v_rcp_f32_e32 v84, v84
	v_rcp_f32_e32 v85, v85
	v_rcp_f32_e32 v86, v86
	v_rcp_f32_e32 v87, v87
	v_add_f32_e64 v88, v88, 1.0
	v_add_f32_e64 v89, v89, 1.0
	v_add_f32_e64 v90, v90, 1.0
	v_add_f32_e64 v91, v91, 1.0
	v_rcp_f32_e32 v88, v88
	v_rcp_f32_e32 v89, v89
	v_rcp_f32_e32 v90, v90
	v_rcp_f32_e32 v91, v91
	v_lshlrev_b32_e32 v136, 1, v140
	v_mul_f32_e64 v84, v60, v84
	v_mul_f32_e64 v85, v61, v85
	v_mul_f32_e64 v86, v62, v86
	v_mul_f32_e64 v87, v63, v87
	v_lshl_add_u64 v[94:95], v[68:69], 0, v[136:137]
	v_mul_f32_e64 v88, v56, v88
	v_mul_f32_e64 v89, v57, v89
	v_mul_f32_e64 v90, v58, v90
	v_mul_f32_e64 v91, v59, v91
	v_cvt_pk_bf16_f32 v84, v84, v85
	v_cvt_pk_bf16_f32 v85, v86, v87
	v_cvt_pk_bf16_f32 v86, v88, v89
	s_nop 0
	v_cvt_pk_bf16_f32 v87, v90, v91
	global_store_dwordx4 v[94:95], v[84:87], off

; __device__ __forceinline__ f32x2 silu_pk(f32x2 x) { const f32x2 t = x * -1.4426950408889634f; f32x2 e; e.x = __builtin_amdgcn_exp2f(t.x); e.y = __builtin_amdgcn_exp2f(t.y); e = e + 1.0f; f32x2 r; r.x = __builtin_amdgcn_rcpf(e.x); r.y = __builtin_amdgcn_rcpf(e.y); return x * r; }
;     __device__ __forceinline__ void operator()(const pg8::f32x4 (&acc)[2][2][4][2], const pg8::Unit& u, int wr, int wc, int fr, int fq) const {
;     ...
;                     } else if (pn < 44) {
; #pragma unroll
;                         for (int e = 0; e < 8; e += 2) { const f32x2 g2 = silu_pk((f32x2){v[e], v[e + 1]}); v[e] = g2.x; v[e + 1] = g2.y; }
;                         st_bf16((bf16*)(ws + WS_ZB) + (size_t)r * 2048 + (pn - 36) * 256 + cl, v);
;                     } else if (pn < 48) {
;                         st_bf16((bf16*)(ws + WS_QC) + (size_t)r * 1024 + (pn - 44) * 256 + cl, v);
;                     } else if (pn < 50) {
;                         const bool isv = pn == 49;
;                         st_bf16((bf16*)(ws + (isv ? WS_VC : WS_KC)) + (size_t)r * 256 + cl, v);
;                         if (r < PT) st_f32(out + (isv ? O_PV : O_PK) + ((size_t)l * PT + r) * 256 + cl, v);
;                         else st_f32(out + (isv ? O_SV : O_SK) + ((size_t)l * ST + (r - PT)) * 256 + cl, v);
;                     } else if (pn < 54) {
; #pragma unroll
;                         for (int e = 0; e < 8; e += 2) { const f32x2 g2 = silu_pk((f32x2){v[e], v[e + 1]}); v[e] = g2.x; v[e + 1] = g2.y; }
;                         st_bf16((bf16*)(ws + WS_ZC) + (size_t)r * 1024 + (pn - 50) * 256 + cl, v);
.LBB0_647:
	s_andn2_b64 vcc, exec, s[6:7]
	s_cbranch_vccnz .LBB0_649
	v_mul_f32_e64 v56, v52, s48
	v_mul_f32_e64 v57, v53, s48
	v_mul_f32_e64 v58, v54, s48
	v_mul_f32_e64 v59, v55, s48
	v_exp_f32_e32 v56, v56
	v_exp_f32_e32 v57, v57
	v_exp_f32_e32 v58, v58
	v_exp_f32_e32 v59, v59
	v_mul_f32_e64 v60, v48, s48
	v_mul_f32_e64 v61, v49, s48
	v_mul_f32_e64 v62, v50, s48
	v_mul_f32_e64 v63, v51, s48
	v_exp_f32_e32 v60, v60
	v_exp_f32_e32 v61, v61
	v_exp_f32_e32 v62, v62
	v_exp_f32_e32 v63, v63
	v_add_f32_e64 v56, v56, 1.0
	v_add_f32_e64 v57, v57, 1.0
	v_add_f32_e64 v58, v58, 1.0
	v_add_f32_e64 v59, v59, 1.0
	v_rcp_f32_e32 v56, v56
	v_rcp_f32_e32 v57, v57
	v_rcp_f32_e32 v58, v58
	v_rcp_f32_e32 v59, v59
	v_add_f32_e64 v60, v60, 1.0
	v_add_f32_e64 v61, v61, 1.0
	v_add_f32_e64 v62, v62, 1.0
	v_add_f32_e64 v63, v63, 1.0
	v_rcp_f32_e32 v60, v60
	v_rcp_f32_e32 v61, v61
	v_rcp_f32_e32 v62, v62
	v_rcp_f32_e32 v63, v63
	v_lshlrev_b32_e32 v136, 1, v142
	v_mul_f32_e64 v56, v52, v56
	v_mul_f32_e64 v57, v53, v57
	v_mul_f32_e64 v58, v54, v58
	v_mul_f32_e64 v59, v55, v59
	v_lshl_add_u64 v[78:79], v[78:79], 0, v[136:137]
	v_mul_f32_e64 v60, v48, v60
	v_mul_f32_e64 v61, v49, v61
	v_mul_f32_e64 v62, v50, v62
	v_mul_f32_e64 v63, v51, v63
	v_cvt_pk_bf16_f32 v56, v56, v57
	v_cvt_pk_bf16_f32 v57, v58, v59
	v_cvt_pk_bf16_f32 v58, v60, v61
	s_nop 0
	v_cvt_pk_bf16_f32 v59, v62, v63
	global_store_dwordx4 v[78:79], v[56:59], off

; __device__ __forceinline__ f32x2 silu_pk(f32x2 x) { const f32x2 t = x * -1.4426950408889634f; f32x2 e; e.x = __builtin_amdgcn_exp2f(t.x); e.y = __builtin_amdgcn_exp2f(t.y); e = e + 1.0f; f32x2 r; r.x = __builtin_amdgcn_rcpf(e.x); r.y = __builtin_amdgcn_rcpf(e.y); return x * r; }
;     __device__ __forceinline__ void operator()(const pg8::f32x4 (&acc)[2][2][4][2], const pg8::Unit& u, int wr, int wc, int fr, int fq) const {
;     ...
;                     } else if (pn < 44) {
; #pragma unroll
;                         for (int e = 0; e < 8; e += 2) { const f32x2 g2 = silu_pk((f32x2){v[e], v[e + 1]}); v[e] = g2.x; v[e + 1] = g2.y; }
;                         st_bf16((bf16*)(ws + WS_ZB) + (size_t)r * 2048 + (pn - 36) * 256 + cl, v);
;                     } else if (pn < 48) {
;                         st_bf16((bf16*)(ws + WS_QC) + (size_t)r * 1024 + (pn - 44) * 256 + cl, v);
;                     } else if (pn < 50) {
;                         const bool isv = pn == 49;
;                         st_bf16((bf16*)(ws + (isv ? WS_VC : WS_KC)) + (size_t)r * 256 + cl, v);
;                         if (r < PT) st_f32(out + (isv ? O_PV : O_PK) + ((size_t)l * PT + r) * 256 + cl, v);
;                         else st_f32(out + (isv ? O_SV : O_SK) + ((size_t)l * ST + (r - PT)) * 256 + cl, v);
;                     } else if (pn < 54) {
; #pragma unroll
;                         for (int e = 0; e < 8; e += 2) { const f32x2 g2 = silu_pk((f32x2){v[e], v[e + 1]}); v[e] = g2.x; v[e + 1] = g2.y; }
;                         st_bf16((bf16*)(ws + WS_ZC) + (size_t)r * 1024 + (pn - 50) * 256 + cl, v);
.LBB0_660:
	s_andn2_b64 vcc, exec, s[6:7]
	s_cbranch_vccnz .LBB0_662
	v_mul_f32_e64 v56, v52, s48
	v_mul_f32_e64 v57, v53, s48
	v_mul_f32_e64 v58, v54, s48
	v_mul_f32_e64 v59, v55, s48
	v_exp_f32_e32 v56, v56
	v_exp_f32_e32 v57, v57
	v_exp_f32_e32 v58, v58
	v_exp_f32_e32 v59, v59
	v_mul_f32_e64 v60, v48, s48
	v_mul_f32_e64 v61, v49, s48
	v_mul_f32_e64 v62, v50, s48
	v_mul_f32_e64 v63, v51, s48
	v_exp_f32_e32 v60, v60
	v_exp_f32_e32 v61, v61
	v_exp_f32_e32 v62, v62
	v_exp_f32_e32 v63, v63
	v_add_f32_e64 v56, v56, 1.0
	v_add_f32_e64 v57, v57, 1.0
	v_add_f32_e64 v58, v58, 1.0
	v_add_f32_e64 v59, v59, 1.0
	v_rcp_f32_e32 v56, v56
	v_rcp_f32_e32 v57, v57
	v_rcp_f32_e32 v58, v58
	v_rcp_f32_e32 v59, v59
	v_add_f32_e64 v60, v60, 1.0
	v_add_f32_e64 v61, v61, 1.0
	v_add_f32_e64 v62, v62, 1.0
	v_add_f32_e64 v63, v63, 1.0
	v_rcp_f32_e32 v60, v60
	v_rcp_f32_e32 v61, v61
	v_rcp_f32_e32 v62, v62
	v_rcp_f32_e32 v63, v63
	v_lshlrev_b32_e32 v136, 1, v142
	v_mul_f32_e64 v56, v52, v56
	v_mul_f32_e64 v57, v53, v57
	v_mul_f32_e64 v58, v54, v58
	v_mul_f32_e64 v59, v55, v59
	v_lshl_add_u64 v[68:69], v[68:69], 0, v[136:137]
	v_mul_f32_e64 v60, v48, v60
	v_mul_f32_e64 v61, v49, v61
	v_mul_f32_e64 v62, v50, v62
	v_mul_f32_e64 v63, v51, v63
	v_cvt_pk_bf16_f32 v56, v56, v57
	v_cvt_pk_bf16_f32 v57, v58, v59
	v_cvt_pk_bf16_f32 v58, v60, v61
	s_nop 0
	v_cvt_pk_bf16_f32 v59, v62, v63
	global_store_dwordx4 v[68:69], v[56:59], off

; __device__ __forceinline__ f32x2 silu_pk(f32x2 x) { const f32x2 t = x * -1.4426950408889634f; f32x2 e; e.x = __builtin_amdgcn_exp2f(t.x); e.y = __builtin_amdgcn_exp2f(t.y); e = e + 1.0f; f32x2 r; r.x = __builtin_amdgcn_rcpf(e.x); r.y = __builtin_amdgcn_rcpf(e.y); return x * r; }
; __device__ __forceinline__ f32x2 gelu_pk(f32x2 x) { const f32x2 x2 = x * x; const f32x2 t = (x2 * 0.044715f + 1.0f) * (x * -2.302208198144325f); f32x2 e; e.x = __builtin_amdgcn_exp2f(t.x); e.y = __builtin_amdgcn_exp2f(t.y); e = e + 1.0f; f32x2 r; r.x = __builtin_amdgcn_rcpf(e.x); r.y = __builtin_amd ...
;     __device__ __forceinline__ void operator()(const pg8::f32x4 (&acc)[2][2][4][2], const pg8::Unit& u, int wr, int wc, int fr, int fq) const {
;     ...
;                     if (pn < 12) {
;                         const int seg = pn >> 2, cc = (pn & 3) * 256 + cl;
;                         if (seg < 2) {
; #pragma unroll
;                             for (int e = 0; e < 8; e += 2) { const f32x2 g2 = gelu_pk((f32x2){v[e], v[e + 1]}); v[e] = g2.x; v[e + 1] = g2.y; }
;                         } else {
; #pragma unroll
;                             for (int e = 0; e < 8; e += 2) { const f32x2 g2 = silu_pk((f32x2){v[e], v[e + 1]}); v[e] = g2.x; v[e + 1] = g2.y; }
;                         }
;                         bf16* base = (bf16*)(ws + (seg == 0 ? WS_UA : seg == 1 ? WS_VA : WS_ZA));
;                         st_bf16(base + (size_t)r * 1024 + cc, v);
.LBB0_669:
	s_andn2_b64 vcc, exec, s[16:17]
	s_mov_b64 s[96:97], -1
	s_cbranch_vccnz .LBB0_671
	v_mul_f32_e64 v86, v62, s48
	v_mul_f32_e64 v87, v63, s48
	v_mul_f32_e64 v84, v60, s48
	v_mul_f32_e64 v85, v61, s48
	v_exp_f32_e32 v86, v86
	v_exp_f32_e32 v87, v87
	v_mul_f32_e64 v88, v56, s48
	v_mul_f32_e64 v89, v57, s48
	v_exp_f32_e32 v84, v84
	v_exp_f32_e32 v85, v85
	v_exp_f32_e32 v88, v88
	v_exp_f32_e32 v89, v89
	v_add_f32_e64 v86, v86, 1.0
	v_add_f32_e64 v87, v87, 1.0
	v_add_f32_e64 v84, v84, 1.0
	v_add_f32_e64 v85, v85, 1.0
	v_rcp_f32_e32 v90, v86
	v_rcp_f32_e32 v91, v87
	v_add_f32_e64 v86, v88, 1.0
	v_add_f32_e64 v87, v89, 1.0
	v_rcp_f32_e32 v84, v84
	v_rcp_f32_e32 v85, v85
	v_rcp_f32_e32 v88, v86
	v_rcp_f32_e32 v89, v87
	s_mov_b64 s[96:97], 0
	v_mul_f32_e64 v86, v60, v84
	v_mul_f32_e64 v87, v61, v85
	v_mul_f32_e64 v84, v62, v90
	v_mul_f32_e64 v85, v63, v91
	v_mul_f32_e64 v88, v56, v88
	v_mul_f32_e64 v89, v57, v89
	v_mul_f32_e64 v90, v58, s48
	v_mul_f32_e64 v91, v59, s48
.LBB0_671:
	s_andn2_b64 vcc, exec, s[96:97]
	s_cbranch_vccnz .LBB0_673
	v_mul_f32_e64 v86, v60, v60
	v_mul_f32_e64 v87, v61, v61
	v_mul_f32_e64 v88, v60, s52
	v_mul_f32_e64 v89, v61, s52
	v_fma_f32 v86, v86, s50, 1.0
	v_fma_f32 v87, v87, s50, 1.0
	v_mul_f32_e64 v84, v62, v62
	v_mul_f32_e64 v85, v63, v63
	v_mul_f32_e64 v86, v88, v86
	v_mul_f32_e64 v87, v89, v87
	v_mul_f32_e64 v88, v56, s52
	v_mul_f32_e64 v89, v57, s52
	v_exp_f32_e32 v86, v86
	v_exp_f32_e32 v87, v87
	s_nop 0
	v_add_f32_e64 v86, v86, 1.0
	v_add_f32_e64 v87, v87, 1.0
	s_nop 0
	v_rcp_f32_e32 v86, v86
	v_rcp_f32_e32 v87, v87
	s_nop 0
	v_mul_f32_e64 v86, v60, v86
	v_mul_f32_e64 v87, v61, v87
	v_fma_f32 v60, v84, s50, 1.0
	v_fma_f32 v61, v85, s50, 1.0
	v_mul_f32_e64 v84, v62, s52
	v_mul_f32_e64 v85, v63, s52
	s_nop 0
	v_mul_f32_e64 v60, v84, v60
	v_mul_f32_e64 v61, v85, v61
	s_nop 0
	v_exp_f32_e32 v60, v60
	v_exp_f32_e32 v61, v61
	s_nop 0
	v_add_f32_e64 v60, v60, 1.0
	v_add_f32_e64 v61, v61, 1.0
	s_nop 0
	v_rcp_f32_e32 v60, v60
	v_rcp_f32_e32 v61, v61
	s_nop 0
	v_mul_f32_e64 v84, v62, v60
	v_mul_f32_e64 v85, v63, v61
	v_mul_f32_e64 v62, v56, v56
	v_mul_f32_e64 v63, v57, v57
	v_mul_f32_e64 v60, v58, v58
	v_mul_f32_e64 v61, v59, v59
	v_fma_f32 v62, v62, s50, 1.0
	v_fma_f32 v63, v63, s50, 1.0
	s_nop 0
	v_mul_f32_e64 v62, v88, v62
	v_mul_f32_e64 v63, v89, v63
	s_nop 0
	v_exp_f32_e32 v62, v62
	v_exp_f32_e32 v63, v63
	s_nop 0
	v_add_f32_e64 v62, v62, 1.0
	v_add_f32_e64 v63, v63, 1.0
	s_nop 0
	v_rcp_f32_e32 v62, v62
	v_rcp_f32_e32 v63, v63
	s_nop 0
	v_mul_f32_e64 v88, v56, v62
	v_mul_f32_e64 v89, v57, v63
	v_fma_f32 v56, v60, s50, 1.0
	v_fma_f32 v57, v61, s50, 1.0
	v_mul_f32_e64 v60, v58, s52
	v_mul_f32_e64 v61, v59, s52
	s_nop 0
	v_mul_f32_e64 v90, v60, v56
	v_mul_f32_e64 v91, v61, v57
.LBB0_673:
	s_nop 0
	v_exp_f32_e32 v56, v90
	v_exp_f32_e32 v57, v91
	v_or_b32_e32 v62, s26, v140
	v_lshlrev_b32_e32 v136, 1, v62
	v_lshl_add_u64 v[62:63], v[80:81], 0, v[136:137]
	v_add_f32_e64 v56, v56, 1.0
	v_add_f32_e64 v57, v57, 1.0
	s_nop 0
	v_rcp_f32_e32 v56, v56
	v_rcp_f32_e32 v57, v57
	s_nop 0
	v_mul_f32_e64 v60, v58, v56
	v_mul_f32_e64 v61, v59, v57
	v_cvt_pk_bf16_f32 v56, v86, v87
	v_cvt_pk_bf16_f32 v57, v84, v85
	v_cvt_pk_bf16_f32 v58, v88, v89
	s_nop 0
	v_cvt_pk_bf16_f32 v59, v60, v61
	global_store_dwordx4 v[62:63], v[56:59], off
	s_and_b64 vcc, exec, s[10:11]
	s_mov_b64 s[6:7], -1
	s_cbranch_vccz .LBB0_639

; __device__ __forceinline__ f32x2 silu_pk(f32x2 x) { const f32x2 t = x * -1.4426950408889634f; f32x2 e; e.x = __builtin_amdgcn_exp2f(t.x); e.y = __builtin_amdgcn_exp2f(t.y); e = e + 1.0f; f32x2 r; r.x = __builtin_amdgcn_rcpf(e.x); r.y = __builtin_amdgcn_rcpf(e.y); return x * r; }
; __device__ __forceinline__ f32x2 gelu_pk(f32x2 x) { const f32x2 x2 = x * x; const f32x2 t = (x2 * 0.044715f + 1.0f) * (x * -2.302208198144325f); f32x2 e; e.x = __builtin_amdgcn_exp2f(t.x); e.y = __builtin_amdgcn_exp2f(t.y); e = e + 1.0f; f32x2 r; r.x = __builtin_amdgcn_rcpf(e.x); r.y = __builtin_amd ...
;     __device__ __forceinline__ void operator()(const pg8::f32x4 (&acc)[2][2][4][2], const pg8::Unit& u, int wr, int wc, int fr, int fq) const {
;     ...
;                     if (pn < 12) {
;                         const int seg = pn >> 2, cc = (pn & 3) * 256 + cl;
;                         if (seg < 2) {
; #pragma unroll
;                             for (int e = 0; e < 8; e += 2) { const f32x2 g2 = gelu_pk((f32x2){v[e], v[e + 1]}); v[e] = g2.x; v[e + 1] = g2.y; }
;                         } else {
; #pragma unroll
;                             for (int e = 0; e < 8; e += 2) { const f32x2 g2 = silu_pk((f32x2){v[e], v[e + 1]}); v[e] = g2.x; v[e + 1] = g2.y; }
;                         }
;                         bf16* base = (bf16*)(ws + (seg == 0 ? WS_UA : seg == 1 ? WS_VA : WS_ZA));
;                         st_bf16(base + (size_t)r * 1024 + cc, v);
.LBB0_675:
	s_andn2_b64 vcc, exec, s[16:17]
	s_mov_b64 s[0:1], -1
	s_cbranch_vccnz .LBB0_677
	v_mul_f32_e64 v56, v52, s48
	v_mul_f32_e64 v57, v53, s48
	v_mul_f32_e64 v58, v54, s48
	v_mul_f32_e64 v59, v55, s48
	v_mul_f32_e64 v60, v48, s48
	v_mul_f32_e64 v61, v49, s48
	v_exp_f32_e32 v56, v56
	v_exp_f32_e32 v57, v57
	v_exp_f32_e32 v58, v58
	v_exp_f32_e32 v59, v59
	v_exp_f32_e32 v60, v60
	v_exp_f32_e32 v61, v61
	v_add_f32_e64 v56, v56, 1.0
	v_add_f32_e64 v57, v57, 1.0
	v_add_f32_e64 v58, v58, 1.0
	v_add_f32_e64 v59, v59, 1.0
	v_rcp_f32_e32 v56, v56
	v_add_f32_e64 v60, v60, 1.0
	v_add_f32_e64 v61, v61, 1.0
	v_rcp_f32_e32 v57, v57
	v_rcp_f32_e32 v58, v58
	v_rcp_f32_e32 v59, v59
	v_rcp_f32_e32 v60, v60
	v_rcp_f32_e32 v61, v61
	v_mul_f32_e64 v56, v52, v56
	v_mul_f32_e64 v57, v53, v57
	v_mul_f32_e64 v58, v54, v58
	v_mul_f32_e64 v59, v55, v59
	v_mul_f32_e64 v62, v50, s48
	v_mul_f32_e64 v63, v51, s48
	v_mul_f32_e64 v60, v48, v60
	v_mul_f32_e64 v61, v49, v61
	s_mov_b64 s[0:1], 0
.LBB0_677:
	s_andn2_b64 vcc, exec, s[0:1]
	s_cbranch_vccnz .LBB0_679
	v_mul_f32_e64 v56, v52, v52
	v_mul_f32_e64 v57, v53, v53
	v_mul_f32_e64 v60, v52, s52
	v_mul_f32_e64 v61, v53, s52
	v_fma_f32 v56, v56, s50, 1.0
	v_fma_f32 v57, v57, s50, 1.0
	v_mul_f32_e64 v58, v54, v54
	v_mul_f32_e64 v59, v55, v55
	v_mul_f32_e64 v56, v60, v56
	v_mul_f32_e64 v57, v61, v57
	v_mul_f32_e64 v60, v48, s52
	v_mul_f32_e64 v61, v49, s52
	v_exp_f32_e32 v56, v56
	v_exp_f32_e32 v57, v57
	s_nop 0
	v_add_f32_e64 v56, v56, 1.0
	v_add_f32_e64 v57, v57, 1.0
	s_nop 0
	v_rcp_f32_e32 v56, v56
	v_rcp_f32_e32 v57, v57
	s_nop 0
	v_mul_f32_e64 v56, v52, v56
	v_mul_f32_e64 v57, v53, v57
	v_fma_f32 v52, v58, s50, 1.0
	v_fma_f32 v53, v59, s50, 1.0
	v_mul_f32_e64 v58, v54, s52
	v_mul_f32_e64 v59, v55, s52
	s_nop 0
	v_mul_f32_e64 v52, v58, v52
	v_mul_f32_e64 v53, v59, v53
	s_nop 0
	v_exp_f32_e32 v52, v52
	v_exp_f32_e32 v53, v53
	s_nop 0
	v_add_f32_e64 v52, v52, 1.0
	v_add_f32_e64 v53, v53, 1.0
	s_nop 0
	v_rcp_f32_e32 v52, v52
	v_rcp_f32_e32 v53, v53
	s_nop 0
	v_mul_f32_e64 v58, v54, v52
	v_mul_f32_e64 v59, v55, v53
	v_mul_f32_e64 v54, v48, v48
	v_mul_f32_e64 v55, v49, v49
	v_mul_f32_e64 v52, v50, v50
	v_mul_f32_e64 v53, v51, v51
	v_fma_f32 v54, v54, s50, 1.0
	v_fma_f32 v55, v55, s50, 1.0
	s_nop 0
	v_mul_f32_e64 v54, v60, v54
	v_mul_f32_e64 v55, v61, v55
	s_nop 0
	v_exp_f32_e32 v54, v54
	v_exp_f32_e32 v55, v55
	s_nop 0
	v_add_f32_e64 v54, v54, 1.0
	v_add_f32_e64 v55, v55, 1.0
	s_nop 0
	v_rcp_f32_e32 v54, v54
	v_rcp_f32_e32 v55, v55
	s_nop 0
	v_mul_f32_e64 v60, v48, v54
	v_mul_f32_e64 v61, v49, v55
	v_fma_f32 v48, v52, s50, 1.0
	v_fma_f32 v49, v53, s50, 1.0
	v_mul_f32_e64 v52, v50, s52
	v_mul_f32_e64 v53, v51, s52
	s_nop 0
	v_mul_f32_e64 v62, v52, v48
	v_mul_f32_e64 v63, v53, v49
.LBB0_679:
	s_nop 0
	v_exp_f32_e32 v48, v62
	v_exp_f32_e32 v49, v63
	v_add_lshl_u32 v136, s26, v140, 1
	v_lshl_add_u64 v[54:55], v[80:81], 0, v[136:137]
	v_add_f32_e64 v48, v48, 1.0
	v_add_f32_e64 v49, v49, 1.0
	s_nop 0
	v_rcp_f32_e32 v48, v48
	v_rcp_f32_e32 v49, v49
	s_nop 0
	v_mul_f32_e64 v52, v50, v48
	v_mul_f32_e64 v53, v51, v49
	v_cvt_pk_bf16_f32 v48, v56, v57
	v_cvt_pk_bf16_f32 v49, v58, v59
	v_cvt_pk_bf16_f32 v50, v60, v61
	s_nop 0
	v_cvt_pk_bf16_f32 v51, v52, v53
	global_store_dwordx4 v[54:55], v[48:51], off offset:256

; __device__ __forceinline__ f32x2 silu_pk(f32x2 x) { const f32x2 t = x * -1.4426950408889634f; f32x2 e; e.x = __builtin_amdgcn_exp2f(t.x); e.y = __builtin_amdgcn_exp2f(t.y); e = e + 1.0f; f32x2 r; r.x = __builtin_amdgcn_rcpf(e.x); r.y = __builtin_amdgcn_rcpf(e.y); return x * r; }
;     __device__ __forceinline__ void operator()(const pg8::f32x4 (&acc)[2][2][4][2], const pg8::Unit& u, int wr, int wc, int fr, int fq) const {
;     ...
;                     } else if (pn < 44) {
; #pragma unroll
;                         for (int e = 0; e < 8; e += 2) { const f32x2 g2 = silu_pk((f32x2){v[e], v[e + 1]}); v[e] = g2.x; v[e + 1] = g2.y; }
;                         st_bf16((bf16*)(ws + WS_ZB) + (size_t)r * 2048 + (pn - 36) * 256 + cl, v);
;                     } else if (pn < 48) {
;                         st_bf16((bf16*)(ws + WS_QC) + (size_t)r * 1024 + (pn - 44) * 256 + cl, v);
;                     } else if (pn < 50) {
;                         const bool isv = pn == 49;
;                         st_bf16((bf16*)(ws + (isv ? WS_VC : WS_KC)) + (size_t)r * 256 + cl, v);
;                         if (r < PT) st_f32(out + (isv ? O_PV : O_PK) + ((size_t)l * PT + r) * 256 + cl, v);
;                         else st_f32(out + (isv ? O_SV : O_SK) + ((size_t)l * ST + (r - PT)) * 256 + cl, v);
;                     } else if (pn < 54) {
; #pragma unroll
;                         for (int e = 0; e < 8; e += 2) { const f32x2 g2 = silu_pk((f32x2){v[e], v[e + 1]}); v[e] = g2.x; v[e + 1] = g2.y; }
;                         st_bf16((bf16*)(ws + WS_ZC) + (size_t)r * 1024 + (pn - 50) * 256 + cl, v);
.LBB0_706:
	s_andn2_b64 vcc, exec, s[6:7]
	s_cbranch_vccnz .LBB0_708
	v_mul_f32_e64 v68, v44, s48
	v_mul_f32_e64 v69, v45, s48
	v_mul_f32_e64 v70, v46, s48
	v_mul_f32_e64 v71, v47, s48
	v_exp_f32_e32 v68, v68
	v_exp_f32_e32 v69, v69
	v_exp_f32_e32 v70, v70
	v_exp_f32_e32 v71, v71
	v_mul_f32_e64 v72, v40, s48
	v_mul_f32_e64 v73, v41, s48
	v_mul_f32_e64 v74, v42, s48
	v_mul_f32_e64 v75, v43, s48
	v_exp_f32_e32 v72, v72
	v_exp_f32_e32 v73, v73
	v_exp_f32_e32 v74, v74
	v_exp_f32_e32 v75, v75
	v_add_f32_e64 v68, v68, 1.0
	v_add_f32_e64 v69, v69, 1.0
	v_add_f32_e64 v70, v70, 1.0
	v_add_f32_e64 v71, v71, 1.0
	v_rcp_f32_e32 v68, v68
	v_rcp_f32_e32 v69, v69
	v_rcp_f32_e32 v70, v70
	v_rcp_f32_e32 v71, v71
	v_add_f32_e64 v72, v72, 1.0
	v_add_f32_e64 v73, v73, 1.0
	v_add_f32_e64 v74, v74, 1.0
	v_add_f32_e64 v75, v75, 1.0
	v_rcp_f32_e32 v72, v72
	v_rcp_f32_e32 v73, v73
	v_rcp_f32_e32 v74, v74
	v_rcp_f32_e32 v75, v75
	v_lshlrev_b32_e32 v136, 1, v140
	v_mul_f32_e64 v68, v44, v68
	v_mul_f32_e64 v69, v45, v69
	v_mul_f32_e64 v70, v46, v70
	v_mul_f32_e64 v71, v47, v71
	v_lshl_add_u64 v[76:77], v[60:61], 0, v[136:137]
	v_mul_f32_e64 v72, v40, v72
	v_mul_f32_e64 v73, v41, v73
	v_mul_f32_e64 v74, v42, v74
	v_mul_f32_e64 v75, v43, v75
	v_cvt_pk_bf16_f32 v68, v68, v69
	v_cvt_pk_bf16_f32 v69, v70, v71
	v_cvt_pk_bf16_f32 v70, v72, v73
	s_nop 0
	v_cvt_pk_bf16_f32 v71, v74, v75
	global_store_dwordx4 v[76:77], v[68:71], off

; __device__ __forceinline__ f32x2 silu_pk(f32x2 x) { const f32x2 t = x * -1.4426950408889634f; f32x2 e; e.x = __builtin_amdgcn_exp2f(t.x); e.y = __builtin_amdgcn_exp2f(t.y); e = e + 1.0f; f32x2 r; r.x = __builtin_amdgcn_rcpf(e.x); r.y = __builtin_amdgcn_rcpf(e.y); return x * r; }
;     __device__ __forceinline__ void operator()(const pg8::f32x4 (&acc)[2][2][4][2], const pg8::Unit& u, int wr, int wc, int fr, int fq) const {
;     ...
;                     } else if (pn < 44) {
; #pragma unroll
;                         for (int e = 0; e < 8; e += 2) { const f32x2 g2 = silu_pk((f32x2){v[e], v[e + 1]}); v[e] = g2.x; v[e + 1] = g2.y; }
;                         st_bf16((bf16*)(ws + WS_ZB) + (size_t)r * 2048 + (pn - 36) * 256 + cl, v);
;                     } else if (pn < 48) {
;                         st_bf16((bf16*)(ws + WS_QC) + (size_t)r * 1024 + (pn - 44) * 256 + cl, v);
;                     } else if (pn < 50) {
;                         const bool isv = pn == 49;
;                         st_bf16((bf16*)(ws + (isv ? WS_VC : WS_KC)) + (size_t)r * 256 + cl, v);
;                         if (r < PT) st_f32(out + (isv ? O_PV : O_PK) + ((size_t)l * PT + r) * 256 + cl, v);
;                         else st_f32(out + (isv ? O_SV : O_SK) + ((size_t)l * ST + (r - PT)) * 256 + cl, v);
;                     } else if (pn < 54) {
; #pragma unroll
;                         for (int e = 0; e < 8; e += 2) { const f32x2 g2 = silu_pk((f32x2){v[e], v[e + 1]}); v[e] = g2.x; v[e + 1] = g2.y; }
;                         st_bf16((bf16*)(ws + WS_ZC) + (size_t)r * 1024 + (pn - 50) * 256 + cl, v);
.LBB0_719:
	s_andn2_b64 vcc, exec, s[6:7]
	s_cbranch_vccnz .LBB0_721
	v_mul_f32_e64 v68, v44, s48
	v_mul_f32_e64 v69, v45, s48
	v_mul_f32_e64 v70, v46, s48
	v_mul_f32_e64 v71, v47, s48
	v_exp_f32_e32 v68, v68
	v_exp_f32_e32 v69, v69
	v_exp_f32_e32 v70, v70
	v_exp_f32_e32 v71, v71
	v_mul_f32_e64 v72, v40, s48
	v_mul_f32_e64 v73, v41, s48
	v_mul_f32_e64 v74, v42, s48
	v_mul_f32_e64 v75, v43, s48
	v_exp_f32_e32 v72, v72
	v_exp_f32_e32 v73, v73
	v_exp_f32_e32 v74, v74
	v_exp_f32_e32 v75, v75
	v_add_f32_e64 v68, v68, 1.0
	v_add_f32_e64 v69, v69, 1.0
	v_add_f32_e64 v70, v70, 1.0
	v_add_f32_e64 v71, v71, 1.0
	v_rcp_f32_e32 v68, v68
	v_rcp_f32_e32 v69, v69
	v_rcp_f32_e32 v70, v70
	v_rcp_f32_e32 v71, v71
	v_add_f32_e64 v72, v72, 1.0
	v_add_f32_e64 v73, v73, 1.0
	v_add_f32_e64 v74, v74, 1.0
	v_add_f32_e64 v75, v75, 1.0
	v_rcp_f32_e32 v72, v72
	v_rcp_f32_e32 v73, v73
	v_rcp_f32_e32 v74, v74
	v_rcp_f32_e32 v75, v75
	v_lshlrev_b32_e32 v136, 1, v140
	v_mul_f32_e64 v68, v44, v68
	v_mul_f32_e64 v69, v45, v69
	v_mul_f32_e64 v70, v46, v70
	v_mul_f32_e64 v71, v47, v71
	v_lshl_add_u64 v[76:77], v[50:51], 0, v[136:137]
	v_mul_f32_e64 v72, v40, v72
	v_mul_f32_e64 v73, v41, v73
	v_mul_f32_e64 v74, v42, v74
	v_mul_f32_e64 v75, v43, v75
	v_cvt_pk_bf16_f32 v68, v68, v69
	v_cvt_pk_bf16_f32 v69, v70, v71
	v_cvt_pk_bf16_f32 v70, v72, v73
	s_nop 0
	v_cvt_pk_bf16_f32 v71, v74, v75
	global_store_dwordx4 v[76:77], v[68:71], off

; __device__ __forceinline__ f32x2 silu_pk(f32x2 x) { const f32x2 t = x * -1.4426950408889634f; f32x2 e; e.x = __builtin_amdgcn_exp2f(t.x); e.y = __builtin_amdgcn_exp2f(t.y); e = e + 1.0f; f32x2 r; r.x = __builtin_amdgcn_rcpf(e.x); r.y = __builtin_amdgcn_rcpf(e.y); return x * r; }
;     __device__ __forceinline__ void operator()(const pg8::f32x4 (&acc)[2][2][4][2], const pg8::Unit& u, int wr, int wc, int fr, int fq) const {
;     ...
;                     } else if (pn < 44) {
; #pragma unroll
;                         for (int e = 0; e < 8; e += 2) { const f32x2 g2 = silu_pk((f32x2){v[e], v[e + 1]}); v[e] = g2.x; v[e + 1] = g2.y; }
;                         st_bf16((bf16*)(ws + WS_ZB) + (size_t)r * 2048 + (pn - 36) * 256 + cl, v);
;                     } else if (pn < 48) {
;                         st_bf16((bf16*)(ws + WS_QC) + (size_t)r * 1024 + (pn - 44) * 256 + cl, v);
;                     } else if (pn < 50) {
;                         const bool isv = pn == 49;
;                         st_bf16((bf16*)(ws + (isv ? WS_VC : WS_KC)) + (size_t)r * 256 + cl, v);
;                         if (r < PT) st_f32(out + (isv ? O_PV : O_PK) + ((size_t)l * PT + r) * 256 + cl, v);
;                         else st_f32(out + (isv ? O_SV : O_SK) + ((size_t)l * ST + (r - PT)) * 256 + cl, v);
;                     } else if (pn < 54) {
; #pragma unroll
;                         for (int e = 0; e < 8; e += 2) { const f32x2 g2 = silu_pk((f32x2){v[e], v[e + 1]}); v[e] = g2.x; v[e + 1] = g2.y; }
;                         st_bf16((bf16*)(ws + WS_ZC) + (size_t)r * 1024 + (pn - 50) * 256 + cl, v);
.LBB0_736:
	s_andn2_b64 vcc, exec, s[6:7]
	s_cbranch_vccnz .LBB0_738
	v_mul_f32_e64 v40, v36, s48
	v_mul_f32_e64 v41, v37, s48
	v_mul_f32_e64 v42, v38, s48
	v_mul_f32_e64 v43, v39, s48
	v_exp_f32_e32 v40, v40
	v_exp_f32_e32 v41, v41
	v_exp_f32_e32 v42, v42
	v_exp_f32_e32 v43, v43
	v_mul_f32_e64 v44, v32, s48
	v_mul_f32_e64 v45, v33, s48
	v_mul_f32_e64 v46, v34, s48
	v_mul_f32_e64 v47, v35, s48
	v_exp_f32_e32 v44, v44
	v_exp_f32_e32 v45, v45
	v_exp_f32_e32 v46, v46
	v_exp_f32_e32 v47, v47
	v_add_f32_e64 v40, v40, 1.0
	v_add_f32_e64 v41, v41, 1.0
	v_add_f32_e64 v42, v42, 1.0
	v_add_f32_e64 v43, v43, 1.0
	v_rcp_f32_e32 v40, v40
	v_rcp_f32_e32 v41, v41
	v_rcp_f32_e32 v42, v42
	v_rcp_f32_e32 v43, v43
	v_add_f32_e64 v44, v44, 1.0
	v_add_f32_e64 v45, v45, 1.0
	v_add_f32_e64 v46, v46, 1.0
	v_add_f32_e64 v47, v47, 1.0
	v_rcp_f32_e32 v44, v44
	v_rcp_f32_e32 v45, v45
	v_rcp_f32_e32 v46, v46
	v_rcp_f32_e32 v47, v47
	v_lshlrev_b32_e32 v136, 1, v142
	v_mul_f32_e64 v40, v36, v40
	v_mul_f32_e64 v41, v37, v41
	v_mul_f32_e64 v42, v38, v42
	v_mul_f32_e64 v43, v39, v43
	v_lshl_add_u64 v[60:61], v[60:61], 0, v[136:137]
	v_mul_f32_e64 v44, v32, v44
	v_mul_f32_e64 v45, v33, v45
	v_mul_f32_e64 v46, v34, v46
	v_mul_f32_e64 v47, v35, v47
	v_cvt_pk_bf16_f32 v40, v40, v41
	v_cvt_pk_bf16_f32 v41, v42, v43
	v_cvt_pk_bf16_f32 v42, v44, v45
	s_nop 0
	v_cvt_pk_bf16_f32 v43, v46, v47
	global_store_dwordx4 v[60:61], v[40:43], off

; __device__ __forceinline__ f32x2 silu_pk(f32x2 x) { const f32x2 t = x * -1.4426950408889634f; f32x2 e; e.x = __builtin_amdgcn_exp2f(t.x); e.y = __builtin_amdgcn_exp2f(t.y); e = e + 1.0f; f32x2 r; r.x = __builtin_amdgcn_rcpf(e.x); r.y = __builtin_amdgcn_rcpf(e.y); return x * r; }
;     __device__ __forceinline__ void operator()(const pg8::f32x4 (&acc)[2][2][4][2], const pg8::Unit& u, int wr, int wc, int fr, int fq) const {
;     ...
;                     } else if (pn < 44) {
; #pragma unroll
;                         for (int e = 0; e < 8; e += 2) { const f32x2 g2 = silu_pk((f32x2){v[e], v[e + 1]}); v[e] = g2.x; v[e + 1] = g2.y; }
;                         st_bf16((bf16*)(ws + WS_ZB) + (size_t)r * 2048 + (pn - 36) * 256 + cl, v);
;                     } else if (pn < 48) {
;                         st_bf16((bf16*)(ws + WS_QC) + (size_t)r * 1024 + (pn - 44) * 256 + cl, v);
;                     } else if (pn < 50) {
;                         const bool isv = pn == 49;
;                         st_bf16((bf16*)(ws + (isv ? WS_VC : WS_KC)) + (size_t)r * 256 + cl, v);
;                         if (r < PT) st_f32(out + (isv ? O_PV : O_PK) + ((size_t)l * PT + r) * 256 + cl, v);
;                         else st_f32(out + (isv ? O_SV : O_SK) + ((size_t)l * ST + (r - PT)) * 256 + cl, v);
;                     } else if (pn < 54) {
; #pragma unroll
;                         for (int e = 0; e < 8; e += 2) { const f32x2 g2 = silu_pk((f32x2){v[e], v[e + 1]}); v[e] = g2.x; v[e + 1] = g2.y; }
;                         st_bf16((bf16*)(ws + WS_ZC) + (size_t)r * 1024 + (pn - 50) * 256 + cl, v);
.LBB0_749:
	s_andn2_b64 vcc, exec, s[6:7]
	s_cbranch_vccnz .LBB0_751
	v_mul_f32_e64 v40, v36, s48
	v_mul_f32_e64 v41, v37, s48
	v_mul_f32_e64 v42, v38, s48
	v_mul_f32_e64 v43, v39, s48
	v_exp_f32_e32 v40, v40
	v_exp_f32_e32 v41, v41
	v_exp_f32_e32 v42, v42
	v_exp_f32_e32 v43, v43
	v_mul_f32_e64 v44, v32, s48
	v_mul_f32_e64 v45, v33, s48
	v_mul_f32_e64 v46, v34, s48
	v_mul_f32_e64 v47, v35, s48
	v_exp_f32_e32 v44, v44
	v_exp_f32_e32 v45, v45
	v_exp_f32_e32 v46, v46
	v_exp_f32_e32 v47, v47
	v_add_f32_e64 v40, v40, 1.0
	v_add_f32_e64 v41, v41, 1.0
	v_add_f32_e64 v42, v42, 1.0
	v_add_f32_e64 v43, v43, 1.0
	v_rcp_f32_e32 v40, v40
	v_rcp_f32_e32 v41, v41
	v_rcp_f32_e32 v42, v42
	v_rcp_f32_e32 v43, v43
	v_add_f32_e64 v44, v44, 1.0
	v_add_f32_e64 v45, v45, 1.0
	v_add_f32_e64 v46, v46, 1.0
	v_add_f32_e64 v47, v47, 1.0
	v_rcp_f32_e32 v44, v44
	v_rcp_f32_e32 v45, v45
	v_rcp_f32_e32 v46, v46
	v_rcp_f32_e32 v47, v47
	v_lshlrev_b32_e32 v136, 1, v142
	v_mul_f32_e64 v40, v36, v40
	v_mul_f32_e64 v41, v37, v41
	v_mul_f32_e64 v42, v38, v42
	v_mul_f32_e64 v43, v39, v43
	v_lshl_add_u64 v[50:51], v[50:51], 0, v[136:137]
	v_mul_f32_e64 v44, v32, v44
	v_mul_f32_e64 v45, v33, v45
	v_mul_f32_e64 v46, v34, v46
	v_mul_f32_e64 v47, v35, v47
	v_cvt_pk_bf16_f32 v40, v40, v41
	v_cvt_pk_bf16_f32 v41, v42, v43
	v_cvt_pk_bf16_f32 v42, v44, v45
	s_nop 0
	v_cvt_pk_bf16_f32 v43, v46, v47
	global_store_dwordx4 v[50:51], v[40:43], off

; __device__ __forceinline__ f32x2 silu_pk(f32x2 x) { const f32x2 t = x * -1.4426950408889634f; f32x2 e; e.x = __builtin_amdgcn_exp2f(t.x); e.y = __builtin_amdgcn_exp2f(t.y); e = e + 1.0f; f32x2 r; r.x = __builtin_amdgcn_rcpf(e.x); r.y = __builtin_amdgcn_rcpf(e.y); return x * r; }
; __device__ __forceinline__ f32x2 gelu_pk(f32x2 x) { const f32x2 x2 = x * x; const f32x2 t = (x2 * 0.044715f + 1.0f) * (x * -2.302208198144325f); f32x2 e; e.x = __builtin_amdgcn_exp2f(t.x); e.y = __builtin_amdgcn_exp2f(t.y); e = e + 1.0f; f32x2 r; r.x = __builtin_amdgcn_rcpf(e.x); r.y = __builtin_amd ...
;     __device__ __forceinline__ void operator()(const pg8::f32x4 (&acc)[2][2][4][2], const pg8::Unit& u, int wr, int wc, int fr, int fq) const {
;     ...
;                     if (pn < 12) {
;                         const int seg = pn >> 2, cc = (pn & 3) * 256 + cl;
;                         if (seg < 2) {
; #pragma unroll
;                             for (int e = 0; e < 8; e += 2) { const f32x2 g2 = gelu_pk((f32x2){v[e], v[e + 1]}); v[e] = g2.x; v[e + 1] = g2.y; }
;                         } else {
; #pragma unroll
;                             for (int e = 0; e < 8; e += 2) { const f32x2 g2 = silu_pk((f32x2){v[e], v[e + 1]}); v[e] = g2.x; v[e + 1] = g2.y; }
;                         }
;                         bf16* base = (bf16*)(ws + (seg == 0 ? WS_UA : seg == 1 ? WS_VA : WS_ZA));
;                         st_bf16(base + (size_t)r * 1024 + cc, v);
.LBB0_758:
	s_andn2_b64 vcc, exec, s[16:17]
	s_mov_b64 s[96:97], -1
	s_cbranch_vccnz .LBB0_760
	v_mul_f32_e64 v70, v46, s48
	v_mul_f32_e64 v71, v47, s48
	v_mul_f32_e64 v68, v44, s48
	v_mul_f32_e64 v69, v45, s48
	v_exp_f32_e32 v70, v70
	v_exp_f32_e32 v71, v71
	v_mul_f32_e64 v72, v40, s48
	v_mul_f32_e64 v73, v41, s48
	v_exp_f32_e32 v68, v68
	v_exp_f32_e32 v69, v69
	v_exp_f32_e32 v72, v72
	v_exp_f32_e32 v73, v73
	v_add_f32_e64 v70, v70, 1.0
	v_add_f32_e64 v71, v71, 1.0
	v_add_f32_e64 v68, v68, 1.0
	v_add_f32_e64 v69, v69, 1.0
	v_rcp_f32_e32 v74, v70
	v_rcp_f32_e32 v75, v71
	v_add_f32_e64 v70, v72, 1.0
	v_add_f32_e64 v71, v73, 1.0
	v_rcp_f32_e32 v68, v68
	v_rcp_f32_e32 v69, v69
	v_rcp_f32_e32 v72, v70
	v_rcp_f32_e32 v73, v71
	s_mov_b64 s[96:97], 0
	v_mul_f32_e64 v70, v44, v68
	v_mul_f32_e64 v71, v45, v69
	v_mul_f32_e64 v68, v46, v74
	v_mul_f32_e64 v69, v47, v75
	v_mul_f32_e64 v72, v40, v72
	v_mul_f32_e64 v73, v41, v73
	v_mul_f32_e64 v74, v42, s48
	v_mul_f32_e64 v75, v43, s48
.LBB0_760:
	s_andn2_b64 vcc, exec, s[96:97]
	s_cbranch_vccnz .LBB0_762
	v_mul_f32_e64 v70, v44, v44
	v_mul_f32_e64 v71, v45, v45
	v_mul_f32_e64 v72, v44, s52
	v_mul_f32_e64 v73, v45, s52
	v_fma_f32 v70, v70, s50, 1.0
	v_fma_f32 v71, v71, s50, 1.0
	v_mul_f32_e64 v68, v46, v46
	v_mul_f32_e64 v69, v47, v47
	v_mul_f32_e64 v70, v72, v70
	v_mul_f32_e64 v71, v73, v71
	v_mul_f32_e64 v72, v40, s52
	v_mul_f32_e64 v73, v41, s52
	v_exp_f32_e32 v70, v70
	v_exp_f32_e32 v71, v71
	s_nop 0
	v_add_f32_e64 v70, v70, 1.0
	v_add_f32_e64 v71, v71, 1.0
	s_nop 0
	v_rcp_f32_e32 v70, v70
	v_rcp_f32_e32 v71, v71
	s_nop 0
	v_mul_f32_e64 v70, v44, v70
	v_mul_f32_e64 v71, v45, v71
	v_fma_f32 v44, v68, s50, 1.0
	v_fma_f32 v45, v69, s50, 1.0
	v_mul_f32_e64 v68, v46, s52
	v_mul_f32_e64 v69, v47, s52
	s_nop 0
	v_mul_f32_e64 v44, v68, v44
	v_mul_f32_e64 v45, v69, v45
	s_nop 0
	v_exp_f32_e32 v44, v44
	v_exp_f32_e32 v45, v45
	s_nop 0
	v_add_f32_e64 v44, v44, 1.0
	v_add_f32_e64 v45, v45, 1.0
	s_nop 0
	v_rcp_f32_e32 v44, v44
	v_rcp_f32_e32 v45, v45
	s_nop 0
	v_mul_f32_e64 v68, v46, v44
	v_mul_f32_e64 v69, v47, v45
	v_mul_f32_e64 v46, v40, v40
	v_mul_f32_e64 v47, v41, v41
	v_mul_f32_e64 v44, v42, v42
	v_mul_f32_e64 v45, v43, v43
	v_fma_f32 v46, v46, s50, 1.0
	v_fma_f32 v47, v47, s50, 1.0
	s_nop 0
	v_mul_f32_e64 v46, v72, v46
	v_mul_f32_e64 v47, v73, v47
	s_nop 0
	v_exp_f32_e32 v46, v46
	v_exp_f32_e32 v47, v47
	s_nop 0
	v_add_f32_e64 v46, v46, 1.0
	v_add_f32_e64 v47, v47, 1.0
	s_nop 0
	v_rcp_f32_e32 v46, v46
	v_rcp_f32_e32 v47, v47
	s_nop 0
	v_mul_f32_e64 v72, v40, v46
	v_mul_f32_e64 v73, v41, v47
	v_fma_f32 v40, v44, s50, 1.0
	v_fma_f32 v41, v45, s50, 1.0
	v_mul_f32_e64 v44, v42, s52
	v_mul_f32_e64 v45, v43, s52
	s_nop 0
	v_mul_f32_e64 v74, v44, v40
	v_mul_f32_e64 v75, v45, v41
.LBB0_762:
	s_nop 0
	v_exp_f32_e32 v40, v74
	v_exp_f32_e32 v41, v75
	v_or_b32_e32 v46, s26, v140
	v_lshlrev_b32_e32 v136, 1, v46
	v_lshl_add_u64 v[46:47], v[62:63], 0, v[136:137]
	v_add_f32_e64 v40, v40, 1.0
	v_add_f32_e64 v41, v41, 1.0
	s_nop 0
	v_rcp_f32_e32 v40, v40
	v_rcp_f32_e32 v41, v41
	s_nop 0
	v_mul_f32_e64 v44, v42, v40
	v_mul_f32_e64 v45, v43, v41
	v_cvt_pk_bf16_f32 v40, v70, v71
	v_cvt_pk_bf16_f32 v41, v68, v69
	v_cvt_pk_bf16_f32 v42, v72, v73
	s_nop 0
	v_cvt_pk_bf16_f32 v43, v44, v45
	global_store_dwordx4 v[46:47], v[40:43], off
	s_and_b64 vcc, exec, s[10:11]
	s_mov_b64 s[6:7], -1
	s_cbranch_vccz .LBB0_728

; __device__ __forceinline__ f32x2 silu_pk(f32x2 x) { const f32x2 t = x * -1.4426950408889634f; f32x2 e; e.x = __builtin_amdgcn_exp2f(t.x); e.y = __builtin_amdgcn_exp2f(t.y); e = e + 1.0f; f32x2 r; r.x = __builtin_amdgcn_rcpf(e.x); r.y = __builtin_amdgcn_rcpf(e.y); return x * r; }
; __device__ __forceinline__ f32x2 gelu_pk(f32x2 x) { const f32x2 x2 = x * x; const f32x2 t = (x2 * 0.044715f + 1.0f) * (x * -2.302208198144325f); f32x2 e; e.x = __builtin_amdgcn_exp2f(t.x); e.y = __builtin_amdgcn_exp2f(t.y); e = e + 1.0f; f32x2 r; r.x = __builtin_amdgcn_rcpf(e.x); r.y = __builtin_amd ...
;     __device__ __forceinline__ void operator()(const pg8::f32x4 (&acc)[2][2][4][2], const pg8::Unit& u, int wr, int wc, int fr, int fq) const {
;     ...
;                     if (pn < 12) {
;                         const int seg = pn >> 2, cc = (pn & 3) * 256 + cl;
;                         if (seg < 2) {
; #pragma unroll
;                             for (int e = 0; e < 8; e += 2) { const f32x2 g2 = gelu_pk((f32x2){v[e], v[e + 1]}); v[e] = g2.x; v[e + 1] = g2.y; }
;                         } else {
; #pragma unroll
;                             for (int e = 0; e < 8; e += 2) { const f32x2 g2 = silu_pk((f32x2){v[e], v[e + 1]}); v[e] = g2.x; v[e + 1] = g2.y; }
;                         }
;                         bf16* base = (bf16*)(ws + (seg == 0 ? WS_UA : seg == 1 ? WS_VA : WS_ZA));
;                         st_bf16(base + (size_t)r * 1024 + cc, v);
.LBB0_764:
	s_andn2_b64 vcc, exec, s[16:17]
	s_mov_b64 s[0:1], -1
	s_cbranch_vccnz .LBB0_766
	v_mul_f32_e64 v40, v36, s48
	v_mul_f32_e64 v41, v37, s48
	v_mul_f32_e64 v42, v38, s48
	v_mul_f32_e64 v43, v39, s48
	v_mul_f32_e64 v44, v32, s48
	v_mul_f32_e64 v45, v33, s48
	v_exp_f32_e32 v40, v40
	v_exp_f32_e32 v41, v41
	v_exp_f32_e32 v42, v42
	v_exp_f32_e32 v43, v43
	v_exp_f32_e32 v44, v44
	v_exp_f32_e32 v45, v45
	v_add_f32_e64 v40, v40, 1.0
	v_add_f32_e64 v41, v41, 1.0
	v_add_f32_e64 v42, v42, 1.0
	v_add_f32_e64 v43, v43, 1.0
	v_rcp_f32_e32 v40, v40
	v_add_f32_e64 v44, v44, 1.0
	v_add_f32_e64 v45, v45, 1.0
	v_rcp_f32_e32 v41, v41
	v_rcp_f32_e32 v42, v42
	v_rcp_f32_e32 v43, v43
	v_rcp_f32_e32 v44, v44
	v_rcp_f32_e32 v45, v45
	v_mul_f32_e64 v40, v36, v40
	v_mul_f32_e64 v41, v37, v41
	v_mul_f32_e64 v42, v38, v42
	v_mul_f32_e64 v43, v39, v43
	v_mul_f32_e64 v46, v34, s48
	v_mul_f32_e64 v47, v35, s48
	v_mul_f32_e64 v44, v32, v44
	v_mul_f32_e64 v45, v33, v45
	s_mov_b64 s[0:1], 0
.LBB0_766:
	s_andn2_b64 vcc, exec, s[0:1]
	s_cbranch_vccnz .LBB0_768
	v_mul_f32_e64 v40, v36, v36
	v_mul_f32_e64 v41, v37, v37
	v_mul_f32_e64 v44, v36, s52
	v_mul_f32_e64 v45, v37, s52
	v_fma_f32 v40, v40, s50, 1.0
	v_fma_f32 v41, v41, s50, 1.0
	v_mul_f32_e64 v42, v38, v38
	v_mul_f32_e64 v43, v39, v39
	v_mul_f32_e64 v40, v44, v40
	v_mul_f32_e64 v41, v45, v41
	v_mul_f32_e64 v44, v32, s52
	v_mul_f32_e64 v45, v33, s52
	v_exp_f32_e32 v40, v40
	v_exp_f32_e32 v41, v41
	s_nop 0
	v_add_f32_e64 v40, v40, 1.0
	v_add_f32_e64 v41, v41, 1.0
	s_nop 0
	v_rcp_f32_e32 v40, v40
	v_rcp_f32_e32 v41, v41
	s_nop 0
	v_mul_f32_e64 v40, v36, v40
	v_mul_f32_e64 v41, v37, v41
	v_fma_f32 v36, v42, s50, 1.0
	v_fma_f32 v37, v43, s50, 1.0
	v_mul_f32_e64 v42, v38, s52
	v_mul_f32_e64 v43, v39, s52
	s_nop 0
	v_mul_f32_e64 v36, v42, v36
	v_mul_f32_e64 v37, v43, v37
	s_nop 0
	v_exp_f32_e32 v36, v36
	v_exp_f32_e32 v37, v37
	s_nop 0
	v_add_f32_e64 v36, v36, 1.0
	v_add_f32_e64 v37, v37, 1.0
	s_nop 0
	v_rcp_f32_e32 v36, v36
	v_rcp_f32_e32 v37, v37
	s_nop 0
	v_mul_f32_e64 v42, v38, v36
	v_mul_f32_e64 v43, v39, v37
	v_mul_f32_e64 v38, v32, v32
	v_mul_f32_e64 v39, v33, v33
	v_mul_f32_e64 v36, v34, v34
	v_mul_f32_e64 v37, v35, v35
	v_fma_f32 v38, v38, s50, 1.0
	v_fma_f32 v39, v39, s50, 1.0
	s_nop 0
	v_mul_f32_e64 v38, v44, v38
	v_mul_f32_e64 v39, v45, v39
	s_nop 0
	v_exp_f32_e32 v38, v38
	v_exp_f32_e32 v39, v39
	s_nop 0
	v_add_f32_e64 v38, v38, 1.0
	v_add_f32_e64 v39, v39, 1.0
	s_nop 0
	v_rcp_f32_e32 v38, v38
	v_rcp_f32_e32 v39, v39
	s_nop 0
	v_mul_f32_e64 v44, v32, v38
	v_mul_f32_e64 v45, v33, v39
	v_fma_f32 v32, v36, s50, 1.0
	v_fma_f32 v33, v37, s50, 1.0
	v_mul_f32_e64 v36, v34, s52
	v_mul_f32_e64 v37, v35, s52
	s_nop 0
	v_mul_f32_e64 v46, v36, v32
	v_mul_f32_e64 v47, v37, v33
.LBB0_768:
	s_nop 0
	v_exp_f32_e32 v32, v46
	v_exp_f32_e32 v33, v47
	v_add_lshl_u32 v136, s26, v140, 1
	v_lshl_add_u64 v[38:39], v[62:63], 0, v[136:137]
	v_add_f32_e64 v32, v32, 1.0
	v_add_f32_e64 v33, v33, 1.0
	s_nop 0
	v_rcp_f32_e32 v32, v32
	v_rcp_f32_e32 v33, v33
	s_nop 0
	v_mul_f32_e64 v36, v34, v32
	v_mul_f32_e64 v37, v35, v33
	v_cvt_pk_bf16_f32 v32, v40, v41
	v_cvt_pk_bf16_f32 v33, v42, v43
	v_cvt_pk_bf16_f32 v34, v44, v45
	s_nop 0
	v_cvt_pk_bf16_f32 v35, v36, v37
	global_store_dwordx4 v[38:39], v[32:35], off offset:256

; __device__ __forceinline__ f32x2 silu_pk(f32x2 x) { const f32x2 t = x * -1.4426950408889634f; f32x2 e; e.x = __builtin_amdgcn_exp2f(t.x); e.y = __builtin_amdgcn_exp2f(t.y); e = e + 1.0f; f32x2 r; r.x = __builtin_amdgcn_rcpf(e.x); r.y = __builtin_amdgcn_rcpf(e.y); return x * r; }
;     __device__ __forceinline__ void operator()(const pg8::f32x4 (&acc)[2][2][4][2], const pg8::Unit& u, int wr, int wc, int fr, int fq) const {
;     ...
;                     } else if (pn < 44) {
; #pragma unroll
;                         for (int e = 0; e < 8; e += 2) { const f32x2 g2 = silu_pk((f32x2){v[e], v[e + 1]}); v[e] = g2.x; v[e + 1] = g2.y; }
;                         st_bf16((bf16*)(ws + WS_ZB) + (size_t)r * 2048 + (pn - 36) * 256 + cl, v);
;                     } else if (pn < 48) {
;                         st_bf16((bf16*)(ws + WS_QC) + (size_t)r * 1024 + (pn - 44) * 256 + cl, v);
;                     } else if (pn < 50) {
;                         const bool isv = pn == 49;
;                         st_bf16((bf16*)(ws + (isv ? WS_VC : WS_KC)) + (size_t)r * 256 + cl, v);
;                         if (r < PT) st_f32(out + (isv ? O_PV : O_PK) + ((size_t)l * PT + r) * 256 + cl, v);
;                         else st_f32(out + (isv ? O_SV : O_SK) + ((size_t)l * ST + (r - PT)) * 256 + cl, v);
;                     } else if (pn < 54) {
; #pragma unroll
;                         for (int e = 0; e < 8; e += 2) { const f32x2 g2 = silu_pk((f32x2){v[e], v[e + 1]}); v[e] = g2.x; v[e + 1] = g2.y; }
;                         st_bf16((bf16*)(ws + WS_ZC) + (size_t)r * 1024 + (pn - 50) * 256 + cl, v);
.LBB0_795:
	s_andn2_b64 vcc, exec, s[6:7]
	s_cbranch_vccnz .LBB0_797
	v_mul_f32_e64 v50, v28, s48
	v_mul_f32_e64 v51, v29, s48
	v_mul_f32_e64 v52, v30, s48
	v_mul_f32_e64 v53, v31, s48
	v_exp_f32_e32 v50, v50
	v_exp_f32_e32 v51, v51
	v_exp_f32_e32 v52, v52
	v_exp_f32_e32 v53, v53
	v_mul_f32_e64 v54, v24, s48
	v_mul_f32_e64 v55, v25, s48
	v_mul_f32_e64 v56, v26, s48
	v_mul_f32_e64 v57, v27, s48
	v_exp_f32_e32 v54, v54
	v_exp_f32_e32 v55, v55
	v_exp_f32_e32 v56, v56
	v_exp_f32_e32 v57, v57
	v_add_f32_e64 v50, v50, 1.0
	v_add_f32_e64 v51, v51, 1.0
	v_add_f32_e64 v52, v52, 1.0
	v_add_f32_e64 v53, v53, 1.0
	v_rcp_f32_e32 v50, v50
	v_rcp_f32_e32 v51, v51
	v_rcp_f32_e32 v52, v52
	v_rcp_f32_e32 v53, v53
	v_add_f32_e64 v54, v54, 1.0
	v_add_f32_e64 v55, v55, 1.0
	v_add_f32_e64 v56, v56, 1.0
	v_add_f32_e64 v57, v57, 1.0
	v_rcp_f32_e32 v54, v54
	v_rcp_f32_e32 v55, v55
	v_rcp_f32_e32 v56, v56
	v_rcp_f32_e32 v57, v57
	v_lshlrev_b32_e32 v136, 1, v140
	v_mul_f32_e64 v50, v28, v50
	v_mul_f32_e64 v51, v29, v51
	v_mul_f32_e64 v52, v30, v52
	v_mul_f32_e64 v53, v31, v53
	v_lshl_add_u64 v[60:61], v[44:45], 0, v[136:137]
	v_mul_f32_e64 v54, v24, v54
	v_mul_f32_e64 v55, v25, v55
	v_mul_f32_e64 v56, v26, v56
	v_mul_f32_e64 v57, v27, v57
	v_cvt_pk_bf16_f32 v50, v50, v51
	v_cvt_pk_bf16_f32 v51, v52, v53
	v_cvt_pk_bf16_f32 v52, v54, v55
	s_nop 0
	v_cvt_pk_bf16_f32 v53, v56, v57
	global_store_dwordx4 v[60:61], v[50:53], off

; __device__ __forceinline__ f32x2 silu_pk(f32x2 x) { const f32x2 t = x * -1.4426950408889634f; f32x2 e; e.x = __builtin_amdgcn_exp2f(t.x); e.y = __builtin_amdgcn_exp2f(t.y); e = e + 1.0f; f32x2 r; r.x = __builtin_amdgcn_rcpf(e.x); r.y = __builtin_amdgcn_rcpf(e.y); return x * r; }
;     __device__ __forceinline__ void operator()(const pg8::f32x4 (&acc)[2][2][4][2], const pg8::Unit& u, int wr, int wc, int fr, int fq) const {
;     ...
;                     } else if (pn < 44) {
; #pragma unroll
;                         for (int e = 0; e < 8; e += 2) { const f32x2 g2 = silu_pk((f32x2){v[e], v[e + 1]}); v[e] = g2.x; v[e + 1] = g2.y; }
;                         st_bf16((bf16*)(ws + WS_ZB) + (size_t)r * 2048 + (pn - 36) * 256 + cl, v);
;                     } else if (pn < 48) {
;                         st_bf16((bf16*)(ws + WS_QC) + (size_t)r * 1024 + (pn - 44) * 256 + cl, v);
;                     } else if (pn < 50) {
;                         const bool isv = pn == 49;
;                         st_bf16((bf16*)(ws + (isv ? WS_VC : WS_KC)) + (size_t)r * 256 + cl, v);
;                         if (r < PT) st_f32(out + (isv ? O_PV : O_PK) + ((size_t)l * PT + r) * 256 + cl, v);
;                         else st_f32(out + (isv ? O_SV : O_SK) + ((size_t)l * ST + (r - PT)) * 256 + cl, v);
;                     } else if (pn < 54) {
; #pragma unroll
;                         for (int e = 0; e < 8; e += 2) { const f32x2 g2 = silu_pk((f32x2){v[e], v[e + 1]}); v[e] = g2.x; v[e + 1] = g2.y; }
;                         st_bf16((bf16*)(ws + WS_ZC) + (size_t)r * 1024 + (pn - 50) * 256 + cl, v);
.LBB0_808:
	s_andn2_b64 vcc, exec, s[6:7]
	s_cbranch_vccnz .LBB0_810
	v_mul_f32_e64 v50, v28, s48
	v_mul_f32_e64 v51, v29, s48
	v_mul_f32_e64 v52, v30, s48
	v_mul_f32_e64 v53, v31, s48
	v_exp_f32_e32 v50, v50
	v_exp_f32_e32 v51, v51
	v_exp_f32_e32 v52, v52
	v_exp_f32_e32 v53, v53
	v_mul_f32_e64 v54, v24, s48
	v_mul_f32_e64 v55, v25, s48
	v_mul_f32_e64 v56, v26, s48
	v_mul_f32_e64 v57, v27, s48
	v_exp_f32_e32 v54, v54
	v_exp_f32_e32 v55, v55
	v_exp_f32_e32 v56, v56
	v_exp_f32_e32 v57, v57
	v_add_f32_e64 v50, v50, 1.0
	v_add_f32_e64 v51, v51, 1.0
	v_add_f32_e64 v52, v52, 1.0
	v_add_f32_e64 v53, v53, 1.0
	v_rcp_f32_e32 v50, v50
	v_rcp_f32_e32 v51, v51
	v_rcp_f32_e32 v52, v52
	v_rcp_f32_e32 v53, v53
	v_add_f32_e64 v54, v54, 1.0
	v_add_f32_e64 v55, v55, 1.0
	v_add_f32_e64 v56, v56, 1.0
	v_add_f32_e64 v57, v57, 1.0
	v_rcp_f32_e32 v54, v54
	v_rcp_f32_e32 v55, v55
	v_rcp_f32_e32 v56, v56
	v_rcp_f32_e32 v57, v57
	v_lshlrev_b32_e32 v136, 1, v140
	v_mul_f32_e64 v50, v28, v50
	v_mul_f32_e64 v51, v29, v51
	v_mul_f32_e64 v52, v30, v52
	v_mul_f32_e64 v53, v31, v53
	v_lshl_add_u64 v[60:61], v[34:35], 0, v[136:137]
	v_mul_f32_e64 v54, v24, v54
	v_mul_f32_e64 v55, v25, v55
	v_mul_f32_e64 v56, v26, v56
	v_mul_f32_e64 v57, v27, v57
	v_cvt_pk_bf16_f32 v50, v50, v51
	v_cvt_pk_bf16_f32 v51, v52, v53
	v_cvt_pk_bf16_f32 v52, v54, v55
	s_nop 0
	v_cvt_pk_bf16_f32 v53, v56, v57
	global_store_dwordx4 v[60:61], v[50:53], off

; __device__ __forceinline__ f32x2 silu_pk(f32x2 x) { const f32x2 t = x * -1.4426950408889634f; f32x2 e; e.x = __builtin_amdgcn_exp2f(t.x); e.y = __builtin_amdgcn_exp2f(t.y); e = e + 1.0f; f32x2 r; r.x = __builtin_amdgcn_rcpf(e.x); r.y = __builtin_amdgcn_rcpf(e.y); return x * r; }
;     __device__ __forceinline__ void operator()(const pg8::f32x4 (&acc)[2][2][4][2], const pg8::Unit& u, int wr, int wc, int fr, int fq) const {
;     ...
;                     } else if (pn < 44) {
; #pragma unroll
;                         for (int e = 0; e < 8; e += 2) { const f32x2 g2 = silu_pk((f32x2){v[e], v[e + 1]}); v[e] = g2.x; v[e + 1] = g2.y; }
;                         st_bf16((bf16*)(ws + WS_ZB) + (size_t)r * 2048 + (pn - 36) * 256 + cl, v);
;                     } else if (pn < 48) {
;                         st_bf16((bf16*)(ws + WS_QC) + (size_t)r * 1024 + (pn - 44) * 256 + cl, v);
;                     } else if (pn < 50) {
;                         const bool isv = pn == 49;
;                         st_bf16((bf16*)(ws + (isv ? WS_VC : WS_KC)) + (size_t)r * 256 + cl, v);
;                         if (r < PT) st_f32(out + (isv ? O_PV : O_PK) + ((size_t)l * PT + r) * 256 + cl, v);
;                         else st_f32(out + (isv ? O_SV : O_SK) + ((size_t)l * ST + (r - PT)) * 256 + cl, v);
;                     } else if (pn < 54) {
; #pragma unroll
;                         for (int e = 0; e < 8; e += 2) { const f32x2 g2 = silu_pk((f32x2){v[e], v[e + 1]}); v[e] = g2.x; v[e + 1] = g2.y; }
;                         st_bf16((bf16*)(ws + WS_ZC) + (size_t)r * 1024 + (pn - 50) * 256 + cl, v);
.LBB0_825:
	s_andn2_b64 vcc, exec, s[6:7]
	s_cbranch_vccnz .LBB0_827
	v_mul_f32_e64 v24, v20, s48
	v_mul_f32_e64 v25, v21, s48
	v_mul_f32_e64 v26, v22, s48
	v_mul_f32_e64 v27, v23, s48
	v_exp_f32_e32 v24, v24
	v_exp_f32_e32 v25, v25
	v_exp_f32_e32 v26, v26
	v_exp_f32_e32 v27, v27
	v_mul_f32_e64 v28, v16, s48
	v_mul_f32_e64 v29, v17, s48
	v_mul_f32_e64 v30, v18, s48
	v_mul_f32_e64 v31, v19, s48
	v_exp_f32_e32 v28, v28
	v_exp_f32_e32 v29, v29
	v_exp_f32_e32 v30, v30
	v_exp_f32_e32 v31, v31
	v_add_f32_e64 v24, v24, 1.0
	v_add_f32_e64 v25, v25, 1.0
	v_add_f32_e64 v26, v26, 1.0
	v_add_f32_e64 v27, v27, 1.0
	v_rcp_f32_e32 v24, v24
	v_rcp_f32_e32 v25, v25
	v_rcp_f32_e32 v26, v26
	v_rcp_f32_e32 v27, v27
	v_add_f32_e64 v28, v28, 1.0
	v_add_f32_e64 v29, v29, 1.0
	v_add_f32_e64 v30, v30, 1.0
	v_add_f32_e64 v31, v31, 1.0
	v_rcp_f32_e32 v28, v28
	v_rcp_f32_e32 v29, v29
	v_rcp_f32_e32 v30, v30
	v_rcp_f32_e32 v31, v31
	v_lshlrev_b32_e32 v136, 1, v142
	v_mul_f32_e64 v24, v20, v24
	v_mul_f32_e64 v25, v21, v25
	v_mul_f32_e64 v26, v22, v26
	v_mul_f32_e64 v27, v23, v27
	v_lshl_add_u64 v[44:45], v[44:45], 0, v[136:137]
	v_mul_f32_e64 v28, v16, v28
	v_mul_f32_e64 v29, v17, v29
	v_mul_f32_e64 v30, v18, v30
	v_mul_f32_e64 v31, v19, v31
	v_cvt_pk_bf16_f32 v24, v24, v25
	v_cvt_pk_bf16_f32 v25, v26, v27
	v_cvt_pk_bf16_f32 v26, v28, v29
	s_nop 0
	v_cvt_pk_bf16_f32 v27, v30, v31
	global_store_dwordx4 v[44:45], v[24:27], off

; __device__ __forceinline__ f32x2 silu_pk(f32x2 x) { const f32x2 t = x * -1.4426950408889634f; f32x2 e; e.x = __builtin_amdgcn_exp2f(t.x); e.y = __builtin_amdgcn_exp2f(t.y); e = e + 1.0f; f32x2 r; r.x = __builtin_amdgcn_rcpf(e.x); r.y = __builtin_amdgcn_rcpf(e.y); return x * r; }
;     __device__ __forceinline__ void operator()(const pg8::f32x4 (&acc)[2][2][4][2], const pg8::Unit& u, int wr, int wc, int fr, int fq) const {
;     ...
;                     } else if (pn < 44) {
; #pragma unroll
;                         for (int e = 0; e < 8; e += 2) { const f32x2 g2 = silu_pk((f32x2){v[e], v[e + 1]}); v[e] = g2.x; v[e + 1] = g2.y; }
;                         st_bf16((bf16*)(ws + WS_ZB) + (size_t)r * 2048 + (pn - 36) * 256 + cl, v);
;                     } else if (pn < 48) {
;                         st_bf16((bf16*)(ws + WS_QC) + (size_t)r * 1024 + (pn - 44) * 256 + cl, v);
;                     } else if (pn < 50) {
;                         const bool isv = pn == 49;
;                         st_bf16((bf16*)(ws + (isv ? WS_VC : WS_KC)) + (size_t)r * 256 + cl, v);
;                         if (r < PT) st_f32(out + (isv ? O_PV : O_PK) + ((size_t)l * PT + r) * 256 + cl, v);
;                         else st_f32(out + (isv ? O_SV : O_SK) + ((size_t)l * ST + (r - PT)) * 256 + cl, v);
;                     } else if (pn < 54) {
; #pragma unroll
;                         for (int e = 0; e < 8; e += 2) { const f32x2 g2 = silu_pk((f32x2){v[e], v[e + 1]}); v[e] = g2.x; v[e + 1] = g2.y; }
;                         st_bf16((bf16*)(ws + WS_ZC) + (size_t)r * 1024 + (pn - 50) * 256 + cl, v);
.LBB0_838:
	s_andn2_b64 vcc, exec, s[6:7]
	s_cbranch_vccnz .LBB0_840
	v_mul_f32_e64 v24, v20, s48
	v_mul_f32_e64 v25, v21, s48
	v_mul_f32_e64 v26, v22, s48
	v_mul_f32_e64 v27, v23, s48
	v_exp_f32_e32 v24, v24
	v_exp_f32_e32 v25, v25
	v_exp_f32_e32 v26, v26
	v_exp_f32_e32 v27, v27
	v_mul_f32_e64 v28, v16, s48
	v_mul_f32_e64 v29, v17, s48
	v_mul_f32_e64 v30, v18, s48
	v_mul_f32_e64 v31, v19, s48
	v_exp_f32_e32 v28, v28
	v_exp_f32_e32 v29, v29
	v_exp_f32_e32 v30, v30
	v_exp_f32_e32 v31, v31
	v_add_f32_e64 v24, v24, 1.0
	v_add_f32_e64 v25, v25, 1.0
	v_add_f32_e64 v26, v26, 1.0
	v_add_f32_e64 v27, v27, 1.0
	v_rcp_f32_e32 v24, v24
	v_rcp_f32_e32 v25, v25
	v_rcp_f32_e32 v26, v26
	v_rcp_f32_e32 v27, v27
	v_add_f32_e64 v28, v28, 1.0
	v_add_f32_e64 v29, v29, 1.0
	v_add_f32_e64 v30, v30, 1.0
	v_add_f32_e64 v31, v31, 1.0
	v_rcp_f32_e32 v28, v28
	v_rcp_f32_e32 v29, v29
	v_rcp_f32_e32 v30, v30
	v_rcp_f32_e32 v31, v31
	v_lshlrev_b32_e32 v136, 1, v142
	v_mul_f32_e64 v24, v20, v24
	v_mul_f32_e64 v25, v21, v25
	v_mul_f32_e64 v26, v22, v26
	v_mul_f32_e64 v27, v23, v27
	v_lshl_add_u64 v[34:35], v[34:35], 0, v[136:137]
	v_mul_f32_e64 v28, v16, v28
	v_mul_f32_e64 v29, v17, v29
	v_mul_f32_e64 v30, v18, v30
	v_mul_f32_e64 v31, v19, v31
	v_cvt_pk_bf16_f32 v24, v24, v25
	v_cvt_pk_bf16_f32 v25, v26, v27
	v_cvt_pk_bf16_f32 v26, v28, v29
	s_nop 0
	v_cvt_pk_bf16_f32 v27, v30, v31
	global_store_dwordx4 v[34:35], v[24:27], off

; __device__ __forceinline__ f32x2 silu_pk(f32x2 x) { const f32x2 t = x * -1.4426950408889634f; f32x2 e; e.x = __builtin_amdgcn_exp2f(t.x); e.y = __builtin_amdgcn_exp2f(t.y); e = e + 1.0f; f32x2 r; r.x = __builtin_amdgcn_rcpf(e.x); r.y = __builtin_amdgcn_rcpf(e.y); return x * r; }
; __device__ __forceinline__ f32x2 gelu_pk(f32x2 x) { const f32x2 x2 = x * x; const f32x2 t = (x2 * 0.044715f + 1.0f) * (x * -2.302208198144325f); f32x2 e; e.x = __builtin_amdgcn_exp2f(t.x); e.y = __builtin_amdgcn_exp2f(t.y); e = e + 1.0f; f32x2 r; r.x = __builtin_amdgcn_rcpf(e.x); r.y = __builtin_amd ...
;     __device__ __forceinline__ void operator()(const pg8::f32x4 (&acc)[2][2][4][2], const pg8::Unit& u, int wr, int wc, int fr, int fq) const {
;     ...
;                     if (pn < 12) {
;                         const int seg = pn >> 2, cc = (pn & 3) * 256 + cl;
;                         if (seg < 2) {
; #pragma unroll
;                             for (int e = 0; e < 8; e += 2) { const f32x2 g2 = gelu_pk((f32x2){v[e], v[e + 1]}); v[e] = g2.x; v[e + 1] = g2.y; }
;                         } else {
; #pragma unroll
;                             for (int e = 0; e < 8; e += 2) { const f32x2 g2 = silu_pk((f32x2){v[e], v[e + 1]}); v[e] = g2.x; v[e + 1] = g2.y; }
;                         }
;                         bf16* base = (bf16*)(ws + (seg == 0 ? WS_UA : seg == 1 ? WS_VA : WS_ZA));
;                         st_bf16(base + (size_t)r * 1024 + cc, v);
.LBB0_847:
	s_andn2_b64 vcc, exec, s[16:17]
	s_mov_b64 s[96:97], -1
	s_cbranch_vccnz .LBB0_849
	v_mul_f32_e64 v52, v30, s48
	v_mul_f32_e64 v53, v31, s48
	v_mul_f32_e64 v50, v28, s48
	v_mul_f32_e64 v51, v29, s48
	v_exp_f32_e32 v52, v52
	v_exp_f32_e32 v53, v53
	v_mul_f32_e64 v54, v24, s48
	v_mul_f32_e64 v55, v25, s48
	v_exp_f32_e32 v50, v50
	v_exp_f32_e32 v51, v51
	v_exp_f32_e32 v54, v54
	v_exp_f32_e32 v55, v55
	v_add_f32_e64 v52, v52, 1.0
	v_add_f32_e64 v53, v53, 1.0
	v_add_f32_e64 v50, v50, 1.0
	v_add_f32_e64 v51, v51, 1.0
	v_rcp_f32_e32 v56, v52
	v_rcp_f32_e32 v57, v53
	v_add_f32_e64 v52, v54, 1.0
	v_add_f32_e64 v53, v55, 1.0
	v_rcp_f32_e32 v50, v50
	v_rcp_f32_e32 v51, v51
	v_rcp_f32_e32 v54, v52
	v_rcp_f32_e32 v55, v53
	s_mov_b64 s[96:97], 0
	v_mul_f32_e64 v52, v28, v50
	v_mul_f32_e64 v53, v29, v51
	v_mul_f32_e64 v50, v30, v56
	v_mul_f32_e64 v51, v31, v57
	v_mul_f32_e64 v54, v24, v54
	v_mul_f32_e64 v55, v25, v55
	v_mul_f32_e64 v56, v26, s48
	v_mul_f32_e64 v57, v27, s48
.LBB0_849:
	s_andn2_b64 vcc, exec, s[96:97]
	s_cbranch_vccnz .LBB0_851
	v_mul_f32_e64 v52, v28, v28
	v_mul_f32_e64 v53, v29, v29
	v_mul_f32_e64 v54, v28, s52
	v_mul_f32_e64 v55, v29, s52
	v_fma_f32 v52, v52, s50, 1.0
	v_fma_f32 v53, v53, s50, 1.0
	v_mul_f32_e64 v50, v30, v30
	v_mul_f32_e64 v51, v31, v31
	v_mul_f32_e64 v52, v54, v52
	v_mul_f32_e64 v53, v55, v53
	v_mul_f32_e64 v54, v24, s52
	v_mul_f32_e64 v55, v25, s52
	v_exp_f32_e32 v52, v52
	v_exp_f32_e32 v53, v53
	s_nop 0
	v_add_f32_e64 v52, v52, 1.0
	v_add_f32_e64 v53, v53, 1.0
	s_nop 0
	v_rcp_f32_e32 v52, v52
	v_rcp_f32_e32 v53, v53
	s_nop 0
	v_mul_f32_e64 v52, v28, v52
	v_mul_f32_e64 v53, v29, v53
	v_fma_f32 v28, v50, s50, 1.0
	v_fma_f32 v29, v51, s50, 1.0
	v_mul_f32_e64 v50, v30, s52
	v_mul_f32_e64 v51, v31, s52
	s_nop 0
	v_mul_f32_e64 v28, v50, v28
	v_mul_f32_e64 v29, v51, v29
	s_nop 0
	v_exp_f32_e32 v28, v28
	v_exp_f32_e32 v29, v29
	s_nop 0
	v_add_f32_e64 v28, v28, 1.0
	v_add_f32_e64 v29, v29, 1.0
	s_nop 0
	v_rcp_f32_e32 v28, v28
	v_rcp_f32_e32 v29, v29
	s_nop 0
	v_mul_f32_e64 v50, v30, v28
	v_mul_f32_e64 v51, v31, v29
	v_mul_f32_e64 v30, v24, v24
	v_mul_f32_e64 v31, v25, v25
	v_mul_f32_e64 v28, v26, v26
	v_mul_f32_e64 v29, v27, v27
	v_fma_f32 v30, v30, s50, 1.0
	v_fma_f32 v31, v31, s50, 1.0
	s_nop 0
	v_mul_f32_e64 v30, v54, v30
	v_mul_f32_e64 v31, v55, v31
	s_nop 0
	v_exp_f32_e32 v30, v30
	v_exp_f32_e32 v31, v31
	s_nop 0
	v_add_f32_e64 v30, v30, 1.0
	v_add_f32_e64 v31, v31, 1.0
	s_nop 0
	v_rcp_f32_e32 v30, v30
	v_rcp_f32_e32 v31, v31
	s_nop 0
	v_mul_f32_e64 v54, v24, v30
	v_mul_f32_e64 v55, v25, v31
	v_fma_f32 v24, v28, s50, 1.0
	v_fma_f32 v25, v29, s50, 1.0
	v_mul_f32_e64 v28, v26, s52
	v_mul_f32_e64 v29, v27, s52
	s_nop 0
	v_mul_f32_e64 v56, v28, v24
	v_mul_f32_e64 v57, v29, v25
.LBB0_851:
	s_nop 0
	v_exp_f32_e32 v24, v56
	v_exp_f32_e32 v25, v57
	v_or_b32_e32 v30, s26, v140
	v_lshlrev_b32_e32 v136, 1, v30
	v_lshl_add_u64 v[30:31], v[46:47], 0, v[136:137]
	v_add_f32_e64 v24, v24, 1.0
	v_add_f32_e64 v25, v25, 1.0
	s_nop 0
	v_rcp_f32_e32 v24, v24
	v_rcp_f32_e32 v25, v25
	s_nop 0
	v_mul_f32_e64 v28, v26, v24
	v_mul_f32_e64 v29, v27, v25
	v_cvt_pk_bf16_f32 v24, v52, v53
	v_cvt_pk_bf16_f32 v25, v50, v51
	v_cvt_pk_bf16_f32 v26, v54, v55
	s_nop 0
	v_cvt_pk_bf16_f32 v27, v28, v29
	global_store_dwordx4 v[30:31], v[24:27], off
	s_and_b64 vcc, exec, s[10:11]
	s_mov_b64 s[6:7], -1
	s_cbranch_vccz .LBB0_817

; __device__ __forceinline__ f32x2 silu_pk(f32x2 x) { const f32x2 t = x * -1.4426950408889634f; f32x2 e; e.x = __builtin_amdgcn_exp2f(t.x); e.y = __builtin_amdgcn_exp2f(t.y); e = e + 1.0f; f32x2 r; r.x = __builtin_amdgcn_rcpf(e.x); r.y = __builtin_amdgcn_rcpf(e.y); return x * r; }
; __device__ __forceinline__ f32x2 gelu_pk(f32x2 x) { const f32x2 x2 = x * x; const f32x2 t = (x2 * 0.044715f + 1.0f) * (x * -2.302208198144325f); f32x2 e; e.x = __builtin_amdgcn_exp2f(t.x); e.y = __builtin_amdgcn_exp2f(t.y); e = e + 1.0f; f32x2 r; r.x = __builtin_amdgcn_rcpf(e.x); r.y = __builtin_amd ...
;     __device__ __forceinline__ void operator()(const pg8::f32x4 (&acc)[2][2][4][2], const pg8::Unit& u, int wr, int wc, int fr, int fq) const {
;     ...
;                     if (pn < 12) {
;                         const int seg = pn >> 2, cc = (pn & 3) * 256 + cl;
;                         if (seg < 2) {
; #pragma unroll
;                             for (int e = 0; e < 8; e += 2) { const f32x2 g2 = gelu_pk((f32x2){v[e], v[e + 1]}); v[e] = g2.x; v[e + 1] = g2.y; }
;                         } else {
; #pragma unroll
;                             for (int e = 0; e < 8; e += 2) { const f32x2 g2 = silu_pk((f32x2){v[e], v[e + 1]}); v[e] = g2.x; v[e + 1] = g2.y; }
;                         }
;                         bf16* base = (bf16*)(ws + (seg == 0 ? WS_UA : seg == 1 ? WS_VA : WS_ZA));
;                         st_bf16(base + (size_t)r * 1024 + cc, v);
.LBB0_853:
	s_andn2_b64 vcc, exec, s[16:17]
	s_mov_b64 s[0:1], -1
	s_cbranch_vccnz .LBB0_855
	v_mul_f32_e64 v24, v20, s48
	v_mul_f32_e64 v25, v21, s48
	v_mul_f32_e64 v26, v22, s48
	v_mul_f32_e64 v27, v23, s48
	v_mul_f32_e64 v28, v16, s48
	v_mul_f32_e64 v29, v17, s48
	v_exp_f32_e32 v24, v24
	v_exp_f32_e32 v25, v25
	v_exp_f32_e32 v26, v26
	v_exp_f32_e32 v27, v27
	v_exp_f32_e32 v28, v28
	v_exp_f32_e32 v29, v29
	v_add_f32_e64 v24, v24, 1.0
	v_add_f32_e64 v25, v25, 1.0
	v_add_f32_e64 v26, v26, 1.0
	v_add_f32_e64 v27, v27, 1.0
	v_rcp_f32_e32 v24, v24
	v_add_f32_e64 v28, v28, 1.0
	v_add_f32_e64 v29, v29, 1.0
	v_rcp_f32_e32 v25, v25
	v_rcp_f32_e32 v26, v26
	v_rcp_f32_e32 v27, v27
	v_rcp_f32_e32 v28, v28
	v_rcp_f32_e32 v29, v29
	v_mul_f32_e64 v24, v20, v24
	v_mul_f32_e64 v25, v21, v25
	v_mul_f32_e64 v26, v22, v26
	v_mul_f32_e64 v27, v23, v27
	v_mul_f32_e64 v30, v18, s48
	v_mul_f32_e64 v31, v19, s48
	v_mul_f32_e64 v28, v16, v28
	v_mul_f32_e64 v29, v17, v29
	s_mov_b64 s[0:1], 0
.LBB0_855:
	s_andn2_b64 vcc, exec, s[0:1]
	s_cbranch_vccnz .LBB0_857
	v_mul_f32_e64 v24, v20, v20
	v_mul_f32_e64 v25, v21, v21
	v_mul_f32_e64 v28, v20, s52
	v_mul_f32_e64 v29, v21, s52
	v_fma_f32 v24, v24, s50, 1.0
	v_fma_f32 v25, v25, s50, 1.0
	v_mul_f32_e64 v26, v22, v22
	v_mul_f32_e64 v27, v23, v23
	v_mul_f32_e64 v24, v28, v24
	v_mul_f32_e64 v25, v29, v25
	v_mul_f32_e64 v28, v16, s52
	v_mul_f32_e64 v29, v17, s52
	v_exp_f32_e32 v24, v24
	v_exp_f32_e32 v25, v25
	s_nop 0
	v_add_f32_e64 v24, v24, 1.0
	v_add_f32_e64 v25, v25, 1.0
	s_nop 0
	v_rcp_f32_e32 v24, v24
	v_rcp_f32_e32 v25, v25
	s_nop 0
	v_mul_f32_e64 v24, v20, v24
	v_mul_f32_e64 v25, v21, v25
	v_fma_f32 v20, v26, s50, 1.0
	v_fma_f32 v21, v27, s50, 1.0
	v_mul_f32_e64 v26, v22, s52
	v_mul_f32_e64 v27, v23, s52
	s_nop 0
	v_mul_f32_e64 v20, v26, v20
	v_mul_f32_e64 v21, v27, v21
	s_nop 0
	v_exp_f32_e32 v20, v20
	v_exp_f32_e32 v21, v21
	s_nop 0
	v_add_f32_e64 v20, v20, 1.0
	v_add_f32_e64 v21, v21, 1.0
	s_nop 0
	v_rcp_f32_e32 v20, v20
	v_rcp_f32_e32 v21, v21
	s_nop 0
	v_mul_f32_e64 v26, v22, v20
	v_mul_f32_e64 v27, v23, v21
	v_mul_f32_e64 v22, v16, v16
	v_mul_f32_e64 v23, v17, v17
	v_mul_f32_e64 v20, v18, v18
	v_mul_f32_e64 v21, v19, v19
	v_fma_f32 v22, v22, s50, 1.0
	v_fma_f32 v23, v23, s50, 1.0
	s_nop 0
	v_mul_f32_e64 v22, v28, v22
	v_mul_f32_e64 v23, v29, v23
	s_nop 0
	v_exp_f32_e32 v22, v22
	v_exp_f32_e32 v23, v23
	s_nop 0
	v_add_f32_e64 v22, v22, 1.0
	v_add_f32_e64 v23, v23, 1.0
	s_nop 0
	v_rcp_f32_e32 v22, v22
	v_rcp_f32_e32 v23, v23
	s_nop 0
	v_mul_f32_e64 v28, v16, v22
	v_mul_f32_e64 v29, v17, v23
	v_fma_f32 v16, v20, s50, 1.0
	v_fma_f32 v17, v21, s50, 1.0
	v_mul_f32_e64 v20, v18, s52
	v_mul_f32_e64 v21, v19, s52
	s_nop 0
	v_mul_f32_e64 v30, v20, v16
	v_mul_f32_e64 v31, v21, v17
.LBB0_857:
	s_nop 0
	v_exp_f32_e32 v16, v30
	v_exp_f32_e32 v17, v31
	v_add_lshl_u32 v136, s26, v140, 1
	v_lshl_add_u64 v[22:23], v[46:47], 0, v[136:137]
	v_add_f32_e64 v16, v16, 1.0
	v_add_f32_e64 v17, v17, 1.0
	s_nop 0
	v_rcp_f32_e32 v16, v16
	v_rcp_f32_e32 v17, v17
	s_nop 0
	v_mul_f32_e64 v20, v18, v16
	v_mul_f32_e64 v21, v19, v17
	v_cvt_pk_bf16_f32 v16, v24, v25
	v_cvt_pk_bf16_f32 v17, v26, v27
	v_cvt_pk_bf16_f32 v18, v28, v29
	s_nop 0
	v_cvt_pk_bf16_f32 v19, v20, v21
	global_store_dwordx4 v[22:23], v[16:19], off offset:256

; __device__ __forceinline__ f32x2 silu_pk(f32x2 x) { const f32x2 t = x * -1.4426950408889634f; f32x2 e; e.x = __builtin_amdgcn_exp2f(t.x); e.y = __builtin_amdgcn_exp2f(t.y); e = e + 1.0f; f32x2 r; r.x = __builtin_amdgcn_rcpf(e.x); r.y = __builtin_amdgcn_rcpf(e.y); return x * r; }
;     __device__ __forceinline__ void operator()(const pg8::f32x4 (&acc)[2][2][4][2], const pg8::Unit& u, int wr, int wc, int fr, int fq) const {
;     ...
;                     } else if (pn < 44) {
; #pragma unroll
;                         for (int e = 0; e < 8; e += 2) { const f32x2 g2 = silu_pk((f32x2){v[e], v[e + 1]}); v[e] = g2.x; v[e + 1] = g2.y; }
;                         st_bf16((bf16*)(ws + WS_ZB) + (size_t)r * 2048 + (pn - 36) * 256 + cl, v);
;                     } else if (pn < 48) {
;                         st_bf16((bf16*)(ws + WS_QC) + (size_t)r * 1024 + (pn - 44) * 256 + cl, v);
;                     } else if (pn < 50) {
;                         const bool isv = pn == 49;
;                         st_bf16((bf16*)(ws + (isv ? WS_VC : WS_KC)) + (size_t)r * 256 + cl, v);
;                         if (r < PT) st_f32(out + (isv ? O_PV : O_PK) + ((size_t)l * PT + r) * 256 + cl, v);
;                         else st_f32(out + (isv ? O_SV : O_SK) + ((size_t)l * ST + (r - PT)) * 256 + cl, v);
;                     } else if (pn < 54) {
; #pragma unroll
;                         for (int e = 0; e < 8; e += 2) { const f32x2 g2 = silu_pk((f32x2){v[e], v[e + 1]}); v[e] = g2.x; v[e + 1] = g2.y; }
;                         st_bf16((bf16*)(ws + WS_ZC) + (size_t)r * 1024 + (pn - 50) * 256 + cl, v);
.LBB0_884:
	s_andn2_b64 vcc, exec, s[6:7]
	s_cbranch_vccnz .LBB0_886
	v_mul_f32_e64 v36, v12, s48
	v_mul_f32_e64 v37, v13, s48
	v_mul_f32_e64 v38, v14, s48
	v_mul_f32_e64 v39, v15, s48
	v_exp_f32_e32 v36, v36
	v_exp_f32_e32 v37, v37
	v_exp_f32_e32 v38, v38
	v_exp_f32_e32 v39, v39
	v_mul_f32_e64 v40, v8, s48
	v_mul_f32_e64 v41, v9, s48
	v_mul_f32_e64 v42, v10, s48
	v_mul_f32_e64 v43, v11, s48
	v_exp_f32_e32 v40, v40
	v_exp_f32_e32 v41, v41
	v_exp_f32_e32 v42, v42
	v_exp_f32_e32 v43, v43
	v_add_f32_e64 v36, v36, 1.0
	v_add_f32_e64 v37, v37, 1.0
	v_add_f32_e64 v38, v38, 1.0
	v_add_f32_e64 v39, v39, 1.0
	v_rcp_f32_e32 v36, v36
	v_rcp_f32_e32 v37, v37
	v_rcp_f32_e32 v38, v38
	v_rcp_f32_e32 v39, v39
	v_add_f32_e64 v40, v40, 1.0
	v_add_f32_e64 v41, v41, 1.0
	v_add_f32_e64 v42, v42, 1.0
	v_add_f32_e64 v43, v43, 1.0
	v_rcp_f32_e32 v40, v40
	v_rcp_f32_e32 v41, v41
	v_rcp_f32_e32 v42, v42
	v_rcp_f32_e32 v43, v43
	v_lshlrev_b32_e32 v136, 1, v140
	v_mul_f32_e64 v36, v12, v36
	v_mul_f32_e64 v37, v13, v37
	v_mul_f32_e64 v38, v14, v38
	v_mul_f32_e64 v39, v15, v39
	v_lshl_add_u64 v[46:47], v[30:31], 0, v[136:137]
	v_mul_f32_e64 v40, v8, v40
	v_mul_f32_e64 v41, v9, v41
	v_mul_f32_e64 v42, v10, v42
	v_mul_f32_e64 v43, v11, v43
	v_cvt_pk_bf16_f32 v36, v36, v37
	v_cvt_pk_bf16_f32 v37, v38, v39
	v_cvt_pk_bf16_f32 v38, v40, v41
	s_nop 0
	v_cvt_pk_bf16_f32 v39, v42, v43
	global_store_dwordx4 v[46:47], v[36:39], off

; __device__ __forceinline__ f32x2 silu_pk(f32x2 x) { const f32x2 t = x * -1.4426950408889634f; f32x2 e; e.x = __builtin_amdgcn_exp2f(t.x); e.y = __builtin_amdgcn_exp2f(t.y); e = e + 1.0f; f32x2 r; r.x = __builtin_amdgcn_rcpf(e.x); r.y = __builtin_amdgcn_rcpf(e.y); return x * r; }
;     __device__ __forceinline__ void operator()(const pg8::f32x4 (&acc)[2][2][4][2], const pg8::Unit& u, int wr, int wc, int fr, int fq) const {
;     ...
;                     } else if (pn < 44) {
; #pragma unroll
;                         for (int e = 0; e < 8; e += 2) { const f32x2 g2 = silu_pk((f32x2){v[e], v[e + 1]}); v[e] = g2.x; v[e + 1] = g2.y; }
;                         st_bf16((bf16*)(ws + WS_ZB) + (size_t)r * 2048 + (pn - 36) * 256 + cl, v);
;                     } else if (pn < 48) {
;                         st_bf16((bf16*)(ws + WS_QC) + (size_t)r * 1024 + (pn - 44) * 256 + cl, v);
;                     } else if (pn < 50) {
;                         const bool isv = pn == 49;
;                         st_bf16((bf16*)(ws + (isv ? WS_VC : WS_KC)) + (size_t)r * 256 + cl, v);
;                         if (r < PT) st_f32(out + (isv ? O_PV : O_PK) + ((size_t)l * PT + r) * 256 + cl, v);
;                         else st_f32(out + (isv ? O_SV : O_SK) + ((size_t)l * ST + (r - PT)) * 256 + cl, v);
;                     } else if (pn < 54) {
; #pragma unroll
;                         for (int e = 0; e < 8; e += 2) { const f32x2 g2 = silu_pk((f32x2){v[e], v[e + 1]}); v[e] = g2.x; v[e + 1] = g2.y; }
;                         st_bf16((bf16*)(ws + WS_ZC) + (size_t)r * 1024 + (pn - 50) * 256 + cl, v);
.LBB0_897:
	s_andn2_b64 vcc, exec, s[6:7]
	s_cbranch_vccnz .LBB0_899
	v_mul_f32_e64 v36, v12, s48
	v_mul_f32_e64 v37, v13, s48
	v_mul_f32_e64 v38, v14, s48
	v_mul_f32_e64 v39, v15, s48
	v_exp_f32_e32 v36, v36
	v_exp_f32_e32 v37, v37
	v_exp_f32_e32 v38, v38
	v_exp_f32_e32 v39, v39
	v_mul_f32_e64 v40, v8, s48
	v_mul_f32_e64 v41, v9, s48
	v_mul_f32_e64 v42, v10, s48
	v_mul_f32_e64 v43, v11, s48
	v_exp_f32_e32 v40, v40
	v_exp_f32_e32 v41, v41
	v_exp_f32_e32 v42, v42
	v_exp_f32_e32 v43, v43
	v_add_f32_e64 v36, v36, 1.0
	v_add_f32_e64 v37, v37, 1.0
	v_add_f32_e64 v38, v38, 1.0
	v_add_f32_e64 v39, v39, 1.0
	v_rcp_f32_e32 v36, v36
	v_rcp_f32_e32 v37, v37
	v_rcp_f32_e32 v38, v38
	v_rcp_f32_e32 v39, v39
	v_add_f32_e64 v40, v40, 1.0
	v_add_f32_e64 v41, v41, 1.0
	v_add_f32_e64 v42, v42, 1.0
	v_add_f32_e64 v43, v43, 1.0
	v_rcp_f32_e32 v40, v40
	v_rcp_f32_e32 v41, v41
	v_rcp_f32_e32 v42, v42
	v_rcp_f32_e32 v43, v43
	v_lshlrev_b32_e32 v136, 1, v140
	v_mul_f32_e64 v36, v12, v36
	v_mul_f32_e64 v37, v13, v37
	v_mul_f32_e64 v38, v14, v38
	v_mul_f32_e64 v39, v15, v39
	v_lshl_add_u64 v[46:47], v[20:21], 0, v[136:137]
	v_mul_f32_e64 v40, v8, v40
	v_mul_f32_e64 v41, v9, v41
	v_mul_f32_e64 v42, v10, v42
	v_mul_f32_e64 v43, v11, v43
	v_cvt_pk_bf16_f32 v36, v36, v37
	v_cvt_pk_bf16_f32 v37, v38, v39
	v_cvt_pk_bf16_f32 v38, v40, v41
	s_nop 0
	v_cvt_pk_bf16_f32 v39, v42, v43
	global_store_dwordx4 v[46:47], v[36:39], off

; __device__ __forceinline__ f32x2 silu_pk(f32x2 x) { const f32x2 t = x * -1.4426950408889634f; f32x2 e; e.x = __builtin_amdgcn_exp2f(t.x); e.y = __builtin_amdgcn_exp2f(t.y); e = e + 1.0f; f32x2 r; r.x = __builtin_amdgcn_rcpf(e.x); r.y = __builtin_amdgcn_rcpf(e.y); return x * r; }
; __device__ __forceinline__ f32x2 gelu_pk(f32x2 x) { const f32x2 x2 = x * x; const f32x2 t = (x2 * 0.044715f + 1.0f) * (x * -2.302208198144325f); f32x2 e; e.x = __builtin_amdgcn_exp2f(t.x); e.y = __builtin_amdgcn_exp2f(t.y); e = e + 1.0f; f32x2 r; r.x = __builtin_amdgcn_rcpf(e.x); r.y = __builtin_amd ...
;     __device__ __forceinline__ void operator()(const pg8::f32x4 (&acc)[2][2][4][2], const pg8::Unit& u, int wr, int wc, int fr, int fq) const {
;     ...
;                     if (pn < 12) {
;                         const int seg = pn >> 2, cc = (pn & 3) * 256 + cl;
;                         if (seg < 2) {
; #pragma unroll
;                             for (int e = 0; e < 8; e += 2) { const f32x2 g2 = gelu_pk((f32x2){v[e], v[e + 1]}); v[e] = g2.x; v[e + 1] = g2.y; }
;                         } else {
; #pragma unroll
;                             for (int e = 0; e < 8; e += 2) { const f32x2 g2 = silu_pk((f32x2){v[e], v[e + 1]}); v[e] = g2.x; v[e + 1] = g2.y; }
;                         }
;                         bf16* base = (bf16*)(ws + (seg == 0 ? WS_UA : seg == 1 ? WS_VA : WS_ZA));
;                         st_bf16(base + (size_t)r * 1024 + cc, v);
.LBB0_911:
	v_cndmask_b32_e64 v36, 0, 1, s[16:17]
	v_lshl_add_u64 v[34:35], s[74:75], 0, v[34:35]
	s_andn2_b64 vcc, exec, s[6:7]
	v_cmp_ne_u32_e64 s[16:17], 1, v36
	s_cbranch_vccnz .LBB0_918
	s_and_b64 vcc, exec, s[16:17]
	s_mov_b64 s[22:23], -1
	s_cbranch_vccnz .LBB0_914
	v_mul_f32_e64 v38, v14, s48
	v_mul_f32_e64 v39, v15, s48
	v_mul_f32_e64 v36, v12, s48
	v_mul_f32_e64 v37, v13, s48
	v_exp_f32_e32 v38, v38
	v_exp_f32_e32 v39, v39
	v_mul_f32_e64 v40, v8, s48
	v_mul_f32_e64 v41, v9, s48
	v_exp_f32_e32 v36, v36
	v_exp_f32_e32 v37, v37
	v_exp_f32_e32 v40, v40
	v_exp_f32_e32 v41, v41
	v_add_f32_e64 v38, v38, 1.0
	v_add_f32_e64 v39, v39, 1.0
	v_add_f32_e64 v36, v36, 1.0
	v_add_f32_e64 v37, v37, 1.0
	v_rcp_f32_e32 v42, v38
	v_rcp_f32_e32 v43, v39
	v_add_f32_e64 v38, v40, 1.0
	v_add_f32_e64 v39, v41, 1.0
	v_rcp_f32_e32 v36, v36
	v_rcp_f32_e32 v37, v37
	v_rcp_f32_e32 v40, v38
	v_rcp_f32_e32 v41, v39
	s_mov_b64 s[22:23], 0
	v_mul_f32_e64 v38, v12, v36
	v_mul_f32_e64 v39, v13, v37
	v_mul_f32_e64 v36, v14, v42
	v_mul_f32_e64 v37, v15, v43
	v_mul_f32_e64 v40, v8, v40
	v_mul_f32_e64 v41, v9, v41
	v_mul_f32_e64 v42, v10, s48
	v_mul_f32_e64 v43, v11, s48
.LBB0_914:
	s_andn2_b64 vcc, exec, s[22:23]
	s_cbranch_vccnz .LBB0_916
	v_mul_f32_e64 v38, v12, v12
	v_mul_f32_e64 v39, v13, v13
	v_mul_f32_e64 v40, v12, s52
	v_mul_f32_e64 v41, v13, s52
	v_fma_f32 v38, v38, s50, 1.0
	v_fma_f32 v39, v39, s50, 1.0
	v_mul_f32_e64 v36, v14, v14
	v_mul_f32_e64 v37, v15, v15
	v_mul_f32_e64 v38, v40, v38
	v_mul_f32_e64 v39, v41, v39
	v_mul_f32_e64 v40, v8, s52
	v_mul_f32_e64 v41, v9, s52
	v_exp_f32_e32 v38, v38
	v_exp_f32_e32 v39, v39
	s_nop 0
	v_add_f32_e64 v38, v38, 1.0
	v_add_f32_e64 v39, v39, 1.0
	s_nop 0
	v_rcp_f32_e32 v38, v38
	v_rcp_f32_e32 v39, v39
	s_nop 0
	v_mul_f32_e64 v38, v12, v38
	v_mul_f32_e64 v39, v13, v39
	v_fma_f32 v12, v36, s50, 1.0
	v_fma_f32 v13, v37, s50, 1.0
	v_mul_f32_e64 v36, v14, s52
	v_mul_f32_e64 v37, v15, s52
	s_nop 0
	v_mul_f32_e64 v12, v36, v12
	v_mul_f32_e64 v13, v37, v13
	s_nop 0
	v_exp_f32_e32 v12, v12
	v_exp_f32_e32 v13, v13
	s_nop 0
	v_add_f32_e64 v12, v12, 1.0
	v_add_f32_e64 v13, v13, 1.0
	s_nop 0
	v_rcp_f32_e32 v12, v12
	v_rcp_f32_e32 v13, v13
	s_nop 0
	v_mul_f32_e64 v36, v14, v12
	v_mul_f32_e64 v37, v15, v13
	v_mul_f32_e64 v14, v8, v8
	v_mul_f32_e64 v15, v9, v9
	v_mul_f32_e64 v12, v10, v10
	v_mul_f32_e64 v13, v11, v11
	v_fma_f32 v14, v14, s50, 1.0
	v_fma_f32 v15, v15, s50, 1.0
	s_nop 0
	v_mul_f32_e64 v14, v40, v14
	v_mul_f32_e64 v15, v41, v15
	s_nop 0
	v_exp_f32_e32 v14, v14
	v_exp_f32_e32 v15, v15
	s_nop 0
	v_add_f32_e64 v14, v14, 1.0
	v_add_f32_e64 v15, v15, 1.0
	s_nop 0
	v_rcp_f32_e32 v14, v14
	v_rcp_f32_e32 v15, v15
	s_nop 0
	v_mul_f32_e64 v40, v8, v14
	v_mul_f32_e64 v41, v9, v15
	v_fma_f32 v8, v12, s50, 1.0
	v_fma_f32 v9, v13, s50, 1.0
	v_mul_f32_e64 v12, v10, s52
	v_mul_f32_e64 v13, v11, s52
	s_nop 0
	v_mul_f32_e64 v42, v12, v8
	v_mul_f32_e64 v43, v13, v9
.LBB0_916:
	s_nop 0
	v_exp_f32_e32 v8, v42
	v_exp_f32_e32 v9, v43
	v_or_b32_e32 v14, s26, v140
	v_lshlrev_b32_e32 v136, 1, v14
	v_lshl_add_u64 v[14:15], v[34:35], 0, v[136:137]
	v_add_f32_e64 v8, v8, 1.0
	v_add_f32_e64 v9, v9, 1.0
	s_nop 0
	v_rcp_f32_e32 v8, v8
	v_rcp_f32_e32 v9, v9
	s_nop 0
	v_mul_f32_e64 v12, v10, v8
	v_mul_f32_e64 v13, v11, v9
	v_cvt_pk_bf16_f32 v8, v38, v39
	v_cvt_pk_bf16_f32 v9, v36, v37
	v_cvt_pk_bf16_f32 v10, v40, v41
	s_nop 0
	v_cvt_pk_bf16_f32 v11, v12, v13
	global_store_dwordx4 v[14:15], v[8:11], off
	s_and_b64 vcc, exec, s[10:11]
	s_mov_b64 s[6:7], -1
	s_cbranch_vccz .LBB0_919

; __device__ __forceinline__ f32x2 silu_pk(f32x2 x) { const f32x2 t = x * -1.4426950408889634f; f32x2 e; e.x = __builtin_amdgcn_exp2f(t.x); e.y = __builtin_amdgcn_exp2f(t.y); e = e + 1.0f; f32x2 r; r.x = __builtin_amdgcn_rcpf(e.x); r.y = __builtin_amdgcn_rcpf(e.y); return x * r; }
;     __device__ __forceinline__ void operator()(const pg8::f32x4 (&acc)[2][2][4][2], const pg8::Unit& u, int wr, int wc, int fr, int fq) const {
;     ...
;                     } else if (pn < 44) {
; #pragma unroll
;                         for (int e = 0; e < 8; e += 2) { const f32x2 g2 = silu_pk((f32x2){v[e], v[e + 1]}); v[e] = g2.x; v[e + 1] = g2.y; }
;                         st_bf16((bf16*)(ws + WS_ZB) + (size_t)r * 2048 + (pn - 36) * 256 + cl, v);
;                     } else if (pn < 48) {
;                         st_bf16((bf16*)(ws + WS_QC) + (size_t)r * 1024 + (pn - 44) * 256 + cl, v);
;                     } else if (pn < 50) {
;                         const bool isv = pn == 49;
;                         st_bf16((bf16*)(ws + (isv ? WS_VC : WS_KC)) + (size_t)r * 256 + cl, v);
;                         if (r < PT) st_f32(out + (isv ? O_PV : O_PK) + ((size_t)l * PT + r) * 256 + cl, v);
;                         else st_f32(out + (isv ? O_SV : O_SK) + ((size_t)l * ST + (r - PT)) * 256 + cl, v);
;                     } else if (pn < 54) {
; #pragma unroll
;                         for (int e = 0; e < 8; e += 2) { const f32x2 g2 = silu_pk((f32x2){v[e], v[e + 1]}); v[e] = g2.x; v[e + 1] = g2.y; }
;                         st_bf16((bf16*)(ws + WS_ZC) + (size_t)r * 1024 + (pn - 50) * 256 + cl, v);
.LBB0_927:
	s_andn2_b64 vcc, exec, s[6:7]
	s_cbranch_vccnz .LBB0_929
	v_mul_f32_e64 v8, v4, s48
	v_mul_f32_e64 v9, v5, s48
	v_mul_f32_e64 v10, v6, s48
	v_mul_f32_e64 v11, v7, s48
	v_exp_f32_e32 v8, v8
	v_exp_f32_e32 v9, v9
	v_exp_f32_e32 v10, v10
	v_exp_f32_e32 v11, v11
	v_mul_f32_e64 v12, v0, s48
	v_mul_f32_e64 v13, v1, s48
	v_mul_f32_e64 v14, v2, s48
	v_mul_f32_e64 v15, v3, s48
	v_exp_f32_e32 v12, v12
	v_exp_f32_e32 v13, v13
	v_exp_f32_e32 v14, v14
	v_exp_f32_e32 v15, v15
	v_add_f32_e64 v8, v8, 1.0
	v_add_f32_e64 v9, v9, 1.0
	v_add_f32_e64 v10, v10, 1.0
	v_add_f32_e64 v11, v11, 1.0
	v_rcp_f32_e32 v8, v8
	v_rcp_f32_e32 v9, v9
	v_rcp_f32_e32 v10, v10
	v_rcp_f32_e32 v11, v11
	v_add_f32_e64 v12, v12, 1.0
	v_add_f32_e64 v13, v13, 1.0
	v_add_f32_e64 v14, v14, 1.0
	v_add_f32_e64 v15, v15, 1.0
	v_rcp_f32_e32 v12, v12
	v_rcp_f32_e32 v13, v13
	v_rcp_f32_e32 v14, v14
	v_rcp_f32_e32 v15, v15
	v_lshlrev_b32_e32 v136, 1, v142
	v_mul_f32_e64 v8, v4, v8
	v_mul_f32_e64 v9, v5, v9
	v_mul_f32_e64 v10, v6, v10
	v_mul_f32_e64 v11, v7, v11
	v_lshl_add_u64 v[30:31], v[30:31], 0, v[136:137]
	v_mul_f32_e64 v12, v0, v12
	v_mul_f32_e64 v13, v1, v13
	v_mul_f32_e64 v14, v2, v14
	v_mul_f32_e64 v15, v3, v15
	v_cvt_pk_bf16_f32 v8, v8, v9
	v_cvt_pk_bf16_f32 v9, v10, v11
	v_cvt_pk_bf16_f32 v10, v12, v13
	s_nop 0
	v_cvt_pk_bf16_f32 v11, v14, v15
	global_store_dwordx4 v[30:31], v[8:11], off

; __device__ __forceinline__ f32x2 silu_pk(f32x2 x) { const f32x2 t = x * -1.4426950408889634f; f32x2 e; e.x = __builtin_amdgcn_exp2f(t.x); e.y = __builtin_amdgcn_exp2f(t.y); e = e + 1.0f; f32x2 r; r.x = __builtin_amdgcn_rcpf(e.x); r.y = __builtin_amdgcn_rcpf(e.y); return x * r; }
;     __device__ __forceinline__ void operator()(const pg8::f32x4 (&acc)[2][2][4][2], const pg8::Unit& u, int wr, int wc, int fr, int fq) const {
;     ...
;                     } else if (pn < 44) {
; #pragma unroll
;                         for (int e = 0; e < 8; e += 2) { const f32x2 g2 = silu_pk((f32x2){v[e], v[e + 1]}); v[e] = g2.x; v[e + 1] = g2.y; }
;                         st_bf16((bf16*)(ws + WS_ZB) + (size_t)r * 2048 + (pn - 36) * 256 + cl, v);
;                     } else if (pn < 48) {
;                         st_bf16((bf16*)(ws + WS_QC) + (size_t)r * 1024 + (pn - 44) * 256 + cl, v);
;                     } else if (pn < 50) {
;                         const bool isv = pn == 49;
;                         st_bf16((bf16*)(ws + (isv ? WS_VC : WS_KC)) + (size_t)r * 256 + cl, v);
;                         if (r < PT) st_f32(out + (isv ? O_PV : O_PK) + ((size_t)l * PT + r) * 256 + cl, v);
;                         else st_f32(out + (isv ? O_SV : O_SK) + ((size_t)l * ST + (r - PT)) * 256 + cl, v);
;                     } else if (pn < 54) {
; #pragma unroll
;                         for (int e = 0; e < 8; e += 2) { const f32x2 g2 = silu_pk((f32x2){v[e], v[e + 1]}); v[e] = g2.x; v[e + 1] = g2.y; }
;                         st_bf16((bf16*)(ws + WS_ZC) + (size_t)r * 1024 + (pn - 50) * 256 + cl, v);
.LBB0_940:
	s_andn2_b64 vcc, exec, s[6:7]
	s_cbranch_vccnz .LBB0_942
	v_mul_f32_e64 v8, v4, s48
	v_mul_f32_e64 v9, v5, s48
	v_mul_f32_e64 v10, v6, s48
	v_mul_f32_e64 v11, v7, s48
	v_exp_f32_e32 v8, v8
	v_exp_f32_e32 v9, v9
	v_exp_f32_e32 v10, v10
	v_exp_f32_e32 v11, v11
	v_mul_f32_e64 v12, v0, s48
	v_mul_f32_e64 v13, v1, s48
	v_mul_f32_e64 v14, v2, s48
	v_mul_f32_e64 v15, v3, s48
	v_exp_f32_e32 v12, v12
	v_exp_f32_e32 v13, v13
	v_exp_f32_e32 v14, v14
	v_exp_f32_e32 v15, v15
	v_add_f32_e64 v8, v8, 1.0
	v_add_f32_e64 v9, v9, 1.0
	v_add_f32_e64 v10, v10, 1.0
	v_add_f32_e64 v11, v11, 1.0
	v_rcp_f32_e32 v8, v8
	v_rcp_f32_e32 v9, v9
	v_rcp_f32_e32 v10, v10
	v_rcp_f32_e32 v11, v11
	v_add_f32_e64 v12, v12, 1.0
	v_add_f32_e64 v13, v13, 1.0
	v_add_f32_e64 v14, v14, 1.0
	v_add_f32_e64 v15, v15, 1.0
	v_rcp_f32_e32 v12, v12
	v_rcp_f32_e32 v13, v13
	v_rcp_f32_e32 v14, v14
	v_rcp_f32_e32 v15, v15
	v_lshlrev_b32_e32 v136, 1, v142
	v_mul_f32_e64 v8, v4, v8
	v_mul_f32_e64 v9, v5, v9
	v_mul_f32_e64 v10, v6, v10
	v_mul_f32_e64 v11, v7, v11
	v_lshl_add_u64 v[20:21], v[20:21], 0, v[136:137]
	v_mul_f32_e64 v12, v0, v12
	v_mul_f32_e64 v13, v1, v13
	v_mul_f32_e64 v14, v2, v14
	v_mul_f32_e64 v15, v3, v15
	v_cvt_pk_bf16_f32 v8, v8, v9
	v_cvt_pk_bf16_f32 v9, v10, v11
	v_cvt_pk_bf16_f32 v10, v12, v13
	s_nop 0
	v_cvt_pk_bf16_f32 v11, v14, v15
	global_store_dwordx4 v[20:21], v[8:11], off

; __device__ __forceinline__ f32x2 silu_pk(f32x2 x) { const f32x2 t = x * -1.4426950408889634f; f32x2 e; e.x = __builtin_amdgcn_exp2f(t.x); e.y = __builtin_amdgcn_exp2f(t.y); e = e + 1.0f; f32x2 r; r.x = __builtin_amdgcn_rcpf(e.x); r.y = __builtin_amdgcn_rcpf(e.y); return x * r; }
; __device__ __forceinline__ f32x2 gelu_pk(f32x2 x) { const f32x2 x2 = x * x; const f32x2 t = (x2 * 0.044715f + 1.0f) * (x * -2.302208198144325f); f32x2 e; e.x = __builtin_amdgcn_exp2f(t.x); e.y = __builtin_amdgcn_exp2f(t.y); e = e + 1.0f; f32x2 r; r.x = __builtin_amdgcn_rcpf(e.x); r.y = __builtin_amd ...
;     __device__ __forceinline__ void operator()(const pg8::f32x4 (&acc)[2][2][4][2], const pg8::Unit& u, int wr, int wc, int fr, int fq) const {
;     ...
;                     if (pn < 12) {
;                         const int seg = pn >> 2, cc = (pn & 3) * 256 + cl;
;                         if (seg < 2) {
; #pragma unroll
;                             for (int e = 0; e < 8; e += 2) { const f32x2 g2 = gelu_pk((f32x2){v[e], v[e + 1]}); v[e] = g2.x; v[e + 1] = g2.y; }
;                         } else {
; #pragma unroll
;                             for (int e = 0; e < 8; e += 2) { const f32x2 g2 = silu_pk((f32x2){v[e], v[e + 1]}); v[e] = g2.x; v[e + 1] = g2.y; }
;                         }
;                         bf16* base = (bf16*)(ws + (seg == 0 ? WS_UA : seg == 1 ? WS_VA : WS_ZA));
;                         st_bf16(base + (size_t)r * 1024 + cc, v);
.LBB0_954:
	s_and_b64 vcc, exec, s[16:17]
	s_mov_b64 s[0:1], -1
	s_cbranch_vccnz .LBB0_956
	v_mul_f32_e64 v8, v4, s48
	v_mul_f32_e64 v9, v5, s48
	v_mul_f32_e64 v10, v6, s48
	v_mul_f32_e64 v11, v7, s48
	v_mul_f32_e64 v12, v0, s48
	v_mul_f32_e64 v13, v1, s48
	v_exp_f32_e32 v8, v8
	v_exp_f32_e32 v9, v9
	v_exp_f32_e32 v10, v10
	v_exp_f32_e32 v11, v11
	v_exp_f32_e32 v12, v12
	v_exp_f32_e32 v13, v13
	v_add_f32_e64 v8, v8, 1.0
	v_add_f32_e64 v9, v9, 1.0
	v_add_f32_e64 v10, v10, 1.0
	v_add_f32_e64 v11, v11, 1.0
	v_rcp_f32_e32 v8, v8
	v_add_f32_e64 v12, v12, 1.0
	v_add_f32_e64 v13, v13, 1.0
	v_rcp_f32_e32 v9, v9
	v_rcp_f32_e32 v10, v10
	v_rcp_f32_e32 v11, v11
	v_rcp_f32_e32 v14, v12
	v_rcp_f32_e32 v15, v13
	v_mul_f32_e64 v12, v4, v8
	v_mul_f32_e64 v13, v5, v9
	v_mul_f32_e64 v10, v6, v10
	v_mul_f32_e64 v11, v7, v11
	s_mov_b64 s[0:1], 0
	v_mul_f32_e64 v8, v0, v14
	v_mul_f32_e64 v9, v1, v15
	v_mul_f32_e64 v14, v2, s48
	v_mul_f32_e64 v15, v3, s48
.LBB0_956:
	s_andn2_b64 vcc, exec, s[0:1]
	s_cbranch_vccnz .LBB0_958
	v_mul_f32_e64 v8, v4, v4
	v_mul_f32_e64 v9, v5, v5
	v_mul_f32_e64 v10, v4, s52
	v_mul_f32_e64 v11, v5, s52
	v_fma_f32 v8, v8, s50, 1.0
	v_fma_f32 v9, v9, s50, 1.0
	v_mul_f32_e64 v12, v6, s52
	v_mul_f32_e64 v13, v7, s52
	v_mul_f32_e64 v8, v10, v8
	v_mul_f32_e64 v9, v11, v9
	v_mul_f32_e64 v10, v6, v6
	v_mul_f32_e64 v11, v7, v7
	v_mul_f32_e64 v14, v0, s52
	v_mul_f32_e64 v15, v1, s52
	v_fma_f32 v10, v10, s50, 1.0
	v_fma_f32 v11, v11, s50, 1.0
	v_exp_f32_e32 v8, v8
	v_mul_f32_e64 v10, v12, v10
	v_mul_f32_e64 v11, v13, v11
	v_mul_f32_e64 v12, v0, v0
	v_mul_f32_e64 v13, v1, v1
	v_exp_f32_e32 v9, v9
	v_fma_f32 v12, v12, s50, 1.0
	v_fma_f32 v13, v13, s50, 1.0
	v_exp_f32_e32 v10, v10
	v_mul_f32_e64 v12, v14, v12
	v_mul_f32_e64 v13, v15, v13
	v_exp_f32_e32 v11, v11
	v_exp_f32_e32 v12, v12
	v_exp_f32_e32 v13, v13
	v_add_f32_e64 v8, v8, 1.0
	v_add_f32_e64 v9, v9, 1.0
	v_add_f32_e64 v10, v10, 1.0
	v_add_f32_e64 v11, v11, 1.0
	v_rcp_f32_e32 v8, v8
	v_rcp_f32_e32 v9, v9
	v_add_f32_e64 v12, v12, 1.0
	v_add_f32_e64 v13, v13, 1.0
	v_rcp_f32_e32 v10, v10
	v_rcp_f32_e32 v14, v12
	v_rcp_f32_e32 v15, v13
	v_rcp_f32_e32 v11, v11
	v_mul_f32_e64 v12, v4, v8
	v_mul_f32_e64 v13, v5, v9
	v_mul_f32_e64 v4, v2, v2
	v_mul_f32_e64 v5, v3, v3
	v_mul_f32_e64 v8, v0, v14
	v_mul_f32_e64 v9, v1, v15
	v_fma_f32 v0, v4, s50, 1.0
	v_fma_f32 v1, v5, s50, 1.0
	v_mul_f32_e64 v4, v2, s52
	v_mul_f32_e64 v5, v3, s52
	v_mul_f32_e64 v10, v6, v10
	v_mul_f32_e64 v11, v7, v11
	v_mul_f32_e64 v14, v4, v0
	v_mul_f32_e64 v15, v5, v1
.LBB0_958:
	s_nop 0
	v_exp_f32_e32 v0, v14
	v_exp_f32_e32 v1, v15
	v_add_lshl_u32 v136, s26, v140, 1
	v_lshl_add_u64 v[6:7], v[34:35], 0, v[136:137]
	v_add_f32_e64 v0, v0, 1.0
	v_add_f32_e64 v1, v1, 1.0
	s_nop 0
	v_rcp_f32_e32 v4, v0
	v_rcp_f32_e32 v5, v1
	v_cvt_pk_bf16_f32 v0, v12, v13
	v_cvt_pk_bf16_f32 v1, v10, v11
	s_nop 0
	v_mul_f32_e64 v4, v2, v4
	v_mul_f32_e64 v5, v3, v5
	v_cvt_pk_bf16_f32 v2, v8, v9
	s_nop 0
	v_cvt_pk_bf16_f32 v3, v4, v5
	global_store_dwordx4 v[6:7], v[0:3], off offset:256

; #define LAS __attribute__((address_space(3)))
;     template <class T> __device__ __forceinline__ T* w(size_t off) const { return (T*)(pp->ws + off); }
; __device__ __forceinline__ void mod_unit(const Ctx& c, int u) {
;     ...
;         const float* wp = c.f(I_WADA) + ((size_t)(l * 4096 + ch * 512 + kg * 32)) * 12288 + j0 + 4 * cl;
; #pragma unroll 2
;         for (int i = 0; i < 32; i += 4) {
;             f32x4 w[4];
; #pragma unroll
;             for (int e = 0; e < 4; ++e) w[e] = *(const f32x4*)(wp + (size_t)(i + e) * 12288);
; #pragma unroll
;             for (int r = 0; r < 12; ++r) {
;                 const f32x4 s4 = *(const LAS f32x4*)(sc + r * 512 + kg * 32 + i);
; #pragma unroll
;                 for (int e = 0; e < 4; ++e) { acc2[r][0] += (f32x2){w[e][0], w[e][1]} * s4[e]; acc2[r][1] += (f32x2){w[e][2], w[e][3]} * s4[e]; }
;             }
.LBB0_973:
	v_add_co_u32_e64 v96, s[0:1], s18, v94
	ds_read_b128 v[52:55], v88
	ds_read_b128 v[48:51], v88 offset:16
	v_addc_co_u32_e64 v97, s[0:1], -1, v95, s[0:1]
	v_add_co_u32_e64 v98, s[0:1], s19, v94
	ds_read_b128 v[84:87], v88 offset:2048
	ds_read_b128 v[56:59], v88 offset:2064
	ds_read_b128 v[110:113], v88 offset:4096
	ds_read_b128 v[60:63], v88 offset:4112
	ds_read_b128 v[114:117], v88 offset:6144
	ds_read_b128 v[64:67], v88 offset:6160
	ds_read_b128 v[118:121], v88 offset:8192
	ds_read_b128 v[68:71], v88 offset:8208
	ds_read_b128 v[122:125], v88 offset:10240
	ds_read_b128 v[72:75], v88 offset:10256
	ds_read_b128 v[126:129], v88 offset:12288
	ds_read_b128 v[76:79], v88 offset:12304
	ds_read_b128 v[130:133], v88 offset:14336
	ds_read_b128 v[80:83], v88 offset:14352
	ds_read_b128 v[134:137], v88 offset:16384
	ds_read_b128 v[142:145], v88 offset:16400
	ds_read_b128 v[146:149], v88 offset:18432
	ds_read_b128 v[150:153], v88 offset:18448
	ds_read_b128 v[154:157], v88 offset:20480
	ds_read_b128 v[158:161], v88 offset:20496
	ds_read_b128 v[162:165], v88 offset:22528
	ds_read_b128 v[166:169], v88 offset:22544
	v_addc_co_u32_e64 v99, s[0:1], -1, v95, s[0:1]
	v_add_co_u32_e64 v100, s[0:1], s20, v94
	s_waitcnt lgkmcnt(14)
	v_mov_b32_e32 v140, v87
	v_addc_co_u32_e64 v101, s[0:1], -1, v95, s[0:1]
	v_add_co_u32_e64 v102, s[0:1], s21, v94
	v_mov_b32_e32 v194, v113
	s_nop 0
	v_addc_co_u32_e64 v103, s[0:1], -1, v95, s[0:1]
	v_add_co_u32_e64 v138, s[0:1], s22, v94
	v_mov_b32_e32 v196, v117
	s_nop 0
	v_addc_co_u32_e64 v139, s[0:1], -1, v95, s[0:1]
	v_add_co_u32_e64 v182, s[0:1], s23, v94
	v_mov_b32_e32 v198, v121
	s_nop 0
	v_addc_co_u32_e64 v183, s[0:1], -1, v95, s[0:1]
	v_add_co_u32_e64 v186, s[0:1], s24, v94
	s_waitcnt lgkmcnt(13)
	v_mov_b32_e32 v200, v125
	v_addc_co_u32_e64 v187, s[0:1], -1, v95, s[0:1]
	global_load_dwordx4 v[170:173], v[96:97], off
	s_nop 0
	global_load_dwordx4 v[96:99], v[98:99], off
	s_nop 0
	global_load_dwordx4 v[174:177], v[100:101], off
	s_nop 0
	global_load_dwordx4 v[100:103], v[102:103], off
	s_nop 0
	global_load_dwordx4 v[178:181], v[138:139], off
	s_nop 0
	global_load_dwordx4 v[182:185], v[182:183], off
	s_nop 0
	global_load_dwordx4 v[186:189], v[186:187], off
	s_nop 0
	global_load_dwordx4 v[190:193], v[94:95], off
	v_mov_b32_e32 v138, v55
	s_waitcnt lgkmcnt(11)
	v_mov_b32_e32 v202, v129
	s_waitcnt lgkmcnt(9)
	v_mov_b32_e32 v204, v133
	s_waitcnt lgkmcnt(7)
	v_mov_b32_e32 v206, v137
	s_waitcnt lgkmcnt(5)
	v_mov_b32_e32 v208, v149
	s_waitcnt lgkmcnt(3)
	v_mov_b32_e32 v210, v157
	s_waitcnt lgkmcnt(1)
	v_mov_b32_e32 v212, v165
	s_add_i32 s14, s14, 8
	v_mov_b32_e32 v214, v51
	v_mov_b32_e32 v216, v59
	v_mov_b32_e32 v218, v63
	v_mov_b32_e32 v220, v67
	v_mov_b32_e32 v222, v71
	v_mov_b32_e32 v224, v75
	v_mov_b32_e32 v226, v79
	v_mov_b32_e32 v228, v83
	v_mov_b32_e32 v230, v145
	v_mov_b32_e32 v232, v153
	v_mov_b32_e32 v234, v161
	s_waitcnt lgkmcnt(0)
	v_mov_b32_e32 v236, v169
	v_add_u32_e32 v88, 32, v88
	v_lshl_add_u64 v[94:95], v[94:95], 0, s[12:13]
	s_cmp_gt_u32 s14, 27
	s_waitcnt vmcnt(7)
	v_fma_f32 v44, v170, v52, v44
	v_fma_f32 v45, v171, v52, v45
	v_fma_f32 v46, v172, v52, v46
	v_fma_f32 v47, v173, v52, v47
	v_fma_f32 v40, v170, v84, v40
	v_fma_f32 v41, v171, v84, v41
	v_fma_f32 v42, v172, v84, v42
	v_fma_f32 v43, v173, v84, v43
	v_fma_f32 v36, v170, v110, v36
	v_fma_f32 v37, v171, v110, v37
	v_fma_f32 v38, v172, v110, v38
	v_fma_f32 v39, v173, v110, v39
	v_fma_f32 v32, v170, v114, v32
	v_fma_f32 v33, v171, v114, v33
	v_fma_f32 v34, v172, v114, v34
	v_fma_f32 v35, v173, v114, v35
	v_fma_f32 v28, v170, v118, v28
	v_fma_f32 v29, v171, v118, v29
	v_fma_f32 v30, v172, v118, v30
	v_fma_f32 v31, v173, v118, v31
	v_fma_f32 v24, v170, v122, v24
	v_fma_f32 v25, v171, v122, v25
	v_fma_f32 v26, v172, v122, v26
	v_fma_f32 v27, v173, v122, v27
	v_fma_f32 v20, v170, v126, v20
	v_fma_f32 v21, v171, v126, v21
	v_fma_f32 v22, v172, v126, v22
	v_fma_f32 v23, v173, v126, v23
	v_fma_f32 v12, v170, v130, v12
	v_fma_f32 v13, v171, v130, v13
	v_fma_f32 v14, v172, v130, v14
	v_fma_f32 v15, v173, v130, v15
	v_fma_f32 v4, v170, v134, v4
	v_fma_f32 v5, v171, v134, v5
	v_fma_f32 v6, v172, v134, v6
	v_fma_f32 v7, v173, v134, v7
	v_fma_f32 v0, v170, v146, v0
	v_fma_f32 v1, v171, v146, v1
	v_fma_f32 v2, v172, v146, v2
	v_fma_f32 v3, v173, v146, v3
	v_fma_f32 v16, v170, v154, v16
	v_fma_f32 v17, v171, v154, v17
	v_fma_f32 v18, v172, v154, v18
	v_fma_f32 v19, v173, v154, v19
	v_fma_f32 v8, v170, v162, v8
	v_fma_f32 v9, v171, v162, v9
	v_fma_f32 v10, v172, v162, v10
	v_fma_f32 v11, v173, v162, v11
	s_waitcnt vmcnt(6)
	v_fma_f32 v44, v96, v53, v44
	v_fma_f32 v45, v97, v53, v45
	v_fma_f32 v46, v98, v53, v46
	v_fma_f32 v47, v99, v53, v47
	v_fma_f32 v40, v96, v85, v40
	v_fma_f32 v41, v97, v85, v41
	v_fma_f32 v42, v98, v85, v42
	v_fma_f32 v43, v99, v85, v43
	v_fma_f32 v36, v96, v111, v36
	v_fma_f32 v37, v97, v111, v37
	v_fma_f32 v38, v98, v111, v38
	v_fma_f32 v39, v99, v111, v39
	v_fma_f32 v32, v96, v115, v32
	v_fma_f32 v33, v97, v115, v33
	v_fma_f32 v34, v98, v115, v34
	v_fma_f32 v35, v99, v115, v35
	v_fma_f32 v28, v96, v119, v28
	v_fma_f32 v29, v97, v119, v29
	v_fma_f32 v30, v98, v119, v30
	v_fma_f32 v31, v99, v119, v31
	v_fma_f32 v24, v96, v123, v24
	v_fma_f32 v25, v97, v123, v25
	v_fma_f32 v26, v98, v123, v26
	v_fma_f32 v27, v99, v123, v27
	v_fma_f32 v20, v96, v127, v20
	v_fma_f32 v21, v97, v127, v21
	v_fma_f32 v22, v98, v127, v22
	v_fma_f32 v23, v99, v127, v23
	v_fma_f32 v12, v96, v131, v12
	v_fma_f32 v13, v97, v131, v13
	v_fma_f32 v14, v98, v131, v14
	v_fma_f32 v15, v99, v131, v15
	v_fma_f32 v4, v96, v135, v4
	v_fma_f32 v5, v97, v135, v5
	v_fma_f32 v6, v98, v135, v6
	v_fma_f32 v7, v99, v135, v7
	v_fma_f32 v0, v96, v147, v0
	v_fma_f32 v1, v97, v147, v1
	v_fma_f32 v2, v98, v147, v2
	v_fma_f32 v3, v99, v147, v3
	v_fma_f32 v16, v96, v155, v16
	v_fma_f32 v17, v97, v155, v17
	v_fma_f32 v18, v98, v155, v18
	v_fma_f32 v19, v99, v155, v19
	v_fma_f32 v8, v96, v163, v8
	v_fma_f32 v9, v97, v163, v9
	v_fma_f32 v10, v98, v163, v10
	v_fma_f32 v11, v99, v163, v11
	s_waitcnt vmcnt(5)
; #define LAS __attribute__((address_space(3)))
;     template <class T> __device__ __forceinline__ T* w(size_t off) const { return (T*)(pp->ws + off); }
; __device__ __forceinline__ void mod_unit(const Ctx& c, int u) {
;     ...
;             for (int e = 0; e < 4; ++e) w[e] = *(const f32x4*)(wp + (size_t)(i + e) * 12288);
; #pragma unroll
;             for (int r = 0; r < 12; ++r) {
;                 const f32x4 s4 = *(const LAS f32x4*)(sc + r * 512 + kg * 32 + i);
; #pragma unroll
;                 for (int e = 0; e < 4; ++e) { acc2[r][0] += (f32x2){w[e][0], w[e][1]} * s4[e]; acc2[r][1] += (f32x2){w[e][2], w[e][3]} * s4[e]; }
;             }
	v_fma_f32 v44, v174, v54, v44
	v_fma_f32 v45, v175, v54, v45
	v_fma_f32 v46, v176, v54, v46
	v_fma_f32 v47, v177, v54, v47
	v_fma_f32 v40, v174, v86, v40
	v_fma_f32 v41, v175, v86, v41
	v_fma_f32 v42, v176, v86, v42
	v_fma_f32 v43, v177, v86, v43
	v_fma_f32 v36, v174, v112, v36
	v_fma_f32 v37, v175, v112, v37
	v_fma_f32 v38, v176, v112, v38
	v_fma_f32 v39, v177, v112, v39
	v_fma_f32 v32, v174, v116, v32
	v_fma_f32 v33, v175, v116, v33
	v_fma_f32 v34, v176, v116, v34
	v_fma_f32 v35, v177, v116, v35
	v_fma_f32 v28, v174, v120, v28
	v_fma_f32 v29, v175, v120, v29
	v_fma_f32 v30, v176, v120, v30
	v_fma_f32 v31, v177, v120, v31
	v_fma_f32 v24, v174, v124, v24
	v_fma_f32 v25, v175, v124, v25
	v_fma_f32 v26, v176, v124, v26
	v_fma_f32 v27, v177, v124, v27
	v_fma_f32 v20, v174, v128, v20
	v_fma_f32 v21, v175, v128, v21
	v_fma_f32 v22, v176, v128, v22
	v_fma_f32 v23, v177, v128, v23
	v_fma_f32 v12, v174, v132, v12
	v_fma_f32 v13, v175, v132, v13
	v_fma_f32 v14, v176, v132, v14
	v_fma_f32 v15, v177, v132, v15
	v_fma_f32 v4, v174, v136, v4
	v_fma_f32 v5, v175, v136, v5
	v_fma_f32 v6, v176, v136, v6
	v_fma_f32 v7, v177, v136, v7
	v_fma_f32 v0, v174, v148, v0
	v_fma_f32 v1, v175, v148, v1
	v_fma_f32 v2, v176, v148, v2
	v_fma_f32 v3, v177, v148, v3
	v_fma_f32 v16, v174, v156, v16
	v_fma_f32 v17, v175, v156, v17
	v_fma_f32 v18, v176, v156, v18
	v_fma_f32 v19, v177, v156, v19
	v_fma_f32 v8, v174, v164, v8
	v_fma_f32 v9, v175, v164, v9
	v_fma_f32 v10, v176, v164, v10
	v_fma_f32 v11, v177, v164, v11
	s_waitcnt vmcnt(4)
	v_fma_f32 v44, v100, v138, v44
	v_fma_f32 v45, v101, v138, v45
	v_fma_f32 v46, v102, v138, v46
	v_fma_f32 v47, v103, v138, v47
	v_fma_f32 v40, v100, v140, v40
	v_fma_f32 v41, v101, v140, v41
	v_fma_f32 v42, v102, v140, v42
	v_fma_f32 v43, v103, v140, v43
	v_fma_f32 v36, v100, v194, v36
	v_fma_f32 v37, v101, v194, v37
	v_fma_f32 v38, v102, v194, v38
	v_fma_f32 v39, v103, v194, v39
	v_fma_f32 v32, v100, v196, v32
	v_fma_f32 v33, v101, v196, v33
	v_fma_f32 v34, v102, v196, v34
	v_fma_f32 v35, v103, v196, v35
	v_fma_f32 v28, v100, v198, v28
	v_fma_f32 v29, v101, v198, v29
	v_fma_f32 v30, v102, v198, v30
	v_fma_f32 v31, v103, v198, v31
	v_fma_f32 v24, v100, v200, v24
	v_fma_f32 v25, v101, v200, v25
	v_fma_f32 v26, v102, v200, v26
	v_fma_f32 v27, v103, v200, v27
	v_fma_f32 v20, v100, v202, v20
	v_fma_f32 v21, v101, v202, v21
	v_fma_f32 v22, v102, v202, v22
	v_fma_f32 v23, v103, v202, v23
	v_fma_f32 v12, v100, v204, v12
	v_fma_f32 v13, v101, v204, v13
	v_fma_f32 v14, v102, v204, v14
	v_fma_f32 v15, v103, v204, v15
	v_fma_f32 v4, v100, v206, v4
	v_fma_f32 v5, v101, v206, v5
	v_fma_f32 v6, v102, v206, v6
	v_fma_f32 v7, v103, v206, v7
	v_fma_f32 v0, v100, v208, v0
	v_fma_f32 v1, v101, v208, v1
	v_fma_f32 v2, v102, v208, v2
	v_fma_f32 v3, v103, v208, v3
	v_fma_f32 v16, v100, v210, v16
	v_fma_f32 v17, v101, v210, v17
	v_fma_f32 v18, v102, v210, v18
	v_fma_f32 v19, v103, v210, v19
	v_fma_f32 v8, v100, v212, v8
	v_fma_f32 v9, v101, v212, v9
	v_fma_f32 v10, v102, v212, v10
	v_fma_f32 v11, v103, v212, v11
	s_waitcnt vmcnt(3)
	v_fma_f32 v44, v178, v48, v44
	v_fma_f32 v45, v179, v48, v45
	v_fma_f32 v46, v180, v48, v46
	v_fma_f32 v47, v181, v48, v47
	v_fma_f32 v40, v178, v56, v40
	v_fma_f32 v41, v179, v56, v41
	v_fma_f32 v42, v180, v56, v42
	v_fma_f32 v43, v181, v56, v43
	v_fma_f32 v36, v178, v60, v36
	v_fma_f32 v37, v179, v60, v37
	v_fma_f32 v38, v180, v60, v38
	v_fma_f32 v39, v181, v60, v39
	v_fma_f32 v32, v178, v64, v32
	v_fma_f32 v33, v179, v64, v33
	v_fma_f32 v34, v180, v64, v34
	v_fma_f32 v35, v181, v64, v35
	v_fma_f32 v28, v178, v68, v28
	v_fma_f32 v29, v179, v68, v29
	v_fma_f32 v30, v180, v68, v30
	v_fma_f32 v31, v181, v68, v31
	v_fma_f32 v24, v178, v72, v24
	v_fma_f32 v25, v179, v72, v25
	v_fma_f32 v26, v180, v72, v26
	v_fma_f32 v27, v181, v72, v27
	v_fma_f32 v20, v178, v76, v20
	v_fma_f32 v21, v179, v76, v21
	v_fma_f32 v22, v180, v76, v22
	v_fma_f32 v23, v181, v76, v23
	v_fma_f32 v12, v178, v80, v12
	v_fma_f32 v13, v179, v80, v13
	v_fma_f32 v14, v180, v80, v14
	v_fma_f32 v15, v181, v80, v15
	v_fma_f32 v4, v178, v142, v4
	v_fma_f32 v5, v179, v142, v5
	v_fma_f32 v6, v180, v142, v6
	v_fma_f32 v7, v181, v142, v7
	v_fma_f32 v0, v178, v150, v0
	v_fma_f32 v1, v179, v150, v1
	v_fma_f32 v2, v180, v150, v2
	v_fma_f32 v3, v181, v150, v3
	v_fma_f32 v16, v178, v158, v16
	v_fma_f32 v17, v179, v158, v17
	v_fma_f32 v18, v180, v158, v18
	v_fma_f32 v19, v181, v158, v19
	v_fma_f32 v8, v178, v166, v8
	v_fma_f32 v9, v179, v166, v9
	v_fma_f32 v10, v180, v166, v10
	v_fma_f32 v11, v181, v166, v11
	s_waitcnt vmcnt(2)
; #define LAS __attribute__((address_space(3)))
;     template <class T> __device__ __forceinline__ T* w(size_t off) const { return (T*)(pp->ws + off); }
; __device__ __forceinline__ void mod_unit(const Ctx& c, int u) {
;     ...
;             for (int r = 0; r < 12; ++r) {
;                 const f32x4 s4 = *(const LAS f32x4*)(sc + r * 512 + kg * 32 + i);
; #pragma unroll
;                 for (int e = 0; e < 4; ++e) { acc2[r][0] += (f32x2){w[e][0], w[e][1]} * s4[e]; acc2[r][1] += (f32x2){w[e][2], w[e][3]} * s4[e]; }
;             }
;         }
;     }
;     __syncthreads();
; #pragma unroll
;     for (int r = 0; r < 12; ++r) *(LAS f32x4*)(red + (kg * 12 + r) * 128 + 4 * cl) = (f32x4){acc2[r][0].x, acc2[r][0].y, acc2[r][1].x, acc2[r][1].y};
;     __syncthreads();
;     float* MOD = c.w<float>(WS_MOD);
;     for (int o = c.tid; o < 1536; o += 512) {
;         const int r = o >> 7, cc = o & 127; float s = 0.f;
; #pragma unroll
;         for (int k2 = 0; k2 < 16; ++k2) s += red[(k2 * 12 + r) * 128 + cc];
;         MOD[(size_t)(l * 12 + r) * 12288 + j0 + cc] = s + c.f(I_BADA)[l * 12288 + j0 + cc];
	v_fma_f32 v44, v182, v49, v44
	v_fma_f32 v45, v183, v49, v45
	v_fma_f32 v46, v184, v49, v46
	v_fma_f32 v47, v185, v49, v47
	v_fma_f32 v40, v182, v57, v40
	v_fma_f32 v41, v183, v57, v41
	v_fma_f32 v42, v184, v57, v42
	v_fma_f32 v43, v185, v57, v43
	v_fma_f32 v36, v182, v61, v36
	v_fma_f32 v37, v183, v61, v37
	v_fma_f32 v38, v184, v61, v38
	v_fma_f32 v39, v185, v61, v39
	v_fma_f32 v32, v182, v65, v32
	v_fma_f32 v33, v183, v65, v33
	v_fma_f32 v34, v184, v65, v34
	v_fma_f32 v35, v185, v65, v35
	v_fma_f32 v28, v182, v69, v28
	v_fma_f32 v29, v183, v69, v29
	v_fma_f32 v30, v184, v69, v30
	v_fma_f32 v31, v185, v69, v31
	v_fma_f32 v24, v182, v73, v24
	v_fma_f32 v25, v183, v73, v25
	v_fma_f32 v26, v184, v73, v26
	v_fma_f32 v27, v185, v73, v27
	v_fma_f32 v20, v182, v77, v20
	v_fma_f32 v21, v183, v77, v21
	v_fma_f32 v22, v184, v77, v22
	v_fma_f32 v23, v185, v77, v23
	v_fma_f32 v12, v182, v81, v12
	v_fma_f32 v13, v183, v81, v13
	v_fma_f32 v14, v184, v81, v14
	v_fma_f32 v15, v185, v81, v15
	v_fma_f32 v4, v182, v143, v4
	v_fma_f32 v5, v183, v143, v5
	v_fma_f32 v6, v184, v143, v6
	v_fma_f32 v7, v185, v143, v7
	v_fma_f32 v0, v182, v151, v0
	v_fma_f32 v1, v183, v151, v1
	v_fma_f32 v2, v184, v151, v2
	v_fma_f32 v3, v185, v151, v3
	v_fma_f32 v16, v182, v159, v16
	v_fma_f32 v17, v183, v159, v17
	v_fma_f32 v18, v184, v159, v18
	v_fma_f32 v19, v185, v159, v19
	v_fma_f32 v8, v182, v167, v8
	v_fma_f32 v9, v183, v167, v9
	v_fma_f32 v10, v184, v167, v10
	v_fma_f32 v11, v185, v167, v11
	s_waitcnt vmcnt(1)
	v_fma_f32 v44, v186, v50, v44
	v_fma_f32 v45, v187, v50, v45
	v_fma_f32 v46, v188, v50, v46
	v_fma_f32 v47, v189, v50, v47
	v_fma_f32 v40, v186, v58, v40
	v_fma_f32 v41, v187, v58, v41
	v_fma_f32 v42, v188, v58, v42
	v_fma_f32 v43, v189, v58, v43
	v_fma_f32 v36, v186, v62, v36
	v_fma_f32 v37, v187, v62, v37
	v_fma_f32 v38, v188, v62, v38
	v_fma_f32 v39, v189, v62, v39
	v_fma_f32 v32, v186, v66, v32
	v_fma_f32 v33, v187, v66, v33
	v_fma_f32 v34, v188, v66, v34
	v_fma_f32 v35, v189, v66, v35
	v_fma_f32 v28, v186, v70, v28
	v_fma_f32 v29, v187, v70, v29
	v_fma_f32 v30, v188, v70, v30
	v_fma_f32 v31, v189, v70, v31
	v_fma_f32 v24, v186, v74, v24
	v_fma_f32 v25, v187, v74, v25
	v_fma_f32 v26, v188, v74, v26
	v_fma_f32 v27, v189, v74, v27
	v_fma_f32 v20, v186, v78, v20
	v_fma_f32 v21, v187, v78, v21
	v_fma_f32 v22, v188, v78, v22
	v_fma_f32 v23, v189, v78, v23
	v_fma_f32 v12, v186, v82, v12
	v_fma_f32 v13, v187, v82, v13
	v_fma_f32 v14, v188, v82, v14
	v_fma_f32 v15, v189, v82, v15
	v_fma_f32 v4, v186, v144, v4
	v_fma_f32 v5, v187, v144, v5
	v_fma_f32 v6, v188, v144, v6
	v_fma_f32 v7, v189, v144, v7
	v_fma_f32 v0, v186, v152, v0
	v_fma_f32 v1, v187, v152, v1
	v_fma_f32 v2, v188, v152, v2
	v_fma_f32 v3, v189, v152, v3
	v_fma_f32 v16, v186, v160, v16
	v_fma_f32 v17, v187, v160, v17
	v_fma_f32 v18, v188, v160, v18
	v_fma_f32 v19, v189, v160, v19
	v_fma_f32 v8, v186, v168, v8
	v_fma_f32 v9, v187, v168, v9
	v_fma_f32 v10, v188, v168, v10
	v_fma_f32 v11, v189, v168, v11
	s_waitcnt vmcnt(0)
	v_fma_f32 v44, v190, v214, v44
	v_fma_f32 v45, v191, v214, v45
	v_fma_f32 v46, v192, v214, v46
	v_fma_f32 v47, v193, v214, v47
	v_fma_f32 v40, v190, v216, v40
	v_fma_f32 v41, v191, v216, v41
	v_fma_f32 v42, v192, v216, v42
	v_fma_f32 v43, v193, v216, v43
	v_fma_f32 v36, v190, v218, v36
	v_fma_f32 v37, v191, v218, v37
	v_fma_f32 v38, v192, v218, v38
	v_fma_f32 v39, v193, v218, v39
	v_fma_f32 v32, v190, v220, v32
	v_fma_f32 v33, v191, v220, v33
	v_fma_f32 v34, v192, v220, v34
	v_fma_f32 v35, v193, v220, v35
	v_fma_f32 v28, v190, v222, v28
	v_fma_f32 v29, v191, v222, v29
	v_fma_f32 v30, v192, v222, v30
	v_fma_f32 v31, v193, v222, v31
	v_fma_f32 v24, v190, v224, v24
	v_fma_f32 v25, v191, v224, v25
	v_fma_f32 v26, v192, v224, v26
	v_fma_f32 v27, v193, v224, v27
	v_fma_f32 v20, v190, v226, v20
	v_fma_f32 v21, v191, v226, v21
	v_fma_f32 v22, v192, v226, v22
	v_fma_f32 v23, v193, v226, v23
	v_fma_f32 v12, v190, v228, v12
	v_fma_f32 v13, v191, v228, v13
	v_fma_f32 v14, v192, v228, v14
	v_fma_f32 v15, v193, v228, v15
	v_fma_f32 v4, v190, v230, v4
	v_fma_f32 v5, v191, v230, v5
	v_fma_f32 v6, v192, v230, v6
	v_fma_f32 v7, v193, v230, v7
	v_fma_f32 v0, v190, v232, v0
	v_fma_f32 v1, v191, v232, v1
	v_fma_f32 v2, v192, v232, v2
	v_fma_f32 v3, v193, v232, v3
	v_fma_f32 v16, v190, v234, v16
	v_fma_f32 v17, v191, v234, v17
	v_fma_f32 v18, v192, v234, v18
	v_fma_f32 v19, v193, v234, v19
	v_fma_f32 v8, v190, v236, v8
	v_fma_f32 v9, v191, v236, v9
	v_fma_f32 v10, v192, v236, v10
	v_fma_f32 v11, v193, v236, v11
	s_cbranch_scc0 .LBB0_973
	s_add_i32 s9, s9, 1
	s_cmp_eq_u32 s9, 8
	v_add_u32_e32 v91, 0x200, v91
	s_cbranch_scc0 .LBB0_965
	v_lshrrev_b32_e32 v48, 5, v141
	s_movk_i32 s0, 0x1800
	v_mul_lo_u32 v48, v48, s0
	s_movk_i32 s0, 0x600
	v_cmp_gt_i32_e32 vcc, s0, v141
	v_add3_u32 v48, v104, v90, v48
	s_barrier
	ds_write_b128 v48, v[44:47]
	ds_write_b128 v48, v[40:43] offset:512
	ds_write_b128 v48, v[36:39] offset:1024
	ds_write_b128 v48, v[32:35] offset:1536
	ds_write_b128 v48, v[28:31] offset:2048
	ds_write_b128 v48, v[24:27] offset:2560
	ds_write_b128 v48, v[20:23] offset:3072
	ds_write_b128 v48, v[12:15] offset:3584
	ds_write_b128 v48, v[4:7] offset:4096
	ds_write_b128 v48, v[0:3] offset:4608
	ds_write_b128 v48, v[16:19] offset:5120
	ds_write_b128 v48, v[8:11] offset:5632
	s_waitcnt lgkmcnt(0)
	s_barrier
	s_and_saveexec_b64 s[0:1], vcc
	s_cbranch_execz .LBB0_978
	s_add_i32 s4, s8, 0x3000
	s_add_u32 s2, s34, s10
	v_and_b32_e32 v0, 0x7f, v141
	v_mov_b32_e32 v3, 0
	s_addc_u32 s3, s35, s11
	v_lshlrev_b32_e32 v4, 2, v0
	v_mov_b32_e32 v5, v3
	v_or_b32_e32 v2, s4, v0
	v_lshl_add_u64 v[0:1], s[2:3], 0, v[4:5]
	s_load_dwordx2 s[2:3], s[90:91], 0x58
	s_mov_b64 s[4:5], 0x100000
	v_lshl_add_u64 v[0:1], v[0:1], 0, s[4:5]
	v_add_u32_e32 v4, v104, v4
	s_mov_b64 s[4:5], 0
	s_waitcnt lgkmcnt(0)
	v_lshl_add_u64 v[2:3], v[2:3], 2, s[2:3]
	s_mov_b32 s2, 0xc000
	s_movk_i32 s3, 0x3ff
	v_mov_b32_e32 v5, v141

; __device__ __forceinline__ f32x2 silu_pk(f32x2 x) { const f32x2 t = x * -1.4426950408889634f; f32x2 e; e.x = __builtin_amdgcn_exp2f(t.x); e.y = __builtin_amdgcn_exp2f(t.y); e = e + 1.0f; f32x2 r; r.x = __builtin_amdgcn_rcpf(e.x); r.y = __builtin_amdgcn_rcpf(e.y); return x * r; }
;     __device__ __forceinline__ void operator()(const pg8::f32x4 (&acc)[2][2][4][2], const pg8::Unit& u, int wr, int wc, int fr, int fq) const {
;     ...
;                     } else if (pn < 44) {
; #pragma unroll
;                         for (int e = 0; e < 8; e += 2) { const f32x2 g2 = silu_pk((f32x2){v[e], v[e + 1]}); v[e] = g2.x; v[e + 1] = g2.y; }
;                         st_bf16((bf16*)(ws + WS_ZB) + (size_t)r * 2048 + (pn - 36) * 256 + cl, v);
;                     } else if (pn < 48) {
;                         st_bf16((bf16*)(ws + WS_QC) + (size_t)r * 1024 + (pn - 44) * 256 + cl, v);
;                     } else if (pn < 50) {
;                         const bool isv = pn == 49;
;                         st_bf16((bf16*)(ws + (isv ? WS_VC : WS_KC)) + (size_t)r * 256 + cl, v);
;                         if (r < PT) st_f32(out + (isv ? O_PV : O_PK) + ((size_t)l * PT + r) * 256 + cl, v);
;                         else st_f32(out + (isv ? O_SV : O_SK) + ((size_t)l * ST + (r - PT)) * 256 + cl, v);
;                     } else if (pn < 54) {
; #pragma unroll
;                         for (int e = 0; e < 8; e += 2) { const f32x2 g2 = silu_pk((f32x2){v[e], v[e + 1]}); v[e] = g2.x; v[e + 1] = g2.y; }
;                         st_bf16((bf16*)(ws + WS_ZC) + (size_t)r * 1024 + (pn - 50) * 256 + cl, v);
.LBB0_1788:
	s_andn2_b64 vcc, exec, s[4:5]
	s_cbranch_vccnz .LBB0_1790
	v_mul_f32_e64 v172, v124, s50
	v_mul_f32_e64 v173, v125, s50
	v_mul_f32_e64 v174, v126, s50
	v_mul_f32_e64 v175, v127, s50
	v_exp_f32_e32 v172, v172
	v_exp_f32_e32 v173, v173
	v_exp_f32_e32 v174, v174
	v_exp_f32_e32 v175, v175
	v_mul_f32_e64 v176, v120, s50
	v_mul_f32_e64 v177, v121, s50
	v_mul_f32_e64 v178, v122, s50
	v_mul_f32_e64 v179, v123, s50
	v_exp_f32_e32 v176, v176
	v_exp_f32_e32 v177, v177
	v_exp_f32_e32 v178, v178
	v_exp_f32_e32 v179, v179
	v_add_f32_e64 v172, v172, 1.0
	v_add_f32_e64 v173, v173, 1.0
	v_add_f32_e64 v174, v174, 1.0
	v_add_f32_e64 v175, v175, 1.0
	v_rcp_f32_e32 v172, v172
	v_rcp_f32_e32 v173, v173
	v_rcp_f32_e32 v174, v174
	v_rcp_f32_e32 v175, v175
	v_add_f32_e64 v176, v176, 1.0
	v_add_f32_e64 v177, v177, 1.0
	v_add_f32_e64 v178, v178, 1.0
	v_add_f32_e64 v179, v179, 1.0
	v_rcp_f32_e32 v176, v176
	v_rcp_f32_e32 v177, v177
	v_rcp_f32_e32 v178, v178
	v_rcp_f32_e32 v179, v179
	v_lshlrev_b32_e32 v136, 1, v140
	v_mul_f32_e64 v172, v124, v172
	v_mul_f32_e64 v173, v125, v173
	v_mul_f32_e64 v174, v126, v174
	v_mul_f32_e64 v175, v127, v175
	v_lshl_add_u64 v[186:187], v[166:167], 0, v[136:137]
	v_mul_f32_e64 v176, v120, v176
	v_mul_f32_e64 v177, v121, v177
	v_mul_f32_e64 v178, v122, v178
	v_mul_f32_e64 v179, v123, v179
	v_cvt_pk_bf16_f32 v172, v172, v173
	v_cvt_pk_bf16_f32 v173, v174, v175
	v_cvt_pk_bf16_f32 v174, v176, v177
	s_nop 0
	v_cvt_pk_bf16_f32 v175, v178, v179
	global_store_dwordx4 v[186:187], v[172:175], off

; __device__ __forceinline__ f32x2 silu_pk(f32x2 x) { const f32x2 t = x * -1.4426950408889634f; f32x2 e; e.x = __builtin_amdgcn_exp2f(t.x); e.y = __builtin_amdgcn_exp2f(t.y); e = e + 1.0f; f32x2 r; r.x = __builtin_amdgcn_rcpf(e.x); r.y = __builtin_amdgcn_rcpf(e.y); return x * r; }
;     __device__ __forceinline__ void operator()(const pg8::f32x4 (&acc)[2][2][4][2], const pg8::Unit& u, int wr, int wc, int fr, int fq) const {
;     ...
;                     } else if (pn < 44) {
; #pragma unroll
;                         for (int e = 0; e < 8; e += 2) { const f32x2 g2 = silu_pk((f32x2){v[e], v[e + 1]}); v[e] = g2.x; v[e + 1] = g2.y; }
;                         st_bf16((bf16*)(ws + WS_ZB) + (size_t)r * 2048 + (pn - 36) * 256 + cl, v);
;                     } else if (pn < 48) {
;                         st_bf16((bf16*)(ws + WS_QC) + (size_t)r * 1024 + (pn - 44) * 256 + cl, v);
;                     } else if (pn < 50) {
;                         const bool isv = pn == 49;
;                         st_bf16((bf16*)(ws + (isv ? WS_VC : WS_KC)) + (size_t)r * 256 + cl, v);
;                         if (r < PT) st_f32(out + (isv ? O_PV : O_PK) + ((size_t)l * PT + r) * 256 + cl, v);
;                         else st_f32(out + (isv ? O_SV : O_SK) + ((size_t)l * ST + (r - PT)) * 256 + cl, v);
;                     } else if (pn < 54) {
; #pragma unroll
;                         for (int e = 0; e < 8; e += 2) { const f32x2 g2 = silu_pk((f32x2){v[e], v[e + 1]}); v[e] = g2.x; v[e + 1] = g2.y; }
;                         st_bf16((bf16*)(ws + WS_ZC) + (size_t)r * 1024 + (pn - 50) * 256 + cl, v);
.LBB0_1801:
	s_andn2_b64 vcc, exec, s[4:5]
	s_cbranch_vccnz .LBB0_1803
	v_mul_f32_e64 v172, v124, s50
	v_mul_f32_e64 v173, v125, s50
	v_mul_f32_e64 v174, v126, s50
	v_mul_f32_e64 v175, v127, s50
	v_exp_f32_e32 v172, v172
	v_exp_f32_e32 v173, v173
	v_exp_f32_e32 v174, v174
	v_exp_f32_e32 v175, v175
	v_mul_f32_e64 v176, v120, s50
	v_mul_f32_e64 v177, v121, s50
	v_mul_f32_e64 v178, v122, s50
	v_mul_f32_e64 v179, v123, s50
	v_exp_f32_e32 v176, v176
	v_exp_f32_e32 v177, v177
	v_exp_f32_e32 v178, v178
	v_exp_f32_e32 v179, v179
	v_add_f32_e64 v172, v172, 1.0
	v_add_f32_e64 v173, v173, 1.0
	v_add_f32_e64 v174, v174, 1.0
	v_add_f32_e64 v175, v175, 1.0
	v_rcp_f32_e32 v172, v172
	v_rcp_f32_e32 v173, v173
	v_rcp_f32_e32 v174, v174
	v_rcp_f32_e32 v175, v175
	v_add_f32_e64 v176, v176, 1.0
	v_add_f32_e64 v177, v177, 1.0
	v_add_f32_e64 v178, v178, 1.0
	v_add_f32_e64 v179, v179, 1.0
	v_rcp_f32_e32 v176, v176
	v_rcp_f32_e32 v177, v177
	v_rcp_f32_e32 v178, v178
	v_rcp_f32_e32 v179, v179
	v_lshlrev_b32_e32 v136, 1, v140
	v_mul_f32_e64 v172, v124, v172
	v_mul_f32_e64 v173, v125, v173
	v_mul_f32_e64 v174, v126, v174
	v_mul_f32_e64 v175, v127, v175
	v_lshl_add_u64 v[186:187], v[156:157], 0, v[136:137]
	v_mul_f32_e64 v176, v120, v176
	v_mul_f32_e64 v177, v121, v177
	v_mul_f32_e64 v178, v122, v178
	v_mul_f32_e64 v179, v123, v179
	v_cvt_pk_bf16_f32 v172, v172, v173
	v_cvt_pk_bf16_f32 v173, v174, v175
	v_cvt_pk_bf16_f32 v174, v176, v177
	s_nop 0
	v_cvt_pk_bf16_f32 v175, v178, v179
	global_store_dwordx4 v[186:187], v[172:175], off

; __device__ __forceinline__ f32x2 silu_pk(f32x2 x) { const f32x2 t = x * -1.4426950408889634f; f32x2 e; e.x = __builtin_amdgcn_exp2f(t.x); e.y = __builtin_amdgcn_exp2f(t.y); e = e + 1.0f; f32x2 r; r.x = __builtin_amdgcn_rcpf(e.x); r.y = __builtin_amdgcn_rcpf(e.y); return x * r; }
;     __device__ __forceinline__ void operator()(const pg8::f32x4 (&acc)[2][2][4][2], const pg8::Unit& u, int wr, int wc, int fr, int fq) const {
;     ...
;                     } else if (pn < 44) {
; #pragma unroll
;                         for (int e = 0; e < 8; e += 2) { const f32x2 g2 = silu_pk((f32x2){v[e], v[e + 1]}); v[e] = g2.x; v[e + 1] = g2.y; }
;                         st_bf16((bf16*)(ws + WS_ZB) + (size_t)r * 2048 + (pn - 36) * 256 + cl, v);
;                     } else if (pn < 48) {
;                         st_bf16((bf16*)(ws + WS_QC) + (size_t)r * 1024 + (pn - 44) * 256 + cl, v);
;                     } else if (pn < 50) {
;                         const bool isv = pn == 49;
;                         st_bf16((bf16*)(ws + (isv ? WS_VC : WS_KC)) + (size_t)r * 256 + cl, v);
;                         if (r < PT) st_f32(out + (isv ? O_PV : O_PK) + ((size_t)l * PT + r) * 256 + cl, v);
;                         else st_f32(out + (isv ? O_SV : O_SK) + ((size_t)l * ST + (r - PT)) * 256 + cl, v);
;                     } else if (pn < 54) {
; #pragma unroll
;                         for (int e = 0; e < 8; e += 2) { const f32x2 g2 = silu_pk((f32x2){v[e], v[e + 1]}); v[e] = g2.x; v[e + 1] = g2.y; }
;                         st_bf16((bf16*)(ws + WS_ZC) + (size_t)r * 1024 + (pn - 50) * 256 + cl, v);
.LBB0_1818:
	s_andn2_b64 vcc, exec, s[4:5]
	s_cbranch_vccnz .LBB0_1820
	v_mul_f32_e64 v120, v116, s50
	v_mul_f32_e64 v121, v117, s50
	v_mul_f32_e64 v122, v118, s50
	v_mul_f32_e64 v123, v119, s50
	v_exp_f32_e32 v120, v120
	v_exp_f32_e32 v121, v121
	v_exp_f32_e32 v122, v122
	v_exp_f32_e32 v123, v123
	v_mul_f32_e64 v124, v112, s50
	v_mul_f32_e64 v125, v113, s50
	v_mul_f32_e64 v126, v114, s50
	v_mul_f32_e64 v127, v115, s50
	v_exp_f32_e32 v124, v124
	v_exp_f32_e32 v125, v125
	v_exp_f32_e32 v126, v126
	v_exp_f32_e32 v127, v127
	v_add_f32_e64 v120, v120, 1.0
	v_add_f32_e64 v121, v121, 1.0
	v_add_f32_e64 v122, v122, 1.0
	v_add_f32_e64 v123, v123, 1.0
	v_rcp_f32_e32 v120, v120
	v_rcp_f32_e32 v121, v121
	v_rcp_f32_e32 v122, v122
	v_rcp_f32_e32 v123, v123
	v_add_f32_e64 v124, v124, 1.0
	v_add_f32_e64 v125, v125, 1.0
	v_add_f32_e64 v126, v126, 1.0
	v_add_f32_e64 v127, v127, 1.0
	v_rcp_f32_e32 v124, v124
	v_rcp_f32_e32 v125, v125
	v_rcp_f32_e32 v126, v126
	v_rcp_f32_e32 v127, v127
	v_lshlrev_b32_e32 v136, 1, v142
	v_mul_f32_e64 v120, v116, v120
	v_mul_f32_e64 v121, v117, v121
	v_mul_f32_e64 v122, v118, v122
	v_mul_f32_e64 v123, v119, v123
	v_lshl_add_u64 v[166:167], v[166:167], 0, v[136:137]
	v_mul_f32_e64 v124, v112, v124
	v_mul_f32_e64 v125, v113, v125
	v_mul_f32_e64 v126, v114, v126
	v_mul_f32_e64 v127, v115, v127
	v_cvt_pk_bf16_f32 v120, v120, v121
	v_cvt_pk_bf16_f32 v121, v122, v123
	v_cvt_pk_bf16_f32 v122, v124, v125
	s_nop 0
	v_cvt_pk_bf16_f32 v123, v126, v127
	global_store_dwordx4 v[166:167], v[120:123], off

; __device__ __forceinline__ f32x2 silu_pk(f32x2 x) { const f32x2 t = x * -1.4426950408889634f; f32x2 e; e.x = __builtin_amdgcn_exp2f(t.x); e.y = __builtin_amdgcn_exp2f(t.y); e = e + 1.0f; f32x2 r; r.x = __builtin_amdgcn_rcpf(e.x); r.y = __builtin_amdgcn_rcpf(e.y); return x * r; }
;     __device__ __forceinline__ void operator()(const pg8::f32x4 (&acc)[2][2][4][2], const pg8::Unit& u, int wr, int wc, int fr, int fq) const {
;     ...
;                     } else if (pn < 44) {
; #pragma unroll
;                         for (int e = 0; e < 8; e += 2) { const f32x2 g2 = silu_pk((f32x2){v[e], v[e + 1]}); v[e] = g2.x; v[e + 1] = g2.y; }
;                         st_bf16((bf16*)(ws + WS_ZB) + (size_t)r * 2048 + (pn - 36) * 256 + cl, v);
;                     } else if (pn < 48) {
;                         st_bf16((bf16*)(ws + WS_QC) + (size_t)r * 1024 + (pn - 44) * 256 + cl, v);
;                     } else if (pn < 50) {
;                         const bool isv = pn == 49;
;                         st_bf16((bf16*)(ws + (isv ? WS_VC : WS_KC)) + (size_t)r * 256 + cl, v);
;                         if (r < PT) st_f32(out + (isv ? O_PV : O_PK) + ((size_t)l * PT + r) * 256 + cl, v);
;                         else st_f32(out + (isv ? O_SV : O_SK) + ((size_t)l * ST + (r - PT)) * 256 + cl, v);
;                     } else if (pn < 54) {
; #pragma unroll
;                         for (int e = 0; e < 8; e += 2) { const f32x2 g2 = silu_pk((f32x2){v[e], v[e + 1]}); v[e] = g2.x; v[e + 1] = g2.y; }
;                         st_bf16((bf16*)(ws + WS_ZC) + (size_t)r * 1024 + (pn - 50) * 256 + cl, v);
.LBB0_1831:
	s_andn2_b64 vcc, exec, s[4:5]
	s_cbranch_vccnz .LBB0_1833
	v_mul_f32_e64 v120, v116, s50
	v_mul_f32_e64 v121, v117, s50
	v_mul_f32_e64 v122, v118, s50
	v_mul_f32_e64 v123, v119, s50
	v_exp_f32_e32 v120, v120
	v_exp_f32_e32 v121, v121
	v_exp_f32_e32 v122, v122
	v_exp_f32_e32 v123, v123
	v_mul_f32_e64 v124, v112, s50
	v_mul_f32_e64 v125, v113, s50
	v_mul_f32_e64 v126, v114, s50
	v_mul_f32_e64 v127, v115, s50
	v_exp_f32_e32 v124, v124
	v_exp_f32_e32 v125, v125
	v_exp_f32_e32 v126, v126
	v_exp_f32_e32 v127, v127
	v_add_f32_e64 v120, v120, 1.0
	v_add_f32_e64 v121, v121, 1.0
	v_add_f32_e64 v122, v122, 1.0
	v_add_f32_e64 v123, v123, 1.0
	v_rcp_f32_e32 v120, v120
	v_rcp_f32_e32 v121, v121
	v_rcp_f32_e32 v122, v122
	v_rcp_f32_e32 v123, v123
	v_add_f32_e64 v124, v124, 1.0
	v_add_f32_e64 v125, v125, 1.0
	v_add_f32_e64 v126, v126, 1.0
	v_add_f32_e64 v127, v127, 1.0
	v_rcp_f32_e32 v124, v124
	v_rcp_f32_e32 v125, v125
	v_rcp_f32_e32 v126, v126
	v_rcp_f32_e32 v127, v127
	v_lshlrev_b32_e32 v136, 1, v142
	v_mul_f32_e64 v120, v116, v120
	v_mul_f32_e64 v121, v117, v121
	v_mul_f32_e64 v122, v118, v122
	v_mul_f32_e64 v123, v119, v123
	v_lshl_add_u64 v[156:157], v[156:157], 0, v[136:137]
	v_mul_f32_e64 v124, v112, v124
	v_mul_f32_e64 v125, v113, v125
	v_mul_f32_e64 v126, v114, v126
	v_mul_f32_e64 v127, v115, v127
	v_cvt_pk_bf16_f32 v120, v120, v121
	v_cvt_pk_bf16_f32 v121, v122, v123
	v_cvt_pk_bf16_f32 v122, v124, v125
	s_nop 0
	v_cvt_pk_bf16_f32 v123, v126, v127
	global_store_dwordx4 v[156:157], v[120:123], off

; __device__ __forceinline__ f32x2 silu_pk(f32x2 x) { const f32x2 t = x * -1.4426950408889634f; f32x2 e; e.x = __builtin_amdgcn_exp2f(t.x); e.y = __builtin_amdgcn_exp2f(t.y); e = e + 1.0f; f32x2 r; r.x = __builtin_amdgcn_rcpf(e.x); r.y = __builtin_amdgcn_rcpf(e.y); return x * r; }
; __device__ __forceinline__ f32x2 gelu_pk(f32x2 x) { const f32x2 x2 = x * x; const f32x2 t = (x2 * 0.044715f + 1.0f) * (x * -2.302208198144325f); f32x2 e; e.x = __builtin_amdgcn_exp2f(t.x); e.y = __builtin_amdgcn_exp2f(t.y); e = e + 1.0f; f32x2 r; r.x = __builtin_amdgcn_rcpf(e.x); r.y = __builtin_amd ...
;     __device__ __forceinline__ void operator()(const pg8::f32x4 (&acc)[2][2][4][2], const pg8::Unit& u, int wr, int wc, int fr, int fq) const {
;     ...
;                     if (pn < 12) {
;                         const int seg = pn >> 2, cc = (pn & 3) * 256 + cl;
;                         if (seg < 2) {
; #pragma unroll
;                             for (int e = 0; e < 8; e += 2) { const f32x2 g2 = gelu_pk((f32x2){v[e], v[e + 1]}); v[e] = g2.x; v[e + 1] = g2.y; }
;                         } else {
; #pragma unroll
;                             for (int e = 0; e < 8; e += 2) { const f32x2 g2 = silu_pk((f32x2){v[e], v[e + 1]}); v[e] = g2.x; v[e + 1] = g2.y; }
;                         }
;                         bf16* base = (bf16*)(ws + (seg == 0 ? WS_UA : seg == 1 ? WS_VA : WS_ZA));
;                         st_bf16(base + (size_t)r * 1024 + cc, v);
.LBB0_1840:
	s_andn2_b64 vcc, exec, s[16:17]
	s_mov_b64 s[6:7], -1
	s_cbranch_vccnz .LBB0_1842
	v_mul_f32_e64 v174, v126, s50
	v_mul_f32_e64 v175, v127, s50
	v_mul_f32_e64 v172, v124, s50
	v_mul_f32_e64 v173, v125, s50
	v_exp_f32_e32 v174, v174
	v_exp_f32_e32 v175, v175
	v_mul_f32_e64 v176, v120, s50
	v_mul_f32_e64 v177, v121, s50
	v_exp_f32_e32 v172, v172
	v_exp_f32_e32 v173, v173
	v_exp_f32_e32 v176, v176
	v_exp_f32_e32 v177, v177
	v_add_f32_e64 v174, v174, 1.0
	v_add_f32_e64 v175, v175, 1.0
	v_add_f32_e64 v172, v172, 1.0
	v_add_f32_e64 v173, v173, 1.0
	v_rcp_f32_e32 v178, v174
	v_rcp_f32_e32 v179, v175
	v_add_f32_e64 v174, v176, 1.0
	v_add_f32_e64 v175, v177, 1.0
	v_rcp_f32_e32 v172, v172
	v_rcp_f32_e32 v173, v173
	v_rcp_f32_e32 v176, v174
	v_rcp_f32_e32 v177, v175
	s_mov_b64 s[6:7], 0
	v_mul_f32_e64 v174, v124, v172
	v_mul_f32_e64 v175, v125, v173
	v_mul_f32_e64 v172, v126, v178
	v_mul_f32_e64 v173, v127, v179
	v_mul_f32_e64 v176, v120, v176
	v_mul_f32_e64 v177, v121, v177
	v_mul_f32_e64 v178, v122, s50
	v_mul_f32_e64 v179, v123, s50
.LBB0_1842:
	s_andn2_b64 vcc, exec, s[6:7]
	s_cbranch_vccnz .LBB0_1844
	v_mul_f32_e64 v174, v124, v124
	v_mul_f32_e64 v175, v125, v125
	v_mul_f32_e64 v176, v124, s58
	v_mul_f32_e64 v177, v125, s58
	v_fma_f32 v174, v174, s56, 1.0
	v_fma_f32 v175, v175, s56, 1.0
	v_mul_f32_e64 v172, v126, v126
	v_mul_f32_e64 v173, v127, v127
	v_mul_f32_e64 v174, v176, v174
	v_mul_f32_e64 v175, v177, v175
	v_mul_f32_e64 v176, v120, s58
	v_mul_f32_e64 v177, v121, s58
	v_exp_f32_e32 v174, v174
	v_exp_f32_e32 v175, v175
	s_nop 0
	v_add_f32_e64 v174, v174, 1.0
	v_add_f32_e64 v175, v175, 1.0
	s_nop 0
	v_rcp_f32_e32 v174, v174
	v_rcp_f32_e32 v175, v175
	s_nop 0
	v_mul_f32_e64 v174, v124, v174
	v_mul_f32_e64 v175, v125, v175
	v_fma_f32 v124, v172, s56, 1.0
	v_fma_f32 v125, v173, s56, 1.0
	v_mul_f32_e64 v172, v126, s58
	v_mul_f32_e64 v173, v127, s58
	s_nop 0
	v_mul_f32_e64 v124, v172, v124
	v_mul_f32_e64 v125, v173, v125
	s_nop 0
	v_exp_f32_e32 v124, v124
	v_exp_f32_e32 v125, v125
	s_nop 0
	v_add_f32_e64 v124, v124, 1.0
	v_add_f32_e64 v125, v125, 1.0
	s_nop 0
	v_rcp_f32_e32 v124, v124
	v_rcp_f32_e32 v125, v125
	s_nop 0
	v_mul_f32_e64 v172, v126, v124
	v_mul_f32_e64 v173, v127, v125
	v_mul_f32_e64 v126, v120, v120
	v_mul_f32_e64 v127, v121, v121
	v_mul_f32_e64 v124, v122, v122
	v_mul_f32_e64 v125, v123, v123
	v_fma_f32 v126, v126, s56, 1.0
	v_fma_f32 v127, v127, s56, 1.0
	s_nop 0
	v_mul_f32_e64 v126, v176, v126
	v_mul_f32_e64 v127, v177, v127
	s_nop 0
	v_exp_f32_e32 v126, v126
	v_exp_f32_e32 v127, v127
	s_nop 0
	v_add_f32_e64 v126, v126, 1.0
	v_add_f32_e64 v127, v127, 1.0
	s_nop 0
	v_rcp_f32_e32 v126, v126
	v_rcp_f32_e32 v127, v127
	s_nop 0
	v_mul_f32_e64 v176, v120, v126
	v_mul_f32_e64 v177, v121, v127
	v_fma_f32 v120, v124, s56, 1.0
	v_fma_f32 v121, v125, s56, 1.0
	v_mul_f32_e64 v124, v122, s58
	v_mul_f32_e64 v125, v123, s58
	s_nop 0
	v_mul_f32_e64 v178, v124, v120
	v_mul_f32_e64 v179, v125, v121
.LBB0_1844:
	s_nop 0
	v_exp_f32_e32 v120, v178
	v_exp_f32_e32 v121, v179
	v_or_b32_e32 v126, s24, v140
	v_lshlrev_b32_e32 v136, 1, v126
	v_lshl_add_u64 v[126:127], v[168:169], 0, v[136:137]
	v_add_f32_e64 v120, v120, 1.0
	v_add_f32_e64 v121, v121, 1.0
	s_nop 0
	v_rcp_f32_e32 v120, v120
	v_rcp_f32_e32 v121, v121
	s_nop 0
	v_mul_f32_e64 v124, v122, v120
	v_mul_f32_e64 v125, v123, v121
	v_cvt_pk_bf16_f32 v120, v174, v175
	v_cvt_pk_bf16_f32 v121, v172, v173
	v_cvt_pk_bf16_f32 v122, v176, v177
	s_nop 0
	v_cvt_pk_bf16_f32 v123, v124, v125
	global_store_dwordx4 v[126:127], v[120:123], off
	s_andn2_b64 vcc, exec, s[12:13]
	s_mov_b64 s[4:5], -1
	s_cbranch_vccz .LBB0_1810

; __device__ __forceinline__ f32x2 silu_pk(f32x2 x) { const f32x2 t = x * -1.4426950408889634f; f32x2 e; e.x = __builtin_amdgcn_exp2f(t.x); e.y = __builtin_amdgcn_exp2f(t.y); e = e + 1.0f; f32x2 r; r.x = __builtin_amdgcn_rcpf(e.x); r.y = __builtin_amdgcn_rcpf(e.y); return x * r; }
; __device__ __forceinline__ f32x2 gelu_pk(f32x2 x) { const f32x2 x2 = x * x; const f32x2 t = (x2 * 0.044715f + 1.0f) * (x * -2.302208198144325f); f32x2 e; e.x = __builtin_amdgcn_exp2f(t.x); e.y = __builtin_amdgcn_exp2f(t.y); e = e + 1.0f; f32x2 r; r.x = __builtin_amdgcn_rcpf(e.x); r.y = __builtin_amd ...
;     __device__ __forceinline__ void operator()(const pg8::f32x4 (&acc)[2][2][4][2], const pg8::Unit& u, int wr, int wc, int fr, int fq) const {
;     ...
;                     if (pn < 12) {
;                         const int seg = pn >> 2, cc = (pn & 3) * 256 + cl;
;                         if (seg < 2) {
; #pragma unroll
;                             for (int e = 0; e < 8; e += 2) { const f32x2 g2 = gelu_pk((f32x2){v[e], v[e + 1]}); v[e] = g2.x; v[e + 1] = g2.y; }
;                         } else {
; #pragma unroll
;                             for (int e = 0; e < 8; e += 2) { const f32x2 g2 = silu_pk((f32x2){v[e], v[e + 1]}); v[e] = g2.x; v[e + 1] = g2.y; }
;                         }
;                         bf16* base = (bf16*)(ws + (seg == 0 ? WS_UA : seg == 1 ? WS_VA : WS_ZA));
;                         st_bf16(base + (size_t)r * 1024 + cc, v);
.LBB0_1846:
	s_andn2_b64 vcc, exec, s[16:17]
	s_mov_b64 s[0:1], -1
	s_cbranch_vccnz .LBB0_1848
	v_mul_f32_e64 v120, v116, s50
	v_mul_f32_e64 v121, v117, s50
	v_mul_f32_e64 v122, v118, s50
	v_mul_f32_e64 v123, v119, s50
	v_mul_f32_e64 v124, v112, s50
	v_mul_f32_e64 v125, v113, s50
	v_exp_f32_e32 v120, v120
	v_exp_f32_e32 v121, v121
	v_exp_f32_e32 v122, v122
	v_exp_f32_e32 v123, v123
	v_exp_f32_e32 v124, v124
	v_exp_f32_e32 v125, v125
	v_add_f32_e64 v120, v120, 1.0
	v_add_f32_e64 v121, v121, 1.0
	v_add_f32_e64 v122, v122, 1.0
	v_add_f32_e64 v123, v123, 1.0
	v_rcp_f32_e32 v120, v120
	v_add_f32_e64 v124, v124, 1.0
	v_add_f32_e64 v125, v125, 1.0
	v_rcp_f32_e32 v121, v121
	v_rcp_f32_e32 v122, v122
	v_rcp_f32_e32 v123, v123
	v_rcp_f32_e32 v124, v124
	v_rcp_f32_e32 v125, v125
	v_mul_f32_e64 v120, v116, v120
	v_mul_f32_e64 v121, v117, v121
	v_mul_f32_e64 v122, v118, v122
	v_mul_f32_e64 v123, v119, v123
	v_mul_f32_e64 v126, v114, s50
	v_mul_f32_e64 v127, v115, s50
	v_mul_f32_e64 v124, v112, v124
	v_mul_f32_e64 v125, v113, v125
	s_mov_b64 s[0:1], 0
.LBB0_1848:
	s_andn2_b64 vcc, exec, s[0:1]
	s_cbranch_vccnz .LBB0_1850
	v_mul_f32_e64 v120, v116, v116
	v_mul_f32_e64 v121, v117, v117
	v_mul_f32_e64 v124, v116, s58
	v_mul_f32_e64 v125, v117, s58
	v_fma_f32 v120, v120, s56, 1.0
	v_fma_f32 v121, v121, s56, 1.0
	v_mul_f32_e64 v122, v118, v118
	v_mul_f32_e64 v123, v119, v119
	v_mul_f32_e64 v120, v124, v120
	v_mul_f32_e64 v121, v125, v121
	v_mul_f32_e64 v124, v112, s58
	v_mul_f32_e64 v125, v113, s58
	v_exp_f32_e32 v120, v120
	v_exp_f32_e32 v121, v121
	s_nop 0
	v_add_f32_e64 v120, v120, 1.0
	v_add_f32_e64 v121, v121, 1.0
	s_nop 0
	v_rcp_f32_e32 v120, v120
	v_rcp_f32_e32 v121, v121
	s_nop 0
	v_mul_f32_e64 v120, v116, v120
	v_mul_f32_e64 v121, v117, v121
	v_fma_f32 v116, v122, s56, 1.0
	v_fma_f32 v117, v123, s56, 1.0
	v_mul_f32_e64 v122, v118, s58
	v_mul_f32_e64 v123, v119, s58
	s_nop 0
	v_mul_f32_e64 v116, v122, v116
	v_mul_f32_e64 v117, v123, v117
	s_nop 0
	v_exp_f32_e32 v116, v116
	v_exp_f32_e32 v117, v117
	s_nop 0
	v_add_f32_e64 v116, v116, 1.0
	v_add_f32_e64 v117, v117, 1.0
	s_nop 0
	v_rcp_f32_e32 v116, v116
	v_rcp_f32_e32 v117, v117
	s_nop 0
	v_mul_f32_e64 v122, v118, v116
	v_mul_f32_e64 v123, v119, v117
	v_mul_f32_e64 v118, v112, v112
	v_mul_f32_e64 v119, v113, v113
	v_mul_f32_e64 v116, v114, v114
	v_mul_f32_e64 v117, v115, v115
	v_fma_f32 v118, v118, s56, 1.0
	v_fma_f32 v119, v119, s56, 1.0
	s_nop 0
	v_mul_f32_e64 v118, v124, v118
	v_mul_f32_e64 v119, v125, v119
	s_nop 0
	v_exp_f32_e32 v118, v118
	v_exp_f32_e32 v119, v119
	s_nop 0
	v_add_f32_e64 v118, v118, 1.0
	v_add_f32_e64 v119, v119, 1.0
	s_nop 0
	v_rcp_f32_e32 v118, v118
	v_rcp_f32_e32 v119, v119
	s_nop 0
	v_mul_f32_e64 v124, v112, v118
	v_mul_f32_e64 v125, v113, v119
	v_fma_f32 v112, v116, s56, 1.0
	v_fma_f32 v113, v117, s56, 1.0
	v_mul_f32_e64 v116, v114, s58
	v_mul_f32_e64 v117, v115, s58
	s_nop 0
	v_mul_f32_e64 v126, v116, v112
	v_mul_f32_e64 v127, v117, v113
.LBB0_1850:
	s_nop 0
	v_exp_f32_e32 v112, v126
	v_exp_f32_e32 v113, v127
	v_add_lshl_u32 v136, s24, v140, 1
	v_lshl_add_u64 v[118:119], v[168:169], 0, v[136:137]
	v_add_f32_e64 v112, v112, 1.0
	v_add_f32_e64 v113, v113, 1.0
	s_nop 0
	v_rcp_f32_e32 v112, v112
	v_rcp_f32_e32 v113, v113
	s_nop 0
	v_mul_f32_e64 v116, v114, v112
	v_mul_f32_e64 v117, v115, v113
	v_cvt_pk_bf16_f32 v112, v120, v121
	v_cvt_pk_bf16_f32 v113, v122, v123
	v_cvt_pk_bf16_f32 v114, v124, v125
	s_nop 0
	v_cvt_pk_bf16_f32 v115, v116, v117
	global_store_dwordx4 v[118:119], v[112:115], off offset:256

; __device__ __forceinline__ f32x2 silu_pk(f32x2 x) { const f32x2 t = x * -1.4426950408889634f; f32x2 e; e.x = __builtin_amdgcn_exp2f(t.x); e.y = __builtin_amdgcn_exp2f(t.y); e = e + 1.0f; f32x2 r; r.x = __builtin_amdgcn_rcpf(e.x); r.y = __builtin_amdgcn_rcpf(e.y); return x * r; }
;     __device__ __forceinline__ void operator()(const pg8::f32x4 (&acc)[2][2][4][2], const pg8::Unit& u, int wr, int wc, int fr, int fq) const {
;     ...
;                     } else if (pn < 44) {
; #pragma unroll
;                         for (int e = 0; e < 8; e += 2) { const f32x2 g2 = silu_pk((f32x2){v[e], v[e + 1]}); v[e] = g2.x; v[e + 1] = g2.y; }
;                         st_bf16((bf16*)(ws + WS_ZB) + (size_t)r * 2048 + (pn - 36) * 256 + cl, v);
;                     } else if (pn < 48) {
;                         st_bf16((bf16*)(ws + WS_QC) + (size_t)r * 1024 + (pn - 44) * 256 + cl, v);
;                     } else if (pn < 50) {
;                         const bool isv = pn == 49;
;                         st_bf16((bf16*)(ws + (isv ? WS_VC : WS_KC)) + (size_t)r * 256 + cl, v);
;                         if (r < PT) st_f32(out + (isv ? O_PV : O_PK) + ((size_t)l * PT + r) * 256 + cl, v);
;                         else st_f32(out + (isv ? O_SV : O_SK) + ((size_t)l * ST + (r - PT)) * 256 + cl, v);
;                     } else if (pn < 54) {
; #pragma unroll
;                         for (int e = 0; e < 8; e += 2) { const f32x2 g2 = silu_pk((f32x2){v[e], v[e + 1]}); v[e] = g2.x; v[e + 1] = g2.y; }
;                         st_bf16((bf16*)(ws + WS_ZC) + (size_t)r * 1024 + (pn - 50) * 256 + cl, v);
.LBB0_1877:
	s_andn2_b64 vcc, exec, s[4:5]
	s_cbranch_vccnz .LBB0_1879
	v_mul_f32_e64 v156, v108, s50
	v_mul_f32_e64 v157, v109, s50
	v_mul_f32_e64 v158, v110, s50
	v_mul_f32_e64 v159, v111, s50
	v_exp_f32_e32 v156, v156
	v_exp_f32_e32 v157, v157
	v_exp_f32_e32 v158, v158
	v_exp_f32_e32 v159, v159
	v_mul_f32_e64 v160, v104, s50
	v_mul_f32_e64 v161, v105, s50
	v_mul_f32_e64 v162, v106, s50
	v_mul_f32_e64 v163, v107, s50
	v_exp_f32_e32 v160, v160
	v_exp_f32_e32 v161, v161
	v_exp_f32_e32 v162, v162
	v_exp_f32_e32 v163, v163
	v_add_f32_e64 v156, v156, 1.0
	v_add_f32_e64 v157, v157, 1.0
	v_add_f32_e64 v158, v158, 1.0
	v_add_f32_e64 v159, v159, 1.0
	v_rcp_f32_e32 v156, v156
	v_rcp_f32_e32 v157, v157
	v_rcp_f32_e32 v158, v158
	v_rcp_f32_e32 v159, v159
	v_add_f32_e64 v160, v160, 1.0
	v_add_f32_e64 v161, v161, 1.0
	v_add_f32_e64 v162, v162, 1.0
	v_add_f32_e64 v163, v163, 1.0
	v_rcp_f32_e32 v160, v160
	v_rcp_f32_e32 v161, v161
	v_rcp_f32_e32 v162, v162
	v_rcp_f32_e32 v163, v163
	v_lshlrev_b32_e32 v136, 1, v140
	v_mul_f32_e64 v156, v108, v156
	v_mul_f32_e64 v157, v109, v157
	v_mul_f32_e64 v158, v110, v158
	v_mul_f32_e64 v159, v111, v159
	v_lshl_add_u64 v[164:165], v[124:125], 0, v[136:137]
	v_mul_f32_e64 v160, v104, v160
	v_mul_f32_e64 v161, v105, v161
	v_mul_f32_e64 v162, v106, v162
	v_mul_f32_e64 v163, v107, v163
	v_cvt_pk_bf16_f32 v156, v156, v157
	v_cvt_pk_bf16_f32 v157, v158, v159
	v_cvt_pk_bf16_f32 v158, v160, v161
	s_nop 0
	v_cvt_pk_bf16_f32 v159, v162, v163
	global_store_dwordx4 v[164:165], v[156:159], off

; __device__ __forceinline__ f32x2 silu_pk(f32x2 x) { const f32x2 t = x * -1.4426950408889634f; f32x2 e; e.x = __builtin_amdgcn_exp2f(t.x); e.y = __builtin_amdgcn_exp2f(t.y); e = e + 1.0f; f32x2 r; r.x = __builtin_amdgcn_rcpf(e.x); r.y = __builtin_amdgcn_rcpf(e.y); return x * r; }
;     __device__ __forceinline__ void operator()(const pg8::f32x4 (&acc)[2][2][4][2], const pg8::Unit& u, int wr, int wc, int fr, int fq) const {
;     ...
;                     } else if (pn < 44) {
; #pragma unroll
;                         for (int e = 0; e < 8; e += 2) { const f32x2 g2 = silu_pk((f32x2){v[e], v[e + 1]}); v[e] = g2.x; v[e + 1] = g2.y; }
;                         st_bf16((bf16*)(ws + WS_ZB) + (size_t)r * 2048 + (pn - 36) * 256 + cl, v);
;                     } else if (pn < 48) {
;                         st_bf16((bf16*)(ws + WS_QC) + (size_t)r * 1024 + (pn - 44) * 256 + cl, v);
;                     } else if (pn < 50) {
;                         const bool isv = pn == 49;
;                         st_bf16((bf16*)(ws + (isv ? WS_VC : WS_KC)) + (size_t)r * 256 + cl, v);
;                         if (r < PT) st_f32(out + (isv ? O_PV : O_PK) + ((size_t)l * PT + r) * 256 + cl, v);
;                         else st_f32(out + (isv ? O_SV : O_SK) + ((size_t)l * ST + (r - PT)) * 256 + cl, v);
;                     } else if (pn < 54) {
; #pragma unroll
;                         for (int e = 0; e < 8; e += 2) { const f32x2 g2 = silu_pk((f32x2){v[e], v[e + 1]}); v[e] = g2.x; v[e + 1] = g2.y; }
;                         st_bf16((bf16*)(ws + WS_ZC) + (size_t)r * 1024 + (pn - 50) * 256 + cl, v);
.LBB0_1890:
	s_andn2_b64 vcc, exec, s[4:5]
	s_cbranch_vccnz .LBB0_1892
	v_mul_f32_e64 v156, v108, s50
	v_mul_f32_e64 v157, v109, s50
	v_mul_f32_e64 v158, v110, s50
	v_mul_f32_e64 v159, v111, s50
	v_exp_f32_e32 v156, v156
	v_exp_f32_e32 v157, v157
	v_exp_f32_e32 v158, v158
	v_exp_f32_e32 v159, v159
	v_mul_f32_e64 v160, v104, s50
	v_mul_f32_e64 v161, v105, s50
	v_mul_f32_e64 v162, v106, s50
	v_mul_f32_e64 v163, v107, s50
	v_exp_f32_e32 v160, v160
	v_exp_f32_e32 v161, v161
	v_exp_f32_e32 v162, v162
	v_exp_f32_e32 v163, v163
	v_add_f32_e64 v156, v156, 1.0
	v_add_f32_e64 v157, v157, 1.0
	v_add_f32_e64 v158, v158, 1.0
	v_add_f32_e64 v159, v159, 1.0
	v_rcp_f32_e32 v156, v156
	v_rcp_f32_e32 v157, v157
	v_rcp_f32_e32 v158, v158
	v_rcp_f32_e32 v159, v159
	v_add_f32_e64 v160, v160, 1.0
	v_add_f32_e64 v161, v161, 1.0
	v_add_f32_e64 v162, v162, 1.0
	v_add_f32_e64 v163, v163, 1.0
	v_rcp_f32_e32 v160, v160
	v_rcp_f32_e32 v161, v161
	v_rcp_f32_e32 v162, v162
	v_rcp_f32_e32 v163, v163
	v_lshlrev_b32_e32 v136, 1, v140
	v_mul_f32_e64 v156, v108, v156
	v_mul_f32_e64 v157, v109, v157
	v_mul_f32_e64 v158, v110, v158
	v_mul_f32_e64 v159, v111, v159
	v_lshl_add_u64 v[164:165], v[114:115], 0, v[136:137]
	v_mul_f32_e64 v160, v104, v160
	v_mul_f32_e64 v161, v105, v161
	v_mul_f32_e64 v162, v106, v162
	v_mul_f32_e64 v163, v107, v163
	v_cvt_pk_bf16_f32 v156, v156, v157
	v_cvt_pk_bf16_f32 v157, v158, v159
	v_cvt_pk_bf16_f32 v158, v160, v161
	s_nop 0
	v_cvt_pk_bf16_f32 v159, v162, v163
	global_store_dwordx4 v[164:165], v[156:159], off

; __device__ __forceinline__ f32x2 silu_pk(f32x2 x) { const f32x2 t = x * -1.4426950408889634f; f32x2 e; e.x = __builtin_amdgcn_exp2f(t.x); e.y = __builtin_amdgcn_exp2f(t.y); e = e + 1.0f; f32x2 r; r.x = __builtin_amdgcn_rcpf(e.x); r.y = __builtin_amdgcn_rcpf(e.y); return x * r; }
;     __device__ __forceinline__ void operator()(const pg8::f32x4 (&acc)[2][2][4][2], const pg8::Unit& u, int wr, int wc, int fr, int fq) const {
;     ...
;                     } else if (pn < 44) {
; #pragma unroll
;                         for (int e = 0; e < 8; e += 2) { const f32x2 g2 = silu_pk((f32x2){v[e], v[e + 1]}); v[e] = g2.x; v[e + 1] = g2.y; }
;                         st_bf16((bf16*)(ws + WS_ZB) + (size_t)r * 2048 + (pn - 36) * 256 + cl, v);
;                     } else if (pn < 48) {
;                         st_bf16((bf16*)(ws + WS_QC) + (size_t)r * 1024 + (pn - 44) * 256 + cl, v);
;                     } else if (pn < 50) {
;                         const bool isv = pn == 49;
;                         st_bf16((bf16*)(ws + (isv ? WS_VC : WS_KC)) + (size_t)r * 256 + cl, v);
;                         if (r < PT) st_f32(out + (isv ? O_PV : O_PK) + ((size_t)l * PT + r) * 256 + cl, v);
;                         else st_f32(out + (isv ? O_SV : O_SK) + ((size_t)l * ST + (r - PT)) * 256 + cl, v);
;                     } else if (pn < 54) {
; #pragma unroll
;                         for (int e = 0; e < 8; e += 2) { const f32x2 g2 = silu_pk((f32x2){v[e], v[e + 1]}); v[e] = g2.x; v[e + 1] = g2.y; }
;                         st_bf16((bf16*)(ws + WS_ZC) + (size_t)r * 1024 + (pn - 50) * 256 + cl, v);
.LBB0_1907:
	s_andn2_b64 vcc, exec, s[4:5]
	s_cbranch_vccnz .LBB0_1909
	v_mul_f32_e64 v104, v100, s50
	v_mul_f32_e64 v105, v101, s50
	v_mul_f32_e64 v106, v102, s50
	v_mul_f32_e64 v107, v103, s50
	v_exp_f32_e32 v104, v104
	v_exp_f32_e32 v105, v105
	v_exp_f32_e32 v106, v106
	v_exp_f32_e32 v107, v107
	v_mul_f32_e64 v108, v96, s50
	v_mul_f32_e64 v109, v97, s50
	v_mul_f32_e64 v110, v98, s50
	v_mul_f32_e64 v111, v99, s50
	v_exp_f32_e32 v108, v108
	v_exp_f32_e32 v109, v109
	v_exp_f32_e32 v110, v110
	v_exp_f32_e32 v111, v111
	v_add_f32_e64 v104, v104, 1.0
	v_add_f32_e64 v105, v105, 1.0
	v_add_f32_e64 v106, v106, 1.0
	v_add_f32_e64 v107, v107, 1.0
	v_rcp_f32_e32 v104, v104
	v_rcp_f32_e32 v105, v105
	v_rcp_f32_e32 v106, v106
	v_rcp_f32_e32 v107, v107
	v_add_f32_e64 v108, v108, 1.0
	v_add_f32_e64 v109, v109, 1.0
	v_add_f32_e64 v110, v110, 1.0
	v_add_f32_e64 v111, v111, 1.0
	v_rcp_f32_e32 v108, v108
	v_rcp_f32_e32 v109, v109
	v_rcp_f32_e32 v110, v110
	v_rcp_f32_e32 v111, v111
	v_lshlrev_b32_e32 v136, 1, v142
	v_mul_f32_e64 v104, v100, v104
	v_mul_f32_e64 v105, v101, v105
	v_mul_f32_e64 v106, v102, v106
	v_mul_f32_e64 v107, v103, v107
	v_lshl_add_u64 v[124:125], v[124:125], 0, v[136:137]
	v_mul_f32_e64 v108, v96, v108
	v_mul_f32_e64 v109, v97, v109
	v_mul_f32_e64 v110, v98, v110
	v_mul_f32_e64 v111, v99, v111
	v_cvt_pk_bf16_f32 v104, v104, v105
	v_cvt_pk_bf16_f32 v105, v106, v107
	v_cvt_pk_bf16_f32 v106, v108, v109
	s_nop 0
	v_cvt_pk_bf16_f32 v107, v110, v111
	global_store_dwordx4 v[124:125], v[104:107], off

; __device__ __forceinline__ f32x2 silu_pk(f32x2 x) { const f32x2 t = x * -1.4426950408889634f; f32x2 e; e.x = __builtin_amdgcn_exp2f(t.x); e.y = __builtin_amdgcn_exp2f(t.y); e = e + 1.0f; f32x2 r; r.x = __builtin_amdgcn_rcpf(e.x); r.y = __builtin_amdgcn_rcpf(e.y); return x * r; }
;     __device__ __forceinline__ void operator()(const pg8::f32x4 (&acc)[2][2][4][2], const pg8::Unit& u, int wr, int wc, int fr, int fq) const {
;     ...
;                     } else if (pn < 44) {
; #pragma unroll
;                         for (int e = 0; e < 8; e += 2) { const f32x2 g2 = silu_pk((f32x2){v[e], v[e + 1]}); v[e] = g2.x; v[e + 1] = g2.y; }
;                         st_bf16((bf16*)(ws + WS_ZB) + (size_t)r * 2048 + (pn - 36) * 256 + cl, v);
;                     } else if (pn < 48) {
;                         st_bf16((bf16*)(ws + WS_QC) + (size_t)r * 1024 + (pn - 44) * 256 + cl, v);
;                     } else if (pn < 50) {
;                         const bool isv = pn == 49;
;                         st_bf16((bf16*)(ws + (isv ? WS_VC : WS_KC)) + (size_t)r * 256 + cl, v);
;                         if (r < PT) st_f32(out + (isv ? O_PV : O_PK) + ((size_t)l * PT + r) * 256 + cl, v);
;                         else st_f32(out + (isv ? O_SV : O_SK) + ((size_t)l * ST + (r - PT)) * 256 + cl, v);
;                     } else if (pn < 54) {
; #pragma unroll
;                         for (int e = 0; e < 8; e += 2) { const f32x2 g2 = silu_pk((f32x2){v[e], v[e + 1]}); v[e] = g2.x; v[e + 1] = g2.y; }
;                         st_bf16((bf16*)(ws + WS_ZC) + (size_t)r * 1024 + (pn - 50) * 256 + cl, v);
.LBB0_1920:
	s_andn2_b64 vcc, exec, s[4:5]
	s_cbranch_vccnz .LBB0_1922
	v_mul_f32_e64 v104, v100, s50
	v_mul_f32_e64 v105, v101, s50
	v_mul_f32_e64 v106, v102, s50
	v_mul_f32_e64 v107, v103, s50
	v_exp_f32_e32 v104, v104
	v_exp_f32_e32 v105, v105
	v_exp_f32_e32 v106, v106
	v_exp_f32_e32 v107, v107
	v_mul_f32_e64 v108, v96, s50
	v_mul_f32_e64 v109, v97, s50
	v_mul_f32_e64 v110, v98, s50
	v_mul_f32_e64 v111, v99, s50
	v_exp_f32_e32 v108, v108
	v_exp_f32_e32 v109, v109
	v_exp_f32_e32 v110, v110
	v_exp_f32_e32 v111, v111
	v_add_f32_e64 v104, v104, 1.0
	v_add_f32_e64 v105, v105, 1.0
	v_add_f32_e64 v106, v106, 1.0
	v_add_f32_e64 v107, v107, 1.0
	v_rcp_f32_e32 v104, v104
	v_rcp_f32_e32 v105, v105
	v_rcp_f32_e32 v106, v106
	v_rcp_f32_e32 v107, v107
	v_add_f32_e64 v108, v108, 1.0
	v_add_f32_e64 v109, v109, 1.0
	v_add_f32_e64 v110, v110, 1.0
	v_add_f32_e64 v111, v111, 1.0
	v_rcp_f32_e32 v108, v108
	v_rcp_f32_e32 v109, v109
	v_rcp_f32_e32 v110, v110
	v_rcp_f32_e32 v111, v111
	v_lshlrev_b32_e32 v136, 1, v142
	v_mul_f32_e64 v104, v100, v104
	v_mul_f32_e64 v105, v101, v105
	v_mul_f32_e64 v106, v102, v106
	v_mul_f32_e64 v107, v103, v107
	v_lshl_add_u64 v[114:115], v[114:115], 0, v[136:137]
	v_mul_f32_e64 v108, v96, v108
	v_mul_f32_e64 v109, v97, v109
	v_mul_f32_e64 v110, v98, v110
	v_mul_f32_e64 v111, v99, v111
	v_cvt_pk_bf16_f32 v104, v104, v105
	v_cvt_pk_bf16_f32 v105, v106, v107
	v_cvt_pk_bf16_f32 v106, v108, v109
	s_nop 0
	v_cvt_pk_bf16_f32 v107, v110, v111
	global_store_dwordx4 v[114:115], v[104:107], off

; __device__ __forceinline__ f32x2 silu_pk(f32x2 x) { const f32x2 t = x * -1.4426950408889634f; f32x2 e; e.x = __builtin_amdgcn_exp2f(t.x); e.y = __builtin_amdgcn_exp2f(t.y); e = e + 1.0f; f32x2 r; r.x = __builtin_amdgcn_rcpf(e.x); r.y = __builtin_amdgcn_rcpf(e.y); return x * r; }
; __device__ __forceinline__ f32x2 gelu_pk(f32x2 x) { const f32x2 x2 = x * x; const f32x2 t = (x2 * 0.044715f + 1.0f) * (x * -2.302208198144325f); f32x2 e; e.x = __builtin_amdgcn_exp2f(t.x); e.y = __builtin_amdgcn_exp2f(t.y); e = e + 1.0f; f32x2 r; r.x = __builtin_amdgcn_rcpf(e.x); r.y = __builtin_amd ...
;     __device__ __forceinline__ void operator()(const pg8::f32x4 (&acc)[2][2][4][2], const pg8::Unit& u, int wr, int wc, int fr, int fq) const {
;     ...
;                     if (pn < 12) {
;                         const int seg = pn >> 2, cc = (pn & 3) * 256 + cl;
;                         if (seg < 2) {
; #pragma unroll
;                             for (int e = 0; e < 8; e += 2) { const f32x2 g2 = gelu_pk((f32x2){v[e], v[e + 1]}); v[e] = g2.x; v[e + 1] = g2.y; }
;                         } else {
; #pragma unroll
;                             for (int e = 0; e < 8; e += 2) { const f32x2 g2 = silu_pk((f32x2){v[e], v[e + 1]}); v[e] = g2.x; v[e + 1] = g2.y; }
;                         }
;                         bf16* base = (bf16*)(ws + (seg == 0 ? WS_UA : seg == 1 ? WS_VA : WS_ZA));
;                         st_bf16(base + (size_t)r * 1024 + cc, v);
.LBB0_1929:
	s_andn2_b64 vcc, exec, s[16:17]
	s_mov_b64 s[6:7], -1
	s_cbranch_vccnz .LBB0_1931
	v_mul_f32_e64 v158, v110, s50
	v_mul_f32_e64 v159, v111, s50
	v_mul_f32_e64 v156, v108, s50
	v_mul_f32_e64 v157, v109, s50
	v_exp_f32_e32 v158, v158
	v_exp_f32_e32 v159, v159
	v_mul_f32_e64 v160, v104, s50
	v_mul_f32_e64 v161, v105, s50
	v_exp_f32_e32 v156, v156
	v_exp_f32_e32 v157, v157
	v_exp_f32_e32 v160, v160
	v_exp_f32_e32 v161, v161
	v_add_f32_e64 v158, v158, 1.0
	v_add_f32_e64 v159, v159, 1.0
	v_add_f32_e64 v156, v156, 1.0
	v_add_f32_e64 v157, v157, 1.0
	v_rcp_f32_e32 v162, v158
	v_rcp_f32_e32 v163, v159
	v_add_f32_e64 v158, v160, 1.0
	v_add_f32_e64 v159, v161, 1.0
	v_rcp_f32_e32 v156, v156
	v_rcp_f32_e32 v157, v157
	v_rcp_f32_e32 v160, v158
	v_rcp_f32_e32 v161, v159
	s_mov_b64 s[6:7], 0
	v_mul_f32_e64 v158, v108, v156
	v_mul_f32_e64 v159, v109, v157
	v_mul_f32_e64 v156, v110, v162
	v_mul_f32_e64 v157, v111, v163
	v_mul_f32_e64 v160, v104, v160
	v_mul_f32_e64 v161, v105, v161
	v_mul_f32_e64 v162, v106, s50
	v_mul_f32_e64 v163, v107, s50
.LBB0_1931:
	s_andn2_b64 vcc, exec, s[6:7]
	s_cbranch_vccnz .LBB0_1933
	v_mul_f32_e64 v158, v108, v108
	v_mul_f32_e64 v159, v109, v109
	v_mul_f32_e64 v160, v108, s58
	v_mul_f32_e64 v161, v109, s58
	v_fma_f32 v158, v158, s56, 1.0
	v_fma_f32 v159, v159, s56, 1.0
	v_mul_f32_e64 v156, v110, v110
	v_mul_f32_e64 v157, v111, v111
	v_mul_f32_e64 v158, v160, v158
	v_mul_f32_e64 v159, v161, v159
	v_mul_f32_e64 v160, v104, s58
	v_mul_f32_e64 v161, v105, s58
	v_exp_f32_e32 v158, v158
	v_exp_f32_e32 v159, v159
	s_nop 0
	v_add_f32_e64 v158, v158, 1.0
	v_add_f32_e64 v159, v159, 1.0
	s_nop 0
	v_rcp_f32_e32 v158, v158
	v_rcp_f32_e32 v159, v159
	s_nop 0
	v_mul_f32_e64 v158, v108, v158
	v_mul_f32_e64 v159, v109, v159
	v_fma_f32 v108, v156, s56, 1.0
	v_fma_f32 v109, v157, s56, 1.0
	v_mul_f32_e64 v156, v110, s58
	v_mul_f32_e64 v157, v111, s58
	s_nop 0
	v_mul_f32_e64 v108, v156, v108
	v_mul_f32_e64 v109, v157, v109
	s_nop 0
	v_exp_f32_e32 v108, v108
	v_exp_f32_e32 v109, v109
	s_nop 0
	v_add_f32_e64 v108, v108, 1.0
	v_add_f32_e64 v109, v109, 1.0
	s_nop 0
	v_rcp_f32_e32 v108, v108
	v_rcp_f32_e32 v109, v109
	s_nop 0
	v_mul_f32_e64 v156, v110, v108
	v_mul_f32_e64 v157, v111, v109
	v_mul_f32_e64 v110, v104, v104
	v_mul_f32_e64 v111, v105, v105
	v_mul_f32_e64 v108, v106, v106
	v_mul_f32_e64 v109, v107, v107
	v_fma_f32 v110, v110, s56, 1.0
	v_fma_f32 v111, v111, s56, 1.0
	s_nop 0
	v_mul_f32_e64 v110, v160, v110
	v_mul_f32_e64 v111, v161, v111
	s_nop 0
	v_exp_f32_e32 v110, v110
	v_exp_f32_e32 v111, v111
	s_nop 0
	v_add_f32_e64 v110, v110, 1.0
	v_add_f32_e64 v111, v111, 1.0
	s_nop 0
	v_rcp_f32_e32 v110, v110
	v_rcp_f32_e32 v111, v111
	s_nop 0
	v_mul_f32_e64 v160, v104, v110
	v_mul_f32_e64 v161, v105, v111
	v_fma_f32 v104, v108, s56, 1.0
	v_fma_f32 v105, v109, s56, 1.0
	v_mul_f32_e64 v108, v106, s58
	v_mul_f32_e64 v109, v107, s58
	s_nop 0
	v_mul_f32_e64 v162, v108, v104
	v_mul_f32_e64 v163, v109, v105
.LBB0_1933:
	s_nop 0
	v_exp_f32_e32 v104, v162
	v_exp_f32_e32 v105, v163
	v_or_b32_e32 v110, s24, v140
	v_lshlrev_b32_e32 v136, 1, v110
	v_lshl_add_u64 v[110:111], v[126:127], 0, v[136:137]
	v_add_f32_e64 v104, v104, 1.0
	v_add_f32_e64 v105, v105, 1.0
	s_nop 0
	v_rcp_f32_e32 v104, v104
	v_rcp_f32_e32 v105, v105
	s_nop 0
	v_mul_f32_e64 v108, v106, v104
	v_mul_f32_e64 v109, v107, v105
	v_cvt_pk_bf16_f32 v104, v158, v159
	v_cvt_pk_bf16_f32 v105, v156, v157
	v_cvt_pk_bf16_f32 v106, v160, v161
	s_nop 0
	v_cvt_pk_bf16_f32 v107, v108, v109
	global_store_dwordx4 v[110:111], v[104:107], off
	s_and_b64 vcc, exec, s[10:11]
	s_mov_b64 s[4:5], -1
	s_cbranch_vccz .LBB0_1899

; __device__ __forceinline__ f32x2 silu_pk(f32x2 x) { const f32x2 t = x * -1.4426950408889634f; f32x2 e; e.x = __builtin_amdgcn_exp2f(t.x); e.y = __builtin_amdgcn_exp2f(t.y); e = e + 1.0f; f32x2 r; r.x = __builtin_amdgcn_rcpf(e.x); r.y = __builtin_amdgcn_rcpf(e.y); return x * r; }
; __device__ __forceinline__ f32x2 gelu_pk(f32x2 x) { const f32x2 x2 = x * x; const f32x2 t = (x2 * 0.044715f + 1.0f) * (x * -2.302208198144325f); f32x2 e; e.x = __builtin_amdgcn_exp2f(t.x); e.y = __builtin_amdgcn_exp2f(t.y); e = e + 1.0f; f32x2 r; r.x = __builtin_amdgcn_rcpf(e.x); r.y = __builtin_amd ...
;     __device__ __forceinline__ void operator()(const pg8::f32x4 (&acc)[2][2][4][2], const pg8::Unit& u, int wr, int wc, int fr, int fq) const {
;     ...
;                     if (pn < 12) {
;                         const int seg = pn >> 2, cc = (pn & 3) * 256 + cl;
;                         if (seg < 2) {
; #pragma unroll
;                             for (int e = 0; e < 8; e += 2) { const f32x2 g2 = gelu_pk((f32x2){v[e], v[e + 1]}); v[e] = g2.x; v[e + 1] = g2.y; }
;                         } else {
; #pragma unroll
;                             for (int e = 0; e < 8; e += 2) { const f32x2 g2 = silu_pk((f32x2){v[e], v[e + 1]}); v[e] = g2.x; v[e + 1] = g2.y; }
;                         }
;                         bf16* base = (bf16*)(ws + (seg == 0 ? WS_UA : seg == 1 ? WS_VA : WS_ZA));
;                         st_bf16(base + (size_t)r * 1024 + cc, v);
.LBB0_1935:
	s_andn2_b64 vcc, exec, s[16:17]
	s_mov_b64 s[0:1], -1
	s_cbranch_vccnz .LBB0_1937
	v_mul_f32_e64 v104, v100, s50
	v_mul_f32_e64 v105, v101, s50
	v_mul_f32_e64 v106, v102, s50
	v_mul_f32_e64 v107, v103, s50
	v_mul_f32_e64 v108, v96, s50
	v_mul_f32_e64 v109, v97, s50
	v_exp_f32_e32 v104, v104
	v_exp_f32_e32 v105, v105
	v_exp_f32_e32 v106, v106
	v_exp_f32_e32 v107, v107
	v_exp_f32_e32 v108, v108
	v_exp_f32_e32 v109, v109
	v_add_f32_e64 v104, v104, 1.0
	v_add_f32_e64 v105, v105, 1.0
	v_add_f32_e64 v106, v106, 1.0
	v_add_f32_e64 v107, v107, 1.0
	v_rcp_f32_e32 v104, v104
	v_add_f32_e64 v108, v108, 1.0
	v_add_f32_e64 v109, v109, 1.0
	v_rcp_f32_e32 v105, v105
	v_rcp_f32_e32 v106, v106
	v_rcp_f32_e32 v107, v107
	v_rcp_f32_e32 v108, v108
	v_rcp_f32_e32 v109, v109
	v_mul_f32_e64 v104, v100, v104
	v_mul_f32_e64 v105, v101, v105
	v_mul_f32_e64 v106, v102, v106
	v_mul_f32_e64 v107, v103, v107
	v_mul_f32_e64 v110, v98, s50
	v_mul_f32_e64 v111, v99, s50
	v_mul_f32_e64 v108, v96, v108
	v_mul_f32_e64 v109, v97, v109
	s_mov_b64 s[0:1], 0
.LBB0_1937:
	s_andn2_b64 vcc, exec, s[0:1]
	s_cbranch_vccnz .LBB0_1939
	v_mul_f32_e64 v104, v100, v100
	v_mul_f32_e64 v105, v101, v101
	v_mul_f32_e64 v108, v100, s58
	v_mul_f32_e64 v109, v101, s58
	v_fma_f32 v104, v104, s56, 1.0
	v_fma_f32 v105, v105, s56, 1.0
	v_mul_f32_e64 v106, v102, v102
	v_mul_f32_e64 v107, v103, v103
	v_mul_f32_e64 v104, v108, v104
	v_mul_f32_e64 v105, v109, v105
	v_mul_f32_e64 v108, v96, s58
	v_mul_f32_e64 v109, v97, s58
	v_exp_f32_e32 v104, v104
	v_exp_f32_e32 v105, v105
	s_nop 0
	v_add_f32_e64 v104, v104, 1.0
	v_add_f32_e64 v105, v105, 1.0
	s_nop 0
	v_rcp_f32_e32 v104, v104
	v_rcp_f32_e32 v105, v105
	s_nop 0
	v_mul_f32_e64 v104, v100, v104
	v_mul_f32_e64 v105, v101, v105
	v_fma_f32 v100, v106, s56, 1.0
	v_fma_f32 v101, v107, s56, 1.0
	v_mul_f32_e64 v106, v102, s58
	v_mul_f32_e64 v107, v103, s58
	s_nop 0
	v_mul_f32_e64 v100, v106, v100
	v_mul_f32_e64 v101, v107, v101
	s_nop 0
	v_exp_f32_e32 v100, v100
	v_exp_f32_e32 v101, v101
	s_nop 0
	v_add_f32_e64 v100, v100, 1.0
	v_add_f32_e64 v101, v101, 1.0
	s_nop 0
	v_rcp_f32_e32 v100, v100
	v_rcp_f32_e32 v101, v101
	s_nop 0
	v_mul_f32_e64 v106, v102, v100
	v_mul_f32_e64 v107, v103, v101
	v_mul_f32_e64 v102, v96, v96
	v_mul_f32_e64 v103, v97, v97
	v_mul_f32_e64 v100, v98, v98
	v_mul_f32_e64 v101, v99, v99
	v_fma_f32 v102, v102, s56, 1.0
	v_fma_f32 v103, v103, s56, 1.0
	s_nop 0
	v_mul_f32_e64 v102, v108, v102
	v_mul_f32_e64 v103, v109, v103
	s_nop 0
	v_exp_f32_e32 v102, v102
	v_exp_f32_e32 v103, v103
	s_nop 0
	v_add_f32_e64 v102, v102, 1.0
	v_add_f32_e64 v103, v103, 1.0
	s_nop 0
	v_rcp_f32_e32 v102, v102
	v_rcp_f32_e32 v103, v103
	s_nop 0
	v_mul_f32_e64 v108, v96, v102
	v_mul_f32_e64 v109, v97, v103
	v_fma_f32 v96, v100, s56, 1.0
	v_fma_f32 v97, v101, s56, 1.0
	v_mul_f32_e64 v100, v98, s58
	v_mul_f32_e64 v101, v99, s58
	s_nop 0
	v_mul_f32_e64 v110, v100, v96
	v_mul_f32_e64 v111, v101, v97
.LBB0_1939:
	s_nop 0
	v_exp_f32_e32 v96, v110
	v_exp_f32_e32 v97, v111
	v_add_lshl_u32 v136, s24, v140, 1
	v_lshl_add_u64 v[102:103], v[126:127], 0, v[136:137]
	v_add_f32_e64 v96, v96, 1.0
	v_add_f32_e64 v97, v97, 1.0
	s_nop 0
	v_rcp_f32_e32 v96, v96
	v_rcp_f32_e32 v97, v97
	s_nop 0
	v_mul_f32_e64 v100, v98, v96
	v_mul_f32_e64 v101, v99, v97
	v_cvt_pk_bf16_f32 v96, v104, v105
	v_cvt_pk_bf16_f32 v97, v106, v107
	v_cvt_pk_bf16_f32 v98, v108, v109
	s_nop 0
	v_cvt_pk_bf16_f32 v99, v100, v101
	global_store_dwordx4 v[102:103], v[96:99], off offset:256

; __device__ __forceinline__ f32x2 silu_pk(f32x2 x) { const f32x2 t = x * -1.4426950408889634f; f32x2 e; e.x = __builtin_amdgcn_exp2f(t.x); e.y = __builtin_amdgcn_exp2f(t.y); e = e + 1.0f; f32x2 r; r.x = __builtin_amdgcn_rcpf(e.x); r.y = __builtin_amdgcn_rcpf(e.y); return x * r; }
;     __device__ __forceinline__ void operator()(const pg8::f32x4 (&acc)[2][2][4][2], const pg8::Unit& u, int wr, int wc, int fr, int fq) const {
;     ...
;                     } else if (pn < 44) {
; #pragma unroll
;                         for (int e = 0; e < 8; e += 2) { const f32x2 g2 = silu_pk((f32x2){v[e], v[e + 1]}); v[e] = g2.x; v[e + 1] = g2.y; }
;                         st_bf16((bf16*)(ws + WS_ZB) + (size_t)r * 2048 + (pn - 36) * 256 + cl, v);
;                     } else if (pn < 48) {
;                         st_bf16((bf16*)(ws + WS_QC) + (size_t)r * 1024 + (pn - 44) * 256 + cl, v);
;                     } else if (pn < 50) {
;                         const bool isv = pn == 49;
;                         st_bf16((bf16*)(ws + (isv ? WS_VC : WS_KC)) + (size_t)r * 256 + cl, v);
;                         if (r < PT) st_f32(out + (isv ? O_PV : O_PK) + ((size_t)l * PT + r) * 256 + cl, v);
;                         else st_f32(out + (isv ? O_SV : O_SK) + ((size_t)l * ST + (r - PT)) * 256 + cl, v);
;                     } else if (pn < 54) {
; #pragma unroll
;                         for (int e = 0; e < 8; e += 2) { const f32x2 g2 = silu_pk((f32x2){v[e], v[e + 1]}); v[e] = g2.x; v[e + 1] = g2.y; }
;                         st_bf16((bf16*)(ws + WS_ZC) + (size_t)r * 1024 + (pn - 50) * 256 + cl, v);
.LBB0_1966:
	s_andn2_b64 vcc, exec, s[4:5]
	s_cbranch_vccnz .LBB0_1968
	v_mul_f32_e64 v114, v92, s50
	v_mul_f32_e64 v115, v93, s50
	v_mul_f32_e64 v116, v94, s50
	v_mul_f32_e64 v117, v95, s50
	v_exp_f32_e32 v114, v114
	v_exp_f32_e32 v115, v115
	v_exp_f32_e32 v116, v116
	v_exp_f32_e32 v117, v117
	v_mul_f32_e64 v118, v88, s50
	v_mul_f32_e64 v119, v89, s50
	v_mul_f32_e64 v120, v90, s50
	v_mul_f32_e64 v121, v91, s50
	v_exp_f32_e32 v118, v118
	v_exp_f32_e32 v119, v119
	v_exp_f32_e32 v120, v120
	v_exp_f32_e32 v121, v121
	v_add_f32_e64 v114, v114, 1.0
	v_add_f32_e64 v115, v115, 1.0
	v_add_f32_e64 v116, v116, 1.0
	v_add_f32_e64 v117, v117, 1.0
	v_rcp_f32_e32 v114, v114
	v_rcp_f32_e32 v115, v115
	v_rcp_f32_e32 v116, v116
	v_rcp_f32_e32 v117, v117
	v_add_f32_e64 v118, v118, 1.0
	v_add_f32_e64 v119, v119, 1.0
	v_add_f32_e64 v120, v120, 1.0
	v_add_f32_e64 v121, v121, 1.0
	v_rcp_f32_e32 v118, v118
	v_rcp_f32_e32 v119, v119
	v_rcp_f32_e32 v120, v120
	v_rcp_f32_e32 v121, v121
	v_lshlrev_b32_e32 v136, 1, v140
	v_mul_f32_e64 v114, v92, v114
	v_mul_f32_e64 v115, v93, v115
	v_mul_f32_e64 v116, v94, v116
	v_mul_f32_e64 v117, v95, v117
	v_lshl_add_u64 v[124:125], v[108:109], 0, v[136:137]
	v_mul_f32_e64 v118, v88, v118
	v_mul_f32_e64 v119, v89, v119
	v_mul_f32_e64 v120, v90, v120
	v_mul_f32_e64 v121, v91, v121
	v_cvt_pk_bf16_f32 v114, v114, v115
	v_cvt_pk_bf16_f32 v115, v116, v117
	v_cvt_pk_bf16_f32 v116, v118, v119
	s_nop 0
	v_cvt_pk_bf16_f32 v117, v120, v121
	global_store_dwordx4 v[124:125], v[114:117], off

; __device__ __forceinline__ f32x2 silu_pk(f32x2 x) { const f32x2 t = x * -1.4426950408889634f; f32x2 e; e.x = __builtin_amdgcn_exp2f(t.x); e.y = __builtin_amdgcn_exp2f(t.y); e = e + 1.0f; f32x2 r; r.x = __builtin_amdgcn_rcpf(e.x); r.y = __builtin_amdgcn_rcpf(e.y); return x * r; }
;     __device__ __forceinline__ void operator()(const pg8::f32x4 (&acc)[2][2][4][2], const pg8::Unit& u, int wr, int wc, int fr, int fq) const {
;     ...
;                     } else if (pn < 44) {
; #pragma unroll
;                         for (int e = 0; e < 8; e += 2) { const f32x2 g2 = silu_pk((f32x2){v[e], v[e + 1]}); v[e] = g2.x; v[e + 1] = g2.y; }
;                         st_bf16((bf16*)(ws + WS_ZB) + (size_t)r * 2048 + (pn - 36) * 256 + cl, v);
;                     } else if (pn < 48) {
;                         st_bf16((bf16*)(ws + WS_QC) + (size_t)r * 1024 + (pn - 44) * 256 + cl, v);
;                     } else if (pn < 50) {
;                         const bool isv = pn == 49;
;                         st_bf16((bf16*)(ws + (isv ? WS_VC : WS_KC)) + (size_t)r * 256 + cl, v);
;                         if (r < PT) st_f32(out + (isv ? O_PV : O_PK) + ((size_t)l * PT + r) * 256 + cl, v);
;                         else st_f32(out + (isv ? O_SV : O_SK) + ((size_t)l * ST + (r - PT)) * 256 + cl, v);
;                     } else if (pn < 54) {
; #pragma unroll
;                         for (int e = 0; e < 8; e += 2) { const f32x2 g2 = silu_pk((f32x2){v[e], v[e + 1]}); v[e] = g2.x; v[e + 1] = g2.y; }
;                         st_bf16((bf16*)(ws + WS_ZC) + (size_t)r * 1024 + (pn - 50) * 256 + cl, v);
.LBB0_1979:
	s_andn2_b64 vcc, exec, s[4:5]
	s_cbranch_vccnz .LBB0_1981
	v_mul_f32_e64 v114, v92, s50
	v_mul_f32_e64 v115, v93, s50
	v_mul_f32_e64 v116, v94, s50
	v_mul_f32_e64 v117, v95, s50
	v_exp_f32_e32 v114, v114
	v_exp_f32_e32 v115, v115
	v_exp_f32_e32 v116, v116
	v_exp_f32_e32 v117, v117
	v_mul_f32_e64 v118, v88, s50
	v_mul_f32_e64 v119, v89, s50
	v_mul_f32_e64 v120, v90, s50
	v_mul_f32_e64 v121, v91, s50
	v_exp_f32_e32 v118, v118
	v_exp_f32_e32 v119, v119
	v_exp_f32_e32 v120, v120
	v_exp_f32_e32 v121, v121
	v_add_f32_e64 v114, v114, 1.0
	v_add_f32_e64 v115, v115, 1.0
	v_add_f32_e64 v116, v116, 1.0
	v_add_f32_e64 v117, v117, 1.0
	v_rcp_f32_e32 v114, v114
	v_rcp_f32_e32 v115, v115
	v_rcp_f32_e32 v116, v116
	v_rcp_f32_e32 v117, v117
	v_add_f32_e64 v118, v118, 1.0
	v_add_f32_e64 v119, v119, 1.0
	v_add_f32_e64 v120, v120, 1.0
	v_add_f32_e64 v121, v121, 1.0
	v_rcp_f32_e32 v118, v118
	v_rcp_f32_e32 v119, v119
	v_rcp_f32_e32 v120, v120
	v_rcp_f32_e32 v121, v121
	v_lshlrev_b32_e32 v136, 1, v140
	v_mul_f32_e64 v114, v92, v114
	v_mul_f32_e64 v115, v93, v115
	v_mul_f32_e64 v116, v94, v116
	v_mul_f32_e64 v117, v95, v117
	v_lshl_add_u64 v[124:125], v[98:99], 0, v[136:137]
	v_mul_f32_e64 v118, v88, v118
	v_mul_f32_e64 v119, v89, v119
	v_mul_f32_e64 v120, v90, v120
	v_mul_f32_e64 v121, v91, v121
	v_cvt_pk_bf16_f32 v114, v114, v115
	v_cvt_pk_bf16_f32 v115, v116, v117
	v_cvt_pk_bf16_f32 v116, v118, v119
	s_nop 0
	v_cvt_pk_bf16_f32 v117, v120, v121
	global_store_dwordx4 v[124:125], v[114:117], off

; __device__ __forceinline__ f32x2 silu_pk(f32x2 x) { const f32x2 t = x * -1.4426950408889634f; f32x2 e; e.x = __builtin_amdgcn_exp2f(t.x); e.y = __builtin_amdgcn_exp2f(t.y); e = e + 1.0f; f32x2 r; r.x = __builtin_amdgcn_rcpf(e.x); r.y = __builtin_amdgcn_rcpf(e.y); return x * r; }
;     __device__ __forceinline__ void operator()(const pg8::f32x4 (&acc)[2][2][4][2], const pg8::Unit& u, int wr, int wc, int fr, int fq) const {
;     ...
;                     } else if (pn < 44) {
; #pragma unroll
;                         for (int e = 0; e < 8; e += 2) { const f32x2 g2 = silu_pk((f32x2){v[e], v[e + 1]}); v[e] = g2.x; v[e + 1] = g2.y; }
;                         st_bf16((bf16*)(ws + WS_ZB) + (size_t)r * 2048 + (pn - 36) * 256 + cl, v);
;                     } else if (pn < 48) {
;                         st_bf16((bf16*)(ws + WS_QC) + (size_t)r * 1024 + (pn - 44) * 256 + cl, v);
;                     } else if (pn < 50) {
;                         const bool isv = pn == 49;
;                         st_bf16((bf16*)(ws + (isv ? WS_VC : WS_KC)) + (size_t)r * 256 + cl, v);
;                         if (r < PT) st_f32(out + (isv ? O_PV : O_PK) + ((size_t)l * PT + r) * 256 + cl, v);
;                         else st_f32(out + (isv ? O_SV : O_SK) + ((size_t)l * ST + (r - PT)) * 256 + cl, v);
;                     } else if (pn < 54) {
; #pragma unroll
;                         for (int e = 0; e < 8; e += 2) { const f32x2 g2 = silu_pk((f32x2){v[e], v[e + 1]}); v[e] = g2.x; v[e + 1] = g2.y; }
;                         st_bf16((bf16*)(ws + WS_ZC) + (size_t)r * 1024 + (pn - 50) * 256 + cl, v);
.LBB0_1996:
	s_andn2_b64 vcc, exec, s[4:5]
	s_cbranch_vccnz .LBB0_1998
	v_mul_f32_e64 v88, v84, s50
	v_mul_f32_e64 v89, v85, s50
	v_mul_f32_e64 v90, v86, s50
	v_mul_f32_e64 v91, v87, s50
	v_exp_f32_e32 v88, v88
	v_exp_f32_e32 v89, v89
	v_exp_f32_e32 v90, v90
	v_exp_f32_e32 v91, v91
	v_mul_f32_e64 v92, v80, s50
	v_mul_f32_e64 v93, v81, s50
	v_mul_f32_e64 v94, v82, s50
	v_mul_f32_e64 v95, v83, s50
	v_exp_f32_e32 v92, v92
	v_exp_f32_e32 v93, v93
	v_exp_f32_e32 v94, v94
	v_exp_f32_e32 v95, v95
	v_add_f32_e64 v88, v88, 1.0
	v_add_f32_e64 v89, v89, 1.0
	v_add_f32_e64 v90, v90, 1.0
	v_add_f32_e64 v91, v91, 1.0
	v_rcp_f32_e32 v88, v88
	v_rcp_f32_e32 v89, v89
	v_rcp_f32_e32 v90, v90
	v_rcp_f32_e32 v91, v91
	v_add_f32_e64 v92, v92, 1.0
	v_add_f32_e64 v93, v93, 1.0
	v_add_f32_e64 v94, v94, 1.0
	v_add_f32_e64 v95, v95, 1.0
	v_rcp_f32_e32 v92, v92
	v_rcp_f32_e32 v93, v93
	v_rcp_f32_e32 v94, v94
	v_rcp_f32_e32 v95, v95
	v_lshlrev_b32_e32 v136, 1, v142
	v_mul_f32_e64 v88, v84, v88
	v_mul_f32_e64 v89, v85, v89
	v_mul_f32_e64 v90, v86, v90
	v_mul_f32_e64 v91, v87, v91
	v_lshl_add_u64 v[108:109], v[108:109], 0, v[136:137]
	v_mul_f32_e64 v92, v80, v92
	v_mul_f32_e64 v93, v81, v93
	v_mul_f32_e64 v94, v82, v94
	v_mul_f32_e64 v95, v83, v95
	v_cvt_pk_bf16_f32 v88, v88, v89
	v_cvt_pk_bf16_f32 v89, v90, v91
	v_cvt_pk_bf16_f32 v90, v92, v93
	s_nop 0
	v_cvt_pk_bf16_f32 v91, v94, v95
	global_store_dwordx4 v[108:109], v[88:91], off

; __device__ __forceinline__ f32x2 silu_pk(f32x2 x) { const f32x2 t = x * -1.4426950408889634f; f32x2 e; e.x = __builtin_amdgcn_exp2f(t.x); e.y = __builtin_amdgcn_exp2f(t.y); e = e + 1.0f; f32x2 r; r.x = __builtin_amdgcn_rcpf(e.x); r.y = __builtin_amdgcn_rcpf(e.y); return x * r; }
;     __device__ __forceinline__ void operator()(const pg8::f32x4 (&acc)[2][2][4][2], const pg8::Unit& u, int wr, int wc, int fr, int fq) const {
;     ...
;                     } else if (pn < 44) {
; #pragma unroll
;                         for (int e = 0; e < 8; e += 2) { const f32x2 g2 = silu_pk((f32x2){v[e], v[e + 1]}); v[e] = g2.x; v[e + 1] = g2.y; }
;                         st_bf16((bf16*)(ws + WS_ZB) + (size_t)r * 2048 + (pn - 36) * 256 + cl, v);
;                     } else if (pn < 48) {
;                         st_bf16((bf16*)(ws + WS_QC) + (size_t)r * 1024 + (pn - 44) * 256 + cl, v);
;                     } else if (pn < 50) {
;                         const bool isv = pn == 49;
;                         st_bf16((bf16*)(ws + (isv ? WS_VC : WS_KC)) + (size_t)r * 256 + cl, v);
;                         if (r < PT) st_f32(out + (isv ? O_PV : O_PK) + ((size_t)l * PT + r) * 256 + cl, v);
;                         else st_f32(out + (isv ? O_SV : O_SK) + ((size_t)l * ST + (r - PT)) * 256 + cl, v);
;                     } else if (pn < 54) {
; #pragma unroll
;                         for (int e = 0; e < 8; e += 2) { const f32x2 g2 = silu_pk((f32x2){v[e], v[e + 1]}); v[e] = g2.x; v[e + 1] = g2.y; }
;                         st_bf16((bf16*)(ws + WS_ZC) + (size_t)r * 1024 + (pn - 50) * 256 + cl, v);
.LBB0_2009:
	s_andn2_b64 vcc, exec, s[4:5]
	s_cbranch_vccnz .LBB0_2011
	v_mul_f32_e64 v88, v84, s50
	v_mul_f32_e64 v89, v85, s50
	v_mul_f32_e64 v90, v86, s50
	v_mul_f32_e64 v91, v87, s50
	v_exp_f32_e32 v88, v88
	v_exp_f32_e32 v89, v89
	v_exp_f32_e32 v90, v90
	v_exp_f32_e32 v91, v91
	v_mul_f32_e64 v92, v80, s50
	v_mul_f32_e64 v93, v81, s50
	v_mul_f32_e64 v94, v82, s50
	v_mul_f32_e64 v95, v83, s50
	v_exp_f32_e32 v92, v92
	v_exp_f32_e32 v93, v93
	v_exp_f32_e32 v94, v94
	v_exp_f32_e32 v95, v95
	v_add_f32_e64 v88, v88, 1.0
	v_add_f32_e64 v89, v89, 1.0
	v_add_f32_e64 v90, v90, 1.0
	v_add_f32_e64 v91, v91, 1.0
	v_rcp_f32_e32 v88, v88
	v_rcp_f32_e32 v89, v89
	v_rcp_f32_e32 v90, v90
	v_rcp_f32_e32 v91, v91
	v_add_f32_e64 v92, v92, 1.0
	v_add_f32_e64 v93, v93, 1.0
	v_add_f32_e64 v94, v94, 1.0
	v_add_f32_e64 v95, v95, 1.0
	v_rcp_f32_e32 v92, v92
	v_rcp_f32_e32 v93, v93
	v_rcp_f32_e32 v94, v94
	v_rcp_f32_e32 v95, v95
	v_lshlrev_b32_e32 v136, 1, v142
	v_mul_f32_e64 v88, v84, v88
	v_mul_f32_e64 v89, v85, v89
	v_mul_f32_e64 v90, v86, v90
	v_mul_f32_e64 v91, v87, v91
	v_lshl_add_u64 v[98:99], v[98:99], 0, v[136:137]
	v_mul_f32_e64 v92, v80, v92
	v_mul_f32_e64 v93, v81, v93
	v_mul_f32_e64 v94, v82, v94
	v_mul_f32_e64 v95, v83, v95
	v_cvt_pk_bf16_f32 v88, v88, v89
	v_cvt_pk_bf16_f32 v89, v90, v91
	v_cvt_pk_bf16_f32 v90, v92, v93
	s_nop 0
	v_cvt_pk_bf16_f32 v91, v94, v95
	global_store_dwordx4 v[98:99], v[88:91], off

; __device__ __forceinline__ f32x2 silu_pk(f32x2 x) { const f32x2 t = x * -1.4426950408889634f; f32x2 e; e.x = __builtin_amdgcn_exp2f(t.x); e.y = __builtin_amdgcn_exp2f(t.y); e = e + 1.0f; f32x2 r; r.x = __builtin_amdgcn_rcpf(e.x); r.y = __builtin_amdgcn_rcpf(e.y); return x * r; }
; __device__ __forceinline__ f32x2 gelu_pk(f32x2 x) { const f32x2 x2 = x * x; const f32x2 t = (x2 * 0.044715f + 1.0f) * (x * -2.302208198144325f); f32x2 e; e.x = __builtin_amdgcn_exp2f(t.x); e.y = __builtin_amdgcn_exp2f(t.y); e = e + 1.0f; f32x2 r; r.x = __builtin_amdgcn_rcpf(e.x); r.y = __builtin_amd ...
;     __device__ __forceinline__ void operator()(const pg8::f32x4 (&acc)[2][2][4][2], const pg8::Unit& u, int wr, int wc, int fr, int fq) const {
;     ...
;                     if (pn < 12) {
;                         const int seg = pn >> 2, cc = (pn & 3) * 256 + cl;
;                         if (seg < 2) {
; #pragma unroll
;                             for (int e = 0; e < 8; e += 2) { const f32x2 g2 = gelu_pk((f32x2){v[e], v[e + 1]}); v[e] = g2.x; v[e + 1] = g2.y; }
;                         } else {
; #pragma unroll
;                             for (int e = 0; e < 8; e += 2) { const f32x2 g2 = silu_pk((f32x2){v[e], v[e + 1]}); v[e] = g2.x; v[e + 1] = g2.y; }
;                         }
;                         bf16* base = (bf16*)(ws + (seg == 0 ? WS_UA : seg == 1 ? WS_VA : WS_ZA));
;                         st_bf16(base + (size_t)r * 1024 + cc, v);
.LBB0_2018:
	s_andn2_b64 vcc, exec, s[16:17]
	s_mov_b64 s[6:7], -1
	s_cbranch_vccnz .LBB0_2020
	v_mul_f32_e64 v116, v94, s50
	v_mul_f32_e64 v117, v95, s50
	v_mul_f32_e64 v114, v92, s50
	v_mul_f32_e64 v115, v93, s50
	v_exp_f32_e32 v116, v116
	v_exp_f32_e32 v117, v117
	v_mul_f32_e64 v118, v88, s50
	v_mul_f32_e64 v119, v89, s50
	v_exp_f32_e32 v114, v114
	v_exp_f32_e32 v115, v115
	v_exp_f32_e32 v118, v118
	v_exp_f32_e32 v119, v119
	v_add_f32_e64 v116, v116, 1.0
	v_add_f32_e64 v117, v117, 1.0
	v_add_f32_e64 v114, v114, 1.0
	v_add_f32_e64 v115, v115, 1.0
	v_rcp_f32_e32 v120, v116
	v_rcp_f32_e32 v121, v117
	v_add_f32_e64 v116, v118, 1.0
	v_add_f32_e64 v117, v119, 1.0
	v_rcp_f32_e32 v114, v114
	v_rcp_f32_e32 v115, v115
	v_rcp_f32_e32 v118, v116
	v_rcp_f32_e32 v119, v117
	s_mov_b64 s[6:7], 0
	v_mul_f32_e64 v116, v92, v114
	v_mul_f32_e64 v117, v93, v115
	v_mul_f32_e64 v114, v94, v120
	v_mul_f32_e64 v115, v95, v121
	v_mul_f32_e64 v118, v88, v118
	v_mul_f32_e64 v119, v89, v119
	v_mul_f32_e64 v120, v90, s50
	v_mul_f32_e64 v121, v91, s50
.LBB0_2020:
	s_andn2_b64 vcc, exec, s[6:7]
	s_cbranch_vccnz .LBB0_2022
	v_mul_f32_e64 v116, v92, v92
	v_mul_f32_e64 v117, v93, v93
	v_mul_f32_e64 v118, v92, s58
	v_mul_f32_e64 v119, v93, s58
	v_fma_f32 v116, v116, s56, 1.0
	v_fma_f32 v117, v117, s56, 1.0
	v_mul_f32_e64 v114, v94, v94
	v_mul_f32_e64 v115, v95, v95
	v_mul_f32_e64 v116, v118, v116
	v_mul_f32_e64 v117, v119, v117
	v_mul_f32_e64 v118, v88, s58
	v_mul_f32_e64 v119, v89, s58
	v_exp_f32_e32 v116, v116
	v_exp_f32_e32 v117, v117
	s_nop 0
	v_add_f32_e64 v116, v116, 1.0
	v_add_f32_e64 v117, v117, 1.0
	s_nop 0
	v_rcp_f32_e32 v116, v116
	v_rcp_f32_e32 v117, v117
	s_nop 0
	v_mul_f32_e64 v116, v92, v116
	v_mul_f32_e64 v117, v93, v117
	v_fma_f32 v92, v114, s56, 1.0
	v_fma_f32 v93, v115, s56, 1.0
	v_mul_f32_e64 v114, v94, s58
	v_mul_f32_e64 v115, v95, s58
	s_nop 0
	v_mul_f32_e64 v92, v114, v92
	v_mul_f32_e64 v93, v115, v93
	s_nop 0
	v_exp_f32_e32 v92, v92
	v_exp_f32_e32 v93, v93
	s_nop 0
	v_add_f32_e64 v92, v92, 1.0
	v_add_f32_e64 v93, v93, 1.0
	s_nop 0
	v_rcp_f32_e32 v92, v92
	v_rcp_f32_e32 v93, v93
	s_nop 0
	v_mul_f32_e64 v114, v94, v92
	v_mul_f32_e64 v115, v95, v93
	v_mul_f32_e64 v94, v88, v88
	v_mul_f32_e64 v95, v89, v89
	v_mul_f32_e64 v92, v90, v90
	v_mul_f32_e64 v93, v91, v91
	v_fma_f32 v94, v94, s56, 1.0
	v_fma_f32 v95, v95, s56, 1.0
	s_nop 0
	v_mul_f32_e64 v94, v118, v94
	v_mul_f32_e64 v95, v119, v95
	s_nop 0
	v_exp_f32_e32 v94, v94
	v_exp_f32_e32 v95, v95
	s_nop 0
	v_add_f32_e64 v94, v94, 1.0
	v_add_f32_e64 v95, v95, 1.0
	s_nop 0
	v_rcp_f32_e32 v94, v94
	v_rcp_f32_e32 v95, v95
	s_nop 0
	v_mul_f32_e64 v118, v88, v94
	v_mul_f32_e64 v119, v89, v95
	v_fma_f32 v88, v92, s56, 1.0
	v_fma_f32 v89, v93, s56, 1.0
	v_mul_f32_e64 v92, v90, s58
	v_mul_f32_e64 v93, v91, s58
	s_nop 0
	v_mul_f32_e64 v120, v92, v88
	v_mul_f32_e64 v121, v93, v89
.LBB0_2022:
	s_nop 0
	v_exp_f32_e32 v88, v120
	v_exp_f32_e32 v89, v121
	v_or_b32_e32 v94, s24, v140
	v_lshlrev_b32_e32 v136, 1, v94
	v_lshl_add_u64 v[94:95], v[110:111], 0, v[136:137]
	v_add_f32_e64 v88, v88, 1.0
	v_add_f32_e64 v89, v89, 1.0
	s_nop 0
	v_rcp_f32_e32 v88, v88
	v_rcp_f32_e32 v89, v89
	s_nop 0
	v_mul_f32_e64 v92, v90, v88
	v_mul_f32_e64 v93, v91, v89
	v_cvt_pk_bf16_f32 v88, v116, v117
	v_cvt_pk_bf16_f32 v89, v114, v115
	v_cvt_pk_bf16_f32 v90, v118, v119
	s_nop 0
	v_cvt_pk_bf16_f32 v91, v92, v93
	global_store_dwordx4 v[94:95], v[88:91], off
	s_and_b64 vcc, exec, s[10:11]
	s_mov_b64 s[4:5], -1
	s_cbranch_vccz .LBB0_1988

; __device__ __forceinline__ f32x2 silu_pk(f32x2 x) { const f32x2 t = x * -1.4426950408889634f; f32x2 e; e.x = __builtin_amdgcn_exp2f(t.x); e.y = __builtin_amdgcn_exp2f(t.y); e = e + 1.0f; f32x2 r; r.x = __builtin_amdgcn_rcpf(e.x); r.y = __builtin_amdgcn_rcpf(e.y); return x * r; }
; __device__ __forceinline__ f32x2 gelu_pk(f32x2 x) { const f32x2 x2 = x * x; const f32x2 t = (x2 * 0.044715f + 1.0f) * (x * -2.302208198144325f); f32x2 e; e.x = __builtin_amdgcn_exp2f(t.x); e.y = __builtin_amdgcn_exp2f(t.y); e = e + 1.0f; f32x2 r; r.x = __builtin_amdgcn_rcpf(e.x); r.y = __builtin_amd ...
;     __device__ __forceinline__ void operator()(const pg8::f32x4 (&acc)[2][2][4][2], const pg8::Unit& u, int wr, int wc, int fr, int fq) const {
;     ...
;                     if (pn < 12) {
;                         const int seg = pn >> 2, cc = (pn & 3) * 256 + cl;
;                         if (seg < 2) {
; #pragma unroll
;                             for (int e = 0; e < 8; e += 2) { const f32x2 g2 = gelu_pk((f32x2){v[e], v[e + 1]}); v[e] = g2.x; v[e + 1] = g2.y; }
;                         } else {
; #pragma unroll
;                             for (int e = 0; e < 8; e += 2) { const f32x2 g2 = silu_pk((f32x2){v[e], v[e + 1]}); v[e] = g2.x; v[e + 1] = g2.y; }
;                         }
;                         bf16* base = (bf16*)(ws + (seg == 0 ? WS_UA : seg == 1 ? WS_VA : WS_ZA));
;                         st_bf16(base + (size_t)r * 1024 + cc, v);
.LBB0_2024:
	s_andn2_b64 vcc, exec, s[16:17]
	s_mov_b64 s[0:1], -1
	s_cbranch_vccnz .LBB0_2026
	v_mul_f32_e64 v88, v84, s50
	v_mul_f32_e64 v89, v85, s50
	v_mul_f32_e64 v90, v86, s50
	v_mul_f32_e64 v91, v87, s50
	v_mul_f32_e64 v92, v80, s50
	v_mul_f32_e64 v93, v81, s50
	v_exp_f32_e32 v88, v88
	v_exp_f32_e32 v89, v89
	v_exp_f32_e32 v90, v90
	v_exp_f32_e32 v91, v91
	v_exp_f32_e32 v92, v92
	v_exp_f32_e32 v93, v93
	v_add_f32_e64 v88, v88, 1.0
	v_add_f32_e64 v89, v89, 1.0
	v_add_f32_e64 v90, v90, 1.0
	v_add_f32_e64 v91, v91, 1.0
	v_rcp_f32_e32 v88, v88
	v_add_f32_e64 v92, v92, 1.0
	v_add_f32_e64 v93, v93, 1.0
	v_rcp_f32_e32 v89, v89
	v_rcp_f32_e32 v90, v90
	v_rcp_f32_e32 v91, v91
	v_rcp_f32_e32 v92, v92
	v_rcp_f32_e32 v93, v93
	v_mul_f32_e64 v88, v84, v88
	v_mul_f32_e64 v89, v85, v89
	v_mul_f32_e64 v90, v86, v90
	v_mul_f32_e64 v91, v87, v91
	v_mul_f32_e64 v94, v82, s50
	v_mul_f32_e64 v95, v83, s50
	v_mul_f32_e64 v92, v80, v92
	v_mul_f32_e64 v93, v81, v93
	s_mov_b64 s[0:1], 0
.LBB0_2026:
	s_andn2_b64 vcc, exec, s[0:1]
	s_cbranch_vccnz .LBB0_2028
	v_mul_f32_e64 v88, v84, v84
	v_mul_f32_e64 v89, v85, v85
	v_mul_f32_e64 v92, v84, s58
	v_mul_f32_e64 v93, v85, s58
	v_fma_f32 v88, v88, s56, 1.0
	v_fma_f32 v89, v89, s56, 1.0
	v_mul_f32_e64 v90, v86, v86
	v_mul_f32_e64 v91, v87, v87
	v_mul_f32_e64 v88, v92, v88
	v_mul_f32_e64 v89, v93, v89
	v_mul_f32_e64 v92, v80, s58
	v_mul_f32_e64 v93, v81, s58
	v_exp_f32_e32 v88, v88
	v_exp_f32_e32 v89, v89
	s_nop 0
	v_add_f32_e64 v88, v88, 1.0
	v_add_f32_e64 v89, v89, 1.0
	s_nop 0
	v_rcp_f32_e32 v88, v88
	v_rcp_f32_e32 v89, v89
	s_nop 0
	v_mul_f32_e64 v88, v84, v88
	v_mul_f32_e64 v89, v85, v89
	v_fma_f32 v84, v90, s56, 1.0
	v_fma_f32 v85, v91, s56, 1.0
	v_mul_f32_e64 v90, v86, s58
	v_mul_f32_e64 v91, v87, s58
	s_nop 0
	v_mul_f32_e64 v84, v90, v84
	v_mul_f32_e64 v85, v91, v85
	s_nop 0
	v_exp_f32_e32 v84, v84
	v_exp_f32_e32 v85, v85
	s_nop 0
	v_add_f32_e64 v84, v84, 1.0
	v_add_f32_e64 v85, v85, 1.0
	s_nop 0
	v_rcp_f32_e32 v84, v84
	v_rcp_f32_e32 v85, v85
	s_nop 0
	v_mul_f32_e64 v90, v86, v84
	v_mul_f32_e64 v91, v87, v85
	v_mul_f32_e64 v86, v80, v80
	v_mul_f32_e64 v87, v81, v81
	v_mul_f32_e64 v84, v82, v82
	v_mul_f32_e64 v85, v83, v83
	v_fma_f32 v86, v86, s56, 1.0
	v_fma_f32 v87, v87, s56, 1.0
	s_nop 0
	v_mul_f32_e64 v86, v92, v86
	v_mul_f32_e64 v87, v93, v87
	s_nop 0
	v_exp_f32_e32 v86, v86
	v_exp_f32_e32 v87, v87
	s_nop 0
	v_add_f32_e64 v86, v86, 1.0
	v_add_f32_e64 v87, v87, 1.0
	s_nop 0
	v_rcp_f32_e32 v86, v86
	v_rcp_f32_e32 v87, v87
	s_nop 0
	v_mul_f32_e64 v92, v80, v86
	v_mul_f32_e64 v93, v81, v87
	v_fma_f32 v80, v84, s56, 1.0
	v_fma_f32 v81, v85, s56, 1.0
	v_mul_f32_e64 v84, v82, s58
	v_mul_f32_e64 v85, v83, s58
	s_nop 0
	v_mul_f32_e64 v94, v84, v80
	v_mul_f32_e64 v95, v85, v81
.LBB0_2028:
	s_nop 0
	v_exp_f32_e32 v80, v94
	v_exp_f32_e32 v81, v95
	v_add_lshl_u32 v136, s24, v140, 1
	v_lshl_add_u64 v[86:87], v[110:111], 0, v[136:137]
	v_add_f32_e64 v80, v80, 1.0
	v_add_f32_e64 v81, v81, 1.0
	s_nop 0
	v_rcp_f32_e32 v80, v80
	v_rcp_f32_e32 v81, v81
	s_nop 0
	v_mul_f32_e64 v84, v82, v80
	v_mul_f32_e64 v85, v83, v81
	v_cvt_pk_bf16_f32 v80, v88, v89
	v_cvt_pk_bf16_f32 v81, v90, v91
	v_cvt_pk_bf16_f32 v82, v92, v93
	s_nop 0
	v_cvt_pk_bf16_f32 v83, v84, v85
	global_store_dwordx4 v[86:87], v[80:83], off offset:256

; __device__ __forceinline__ f32x2 silu_pk(f32x2 x) { const f32x2 t = x * -1.4426950408889634f; f32x2 e; e.x = __builtin_amdgcn_exp2f(t.x); e.y = __builtin_amdgcn_exp2f(t.y); e = e + 1.0f; f32x2 r; r.x = __builtin_amdgcn_rcpf(e.x); r.y = __builtin_amdgcn_rcpf(e.y); return x * r; }
;     __device__ __forceinline__ void operator()(const pg8::f32x4 (&acc)[2][2][4][2], const pg8::Unit& u, int wr, int wc, int fr, int fq) const {
;     ...
;                     } else if (pn < 44) {
; #pragma unroll
;                         for (int e = 0; e < 8; e += 2) { const f32x2 g2 = silu_pk((f32x2){v[e], v[e + 1]}); v[e] = g2.x; v[e + 1] = g2.y; }
;                         st_bf16((bf16*)(ws + WS_ZB) + (size_t)r * 2048 + (pn - 36) * 256 + cl, v);
;                     } else if (pn < 48) {
;                         st_bf16((bf16*)(ws + WS_QC) + (size_t)r * 1024 + (pn - 44) * 256 + cl, v);
;                     } else if (pn < 50) {
;                         const bool isv = pn == 49;
;                         st_bf16((bf16*)(ws + (isv ? WS_VC : WS_KC)) + (size_t)r * 256 + cl, v);
;                         if (r < PT) st_f32(out + (isv ? O_PV : O_PK) + ((size_t)l * PT + r) * 256 + cl, v);
;                         else st_f32(out + (isv ? O_SV : O_SK) + ((size_t)l * ST + (r - PT)) * 256 + cl, v);
;                     } else if (pn < 54) {
; #pragma unroll
;                         for (int e = 0; e < 8; e += 2) { const f32x2 g2 = silu_pk((f32x2){v[e], v[e + 1]}); v[e] = g2.x; v[e + 1] = g2.y; }
;                         st_bf16((bf16*)(ws + WS_ZC) + (size_t)r * 1024 + (pn - 50) * 256 + cl, v);
.LBB0_2055:
	s_andn2_b64 vcc, exec, s[4:5]
	s_cbranch_vccnz .LBB0_2057
	v_mul_f32_e64 v100, v76, s50
	v_mul_f32_e64 v101, v77, s50
	v_mul_f32_e64 v102, v78, s50
	v_mul_f32_e64 v103, v79, s50
	v_exp_f32_e32 v100, v100
	v_exp_f32_e32 v101, v101
	v_exp_f32_e32 v102, v102
	v_exp_f32_e32 v103, v103
	v_mul_f32_e64 v104, v72, s50
	v_mul_f32_e64 v105, v73, s50
	v_mul_f32_e64 v106, v74, s50
	v_mul_f32_e64 v107, v75, s50
	v_exp_f32_e32 v104, v104
	v_exp_f32_e32 v105, v105
	v_exp_f32_e32 v106, v106
	v_exp_f32_e32 v107, v107
	v_add_f32_e64 v100, v100, 1.0
	v_add_f32_e64 v101, v101, 1.0
	v_add_f32_e64 v102, v102, 1.0
	v_add_f32_e64 v103, v103, 1.0
	v_rcp_f32_e32 v100, v100
	v_rcp_f32_e32 v101, v101
	v_rcp_f32_e32 v102, v102
	v_rcp_f32_e32 v103, v103
	v_add_f32_e64 v104, v104, 1.0
	v_add_f32_e64 v105, v105, 1.0
	v_add_f32_e64 v106, v106, 1.0
	v_add_f32_e64 v107, v107, 1.0
	v_rcp_f32_e32 v104, v104
	v_rcp_f32_e32 v105, v105
	v_rcp_f32_e32 v106, v106
	v_rcp_f32_e32 v107, v107
	v_lshlrev_b32_e32 v136, 1, v140
	v_mul_f32_e64 v100, v76, v100
	v_mul_f32_e64 v101, v77, v101
	v_mul_f32_e64 v102, v78, v102
	v_mul_f32_e64 v103, v79, v103
	v_lshl_add_u64 v[110:111], v[94:95], 0, v[136:137]
	v_mul_f32_e64 v104, v72, v104
	v_mul_f32_e64 v105, v73, v105
	v_mul_f32_e64 v106, v74, v106
	v_mul_f32_e64 v107, v75, v107
	v_cvt_pk_bf16_f32 v100, v100, v101
	v_cvt_pk_bf16_f32 v101, v102, v103
	v_cvt_pk_bf16_f32 v102, v104, v105
	s_nop 0
	v_cvt_pk_bf16_f32 v103, v106, v107
	global_store_dwordx4 v[110:111], v[100:103], off

; __device__ __forceinline__ f32x2 silu_pk(f32x2 x) { const f32x2 t = x * -1.4426950408889634f; f32x2 e; e.x = __builtin_amdgcn_exp2f(t.x); e.y = __builtin_amdgcn_exp2f(t.y); e = e + 1.0f; f32x2 r; r.x = __builtin_amdgcn_rcpf(e.x); r.y = __builtin_amdgcn_rcpf(e.y); return x * r; }
;     __device__ __forceinline__ void operator()(const pg8::f32x4 (&acc)[2][2][4][2], const pg8::Unit& u, int wr, int wc, int fr, int fq) const {
;     ...
;                     } else if (pn < 44) {
; #pragma unroll
;                         for (int e = 0; e < 8; e += 2) { const f32x2 g2 = silu_pk((f32x2){v[e], v[e + 1]}); v[e] = g2.x; v[e + 1] = g2.y; }
;                         st_bf16((bf16*)(ws + WS_ZB) + (size_t)r * 2048 + (pn - 36) * 256 + cl, v);
;                     } else if (pn < 48) {
;                         st_bf16((bf16*)(ws + WS_QC) + (size_t)r * 1024 + (pn - 44) * 256 + cl, v);
;                     } else if (pn < 50) {
;                         const bool isv = pn == 49;
;                         st_bf16((bf16*)(ws + (isv ? WS_VC : WS_KC)) + (size_t)r * 256 + cl, v);
;                         if (r < PT) st_f32(out + (isv ? O_PV : O_PK) + ((size_t)l * PT + r) * 256 + cl, v);
;                         else st_f32(out + (isv ? O_SV : O_SK) + ((size_t)l * ST + (r - PT)) * 256 + cl, v);
;                     } else if (pn < 54) {
; #pragma unroll
;                         for (int e = 0; e < 8; e += 2) { const f32x2 g2 = silu_pk((f32x2){v[e], v[e + 1]}); v[e] = g2.x; v[e + 1] = g2.y; }
;                         st_bf16((bf16*)(ws + WS_ZC) + (size_t)r * 1024 + (pn - 50) * 256 + cl, v);
.LBB0_2068:
	s_andn2_b64 vcc, exec, s[4:5]
	s_cbranch_vccnz .LBB0_2070
	v_mul_f32_e64 v100, v76, s50
	v_mul_f32_e64 v101, v77, s50
	v_mul_f32_e64 v102, v78, s50
	v_mul_f32_e64 v103, v79, s50
	v_exp_f32_e32 v100, v100
	v_exp_f32_e32 v101, v101
	v_exp_f32_e32 v102, v102
	v_exp_f32_e32 v103, v103
	v_mul_f32_e64 v104, v72, s50
	v_mul_f32_e64 v105, v73, s50
	v_mul_f32_e64 v106, v74, s50
	v_mul_f32_e64 v107, v75, s50
	v_exp_f32_e32 v104, v104
	v_exp_f32_e32 v105, v105
	v_exp_f32_e32 v106, v106
	v_exp_f32_e32 v107, v107
	v_add_f32_e64 v100, v100, 1.0
	v_add_f32_e64 v101, v101, 1.0
	v_add_f32_e64 v102, v102, 1.0
	v_add_f32_e64 v103, v103, 1.0
	v_rcp_f32_e32 v100, v100
	v_rcp_f32_e32 v101, v101
	v_rcp_f32_e32 v102, v102
	v_rcp_f32_e32 v103, v103
	v_add_f32_e64 v104, v104, 1.0
	v_add_f32_e64 v105, v105, 1.0
	v_add_f32_e64 v106, v106, 1.0
	v_add_f32_e64 v107, v107, 1.0
	v_rcp_f32_e32 v104, v104
	v_rcp_f32_e32 v105, v105
	v_rcp_f32_e32 v106, v106
	v_rcp_f32_e32 v107, v107
	v_lshlrev_b32_e32 v136, 1, v140
	v_mul_f32_e64 v100, v76, v100
	v_mul_f32_e64 v101, v77, v101
	v_mul_f32_e64 v102, v78, v102
	v_mul_f32_e64 v103, v79, v103
	v_lshl_add_u64 v[110:111], v[84:85], 0, v[136:137]
	v_mul_f32_e64 v104, v72, v104
	v_mul_f32_e64 v105, v73, v105
	v_mul_f32_e64 v106, v74, v106
	v_mul_f32_e64 v107, v75, v107
	v_cvt_pk_bf16_f32 v100, v100, v101
	v_cvt_pk_bf16_f32 v101, v102, v103
	v_cvt_pk_bf16_f32 v102, v104, v105
	s_nop 0
	v_cvt_pk_bf16_f32 v103, v106, v107
	global_store_dwordx4 v[110:111], v[100:103], off

; __device__ __forceinline__ f32x2 silu_pk(f32x2 x) { const f32x2 t = x * -1.4426950408889634f; f32x2 e; e.x = __builtin_amdgcn_exp2f(t.x); e.y = __builtin_amdgcn_exp2f(t.y); e = e + 1.0f; f32x2 r; r.x = __builtin_amdgcn_rcpf(e.x); r.y = __builtin_amdgcn_rcpf(e.y); return x * r; }
;     __device__ __forceinline__ void operator()(const pg8::f32x4 (&acc)[2][2][4][2], const pg8::Unit& u, int wr, int wc, int fr, int fq) const {
;     ...
;                     } else if (pn < 44) {
; #pragma unroll
;                         for (int e = 0; e < 8; e += 2) { const f32x2 g2 = silu_pk((f32x2){v[e], v[e + 1]}); v[e] = g2.x; v[e + 1] = g2.y; }
;                         st_bf16((bf16*)(ws + WS_ZB) + (size_t)r * 2048 + (pn - 36) * 256 + cl, v);
;                     } else if (pn < 48) {
;                         st_bf16((bf16*)(ws + WS_QC) + (size_t)r * 1024 + (pn - 44) * 256 + cl, v);
;                     } else if (pn < 50) {
;                         const bool isv = pn == 49;
;                         st_bf16((bf16*)(ws + (isv ? WS_VC : WS_KC)) + (size_t)r * 256 + cl, v);
;                         if (r < PT) st_f32(out + (isv ? O_PV : O_PK) + ((size_t)l * PT + r) * 256 + cl, v);
;                         else st_f32(out + (isv ? O_SV : O_SK) + ((size_t)l * ST + (r - PT)) * 256 + cl, v);
;                     } else if (pn < 54) {
; #pragma unroll
;                         for (int e = 0; e < 8; e += 2) { const f32x2 g2 = silu_pk((f32x2){v[e], v[e + 1]}); v[e] = g2.x; v[e + 1] = g2.y; }
;                         st_bf16((bf16*)(ws + WS_ZC) + (size_t)r * 1024 + (pn - 50) * 256 + cl, v);
.LBB0_2091:
	s_andn2_b64 vcc, exec, s[4:5]
	s_cbranch_vccnz .LBB0_2093
	v_mul_f32_e64 v72, v68, s50
	v_mul_f32_e64 v73, v69, s50
	v_mul_f32_e64 v74, v70, s50
	v_mul_f32_e64 v75, v71, s50
	v_exp_f32_e32 v72, v72
	v_exp_f32_e32 v73, v73
	v_exp_f32_e32 v74, v74
	v_exp_f32_e32 v75, v75
	v_mul_f32_e64 v76, v64, s50
	v_mul_f32_e64 v77, v65, s50
	v_mul_f32_e64 v78, v66, s50
	v_mul_f32_e64 v79, v67, s50
	v_exp_f32_e32 v76, v76
	v_exp_f32_e32 v77, v77
	v_exp_f32_e32 v78, v78
	v_exp_f32_e32 v79, v79
	v_add_f32_e64 v72, v72, 1.0
	v_add_f32_e64 v73, v73, 1.0
	v_add_f32_e64 v74, v74, 1.0
	v_add_f32_e64 v75, v75, 1.0
	v_rcp_f32_e32 v72, v72
	v_rcp_f32_e32 v73, v73
	v_rcp_f32_e32 v74, v74
	v_rcp_f32_e32 v75, v75
	v_add_f32_e64 v76, v76, 1.0
	v_add_f32_e64 v77, v77, 1.0
	v_add_f32_e64 v78, v78, 1.0
	v_add_f32_e64 v79, v79, 1.0
	v_rcp_f32_e32 v76, v76
	v_rcp_f32_e32 v77, v77
	v_rcp_f32_e32 v78, v78
	v_rcp_f32_e32 v79, v79
	v_lshlrev_b32_e32 v136, 1, v142
	v_mul_f32_e64 v72, v68, v72
	v_mul_f32_e64 v73, v69, v73
	v_mul_f32_e64 v74, v70, v74
	v_mul_f32_e64 v75, v71, v75
	v_lshl_add_u64 v[94:95], v[94:95], 0, v[136:137]
	v_mul_f32_e64 v76, v64, v76
	v_mul_f32_e64 v77, v65, v77
	v_mul_f32_e64 v78, v66, v78
	v_mul_f32_e64 v79, v67, v79
	v_cvt_pk_bf16_f32 v72, v72, v73
	v_cvt_pk_bf16_f32 v73, v74, v75
	v_cvt_pk_bf16_f32 v74, v76, v77
	s_nop 0
	v_cvt_pk_bf16_f32 v75, v78, v79
	global_store_dwordx4 v[94:95], v[72:75], off

; __device__ __forceinline__ f32x2 silu_pk(f32x2 x) { const f32x2 t = x * -1.4426950408889634f; f32x2 e; e.x = __builtin_amdgcn_exp2f(t.x); e.y = __builtin_amdgcn_exp2f(t.y); e = e + 1.0f; f32x2 r; r.x = __builtin_amdgcn_rcpf(e.x); r.y = __builtin_amdgcn_rcpf(e.y); return x * r; }
;     __device__ __forceinline__ void operator()(const pg8::f32x4 (&acc)[2][2][4][2], const pg8::Unit& u, int wr, int wc, int fr, int fq) const {
;     ...
;                     } else if (pn < 44) {
; #pragma unroll
;                         for (int e = 0; e < 8; e += 2) { const f32x2 g2 = silu_pk((f32x2){v[e], v[e + 1]}); v[e] = g2.x; v[e + 1] = g2.y; }
;                         st_bf16((bf16*)(ws + WS_ZB) + (size_t)r * 2048 + (pn - 36) * 256 + cl, v);
;                     } else if (pn < 48) {
;                         st_bf16((bf16*)(ws + WS_QC) + (size_t)r * 1024 + (pn - 44) * 256 + cl, v);
;                     } else if (pn < 50) {
;                         const bool isv = pn == 49;
;                         st_bf16((bf16*)(ws + (isv ? WS_VC : WS_KC)) + (size_t)r * 256 + cl, v);
;                         if (r < PT) st_f32(out + (isv ? O_PV : O_PK) + ((size_t)l * PT + r) * 256 + cl, v);
;                         else st_f32(out + (isv ? O_SV : O_SK) + ((size_t)l * ST + (r - PT)) * 256 + cl, v);
;                     } else if (pn < 54) {
; #pragma unroll
;                         for (int e = 0; e < 8; e += 2) { const f32x2 g2 = silu_pk((f32x2){v[e], v[e + 1]}); v[e] = g2.x; v[e + 1] = g2.y; }
;                         st_bf16((bf16*)(ws + WS_ZC) + (size_t)r * 1024 + (pn - 50) * 256 + cl, v);
.LBB0_2104:
	s_andn2_b64 vcc, exec, s[4:5]
	s_cbranch_vccnz .LBB0_2106
	v_mul_f32_e64 v72, v68, s50
	v_mul_f32_e64 v73, v69, s50
	v_mul_f32_e64 v74, v70, s50
	v_mul_f32_e64 v75, v71, s50
	v_exp_f32_e32 v72, v72
	v_exp_f32_e32 v73, v73
	v_exp_f32_e32 v74, v74
	v_exp_f32_e32 v75, v75
	v_mul_f32_e64 v76, v64, s50
	v_mul_f32_e64 v77, v65, s50
	v_mul_f32_e64 v78, v66, s50
	v_mul_f32_e64 v79, v67, s50
	v_exp_f32_e32 v76, v76
	v_exp_f32_e32 v77, v77
	v_exp_f32_e32 v78, v78
	v_exp_f32_e32 v79, v79
	v_add_f32_e64 v72, v72, 1.0
	v_add_f32_e64 v73, v73, 1.0
	v_add_f32_e64 v74, v74, 1.0
	v_add_f32_e64 v75, v75, 1.0
	v_rcp_f32_e32 v72, v72
	v_rcp_f32_e32 v73, v73
	v_rcp_f32_e32 v74, v74
	v_rcp_f32_e32 v75, v75
	v_add_f32_e64 v76, v76, 1.0
	v_add_f32_e64 v77, v77, 1.0
	v_add_f32_e64 v78, v78, 1.0
	v_add_f32_e64 v79, v79, 1.0
	v_rcp_f32_e32 v76, v76
	v_rcp_f32_e32 v77, v77
	v_rcp_f32_e32 v78, v78
	v_rcp_f32_e32 v79, v79
	v_lshlrev_b32_e32 v136, 1, v142
	v_mul_f32_e64 v72, v68, v72
	v_mul_f32_e64 v73, v69, v73
	v_mul_f32_e64 v74, v70, v74
	v_mul_f32_e64 v75, v71, v75
	v_lshl_add_u64 v[84:85], v[84:85], 0, v[136:137]
	v_mul_f32_e64 v76, v64, v76
	v_mul_f32_e64 v77, v65, v77
	v_mul_f32_e64 v78, v66, v78
	v_mul_f32_e64 v79, v67, v79
	v_cvt_pk_bf16_f32 v72, v72, v73
	v_cvt_pk_bf16_f32 v73, v74, v75
	v_cvt_pk_bf16_f32 v74, v76, v77
	s_nop 0
	v_cvt_pk_bf16_f32 v75, v78, v79
	global_store_dwordx4 v[84:85], v[72:75], off

; __device__ __forceinline__ f32x2 silu_pk(f32x2 x) { const f32x2 t = x * -1.4426950408889634f; f32x2 e; e.x = __builtin_amdgcn_exp2f(t.x); e.y = __builtin_amdgcn_exp2f(t.y); e = e + 1.0f; f32x2 r; r.x = __builtin_amdgcn_rcpf(e.x); r.y = __builtin_amdgcn_rcpf(e.y); return x * r; }
; __device__ __forceinline__ f32x2 gelu_pk(f32x2 x) { const f32x2 x2 = x * x; const f32x2 t = (x2 * 0.044715f + 1.0f) * (x * -2.302208198144325f); f32x2 e; e.x = __builtin_amdgcn_exp2f(t.x); e.y = __builtin_amdgcn_exp2f(t.y); e = e + 1.0f; f32x2 r; r.x = __builtin_amdgcn_rcpf(e.x); r.y = __builtin_amd ...
;     __device__ __forceinline__ void operator()(const pg8::f32x4 (&acc)[2][2][4][2], const pg8::Unit& u, int wr, int wc, int fr, int fq) const {
;     ...
;                     if (pn < 12) {
;                         const int seg = pn >> 2, cc = (pn & 3) * 256 + cl;
;                         if (seg < 2) {
; #pragma unroll
;                             for (int e = 0; e < 8; e += 2) { const f32x2 g2 = gelu_pk((f32x2){v[e], v[e + 1]}); v[e] = g2.x; v[e + 1] = g2.y; }
;                         } else {
; #pragma unroll
;                             for (int e = 0; e < 8; e += 2) { const f32x2 g2 = silu_pk((f32x2){v[e], v[e + 1]}); v[e] = g2.x; v[e + 1] = g2.y; }
;                         }
;                         bf16* base = (bf16*)(ws + (seg == 0 ? WS_UA : seg == 1 ? WS_VA : WS_ZA));
;                         st_bf16(base + (size_t)r * 1024 + cc, v);
.LBB0_2119:
	s_andn2_b64 vcc, exec, s[16:17]
	s_mov_b64 s[6:7], -1
	s_cbranch_vccnz .LBB0_2121
	v_mul_f32_e64 v102, v78, s50
	v_mul_f32_e64 v103, v79, s50
	v_mul_f32_e64 v100, v76, s50
	v_mul_f32_e64 v101, v77, s50
	v_exp_f32_e32 v102, v102
	v_exp_f32_e32 v103, v103
	v_mul_f32_e64 v104, v72, s50
	v_mul_f32_e64 v105, v73, s50
	v_exp_f32_e32 v100, v100
	v_exp_f32_e32 v101, v101
	v_exp_f32_e32 v104, v104
	v_exp_f32_e32 v105, v105
	v_add_f32_e64 v102, v102, 1.0
	v_add_f32_e64 v103, v103, 1.0
	v_add_f32_e64 v100, v100, 1.0
	v_add_f32_e64 v101, v101, 1.0
	v_rcp_f32_e32 v106, v102
	v_rcp_f32_e32 v107, v103
	v_add_f32_e64 v102, v104, 1.0
	v_add_f32_e64 v103, v105, 1.0
	v_rcp_f32_e32 v100, v100
	v_rcp_f32_e32 v101, v101
	v_rcp_f32_e32 v104, v102
	v_rcp_f32_e32 v105, v103
	s_mov_b64 s[6:7], 0
	v_mul_f32_e64 v102, v76, v100
	v_mul_f32_e64 v103, v77, v101
	v_mul_f32_e64 v100, v78, v106
	v_mul_f32_e64 v101, v79, v107
	v_mul_f32_e64 v104, v72, v104
	v_mul_f32_e64 v105, v73, v105
	v_mul_f32_e64 v106, v74, s50
	v_mul_f32_e64 v107, v75, s50
.LBB0_2121:
	s_andn2_b64 vcc, exec, s[6:7]
	s_cbranch_vccnz .LBB0_2123
	v_mul_f32_e64 v102, v76, v76
	v_mul_f32_e64 v103, v77, v77
	v_mul_f32_e64 v104, v76, s58
	v_mul_f32_e64 v105, v77, s58
	v_fma_f32 v102, v102, s56, 1.0
	v_fma_f32 v103, v103, s56, 1.0
	v_mul_f32_e64 v100, v78, v78
	v_mul_f32_e64 v101, v79, v79
	v_mul_f32_e64 v102, v104, v102
	v_mul_f32_e64 v103, v105, v103
	v_mul_f32_e64 v104, v72, s58
	v_mul_f32_e64 v105, v73, s58
	v_exp_f32_e32 v102, v102
	v_exp_f32_e32 v103, v103
	s_nop 0
	v_add_f32_e64 v102, v102, 1.0
	v_add_f32_e64 v103, v103, 1.0
	s_nop 0
	v_rcp_f32_e32 v102, v102
	v_rcp_f32_e32 v103, v103
	s_nop 0
	v_mul_f32_e64 v102, v76, v102
	v_mul_f32_e64 v103, v77, v103
	v_fma_f32 v76, v100, s56, 1.0
	v_fma_f32 v77, v101, s56, 1.0
	v_mul_f32_e64 v100, v78, s58
	v_mul_f32_e64 v101, v79, s58
	s_nop 0
	v_mul_f32_e64 v76, v100, v76
	v_mul_f32_e64 v77, v101, v77
	s_nop 0
	v_exp_f32_e32 v76, v76
	v_exp_f32_e32 v77, v77
	s_nop 0
	v_add_f32_e64 v76, v76, 1.0
	v_add_f32_e64 v77, v77, 1.0
	s_nop 0
	v_rcp_f32_e32 v76, v76
	v_rcp_f32_e32 v77, v77
	s_nop 0
	v_mul_f32_e64 v100, v78, v76
	v_mul_f32_e64 v101, v79, v77
	v_mul_f32_e64 v78, v72, v72
	v_mul_f32_e64 v79, v73, v73
	v_mul_f32_e64 v76, v74, v74
	v_mul_f32_e64 v77, v75, v75
	v_fma_f32 v78, v78, s56, 1.0
	v_fma_f32 v79, v79, s56, 1.0
	s_nop 0
	v_mul_f32_e64 v78, v104, v78
	v_mul_f32_e64 v79, v105, v79
	s_nop 0
	v_exp_f32_e32 v78, v78
	v_exp_f32_e32 v79, v79
	s_nop 0
	v_add_f32_e64 v78, v78, 1.0
	v_add_f32_e64 v79, v79, 1.0
	s_nop 0
	v_rcp_f32_e32 v78, v78
	v_rcp_f32_e32 v79, v79
	s_nop 0
	v_mul_f32_e64 v104, v72, v78
	v_mul_f32_e64 v105, v73, v79
	v_fma_f32 v72, v76, s56, 1.0
	v_fma_f32 v73, v77, s56, 1.0
	v_mul_f32_e64 v76, v74, s58
	v_mul_f32_e64 v77, v75, s58
	s_nop 0
	v_mul_f32_e64 v106, v76, v72
	v_mul_f32_e64 v107, v77, v73
.LBB0_2123:
	s_nop 0
	v_exp_f32_e32 v72, v106
	v_exp_f32_e32 v73, v107
	v_or_b32_e32 v78, s24, v140
	v_lshlrev_b32_e32 v136, 1, v78
	v_lshl_add_u64 v[78:79], v[96:97], 0, v[136:137]
	v_add_f32_e64 v72, v72, 1.0
	v_add_f32_e64 v73, v73, 1.0
	s_nop 0
	v_rcp_f32_e32 v72, v72
	v_rcp_f32_e32 v73, v73
	s_nop 0
	v_mul_f32_e64 v76, v74, v72
	v_mul_f32_e64 v77, v75, v73
	v_cvt_pk_bf16_f32 v72, v102, v103
	v_cvt_pk_bf16_f32 v73, v100, v101
	v_cvt_pk_bf16_f32 v74, v104, v105
	s_nop 0
	v_cvt_pk_bf16_f32 v75, v76, v77
	global_store_dwordx4 v[78:79], v[72:75], off
	s_and_b64 vcc, exec, s[10:11]
	s_mov_b64 s[4:5], -1
	s_cbranch_vccz .LBB0_2083

; __device__ __forceinline__ f32x2 silu_pk(f32x2 x) { const f32x2 t = x * -1.4426950408889634f; f32x2 e; e.x = __builtin_amdgcn_exp2f(t.x); e.y = __builtin_amdgcn_exp2f(t.y); e = e + 1.0f; f32x2 r; r.x = __builtin_amdgcn_rcpf(e.x); r.y = __builtin_amdgcn_rcpf(e.y); return x * r; }
; __device__ __forceinline__ f32x2 gelu_pk(f32x2 x) { const f32x2 x2 = x * x; const f32x2 t = (x2 * 0.044715f + 1.0f) * (x * -2.302208198144325f); f32x2 e; e.x = __builtin_amdgcn_exp2f(t.x); e.y = __builtin_amdgcn_exp2f(t.y); e = e + 1.0f; f32x2 r; r.x = __builtin_amdgcn_rcpf(e.x); r.y = __builtin_amd ...
;     __device__ __forceinline__ void operator()(const pg8::f32x4 (&acc)[2][2][4][2], const pg8::Unit& u, int wr, int wc, int fr, int fq) const {
;     ...
;                     if (pn < 12) {
;                         const int seg = pn >> 2, cc = (pn & 3) * 256 + cl;
;                         if (seg < 2) {
; #pragma unroll
;                             for (int e = 0; e < 8; e += 2) { const f32x2 g2 = gelu_pk((f32x2){v[e], v[e + 1]}); v[e] = g2.x; v[e + 1] = g2.y; }
;                         } else {
; #pragma unroll
;                             for (int e = 0; e < 8; e += 2) { const f32x2 g2 = silu_pk((f32x2){v[e], v[e + 1]}); v[e] = g2.x; v[e + 1] = g2.y; }
;                         }
;                         bf16* base = (bf16*)(ws + (seg == 0 ? WS_UA : seg == 1 ? WS_VA : WS_ZA));
;                         st_bf16(base + (size_t)r * 1024 + cc, v);
.LBB0_2125:
	s_andn2_b64 vcc, exec, s[16:17]
	s_mov_b64 s[0:1], -1
	s_cbranch_vccnz .LBB0_2127
	v_mul_f32_e64 v72, v68, s50
	v_mul_f32_e64 v73, v69, s50
	v_mul_f32_e64 v74, v70, s50
	v_mul_f32_e64 v75, v71, s50
	v_mul_f32_e64 v76, v64, s50
	v_mul_f32_e64 v77, v65, s50
	v_exp_f32_e32 v72, v72
	v_exp_f32_e32 v73, v73
	v_exp_f32_e32 v74, v74
	v_exp_f32_e32 v75, v75
	v_exp_f32_e32 v76, v76
	v_exp_f32_e32 v77, v77
	v_add_f32_e64 v72, v72, 1.0
	v_add_f32_e64 v73, v73, 1.0
	v_add_f32_e64 v74, v74, 1.0
	v_add_f32_e64 v75, v75, 1.0
	v_rcp_f32_e32 v72, v72
	v_add_f32_e64 v76, v76, 1.0
	v_add_f32_e64 v77, v77, 1.0
	v_rcp_f32_e32 v73, v73
	v_rcp_f32_e32 v74, v74
	v_rcp_f32_e32 v75, v75
	v_rcp_f32_e32 v76, v76
	v_rcp_f32_e32 v77, v77
	v_mul_f32_e64 v72, v68, v72
	v_mul_f32_e64 v73, v69, v73
	v_mul_f32_e64 v74, v70, v74
	v_mul_f32_e64 v75, v71, v75
	v_mul_f32_e64 v78, v66, s50
	v_mul_f32_e64 v79, v67, s50
	v_mul_f32_e64 v76, v64, v76
	v_mul_f32_e64 v77, v65, v77
	s_mov_b64 s[0:1], 0
.LBB0_2127:
	s_andn2_b64 vcc, exec, s[0:1]
	s_cbranch_vccnz .LBB0_2129
	v_mul_f32_e64 v72, v68, v68
	v_mul_f32_e64 v73, v69, v69
	v_mul_f32_e64 v76, v68, s58
	v_mul_f32_e64 v77, v69, s58
	v_fma_f32 v72, v72, s56, 1.0
	v_fma_f32 v73, v73, s56, 1.0
	v_mul_f32_e64 v74, v70, v70
	v_mul_f32_e64 v75, v71, v71
	v_mul_f32_e64 v72, v76, v72
	v_mul_f32_e64 v73, v77, v73
	v_mul_f32_e64 v76, v64, s58
	v_mul_f32_e64 v77, v65, s58
	v_exp_f32_e32 v72, v72
	v_exp_f32_e32 v73, v73
	s_nop 0
	v_add_f32_e64 v72, v72, 1.0
	v_add_f32_e64 v73, v73, 1.0
	s_nop 0
	v_rcp_f32_e32 v72, v72
	v_rcp_f32_e32 v73, v73
	s_nop 0
	v_mul_f32_e64 v72, v68, v72
	v_mul_f32_e64 v73, v69, v73
	v_fma_f32 v68, v74, s56, 1.0
	v_fma_f32 v69, v75, s56, 1.0
	v_mul_f32_e64 v74, v70, s58
	v_mul_f32_e64 v75, v71, s58
	s_nop 0
	v_mul_f32_e64 v68, v74, v68
	v_mul_f32_e64 v69, v75, v69
	s_nop 0
	v_exp_f32_e32 v68, v68
	v_exp_f32_e32 v69, v69
	s_nop 0
	v_add_f32_e64 v68, v68, 1.0
	v_add_f32_e64 v69, v69, 1.0
	s_nop 0
	v_rcp_f32_e32 v68, v68
	v_rcp_f32_e32 v69, v69
	s_nop 0
	v_mul_f32_e64 v74, v70, v68
	v_mul_f32_e64 v75, v71, v69
	v_mul_f32_e64 v70, v64, v64
	v_mul_f32_e64 v71, v65, v65
	v_mul_f32_e64 v68, v66, v66
	v_mul_f32_e64 v69, v67, v67
	v_fma_f32 v70, v70, s56, 1.0
	v_fma_f32 v71, v71, s56, 1.0
	s_nop 0
	v_mul_f32_e64 v70, v76, v70
	v_mul_f32_e64 v71, v77, v71
	s_nop 0
	v_exp_f32_e32 v70, v70
	v_exp_f32_e32 v71, v71
	s_nop 0
	v_add_f32_e64 v70, v70, 1.0
	v_add_f32_e64 v71, v71, 1.0
	s_nop 0
	v_rcp_f32_e32 v70, v70
	v_rcp_f32_e32 v71, v71
	s_nop 0
	v_mul_f32_e64 v76, v64, v70
	v_mul_f32_e64 v77, v65, v71
	v_fma_f32 v64, v68, s56, 1.0
	v_fma_f32 v65, v69, s56, 1.0
	v_mul_f32_e64 v68, v66, s58
	v_mul_f32_e64 v69, v67, s58
	s_nop 0
	v_mul_f32_e64 v78, v68, v64
	v_mul_f32_e64 v79, v69, v65
.LBB0_2129:
	s_nop 0
	v_exp_f32_e32 v64, v78
	v_exp_f32_e32 v65, v79
	v_add_lshl_u32 v136, s24, v140, 1
	v_lshl_add_u64 v[70:71], v[96:97], 0, v[136:137]
	v_add_f32_e64 v64, v64, 1.0
	v_add_f32_e64 v65, v65, 1.0
	s_nop 0
	v_rcp_f32_e32 v64, v64
	v_rcp_f32_e32 v65, v65
	s_nop 0
	v_mul_f32_e64 v68, v66, v64
	v_mul_f32_e64 v69, v67, v65
	v_cvt_pk_bf16_f32 v64, v72, v73
	v_cvt_pk_bf16_f32 v65, v74, v75
	v_cvt_pk_bf16_f32 v66, v76, v77
	s_nop 0
	v_cvt_pk_bf16_f32 v67, v68, v69
	global_store_dwordx4 v[70:71], v[64:67], off offset:256

; __device__ __forceinline__ f32x2 silu_pk(f32x2 x) { const f32x2 t = x * -1.4426950408889634f; f32x2 e; e.x = __builtin_amdgcn_exp2f(t.x); e.y = __builtin_amdgcn_exp2f(t.y); e = e + 1.0f; f32x2 r; r.x = __builtin_amdgcn_rcpf(e.x); r.y = __builtin_amdgcn_rcpf(e.y); return x * r; }
;     __device__ __forceinline__ void operator()(const pg8::f32x4 (&acc)[2][2][4][2], const pg8::Unit& u, int wr, int wc, int fr, int fq) const {
;     ...
;                     } else if (pn < 44) {
; #pragma unroll
;                         for (int e = 0; e < 8; e += 2) { const f32x2 g2 = silu_pk((f32x2){v[e], v[e + 1]}); v[e] = g2.x; v[e + 1] = g2.y; }
;                         st_bf16((bf16*)(ws + WS_ZB) + (size_t)r * 2048 + (pn - 36) * 256 + cl, v);
;                     } else if (pn < 48) {
;                         st_bf16((bf16*)(ws + WS_QC) + (size_t)r * 1024 + (pn - 44) * 256 + cl, v);
;                     } else if (pn < 50) {
;                         const bool isv = pn == 49;
;                         st_bf16((bf16*)(ws + (isv ? WS_VC : WS_KC)) + (size_t)r * 256 + cl, v);
;                         if (r < PT) st_f32(out + (isv ? O_PV : O_PK) + ((size_t)l * PT + r) * 256 + cl, v);
;                         else st_f32(out + (isv ? O_SV : O_SK) + ((size_t)l * ST + (r - PT)) * 256 + cl, v);
;                     } else if (pn < 54) {
; #pragma unroll
;                         for (int e = 0; e < 8; e += 2) { const f32x2 g2 = silu_pk((f32x2){v[e], v[e + 1]}); v[e] = g2.x; v[e + 1] = g2.y; }
;                         st_bf16((bf16*)(ws + WS_ZC) + (size_t)r * 1024 + (pn - 50) * 256 + cl, v);
.LBB0_2156:
	s_andn2_b64 vcc, exec, s[4:5]
	s_cbranch_vccnz .LBB0_2158
	v_mul_f32_e64 v84, v60, s50
	v_mul_f32_e64 v85, v61, s50
	v_mul_f32_e64 v86, v62, s50
	v_mul_f32_e64 v87, v63, s50
	v_exp_f32_e32 v84, v84
	v_exp_f32_e32 v85, v85
	v_exp_f32_e32 v86, v86
	v_exp_f32_e32 v87, v87
	v_mul_f32_e64 v88, v56, s50
	v_mul_f32_e64 v89, v57, s50
	v_mul_f32_e64 v90, v58, s50
	v_mul_f32_e64 v91, v59, s50
	v_exp_f32_e32 v88, v88
	v_exp_f32_e32 v89, v89
	v_exp_f32_e32 v90, v90
	v_exp_f32_e32 v91, v91
	v_add_f32_e64 v84, v84, 1.0
	v_add_f32_e64 v85, v85, 1.0
	v_add_f32_e64 v86, v86, 1.0
	v_add_f32_e64 v87, v87, 1.0
	v_rcp_f32_e32 v84, v84
	v_rcp_f32_e32 v85, v85
	v_rcp_f32_e32 v86, v86
	v_rcp_f32_e32 v87, v87
	v_add_f32_e64 v88, v88, 1.0
	v_add_f32_e64 v89, v89, 1.0
	v_add_f32_e64 v90, v90, 1.0
	v_add_f32_e64 v91, v91, 1.0
	v_rcp_f32_e32 v88, v88
	v_rcp_f32_e32 v89, v89
	v_rcp_f32_e32 v90, v90
	v_rcp_f32_e32 v91, v91
	v_lshlrev_b32_e32 v136, 1, v140
	v_mul_f32_e64 v84, v60, v84
	v_mul_f32_e64 v85, v61, v85
	v_mul_f32_e64 v86, v62, v86
	v_mul_f32_e64 v87, v63, v87
	v_lshl_add_u64 v[94:95], v[78:79], 0, v[136:137]
	v_mul_f32_e64 v88, v56, v88
	v_mul_f32_e64 v89, v57, v89
	v_mul_f32_e64 v90, v58, v90
	v_mul_f32_e64 v91, v59, v91
	v_cvt_pk_bf16_f32 v84, v84, v85
	v_cvt_pk_bf16_f32 v85, v86, v87
	v_cvt_pk_bf16_f32 v86, v88, v89
	s_nop 0
	v_cvt_pk_bf16_f32 v87, v90, v91
	global_store_dwordx4 v[94:95], v[84:87], off

; __device__ __forceinline__ f32x2 silu_pk(f32x2 x) { const f32x2 t = x * -1.4426950408889634f; f32x2 e; e.x = __builtin_amdgcn_exp2f(t.x); e.y = __builtin_amdgcn_exp2f(t.y); e = e + 1.0f; f32x2 r; r.x = __builtin_amdgcn_rcpf(e.x); r.y = __builtin_amdgcn_rcpf(e.y); return x * r; }
;     __device__ __forceinline__ void operator()(const pg8::f32x4 (&acc)[2][2][4][2], const pg8::Unit& u, int wr, int wc, int fr, int fq) const {
;     ...
;                     } else if (pn < 44) {
; #pragma unroll
;                         for (int e = 0; e < 8; e += 2) { const f32x2 g2 = silu_pk((f32x2){v[e], v[e + 1]}); v[e] = g2.x; v[e + 1] = g2.y; }
;                         st_bf16((bf16*)(ws + WS_ZB) + (size_t)r * 2048 + (pn - 36) * 256 + cl, v);
;                     } else if (pn < 48) {
;                         st_bf16((bf16*)(ws + WS_QC) + (size_t)r * 1024 + (pn - 44) * 256 + cl, v);
;                     } else if (pn < 50) {
;                         const bool isv = pn == 49;
;                         st_bf16((bf16*)(ws + (isv ? WS_VC : WS_KC)) + (size_t)r * 256 + cl, v);
;                         if (r < PT) st_f32(out + (isv ? O_PV : O_PK) + ((size_t)l * PT + r) * 256 + cl, v);
;                         else st_f32(out + (isv ? O_SV : O_SK) + ((size_t)l * ST + (r - PT)) * 256 + cl, v);
;                     } else if (pn < 54) {
; #pragma unroll
;                         for (int e = 0; e < 8; e += 2) { const f32x2 g2 = silu_pk((f32x2){v[e], v[e + 1]}); v[e] = g2.x; v[e + 1] = g2.y; }
;                         st_bf16((bf16*)(ws + WS_ZC) + (size_t)r * 1024 + (pn - 50) * 256 + cl, v);
.LBB0_2169:
	s_andn2_b64 vcc, exec, s[4:5]
	s_cbranch_vccnz .LBB0_2171
	v_mul_f32_e64 v84, v60, s50
	v_mul_f32_e64 v85, v61, s50
	v_mul_f32_e64 v86, v62, s50
	v_mul_f32_e64 v87, v63, s50
	v_exp_f32_e32 v84, v84
	v_exp_f32_e32 v85, v85
	v_exp_f32_e32 v86, v86
	v_exp_f32_e32 v87, v87
	v_mul_f32_e64 v88, v56, s50
	v_mul_f32_e64 v89, v57, s50
	v_mul_f32_e64 v90, v58, s50
	v_mul_f32_e64 v91, v59, s50
	v_exp_f32_e32 v88, v88
	v_exp_f32_e32 v89, v89
	v_exp_f32_e32 v90, v90
	v_exp_f32_e32 v91, v91
	v_add_f32_e64 v84, v84, 1.0
	v_add_f32_e64 v85, v85, 1.0
	v_add_f32_e64 v86, v86, 1.0
	v_add_f32_e64 v87, v87, 1.0
	v_rcp_f32_e32 v84, v84
	v_rcp_f32_e32 v85, v85
	v_rcp_f32_e32 v86, v86
	v_rcp_f32_e32 v87, v87
	v_add_f32_e64 v88, v88, 1.0
	v_add_f32_e64 v89, v89, 1.0
	v_add_f32_e64 v90, v90, 1.0
	v_add_f32_e64 v91, v91, 1.0
	v_rcp_f32_e32 v88, v88
	v_rcp_f32_e32 v89, v89
	v_rcp_f32_e32 v90, v90
	v_rcp_f32_e32 v91, v91
	v_lshlrev_b32_e32 v136, 1, v140
	v_mul_f32_e64 v84, v60, v84
	v_mul_f32_e64 v85, v61, v85
	v_mul_f32_e64 v86, v62, v86
	v_mul_f32_e64 v87, v63, v87
	v_lshl_add_u64 v[94:95], v[68:69], 0, v[136:137]
	v_mul_f32_e64 v88, v56, v88
	v_mul_f32_e64 v89, v57, v89
	v_mul_f32_e64 v90, v58, v90
	v_mul_f32_e64 v91, v59, v91
	v_cvt_pk_bf16_f32 v84, v84, v85
	v_cvt_pk_bf16_f32 v85, v86, v87
	v_cvt_pk_bf16_f32 v86, v88, v89
	s_nop 0
	v_cvt_pk_bf16_f32 v87, v90, v91
	global_store_dwordx4 v[94:95], v[84:87], off

; __device__ __forceinline__ f32x2 silu_pk(f32x2 x) { const f32x2 t = x * -1.4426950408889634f; f32x2 e; e.x = __builtin_amdgcn_exp2f(t.x); e.y = __builtin_amdgcn_exp2f(t.y); e = e + 1.0f; f32x2 r; r.x = __builtin_amdgcn_rcpf(e.x); r.y = __builtin_amdgcn_rcpf(e.y); return x * r; }
;     __device__ __forceinline__ void operator()(const pg8::f32x4 (&acc)[2][2][4][2], const pg8::Unit& u, int wr, int wc, int fr, int fq) const {
;     ...
;                     } else if (pn < 44) {
; #pragma unroll
;                         for (int e = 0; e < 8; e += 2) { const f32x2 g2 = silu_pk((f32x2){v[e], v[e + 1]}); v[e] = g2.x; v[e + 1] = g2.y; }
;                         st_bf16((bf16*)(ws + WS_ZB) + (size_t)r * 2048 + (pn - 36) * 256 + cl, v);
;                     } else if (pn < 48) {
;                         st_bf16((bf16*)(ws + WS_QC) + (size_t)r * 1024 + (pn - 44) * 256 + cl, v);
;                     } else if (pn < 50) {
;                         const bool isv = pn == 49;
;                         st_bf16((bf16*)(ws + (isv ? WS_VC : WS_KC)) + (size_t)r * 256 + cl, v);
;                         if (r < PT) st_f32(out + (isv ? O_PV : O_PK) + ((size_t)l * PT + r) * 256 + cl, v);
;                         else st_f32(out + (isv ? O_SV : O_SK) + ((size_t)l * ST + (r - PT)) * 256 + cl, v);
;                     } else if (pn < 54) {
; #pragma unroll
;                         for (int e = 0; e < 8; e += 2) { const f32x2 g2 = silu_pk((f32x2){v[e], v[e + 1]}); v[e] = g2.x; v[e + 1] = g2.y; }
;                         st_bf16((bf16*)(ws + WS_ZC) + (size_t)r * 1024 + (pn - 50) * 256 + cl, v);
.LBB0_2186:
	s_andn2_b64 vcc, exec, s[4:5]
	s_cbranch_vccnz .LBB0_2188
	v_mul_f32_e64 v56, v52, s50
	v_mul_f32_e64 v57, v53, s50
	v_mul_f32_e64 v58, v54, s50
	v_mul_f32_e64 v59, v55, s50
	v_exp_f32_e32 v56, v56
	v_exp_f32_e32 v57, v57
	v_exp_f32_e32 v58, v58
	v_exp_f32_e32 v59, v59
	v_mul_f32_e64 v60, v48, s50
	v_mul_f32_e64 v61, v49, s50
	v_mul_f32_e64 v62, v50, s50
	v_mul_f32_e64 v63, v51, s50
	v_exp_f32_e32 v60, v60
	v_exp_f32_e32 v61, v61
	v_exp_f32_e32 v62, v62
	v_exp_f32_e32 v63, v63
	v_add_f32_e64 v56, v56, 1.0
	v_add_f32_e64 v57, v57, 1.0
	v_add_f32_e64 v58, v58, 1.0
	v_add_f32_e64 v59, v59, 1.0
	v_rcp_f32_e32 v56, v56
	v_rcp_f32_e32 v57, v57
	v_rcp_f32_e32 v58, v58
	v_rcp_f32_e32 v59, v59
	v_add_f32_e64 v60, v60, 1.0
	v_add_f32_e64 v61, v61, 1.0
	v_add_f32_e64 v62, v62, 1.0
	v_add_f32_e64 v63, v63, 1.0
	v_rcp_f32_e32 v60, v60
	v_rcp_f32_e32 v61, v61
	v_rcp_f32_e32 v62, v62
	v_rcp_f32_e32 v63, v63
	v_lshlrev_b32_e32 v136, 1, v142
	v_mul_f32_e64 v56, v52, v56
	v_mul_f32_e64 v57, v53, v57
	v_mul_f32_e64 v58, v54, v58
	v_mul_f32_e64 v59, v55, v59
	v_lshl_add_u64 v[78:79], v[78:79], 0, v[136:137]
	v_mul_f32_e64 v60, v48, v60
	v_mul_f32_e64 v61, v49, v61
	v_mul_f32_e64 v62, v50, v62
	v_mul_f32_e64 v63, v51, v63
	v_cvt_pk_bf16_f32 v56, v56, v57
	v_cvt_pk_bf16_f32 v57, v58, v59
	v_cvt_pk_bf16_f32 v58, v60, v61
	s_nop 0
	v_cvt_pk_bf16_f32 v59, v62, v63
	global_store_dwordx4 v[78:79], v[56:59], off

; __device__ __forceinline__ f32x2 silu_pk(f32x2 x) { const f32x2 t = x * -1.4426950408889634f; f32x2 e; e.x = __builtin_amdgcn_exp2f(t.x); e.y = __builtin_amdgcn_exp2f(t.y); e = e + 1.0f; f32x2 r; r.x = __builtin_amdgcn_rcpf(e.x); r.y = __builtin_amdgcn_rcpf(e.y); return x * r; }
;     __device__ __forceinline__ void operator()(const pg8::f32x4 (&acc)[2][2][4][2], const pg8::Unit& u, int wr, int wc, int fr, int fq) const {
;     ...
;                     } else if (pn < 44) {
; #pragma unroll
;                         for (int e = 0; e < 8; e += 2) { const f32x2 g2 = silu_pk((f32x2){v[e], v[e + 1]}); v[e] = g2.x; v[e + 1] = g2.y; }
;                         st_bf16((bf16*)(ws + WS_ZB) + (size_t)r * 2048 + (pn - 36) * 256 + cl, v);
;                     } else if (pn < 48) {
;                         st_bf16((bf16*)(ws + WS_QC) + (size_t)r * 1024 + (pn - 44) * 256 + cl, v);
;                     } else if (pn < 50) {
;                         const bool isv = pn == 49;
;                         st_bf16((bf16*)(ws + (isv ? WS_VC : WS_KC)) + (size_t)r * 256 + cl, v);
;                         if (r < PT) st_f32(out + (isv ? O_PV : O_PK) + ((size_t)l * PT + r) * 256 + cl, v);
;                         else st_f32(out + (isv ? O_SV : O_SK) + ((size_t)l * ST + (r - PT)) * 256 + cl, v);
;                     } else if (pn < 54) {
; #pragma unroll
;                         for (int e = 0; e < 8; e += 2) { const f32x2 g2 = silu_pk((f32x2){v[e], v[e + 1]}); v[e] = g2.x; v[e + 1] = g2.y; }
;                         st_bf16((bf16*)(ws + WS_ZC) + (size_t)r * 1024 + (pn - 50) * 256 + cl, v);
.LBB0_2199:
	s_andn2_b64 vcc, exec, s[4:5]
	s_cbranch_vccnz .LBB0_2201
	v_mul_f32_e64 v56, v52, s50
	v_mul_f32_e64 v57, v53, s50
	v_mul_f32_e64 v58, v54, s50
	v_mul_f32_e64 v59, v55, s50
	v_exp_f32_e32 v56, v56
	v_exp_f32_e32 v57, v57
	v_exp_f32_e32 v58, v58
	v_exp_f32_e32 v59, v59
	v_mul_f32_e64 v60, v48, s50
	v_mul_f32_e64 v61, v49, s50
	v_mul_f32_e64 v62, v50, s50
	v_mul_f32_e64 v63, v51, s50
	v_exp_f32_e32 v60, v60
	v_exp_f32_e32 v61, v61
	v_exp_f32_e32 v62, v62
	v_exp_f32_e32 v63, v63
	v_add_f32_e64 v56, v56, 1.0
	v_add_f32_e64 v57, v57, 1.0
	v_add_f32_e64 v58, v58, 1.0
	v_add_f32_e64 v59, v59, 1.0
	v_rcp_f32_e32 v56, v56
	v_rcp_f32_e32 v57, v57
	v_rcp_f32_e32 v58, v58
	v_rcp_f32_e32 v59, v59
	v_add_f32_e64 v60, v60, 1.0
	v_add_f32_e64 v61, v61, 1.0
	v_add_f32_e64 v62, v62, 1.0
	v_add_f32_e64 v63, v63, 1.0
	v_rcp_f32_e32 v60, v60
	v_rcp_f32_e32 v61, v61
	v_rcp_f32_e32 v62, v62
	v_rcp_f32_e32 v63, v63
	v_lshlrev_b32_e32 v136, 1, v142
	v_mul_f32_e64 v56, v52, v56
	v_mul_f32_e64 v57, v53, v57
	v_mul_f32_e64 v58, v54, v58
	v_mul_f32_e64 v59, v55, v59
	v_lshl_add_u64 v[68:69], v[68:69], 0, v[136:137]
	v_mul_f32_e64 v60, v48, v60
	v_mul_f32_e64 v61, v49, v61
	v_mul_f32_e64 v62, v50, v62
	v_mul_f32_e64 v63, v51, v63
	v_cvt_pk_bf16_f32 v56, v56, v57
	v_cvt_pk_bf16_f32 v57, v58, v59
	v_cvt_pk_bf16_f32 v58, v60, v61
	s_nop 0
	v_cvt_pk_bf16_f32 v59, v62, v63
	global_store_dwordx4 v[68:69], v[56:59], off

; __device__ __forceinline__ f32x2 silu_pk(f32x2 x) { const f32x2 t = x * -1.4426950408889634f; f32x2 e; e.x = __builtin_amdgcn_exp2f(t.x); e.y = __builtin_amdgcn_exp2f(t.y); e = e + 1.0f; f32x2 r; r.x = __builtin_amdgcn_rcpf(e.x); r.y = __builtin_amdgcn_rcpf(e.y); return x * r; }
; __device__ __forceinline__ f32x2 gelu_pk(f32x2 x) { const f32x2 x2 = x * x; const f32x2 t = (x2 * 0.044715f + 1.0f) * (x * -2.302208198144325f); f32x2 e; e.x = __builtin_amdgcn_exp2f(t.x); e.y = __builtin_amdgcn_exp2f(t.y); e = e + 1.0f; f32x2 r; r.x = __builtin_amdgcn_rcpf(e.x); r.y = __builtin_amd ...
;     __device__ __forceinline__ void operator()(const pg8::f32x4 (&acc)[2][2][4][2], const pg8::Unit& u, int wr, int wc, int fr, int fq) const {
;     ...
;                     if (pn < 12) {
;                         const int seg = pn >> 2, cc = (pn & 3) * 256 + cl;
;                         if (seg < 2) {
; #pragma unroll
;                             for (int e = 0; e < 8; e += 2) { const f32x2 g2 = gelu_pk((f32x2){v[e], v[e + 1]}); v[e] = g2.x; v[e + 1] = g2.y; }
;                         } else {
; #pragma unroll
;                             for (int e = 0; e < 8; e += 2) { const f32x2 g2 = silu_pk((f32x2){v[e], v[e + 1]}); v[e] = g2.x; v[e + 1] = g2.y; }
;                         }
;                         bf16* base = (bf16*)(ws + (seg == 0 ? WS_UA : seg == 1 ? WS_VA : WS_ZA));
;                         st_bf16(base + (size_t)r * 1024 + cc, v);
.LBB0_2208:
	s_andn2_b64 vcc, exec, s[16:17]
	s_mov_b64 s[6:7], -1
	s_cbranch_vccnz .LBB0_2210
	v_mul_f32_e64 v86, v62, s50
	v_mul_f32_e64 v87, v63, s50
	v_mul_f32_e64 v84, v60, s50
	v_mul_f32_e64 v85, v61, s50
	v_exp_f32_e32 v86, v86
	v_exp_f32_e32 v87, v87
	v_mul_f32_e64 v88, v56, s50
	v_mul_f32_e64 v89, v57, s50
	v_exp_f32_e32 v84, v84
	v_exp_f32_e32 v85, v85
	v_exp_f32_e32 v88, v88
	v_exp_f32_e32 v89, v89
	v_add_f32_e64 v86, v86, 1.0
	v_add_f32_e64 v87, v87, 1.0
	v_add_f32_e64 v84, v84, 1.0
	v_add_f32_e64 v85, v85, 1.0
	v_rcp_f32_e32 v90, v86
	v_rcp_f32_e32 v91, v87
	v_add_f32_e64 v86, v88, 1.0
	v_add_f32_e64 v87, v89, 1.0
	v_rcp_f32_e32 v84, v84
	v_rcp_f32_e32 v85, v85
	v_rcp_f32_e32 v88, v86
	v_rcp_f32_e32 v89, v87
	s_mov_b64 s[6:7], 0
	v_mul_f32_e64 v86, v60, v84
	v_mul_f32_e64 v87, v61, v85
	v_mul_f32_e64 v84, v62, v90
	v_mul_f32_e64 v85, v63, v91
	v_mul_f32_e64 v88, v56, v88
	v_mul_f32_e64 v89, v57, v89
	v_mul_f32_e64 v90, v58, s50
	v_mul_f32_e64 v91, v59, s50
.LBB0_2210:
	s_andn2_b64 vcc, exec, s[6:7]
	s_cbranch_vccnz .LBB0_2212
	v_mul_f32_e64 v86, v60, v60
	v_mul_f32_e64 v87, v61, v61
	v_mul_f32_e64 v88, v60, s58
	v_mul_f32_e64 v89, v61, s58
	v_fma_f32 v86, v86, s56, 1.0
	v_fma_f32 v87, v87, s56, 1.0
	v_mul_f32_e64 v84, v62, v62
	v_mul_f32_e64 v85, v63, v63
	v_mul_f32_e64 v86, v88, v86
	v_mul_f32_e64 v87, v89, v87
	v_mul_f32_e64 v88, v56, s58
	v_mul_f32_e64 v89, v57, s58
	v_exp_f32_e32 v86, v86
	v_exp_f32_e32 v87, v87
	s_nop 0
	v_add_f32_e64 v86, v86, 1.0
	v_add_f32_e64 v87, v87, 1.0
	s_nop 0
	v_rcp_f32_e32 v86, v86
	v_rcp_f32_e32 v87, v87
	s_nop 0
	v_mul_f32_e64 v86, v60, v86
	v_mul_f32_e64 v87, v61, v87
	v_fma_f32 v60, v84, s56, 1.0
	v_fma_f32 v61, v85, s56, 1.0
	v_mul_f32_e64 v84, v62, s58
	v_mul_f32_e64 v85, v63, s58
	s_nop 0
	v_mul_f32_e64 v60, v84, v60
	v_mul_f32_e64 v61, v85, v61
	s_nop 0
	v_exp_f32_e32 v60, v60
	v_exp_f32_e32 v61, v61
	s_nop 0
	v_add_f32_e64 v60, v60, 1.0
	v_add_f32_e64 v61, v61, 1.0
	s_nop 0
	v_rcp_f32_e32 v60, v60
	v_rcp_f32_e32 v61, v61
	s_nop 0
	v_mul_f32_e64 v84, v62, v60
	v_mul_f32_e64 v85, v63, v61
	v_mul_f32_e64 v62, v56, v56
	v_mul_f32_e64 v63, v57, v57
	v_mul_f32_e64 v60, v58, v58
	v_mul_f32_e64 v61, v59, v59
	v_fma_f32 v62, v62, s56, 1.0
	v_fma_f32 v63, v63, s56, 1.0
	s_nop 0
	v_mul_f32_e64 v62, v88, v62
	v_mul_f32_e64 v63, v89, v63
	s_nop 0
	v_exp_f32_e32 v62, v62
	v_exp_f32_e32 v63, v63
	s_nop 0
	v_add_f32_e64 v62, v62, 1.0
	v_add_f32_e64 v63, v63, 1.0
	s_nop 0
	v_rcp_f32_e32 v62, v62
	v_rcp_f32_e32 v63, v63
	s_nop 0
	v_mul_f32_e64 v88, v56, v62
	v_mul_f32_e64 v89, v57, v63
	v_fma_f32 v56, v60, s56, 1.0
	v_fma_f32 v57, v61, s56, 1.0
	v_mul_f32_e64 v60, v58, s58
	v_mul_f32_e64 v61, v59, s58
	s_nop 0
	v_mul_f32_e64 v90, v60, v56
	v_mul_f32_e64 v91, v61, v57
.LBB0_2212:
	s_nop 0
	v_exp_f32_e32 v56, v90
	v_exp_f32_e32 v57, v91
	v_or_b32_e32 v62, s24, v140
	v_lshlrev_b32_e32 v136, 1, v62
	v_lshl_add_u64 v[62:63], v[80:81], 0, v[136:137]
	v_add_f32_e64 v56, v56, 1.0
	v_add_f32_e64 v57, v57, 1.0
	s_nop 0
	v_rcp_f32_e32 v56, v56
	v_rcp_f32_e32 v57, v57
	s_nop 0
	v_mul_f32_e64 v60, v58, v56
	v_mul_f32_e64 v61, v59, v57
	v_cvt_pk_bf16_f32 v56, v86, v87
	v_cvt_pk_bf16_f32 v57, v84, v85
	v_cvt_pk_bf16_f32 v58, v88, v89
	s_nop 0
	v_cvt_pk_bf16_f32 v59, v60, v61
	global_store_dwordx4 v[62:63], v[56:59], off
	s_and_b64 vcc, exec, s[10:11]
	s_mov_b64 s[4:5], -1
	s_cbranch_vccz .LBB0_2178

; __device__ __forceinline__ f32x2 silu_pk(f32x2 x) { const f32x2 t = x * -1.4426950408889634f; f32x2 e; e.x = __builtin_amdgcn_exp2f(t.x); e.y = __builtin_amdgcn_exp2f(t.y); e = e + 1.0f; f32x2 r; r.x = __builtin_amdgcn_rcpf(e.x); r.y = __builtin_amdgcn_rcpf(e.y); return x * r; }
; __device__ __forceinline__ f32x2 gelu_pk(f32x2 x) { const f32x2 x2 = x * x; const f32x2 t = (x2 * 0.044715f + 1.0f) * (x * -2.302208198144325f); f32x2 e; e.x = __builtin_amdgcn_exp2f(t.x); e.y = __builtin_amdgcn_exp2f(t.y); e = e + 1.0f; f32x2 r; r.x = __builtin_amdgcn_rcpf(e.x); r.y = __builtin_amd ...
;     __device__ __forceinline__ void operator()(const pg8::f32x4 (&acc)[2][2][4][2], const pg8::Unit& u, int wr, int wc, int fr, int fq) const {
;     ...
;                     if (pn < 12) {
;                         const int seg = pn >> 2, cc = (pn & 3) * 256 + cl;
;                         if (seg < 2) {
; #pragma unroll
;                             for (int e = 0; e < 8; e += 2) { const f32x2 g2 = gelu_pk((f32x2){v[e], v[e + 1]}); v[e] = g2.x; v[e + 1] = g2.y; }
;                         } else {
; #pragma unroll
;                             for (int e = 0; e < 8; e += 2) { const f32x2 g2 = silu_pk((f32x2){v[e], v[e + 1]}); v[e] = g2.x; v[e + 1] = g2.y; }
;                         }
;                         bf16* base = (bf16*)(ws + (seg == 0 ? WS_UA : seg == 1 ? WS_VA : WS_ZA));
;                         st_bf16(base + (size_t)r * 1024 + cc, v);
.LBB0_2214:
	s_andn2_b64 vcc, exec, s[16:17]
	s_mov_b64 s[0:1], -1
	s_cbranch_vccnz .LBB0_2216
	v_mul_f32_e64 v56, v52, s50
	v_mul_f32_e64 v57, v53, s50
	v_mul_f32_e64 v58, v54, s50
	v_mul_f32_e64 v59, v55, s50
	v_mul_f32_e64 v60, v48, s50
	v_mul_f32_e64 v61, v49, s50
	v_exp_f32_e32 v56, v56
	v_exp_f32_e32 v57, v57
	v_exp_f32_e32 v58, v58
	v_exp_f32_e32 v59, v59
	v_exp_f32_e32 v60, v60
	v_exp_f32_e32 v61, v61
	v_add_f32_e64 v56, v56, 1.0
	v_add_f32_e64 v57, v57, 1.0
	v_add_f32_e64 v58, v58, 1.0
	v_add_f32_e64 v59, v59, 1.0
	v_rcp_f32_e32 v56, v56
	v_add_f32_e64 v60, v60, 1.0
	v_add_f32_e64 v61, v61, 1.0
	v_rcp_f32_e32 v57, v57
	v_rcp_f32_e32 v58, v58
	v_rcp_f32_e32 v59, v59
	v_rcp_f32_e32 v60, v60
	v_rcp_f32_e32 v61, v61
	v_mul_f32_e64 v56, v52, v56
	v_mul_f32_e64 v57, v53, v57
	v_mul_f32_e64 v58, v54, v58
	v_mul_f32_e64 v59, v55, v59
	v_mul_f32_e64 v62, v50, s50
	v_mul_f32_e64 v63, v51, s50
	v_mul_f32_e64 v60, v48, v60
	v_mul_f32_e64 v61, v49, v61
	s_mov_b64 s[0:1], 0
.LBB0_2216:
	s_andn2_b64 vcc, exec, s[0:1]
	s_cbranch_vccnz .LBB0_2218
	v_mul_f32_e64 v56, v52, v52
	v_mul_f32_e64 v57, v53, v53
	v_mul_f32_e64 v60, v52, s58
	v_mul_f32_e64 v61, v53, s58
	v_fma_f32 v56, v56, s56, 1.0
	v_fma_f32 v57, v57, s56, 1.0
	v_mul_f32_e64 v58, v54, v54
	v_mul_f32_e64 v59, v55, v55
	v_mul_f32_e64 v56, v60, v56
	v_mul_f32_e64 v57, v61, v57
	v_mul_f32_e64 v60, v48, s58
	v_mul_f32_e64 v61, v49, s58
	v_exp_f32_e32 v56, v56
	v_exp_f32_e32 v57, v57
	s_nop 0
	v_add_f32_e64 v56, v56, 1.0
	v_add_f32_e64 v57, v57, 1.0
	s_nop 0
	v_rcp_f32_e32 v56, v56
	v_rcp_f32_e32 v57, v57
	s_nop 0
	v_mul_f32_e64 v56, v52, v56
	v_mul_f32_e64 v57, v53, v57
	v_fma_f32 v52, v58, s56, 1.0
	v_fma_f32 v53, v59, s56, 1.0
	v_mul_f32_e64 v58, v54, s58
	v_mul_f32_e64 v59, v55, s58
	s_nop 0
	v_mul_f32_e64 v52, v58, v52
	v_mul_f32_e64 v53, v59, v53
	s_nop 0
	v_exp_f32_e32 v52, v52
	v_exp_f32_e32 v53, v53
	s_nop 0
	v_add_f32_e64 v52, v52, 1.0
	v_add_f32_e64 v53, v53, 1.0
	s_nop 0
	v_rcp_f32_e32 v52, v52
	v_rcp_f32_e32 v53, v53
	s_nop 0
	v_mul_f32_e64 v58, v54, v52
	v_mul_f32_e64 v59, v55, v53
	v_mul_f32_e64 v54, v48, v48
	v_mul_f32_e64 v55, v49, v49
	v_mul_f32_e64 v52, v50, v50
	v_mul_f32_e64 v53, v51, v51
	v_fma_f32 v54, v54, s56, 1.0
	v_fma_f32 v55, v55, s56, 1.0
	s_nop 0
	v_mul_f32_e64 v54, v60, v54
	v_mul_f32_e64 v55, v61, v55
	s_nop 0
	v_exp_f32_e32 v54, v54
	v_exp_f32_e32 v55, v55
	s_nop 0
	v_add_f32_e64 v54, v54, 1.0
	v_add_f32_e64 v55, v55, 1.0
	s_nop 0
	v_rcp_f32_e32 v54, v54
	v_rcp_f32_e32 v55, v55
	s_nop 0
	v_mul_f32_e64 v60, v48, v54
	v_mul_f32_e64 v61, v49, v55
	v_fma_f32 v48, v52, s56, 1.0
	v_fma_f32 v49, v53, s56, 1.0
	v_mul_f32_e64 v52, v50, s58
	v_mul_f32_e64 v53, v51, s58
	s_nop 0
	v_mul_f32_e64 v62, v52, v48
	v_mul_f32_e64 v63, v53, v49
.LBB0_2218:
	s_nop 0
	v_exp_f32_e32 v48, v62
	v_exp_f32_e32 v49, v63
	v_add_lshl_u32 v136, s24, v140, 1
	v_lshl_add_u64 v[54:55], v[80:81], 0, v[136:137]
	v_add_f32_e64 v48, v48, 1.0
	v_add_f32_e64 v49, v49, 1.0
	s_nop 0
	v_rcp_f32_e32 v48, v48
	v_rcp_f32_e32 v49, v49
	s_nop 0
	v_mul_f32_e64 v52, v50, v48
	v_mul_f32_e64 v53, v51, v49
	v_cvt_pk_bf16_f32 v48, v56, v57
	v_cvt_pk_bf16_f32 v49, v58, v59
	v_cvt_pk_bf16_f32 v50, v60, v61
	s_nop 0
	v_cvt_pk_bf16_f32 v51, v52, v53
	global_store_dwordx4 v[54:55], v[48:51], off offset:256

; __device__ __forceinline__ f32x2 silu_pk(f32x2 x) { const f32x2 t = x * -1.4426950408889634f; f32x2 e; e.x = __builtin_amdgcn_exp2f(t.x); e.y = __builtin_amdgcn_exp2f(t.y); e = e + 1.0f; f32x2 r; r.x = __builtin_amdgcn_rcpf(e.x); r.y = __builtin_amdgcn_rcpf(e.y); return x * r; }
;     __device__ __forceinline__ void operator()(const pg8::f32x4 (&acc)[2][2][4][2], const pg8::Unit& u, int wr, int wc, int fr, int fq) const {
;     ...
;                     } else if (pn < 44) {
; #pragma unroll
;                         for (int e = 0; e < 8; e += 2) { const f32x2 g2 = silu_pk((f32x2){v[e], v[e + 1]}); v[e] = g2.x; v[e + 1] = g2.y; }
;                         st_bf16((bf16*)(ws + WS_ZB) + (size_t)r * 2048 + (pn - 36) * 256 + cl, v);
;                     } else if (pn < 48) {
;                         st_bf16((bf16*)(ws + WS_QC) + (size_t)r * 1024 + (pn - 44) * 256 + cl, v);
;                     } else if (pn < 50) {
;                         const bool isv = pn == 49;
;                         st_bf16((bf16*)(ws + (isv ? WS_VC : WS_KC)) + (size_t)r * 256 + cl, v);
;                         if (r < PT) st_f32(out + (isv ? O_PV : O_PK) + ((size_t)l * PT + r) * 256 + cl, v);
;                         else st_f32(out + (isv ? O_SV : O_SK) + ((size_t)l * ST + (r - PT)) * 256 + cl, v);
;                     } else if (pn < 54) {
; #pragma unroll
;                         for (int e = 0; e < 8; e += 2) { const f32x2 g2 = silu_pk((f32x2){v[e], v[e + 1]}); v[e] = g2.x; v[e + 1] = g2.y; }
;                         st_bf16((bf16*)(ws + WS_ZC) + (size_t)r * 1024 + (pn - 50) * 256 + cl, v);
.LBB0_2245:
	s_andn2_b64 vcc, exec, s[4:5]
	s_cbranch_vccnz .LBB0_2247
	v_mul_f32_e64 v68, v44, s50
	v_mul_f32_e64 v69, v45, s50
	v_mul_f32_e64 v70, v46, s50
	v_mul_f32_e64 v71, v47, s50
	v_exp_f32_e32 v68, v68
	v_exp_f32_e32 v69, v69
	v_exp_f32_e32 v70, v70
	v_exp_f32_e32 v71, v71
	v_mul_f32_e64 v72, v40, s50
	v_mul_f32_e64 v73, v41, s50
	v_mul_f32_e64 v74, v42, s50
	v_mul_f32_e64 v75, v43, s50
	v_exp_f32_e32 v72, v72
	v_exp_f32_e32 v73, v73
	v_exp_f32_e32 v74, v74
	v_exp_f32_e32 v75, v75
	v_add_f32_e64 v68, v68, 1.0
	v_add_f32_e64 v69, v69, 1.0
	v_add_f32_e64 v70, v70, 1.0
	v_add_f32_e64 v71, v71, 1.0
	v_rcp_f32_e32 v68, v68
	v_rcp_f32_e32 v69, v69
	v_rcp_f32_e32 v70, v70
	v_rcp_f32_e32 v71, v71
	v_add_f32_e64 v72, v72, 1.0
	v_add_f32_e64 v73, v73, 1.0
	v_add_f32_e64 v74, v74, 1.0
	v_add_f32_e64 v75, v75, 1.0
	v_rcp_f32_e32 v72, v72
	v_rcp_f32_e32 v73, v73
	v_rcp_f32_e32 v74, v74
	v_rcp_f32_e32 v75, v75
	v_lshlrev_b32_e32 v136, 1, v140
	v_mul_f32_e64 v68, v44, v68
	v_mul_f32_e64 v69, v45, v69
	v_mul_f32_e64 v70, v46, v70
	v_mul_f32_e64 v71, v47, v71
	v_lshl_add_u64 v[76:77], v[60:61], 0, v[136:137]
	v_mul_f32_e64 v72, v40, v72
	v_mul_f32_e64 v73, v41, v73
	v_mul_f32_e64 v74, v42, v74
	v_mul_f32_e64 v75, v43, v75
	v_cvt_pk_bf16_f32 v68, v68, v69
	v_cvt_pk_bf16_f32 v69, v70, v71
	v_cvt_pk_bf16_f32 v70, v72, v73
	s_nop 0
	v_cvt_pk_bf16_f32 v71, v74, v75
	global_store_dwordx4 v[76:77], v[68:71], off

; __device__ __forceinline__ f32x2 silu_pk(f32x2 x) { const f32x2 t = x * -1.4426950408889634f; f32x2 e; e.x = __builtin_amdgcn_exp2f(t.x); e.y = __builtin_amdgcn_exp2f(t.y); e = e + 1.0f; f32x2 r; r.x = __builtin_amdgcn_rcpf(e.x); r.y = __builtin_amdgcn_rcpf(e.y); return x * r; }
;     __device__ __forceinline__ void operator()(const pg8::f32x4 (&acc)[2][2][4][2], const pg8::Unit& u, int wr, int wc, int fr, int fq) const {
;     ...
;                     } else if (pn < 44) {
; #pragma unroll
;                         for (int e = 0; e < 8; e += 2) { const f32x2 g2 = silu_pk((f32x2){v[e], v[e + 1]}); v[e] = g2.x; v[e + 1] = g2.y; }
;                         st_bf16((bf16*)(ws + WS_ZB) + (size_t)r * 2048 + (pn - 36) * 256 + cl, v);
;                     } else if (pn < 48) {
;                         st_bf16((bf16*)(ws + WS_QC) + (size_t)r * 1024 + (pn - 44) * 256 + cl, v);
;                     } else if (pn < 50) {
;                         const bool isv = pn == 49;
;                         st_bf16((bf16*)(ws + (isv ? WS_VC : WS_KC)) + (size_t)r * 256 + cl, v);
;                         if (r < PT) st_f32(out + (isv ? O_PV : O_PK) + ((size_t)l * PT + r) * 256 + cl, v);
;                         else st_f32(out + (isv ? O_SV : O_SK) + ((size_t)l * ST + (r - PT)) * 256 + cl, v);
;                     } else if (pn < 54) {
; #pragma unroll
;                         for (int e = 0; e < 8; e += 2) { const f32x2 g2 = silu_pk((f32x2){v[e], v[e + 1]}); v[e] = g2.x; v[e + 1] = g2.y; }
;                         st_bf16((bf16*)(ws + WS_ZC) + (size_t)r * 1024 + (pn - 50) * 256 + cl, v);
.LBB0_2258:
	s_andn2_b64 vcc, exec, s[4:5]
	s_cbranch_vccnz .LBB0_2260
	v_mul_f32_e64 v68, v44, s50
	v_mul_f32_e64 v69, v45, s50
	v_mul_f32_e64 v70, v46, s50
	v_mul_f32_e64 v71, v47, s50
	v_exp_f32_e32 v68, v68
	v_exp_f32_e32 v69, v69
	v_exp_f32_e32 v70, v70
	v_exp_f32_e32 v71, v71
	v_mul_f32_e64 v72, v40, s50
	v_mul_f32_e64 v73, v41, s50
	v_mul_f32_e64 v74, v42, s50
	v_mul_f32_e64 v75, v43, s50
	v_exp_f32_e32 v72, v72
	v_exp_f32_e32 v73, v73
	v_exp_f32_e32 v74, v74
	v_exp_f32_e32 v75, v75
	v_add_f32_e64 v68, v68, 1.0
	v_add_f32_e64 v69, v69, 1.0
	v_add_f32_e64 v70, v70, 1.0
	v_add_f32_e64 v71, v71, 1.0
	v_rcp_f32_e32 v68, v68
	v_rcp_f32_e32 v69, v69
	v_rcp_f32_e32 v70, v70
	v_rcp_f32_e32 v71, v71
	v_add_f32_e64 v72, v72, 1.0
	v_add_f32_e64 v73, v73, 1.0
	v_add_f32_e64 v74, v74, 1.0
	v_add_f32_e64 v75, v75, 1.0
	v_rcp_f32_e32 v72, v72
	v_rcp_f32_e32 v73, v73
	v_rcp_f32_e32 v74, v74
	v_rcp_f32_e32 v75, v75
	v_lshlrev_b32_e32 v136, 1, v140
	v_mul_f32_e64 v68, v44, v68
	v_mul_f32_e64 v69, v45, v69
	v_mul_f32_e64 v70, v46, v70
	v_mul_f32_e64 v71, v47, v71
	v_lshl_add_u64 v[76:77], v[50:51], 0, v[136:137]
	v_mul_f32_e64 v72, v40, v72
	v_mul_f32_e64 v73, v41, v73
	v_mul_f32_e64 v74, v42, v74
	v_mul_f32_e64 v75, v43, v75
	v_cvt_pk_bf16_f32 v68, v68, v69
	v_cvt_pk_bf16_f32 v69, v70, v71
	v_cvt_pk_bf16_f32 v70, v72, v73
	s_nop 0
	v_cvt_pk_bf16_f32 v71, v74, v75
	global_store_dwordx4 v[76:77], v[68:71], off

; __device__ __forceinline__ f32x2 silu_pk(f32x2 x) { const f32x2 t = x * -1.4426950408889634f; f32x2 e; e.x = __builtin_amdgcn_exp2f(t.x); e.y = __builtin_amdgcn_exp2f(t.y); e = e + 1.0f; f32x2 r; r.x = __builtin_amdgcn_rcpf(e.x); r.y = __builtin_amdgcn_rcpf(e.y); return x * r; }
;     __device__ __forceinline__ void operator()(const pg8::f32x4 (&acc)[2][2][4][2], const pg8::Unit& u, int wr, int wc, int fr, int fq) const {
;     ...
;                     } else if (pn < 44) {
; #pragma unroll
;                         for (int e = 0; e < 8; e += 2) { const f32x2 g2 = silu_pk((f32x2){v[e], v[e + 1]}); v[e] = g2.x; v[e + 1] = g2.y; }
;                         st_bf16((bf16*)(ws + WS_ZB) + (size_t)r * 2048 + (pn - 36) * 256 + cl, v);
;                     } else if (pn < 48) {
;                         st_bf16((bf16*)(ws + WS_QC) + (size_t)r * 1024 + (pn - 44) * 256 + cl, v);
;                     } else if (pn < 50) {
;                         const bool isv = pn == 49;
;                         st_bf16((bf16*)(ws + (isv ? WS_VC : WS_KC)) + (size_t)r * 256 + cl, v);
;                         if (r < PT) st_f32(out + (isv ? O_PV : O_PK) + ((size_t)l * PT + r) * 256 + cl, v);
;                         else st_f32(out + (isv ? O_SV : O_SK) + ((size_t)l * ST + (r - PT)) * 256 + cl, v);
;                     } else if (pn < 54) {
; #pragma unroll
;                         for (int e = 0; e < 8; e += 2) { const f32x2 g2 = silu_pk((f32x2){v[e], v[e + 1]}); v[e] = g2.x; v[e + 1] = g2.y; }
;                         st_bf16((bf16*)(ws + WS_ZC) + (size_t)r * 1024 + (pn - 50) * 256 + cl, v);
.LBB0_2275:
	s_andn2_b64 vcc, exec, s[4:5]
	s_cbranch_vccnz .LBB0_2277
	v_mul_f32_e64 v40, v36, s50
	v_mul_f32_e64 v41, v37, s50
	v_mul_f32_e64 v42, v38, s50
	v_mul_f32_e64 v43, v39, s50
	v_exp_f32_e32 v40, v40
	v_exp_f32_e32 v41, v41
	v_exp_f32_e32 v42, v42
	v_exp_f32_e32 v43, v43
	v_mul_f32_e64 v44, v32, s50
	v_mul_f32_e64 v45, v33, s50
	v_mul_f32_e64 v46, v34, s50
	v_mul_f32_e64 v47, v35, s50
	v_exp_f32_e32 v44, v44
	v_exp_f32_e32 v45, v45
	v_exp_f32_e32 v46, v46
	v_exp_f32_e32 v47, v47
	v_add_f32_e64 v40, v40, 1.0
	v_add_f32_e64 v41, v41, 1.0
	v_add_f32_e64 v42, v42, 1.0
	v_add_f32_e64 v43, v43, 1.0
	v_rcp_f32_e32 v40, v40
	v_rcp_f32_e32 v41, v41
	v_rcp_f32_e32 v42, v42
	v_rcp_f32_e32 v43, v43
	v_add_f32_e64 v44, v44, 1.0
	v_add_f32_e64 v45, v45, 1.0
	v_add_f32_e64 v46, v46, 1.0
	v_add_f32_e64 v47, v47, 1.0
	v_rcp_f32_e32 v44, v44
	v_rcp_f32_e32 v45, v45
	v_rcp_f32_e32 v46, v46
	v_rcp_f32_e32 v47, v47
	v_lshlrev_b32_e32 v136, 1, v142
	v_mul_f32_e64 v40, v36, v40
	v_mul_f32_e64 v41, v37, v41
	v_mul_f32_e64 v42, v38, v42
	v_mul_f32_e64 v43, v39, v43
	v_lshl_add_u64 v[60:61], v[60:61], 0, v[136:137]
	v_mul_f32_e64 v44, v32, v44
	v_mul_f32_e64 v45, v33, v45
	v_mul_f32_e64 v46, v34, v46
	v_mul_f32_e64 v47, v35, v47
	v_cvt_pk_bf16_f32 v40, v40, v41
	v_cvt_pk_bf16_f32 v41, v42, v43
	v_cvt_pk_bf16_f32 v42, v44, v45
	s_nop 0
	v_cvt_pk_bf16_f32 v43, v46, v47
	global_store_dwordx4 v[60:61], v[40:43], off

; __device__ __forceinline__ f32x2 silu_pk(f32x2 x) { const f32x2 t = x * -1.4426950408889634f; f32x2 e; e.x = __builtin_amdgcn_exp2f(t.x); e.y = __builtin_amdgcn_exp2f(t.y); e = e + 1.0f; f32x2 r; r.x = __builtin_amdgcn_rcpf(e.x); r.y = __builtin_amdgcn_rcpf(e.y); return x * r; }
;     __device__ __forceinline__ void operator()(const pg8::f32x4 (&acc)[2][2][4][2], const pg8::Unit& u, int wr, int wc, int fr, int fq) const {
;     ...
;                     } else if (pn < 44) {
; #pragma unroll
;                         for (int e = 0; e < 8; e += 2) { const f32x2 g2 = silu_pk((f32x2){v[e], v[e + 1]}); v[e] = g2.x; v[e + 1] = g2.y; }
;                         st_bf16((bf16*)(ws + WS_ZB) + (size_t)r * 2048 + (pn - 36) * 256 + cl, v);
;                     } else if (pn < 48) {
;                         st_bf16((bf16*)(ws + WS_QC) + (size_t)r * 1024 + (pn - 44) * 256 + cl, v);
;                     } else if (pn < 50) {
;                         const bool isv = pn == 49;
;                         st_bf16((bf16*)(ws + (isv ? WS_VC : WS_KC)) + (size_t)r * 256 + cl, v);
;                         if (r < PT) st_f32(out + (isv ? O_PV : O_PK) + ((size_t)l * PT + r) * 256 + cl, v);
;                         else st_f32(out + (isv ? O_SV : O_SK) + ((size_t)l * ST + (r - PT)) * 256 + cl, v);
;                     } else if (pn < 54) {
; #pragma unroll
;                         for (int e = 0; e < 8; e += 2) { const f32x2 g2 = silu_pk((f32x2){v[e], v[e + 1]}); v[e] = g2.x; v[e + 1] = g2.y; }
;                         st_bf16((bf16*)(ws + WS_ZC) + (size_t)r * 1024 + (pn - 50) * 256 + cl, v);
.LBB0_2288:
	s_andn2_b64 vcc, exec, s[4:5]
	s_cbranch_vccnz .LBB0_2290
	v_mul_f32_e64 v40, v36, s50
	v_mul_f32_e64 v41, v37, s50
	v_mul_f32_e64 v42, v38, s50
	v_mul_f32_e64 v43, v39, s50
	v_exp_f32_e32 v40, v40
	v_exp_f32_e32 v41, v41
	v_exp_f32_e32 v42, v42
	v_exp_f32_e32 v43, v43
	v_mul_f32_e64 v44, v32, s50
	v_mul_f32_e64 v45, v33, s50
	v_mul_f32_e64 v46, v34, s50
	v_mul_f32_e64 v47, v35, s50
	v_exp_f32_e32 v44, v44
	v_exp_f32_e32 v45, v45
	v_exp_f32_e32 v46, v46
	v_exp_f32_e32 v47, v47
	v_add_f32_e64 v40, v40, 1.0
	v_add_f32_e64 v41, v41, 1.0
	v_add_f32_e64 v42, v42, 1.0
	v_add_f32_e64 v43, v43, 1.0
	v_rcp_f32_e32 v40, v40
	v_rcp_f32_e32 v41, v41
	v_rcp_f32_e32 v42, v42
	v_rcp_f32_e32 v43, v43
	v_add_f32_e64 v44, v44, 1.0
	v_add_f32_e64 v45, v45, 1.0
	v_add_f32_e64 v46, v46, 1.0
	v_add_f32_e64 v47, v47, 1.0
	v_rcp_f32_e32 v44, v44
	v_rcp_f32_e32 v45, v45
	v_rcp_f32_e32 v46, v46
	v_rcp_f32_e32 v47, v47
	v_lshlrev_b32_e32 v136, 1, v142
	v_mul_f32_e64 v40, v36, v40
	v_mul_f32_e64 v41, v37, v41
	v_mul_f32_e64 v42, v38, v42
	v_mul_f32_e64 v43, v39, v43
	v_lshl_add_u64 v[50:51], v[50:51], 0, v[136:137]
	v_mul_f32_e64 v44, v32, v44
	v_mul_f32_e64 v45, v33, v45
	v_mul_f32_e64 v46, v34, v46
	v_mul_f32_e64 v47, v35, v47
	v_cvt_pk_bf16_f32 v40, v40, v41
	v_cvt_pk_bf16_f32 v41, v42, v43
	v_cvt_pk_bf16_f32 v42, v44, v45
	s_nop 0
	v_cvt_pk_bf16_f32 v43, v46, v47
	global_store_dwordx4 v[50:51], v[40:43], off

; __device__ __forceinline__ f32x2 silu_pk(f32x2 x) { const f32x2 t = x * -1.4426950408889634f; f32x2 e; e.x = __builtin_amdgcn_exp2f(t.x); e.y = __builtin_amdgcn_exp2f(t.y); e = e + 1.0f; f32x2 r; r.x = __builtin_amdgcn_rcpf(e.x); r.y = __builtin_amdgcn_rcpf(e.y); return x * r; }
; __device__ __forceinline__ f32x2 gelu_pk(f32x2 x) { const f32x2 x2 = x * x; const f32x2 t = (x2 * 0.044715f + 1.0f) * (x * -2.302208198144325f); f32x2 e; e.x = __builtin_amdgcn_exp2f(t.x); e.y = __builtin_amdgcn_exp2f(t.y); e = e + 1.0f; f32x2 r; r.x = __builtin_amdgcn_rcpf(e.x); r.y = __builtin_amd ...
;     __device__ __forceinline__ void operator()(const pg8::f32x4 (&acc)[2][2][4][2], const pg8::Unit& u, int wr, int wc, int fr, int fq) const {
;     ...
;                     if (pn < 12) {
;                         const int seg = pn >> 2, cc = (pn & 3) * 256 + cl;
;                         if (seg < 2) {
; #pragma unroll
;                             for (int e = 0; e < 8; e += 2) { const f32x2 g2 = gelu_pk((f32x2){v[e], v[e + 1]}); v[e] = g2.x; v[e + 1] = g2.y; }
;                         } else {
; #pragma unroll
;                             for (int e = 0; e < 8; e += 2) { const f32x2 g2 = silu_pk((f32x2){v[e], v[e + 1]}); v[e] = g2.x; v[e + 1] = g2.y; }
;                         }
;                         bf16* base = (bf16*)(ws + (seg == 0 ? WS_UA : seg == 1 ? WS_VA : WS_ZA));
;                         st_bf16(base + (size_t)r * 1024 + cc, v);
.LBB0_2297:
	s_andn2_b64 vcc, exec, s[16:17]
	s_mov_b64 s[6:7], -1
	s_cbranch_vccnz .LBB0_2299
	v_mul_f32_e64 v70, v46, s50
	v_mul_f32_e64 v71, v47, s50
	v_mul_f32_e64 v68, v44, s50
	v_mul_f32_e64 v69, v45, s50
	v_exp_f32_e32 v70, v70
	v_exp_f32_e32 v71, v71
	v_mul_f32_e64 v72, v40, s50
	v_mul_f32_e64 v73, v41, s50
	v_exp_f32_e32 v68, v68
	v_exp_f32_e32 v69, v69
	v_exp_f32_e32 v72, v72
	v_exp_f32_e32 v73, v73
	v_add_f32_e64 v70, v70, 1.0
	v_add_f32_e64 v71, v71, 1.0
	v_add_f32_e64 v68, v68, 1.0
	v_add_f32_e64 v69, v69, 1.0
	v_rcp_f32_e32 v74, v70
	v_rcp_f32_e32 v75, v71
	v_add_f32_e64 v70, v72, 1.0
	v_add_f32_e64 v71, v73, 1.0
	v_rcp_f32_e32 v68, v68
	v_rcp_f32_e32 v69, v69
	v_rcp_f32_e32 v72, v70
	v_rcp_f32_e32 v73, v71
	s_mov_b64 s[6:7], 0
	v_mul_f32_e64 v70, v44, v68
	v_mul_f32_e64 v71, v45, v69
	v_mul_f32_e64 v68, v46, v74
	v_mul_f32_e64 v69, v47, v75
	v_mul_f32_e64 v72, v40, v72
	v_mul_f32_e64 v73, v41, v73
	v_mul_f32_e64 v74, v42, s50
	v_mul_f32_e64 v75, v43, s50
.LBB0_2299:
	s_andn2_b64 vcc, exec, s[6:7]
	s_cbranch_vccnz .LBB0_2301
	v_mul_f32_e64 v70, v44, v44
	v_mul_f32_e64 v71, v45, v45
	v_mul_f32_e64 v72, v44, s58
	v_mul_f32_e64 v73, v45, s58
	v_fma_f32 v70, v70, s56, 1.0
	v_fma_f32 v71, v71, s56, 1.0
	v_mul_f32_e64 v68, v46, v46
	v_mul_f32_e64 v69, v47, v47
	v_mul_f32_e64 v70, v72, v70
	v_mul_f32_e64 v71, v73, v71
	v_mul_f32_e64 v72, v40, s58
	v_mul_f32_e64 v73, v41, s58
	v_exp_f32_e32 v70, v70
	v_exp_f32_e32 v71, v71
	s_nop 0
	v_add_f32_e64 v70, v70, 1.0
	v_add_f32_e64 v71, v71, 1.0
	s_nop 0
	v_rcp_f32_e32 v70, v70
	v_rcp_f32_e32 v71, v71
	s_nop 0
	v_mul_f32_e64 v70, v44, v70
	v_mul_f32_e64 v71, v45, v71
	v_fma_f32 v44, v68, s56, 1.0
	v_fma_f32 v45, v69, s56, 1.0
	v_mul_f32_e64 v68, v46, s58
	v_mul_f32_e64 v69, v47, s58
	s_nop 0
	v_mul_f32_e64 v44, v68, v44
	v_mul_f32_e64 v45, v69, v45
	s_nop 0
	v_exp_f32_e32 v44, v44
	v_exp_f32_e32 v45, v45
	s_nop 0
	v_add_f32_e64 v44, v44, 1.0
	v_add_f32_e64 v45, v45, 1.0
	s_nop 0
	v_rcp_f32_e32 v44, v44
	v_rcp_f32_e32 v45, v45
	s_nop 0
	v_mul_f32_e64 v68, v46, v44
	v_mul_f32_e64 v69, v47, v45
	v_mul_f32_e64 v46, v40, v40
	v_mul_f32_e64 v47, v41, v41
	v_mul_f32_e64 v44, v42, v42
	v_mul_f32_e64 v45, v43, v43
	v_fma_f32 v46, v46, s56, 1.0
	v_fma_f32 v47, v47, s56, 1.0
	s_nop 0
	v_mul_f32_e64 v46, v72, v46
	v_mul_f32_e64 v47, v73, v47
	s_nop 0
	v_exp_f32_e32 v46, v46
	v_exp_f32_e32 v47, v47
	s_nop 0
	v_add_f32_e64 v46, v46, 1.0
	v_add_f32_e64 v47, v47, 1.0
	s_nop 0
	v_rcp_f32_e32 v46, v46
	v_rcp_f32_e32 v47, v47
	s_nop 0
	v_mul_f32_e64 v72, v40, v46
	v_mul_f32_e64 v73, v41, v47
	v_fma_f32 v40, v44, s56, 1.0
	v_fma_f32 v41, v45, s56, 1.0
	v_mul_f32_e64 v44, v42, s58
	v_mul_f32_e64 v45, v43, s58
	s_nop 0
	v_mul_f32_e64 v74, v44, v40
	v_mul_f32_e64 v75, v45, v41
.LBB0_2301:
	s_nop 0
	v_exp_f32_e32 v40, v74
	v_exp_f32_e32 v41, v75
	v_or_b32_e32 v46, s24, v140
	v_lshlrev_b32_e32 v136, 1, v46
	v_lshl_add_u64 v[46:47], v[62:63], 0, v[136:137]
	v_add_f32_e64 v40, v40, 1.0
	v_add_f32_e64 v41, v41, 1.0
	s_nop 0
	v_rcp_f32_e32 v40, v40
	v_rcp_f32_e32 v41, v41
	s_nop 0
	v_mul_f32_e64 v44, v42, v40
	v_mul_f32_e64 v45, v43, v41
	v_cvt_pk_bf16_f32 v40, v70, v71
	v_cvt_pk_bf16_f32 v41, v68, v69
	v_cvt_pk_bf16_f32 v42, v72, v73
	s_nop 0
	v_cvt_pk_bf16_f32 v43, v44, v45
	global_store_dwordx4 v[46:47], v[40:43], off
	s_and_b64 vcc, exec, s[10:11]
	s_mov_b64 s[4:5], -1
	s_cbranch_vccz .LBB0_2267

; __device__ __forceinline__ f32x2 silu_pk(f32x2 x) { const f32x2 t = x * -1.4426950408889634f; f32x2 e; e.x = __builtin_amdgcn_exp2f(t.x); e.y = __builtin_amdgcn_exp2f(t.y); e = e + 1.0f; f32x2 r; r.x = __builtin_amdgcn_rcpf(e.x); r.y = __builtin_amdgcn_rcpf(e.y); return x * r; }
; __device__ __forceinline__ f32x2 gelu_pk(f32x2 x) { const f32x2 x2 = x * x; const f32x2 t = (x2 * 0.044715f + 1.0f) * (x * -2.302208198144325f); f32x2 e; e.x = __builtin_amdgcn_exp2f(t.x); e.y = __builtin_amdgcn_exp2f(t.y); e = e + 1.0f; f32x2 r; r.x = __builtin_amdgcn_rcpf(e.x); r.y = __builtin_amd ...
;     __device__ __forceinline__ void operator()(const pg8::f32x4 (&acc)[2][2][4][2], const pg8::Unit& u, int wr, int wc, int fr, int fq) const {
;     ...
;                     if (pn < 12) {
;                         const int seg = pn >> 2, cc = (pn & 3) * 256 + cl;
;                         if (seg < 2) {
; #pragma unroll
;                             for (int e = 0; e < 8; e += 2) { const f32x2 g2 = gelu_pk((f32x2){v[e], v[e + 1]}); v[e] = g2.x; v[e + 1] = g2.y; }
;                         } else {
; #pragma unroll
;                             for (int e = 0; e < 8; e += 2) { const f32x2 g2 = silu_pk((f32x2){v[e], v[e + 1]}); v[e] = g2.x; v[e + 1] = g2.y; }
;                         }
;                         bf16* base = (bf16*)(ws + (seg == 0 ? WS_UA : seg == 1 ? WS_VA : WS_ZA));
;                         st_bf16(base + (size_t)r * 1024 + cc, v);
.LBB0_2303:
	s_andn2_b64 vcc, exec, s[16:17]
	s_mov_b64 s[0:1], -1
	s_cbranch_vccnz .LBB0_2305
	v_mul_f32_e64 v40, v36, s50
	v_mul_f32_e64 v41, v37, s50
	v_mul_f32_e64 v42, v38, s50
	v_mul_f32_e64 v43, v39, s50
	v_mul_f32_e64 v44, v32, s50
	v_mul_f32_e64 v45, v33, s50
	v_exp_f32_e32 v40, v40
	v_exp_f32_e32 v41, v41
	v_exp_f32_e32 v42, v42
	v_exp_f32_e32 v43, v43
	v_exp_f32_e32 v44, v44
	v_exp_f32_e32 v45, v45
	v_add_f32_e64 v40, v40, 1.0
	v_add_f32_e64 v41, v41, 1.0
	v_add_f32_e64 v42, v42, 1.0
	v_add_f32_e64 v43, v43, 1.0
	v_rcp_f32_e32 v40, v40
	v_add_f32_e64 v44, v44, 1.0
	v_add_f32_e64 v45, v45, 1.0
	v_rcp_f32_e32 v41, v41
	v_rcp_f32_e32 v42, v42
	v_rcp_f32_e32 v43, v43
	v_rcp_f32_e32 v44, v44
	v_rcp_f32_e32 v45, v45
	v_mul_f32_e64 v40, v36, v40
	v_mul_f32_e64 v41, v37, v41
	v_mul_f32_e64 v42, v38, v42
	v_mul_f32_e64 v43, v39, v43
	v_mul_f32_e64 v46, v34, s50
	v_mul_f32_e64 v47, v35, s50
	v_mul_f32_e64 v44, v32, v44
	v_mul_f32_e64 v45, v33, v45
	s_mov_b64 s[0:1], 0
.LBB0_2305:
	s_andn2_b64 vcc, exec, s[0:1]
	s_cbranch_vccnz .LBB0_2307
	v_mul_f32_e64 v40, v36, v36
	v_mul_f32_e64 v41, v37, v37
	v_mul_f32_e64 v44, v36, s58
	v_mul_f32_e64 v45, v37, s58
	v_fma_f32 v40, v40, s56, 1.0
	v_fma_f32 v41, v41, s56, 1.0
	v_mul_f32_e64 v42, v38, v38
	v_mul_f32_e64 v43, v39, v39
	v_mul_f32_e64 v40, v44, v40
	v_mul_f32_e64 v41, v45, v41
	v_mul_f32_e64 v44, v32, s58
	v_mul_f32_e64 v45, v33, s58
	v_exp_f32_e32 v40, v40
	v_exp_f32_e32 v41, v41
	s_nop 0
	v_add_f32_e64 v40, v40, 1.0
	v_add_f32_e64 v41, v41, 1.0
	s_nop 0
	v_rcp_f32_e32 v40, v40
	v_rcp_f32_e32 v41, v41
	s_nop 0
	v_mul_f32_e64 v40, v36, v40
	v_mul_f32_e64 v41, v37, v41
	v_fma_f32 v36, v42, s56, 1.0
	v_fma_f32 v37, v43, s56, 1.0
	v_mul_f32_e64 v42, v38, s58
	v_mul_f32_e64 v43, v39, s58
	s_nop 0
	v_mul_f32_e64 v36, v42, v36
	v_mul_f32_e64 v37, v43, v37
	s_nop 0
	v_exp_f32_e32 v36, v36
	v_exp_f32_e32 v37, v37
	s_nop 0
	v_add_f32_e64 v36, v36, 1.0
	v_add_f32_e64 v37, v37, 1.0
	s_nop 0
	v_rcp_f32_e32 v36, v36
	v_rcp_f32_e32 v37, v37
	s_nop 0
	v_mul_f32_e64 v42, v38, v36
	v_mul_f32_e64 v43, v39, v37
	v_mul_f32_e64 v38, v32, v32
	v_mul_f32_e64 v39, v33, v33
	v_mul_f32_e64 v36, v34, v34
	v_mul_f32_e64 v37, v35, v35
	v_fma_f32 v38, v38, s56, 1.0
	v_fma_f32 v39, v39, s56, 1.0
	s_nop 0
	v_mul_f32_e64 v38, v44, v38
	v_mul_f32_e64 v39, v45, v39
	s_nop 0
	v_exp_f32_e32 v38, v38
	v_exp_f32_e32 v39, v39
	s_nop 0
	v_add_f32_e64 v38, v38, 1.0
	v_add_f32_e64 v39, v39, 1.0
	s_nop 0
	v_rcp_f32_e32 v38, v38
	v_rcp_f32_e32 v39, v39
	s_nop 0
	v_mul_f32_e64 v44, v32, v38
	v_mul_f32_e64 v45, v33, v39
	v_fma_f32 v32, v36, s56, 1.0
	v_fma_f32 v33, v37, s56, 1.0
	v_mul_f32_e64 v36, v34, s58
	v_mul_f32_e64 v37, v35, s58
	s_nop 0
	v_mul_f32_e64 v46, v36, v32
	v_mul_f32_e64 v47, v37, v33
.LBB0_2307:
	s_nop 0
	v_exp_f32_e32 v32, v46
	v_exp_f32_e32 v33, v47
	v_add_lshl_u32 v136, s24, v140, 1
	v_lshl_add_u64 v[38:39], v[62:63], 0, v[136:137]
	v_add_f32_e64 v32, v32, 1.0
	v_add_f32_e64 v33, v33, 1.0
	s_nop 0
	v_rcp_f32_e32 v32, v32
	v_rcp_f32_e32 v33, v33
	s_nop 0
	v_mul_f32_e64 v36, v34, v32
	v_mul_f32_e64 v37, v35, v33
	v_cvt_pk_bf16_f32 v32, v40, v41
	v_cvt_pk_bf16_f32 v33, v42, v43
	v_cvt_pk_bf16_f32 v34, v44, v45
	s_nop 0
	v_cvt_pk_bf16_f32 v35, v36, v37
	global_store_dwordx4 v[38:39], v[32:35], off offset:256

; __device__ __forceinline__ f32x2 silu_pk(f32x2 x) { const f32x2 t = x * -1.4426950408889634f; f32x2 e; e.x = __builtin_amdgcn_exp2f(t.x); e.y = __builtin_amdgcn_exp2f(t.y); e = e + 1.0f; f32x2 r; r.x = __builtin_amdgcn_rcpf(e.x); r.y = __builtin_amdgcn_rcpf(e.y); return x * r; }
;     __device__ __forceinline__ void operator()(const pg8::f32x4 (&acc)[2][2][4][2], const pg8::Unit& u, int wr, int wc, int fr, int fq) const {
;     ...
;                     } else if (pn < 44) {
; #pragma unroll
;                         for (int e = 0; e < 8; e += 2) { const f32x2 g2 = silu_pk((f32x2){v[e], v[e + 1]}); v[e] = g2.x; v[e + 1] = g2.y; }
;                         st_bf16((bf16*)(ws + WS_ZB) + (size_t)r * 2048 + (pn - 36) * 256 + cl, v);
;                     } else if (pn < 48) {
;                         st_bf16((bf16*)(ws + WS_QC) + (size_t)r * 1024 + (pn - 44) * 256 + cl, v);
;                     } else if (pn < 50) {
;                         const bool isv = pn == 49;
;                         st_bf16((bf16*)(ws + (isv ? WS_VC : WS_KC)) + (size_t)r * 256 + cl, v);
;                         if (r < PT) st_f32(out + (isv ? O_PV : O_PK) + ((size_t)l * PT + r) * 256 + cl, v);
;                         else st_f32(out + (isv ? O_SV : O_SK) + ((size_t)l * ST + (r - PT)) * 256 + cl, v);
;                     } else if (pn < 54) {
; #pragma unroll
;                         for (int e = 0; e < 8; e += 2) { const f32x2 g2 = silu_pk((f32x2){v[e], v[e + 1]}); v[e] = g2.x; v[e + 1] = g2.y; }
;                         st_bf16((bf16*)(ws + WS_ZC) + (size_t)r * 1024 + (pn - 50) * 256 + cl, v);
.LBB0_2334:
	s_andn2_b64 vcc, exec, s[4:5]
	s_cbranch_vccnz .LBB0_2336
	v_mul_f32_e64 v50, v28, s50
	v_mul_f32_e64 v51, v29, s50
	v_mul_f32_e64 v52, v30, s50
	v_mul_f32_e64 v53, v31, s50
	v_exp_f32_e32 v50, v50
	v_exp_f32_e32 v51, v51
	v_exp_f32_e32 v52, v52
	v_exp_f32_e32 v53, v53
	v_mul_f32_e64 v54, v24, s50
	v_mul_f32_e64 v55, v25, s50
	v_mul_f32_e64 v56, v26, s50
	v_mul_f32_e64 v57, v27, s50
	v_exp_f32_e32 v54, v54
	v_exp_f32_e32 v55, v55
	v_exp_f32_e32 v56, v56
	v_exp_f32_e32 v57, v57
	v_add_f32_e64 v50, v50, 1.0
	v_add_f32_e64 v51, v51, 1.0
	v_add_f32_e64 v52, v52, 1.0
	v_add_f32_e64 v53, v53, 1.0
	v_rcp_f32_e32 v50, v50
	v_rcp_f32_e32 v51, v51
	v_rcp_f32_e32 v52, v52
	v_rcp_f32_e32 v53, v53
	v_add_f32_e64 v54, v54, 1.0
	v_add_f32_e64 v55, v55, 1.0
	v_add_f32_e64 v56, v56, 1.0
	v_add_f32_e64 v57, v57, 1.0
	v_rcp_f32_e32 v54, v54
	v_rcp_f32_e32 v55, v55
	v_rcp_f32_e32 v56, v56
	v_rcp_f32_e32 v57, v57
	v_lshlrev_b32_e32 v136, 1, v140
	v_mul_f32_e64 v50, v28, v50
	v_mul_f32_e64 v51, v29, v51
	v_mul_f32_e64 v52, v30, v52
	v_mul_f32_e64 v53, v31, v53
	v_lshl_add_u64 v[60:61], v[44:45], 0, v[136:137]
	v_mul_f32_e64 v54, v24, v54
	v_mul_f32_e64 v55, v25, v55
	v_mul_f32_e64 v56, v26, v56
	v_mul_f32_e64 v57, v27, v57
	v_cvt_pk_bf16_f32 v50, v50, v51
	v_cvt_pk_bf16_f32 v51, v52, v53
	v_cvt_pk_bf16_f32 v52, v54, v55
	s_nop 0
	v_cvt_pk_bf16_f32 v53, v56, v57
	global_store_dwordx4 v[60:61], v[50:53], off

; __device__ __forceinline__ f32x2 silu_pk(f32x2 x) { const f32x2 t = x * -1.4426950408889634f; f32x2 e; e.x = __builtin_amdgcn_exp2f(t.x); e.y = __builtin_amdgcn_exp2f(t.y); e = e + 1.0f; f32x2 r; r.x = __builtin_amdgcn_rcpf(e.x); r.y = __builtin_amdgcn_rcpf(e.y); return x * r; }
;     __device__ __forceinline__ void operator()(const pg8::f32x4 (&acc)[2][2][4][2], const pg8::Unit& u, int wr, int wc, int fr, int fq) const {
;     ...
;                     } else if (pn < 44) {
; #pragma unroll
;                         for (int e = 0; e < 8; e += 2) { const f32x2 g2 = silu_pk((f32x2){v[e], v[e + 1]}); v[e] = g2.x; v[e + 1] = g2.y; }
;                         st_bf16((bf16*)(ws + WS_ZB) + (size_t)r * 2048 + (pn - 36) * 256 + cl, v);
;                     } else if (pn < 48) {
;                         st_bf16((bf16*)(ws + WS_QC) + (size_t)r * 1024 + (pn - 44) * 256 + cl, v);
;                     } else if (pn < 50) {
;                         const bool isv = pn == 49;
;                         st_bf16((bf16*)(ws + (isv ? WS_VC : WS_KC)) + (size_t)r * 256 + cl, v);
;                         if (r < PT) st_f32(out + (isv ? O_PV : O_PK) + ((size_t)l * PT + r) * 256 + cl, v);
;                         else st_f32(out + (isv ? O_SV : O_SK) + ((size_t)l * ST + (r - PT)) * 256 + cl, v);
;                     } else if (pn < 54) {
; #pragma unroll
;                         for (int e = 0; e < 8; e += 2) { const f32x2 g2 = silu_pk((f32x2){v[e], v[e + 1]}); v[e] = g2.x; v[e + 1] = g2.y; }
;                         st_bf16((bf16*)(ws + WS_ZC) + (size_t)r * 1024 + (pn - 50) * 256 + cl, v);
.LBB0_2347:
	s_andn2_b64 vcc, exec, s[4:5]
	s_cbranch_vccnz .LBB0_2349
	v_mul_f32_e64 v50, v28, s50
	v_mul_f32_e64 v51, v29, s50
	v_mul_f32_e64 v52, v30, s50
	v_mul_f32_e64 v53, v31, s50
	v_exp_f32_e32 v50, v50
	v_exp_f32_e32 v51, v51
	v_exp_f32_e32 v52, v52
	v_exp_f32_e32 v53, v53
	v_mul_f32_e64 v54, v24, s50
	v_mul_f32_e64 v55, v25, s50
	v_mul_f32_e64 v56, v26, s50
	v_mul_f32_e64 v57, v27, s50
	v_exp_f32_e32 v54, v54
	v_exp_f32_e32 v55, v55
	v_exp_f32_e32 v56, v56
	v_exp_f32_e32 v57, v57
	v_add_f32_e64 v50, v50, 1.0
	v_add_f32_e64 v51, v51, 1.0
	v_add_f32_e64 v52, v52, 1.0
	v_add_f32_e64 v53, v53, 1.0
	v_rcp_f32_e32 v50, v50
	v_rcp_f32_e32 v51, v51
	v_rcp_f32_e32 v52, v52
	v_rcp_f32_e32 v53, v53
	v_add_f32_e64 v54, v54, 1.0
	v_add_f32_e64 v55, v55, 1.0
	v_add_f32_e64 v56, v56, 1.0
	v_add_f32_e64 v57, v57, 1.0
	v_rcp_f32_e32 v54, v54
	v_rcp_f32_e32 v55, v55
	v_rcp_f32_e32 v56, v56
	v_rcp_f32_e32 v57, v57
	v_lshlrev_b32_e32 v136, 1, v140
	v_mul_f32_e64 v50, v28, v50
	v_mul_f32_e64 v51, v29, v51
	v_mul_f32_e64 v52, v30, v52
	v_mul_f32_e64 v53, v31, v53
	v_lshl_add_u64 v[60:61], v[34:35], 0, v[136:137]
	v_mul_f32_e64 v54, v24, v54
	v_mul_f32_e64 v55, v25, v55
	v_mul_f32_e64 v56, v26, v56
	v_mul_f32_e64 v57, v27, v57
	v_cvt_pk_bf16_f32 v50, v50, v51
	v_cvt_pk_bf16_f32 v51, v52, v53
	v_cvt_pk_bf16_f32 v52, v54, v55
	s_nop 0
	v_cvt_pk_bf16_f32 v53, v56, v57
	global_store_dwordx4 v[60:61], v[50:53], off

; __device__ __forceinline__ f32x2 silu_pk(f32x2 x) { const f32x2 t = x * -1.4426950408889634f; f32x2 e; e.x = __builtin_amdgcn_exp2f(t.x); e.y = __builtin_amdgcn_exp2f(t.y); e = e + 1.0f; f32x2 r; r.x = __builtin_amdgcn_rcpf(e.x); r.y = __builtin_amdgcn_rcpf(e.y); return x * r; }
;     __device__ __forceinline__ void operator()(const pg8::f32x4 (&acc)[2][2][4][2], const pg8::Unit& u, int wr, int wc, int fr, int fq) const {
;     ...
;                     } else if (pn < 44) {
; #pragma unroll
;                         for (int e = 0; e < 8; e += 2) { const f32x2 g2 = silu_pk((f32x2){v[e], v[e + 1]}); v[e] = g2.x; v[e + 1] = g2.y; }
;                         st_bf16((bf16*)(ws + WS_ZB) + (size_t)r * 2048 + (pn - 36) * 256 + cl, v);
;                     } else if (pn < 48) {
;                         st_bf16((bf16*)(ws + WS_QC) + (size_t)r * 1024 + (pn - 44) * 256 + cl, v);
;                     } else if (pn < 50) {
;                         const bool isv = pn == 49;
;                         st_bf16((bf16*)(ws + (isv ? WS_VC : WS_KC)) + (size_t)r * 256 + cl, v);
;                         if (r < PT) st_f32(out + (isv ? O_PV : O_PK) + ((size_t)l * PT + r) * 256 + cl, v);
;                         else st_f32(out + (isv ? O_SV : O_SK) + ((size_t)l * ST + (r - PT)) * 256 + cl, v);
;                     } else if (pn < 54) {
; #pragma unroll
;                         for (int e = 0; e < 8; e += 2) { const f32x2 g2 = silu_pk((f32x2){v[e], v[e + 1]}); v[e] = g2.x; v[e + 1] = g2.y; }
;                         st_bf16((bf16*)(ws + WS_ZC) + (size_t)r * 1024 + (pn - 50) * 256 + cl, v);
.LBB0_2364:
	s_andn2_b64 vcc, exec, s[4:5]
	s_cbranch_vccnz .LBB0_2366
	v_mul_f32_e64 v24, v20, s50
	v_mul_f32_e64 v25, v21, s50
	v_mul_f32_e64 v26, v22, s50
	v_mul_f32_e64 v27, v23, s50
	v_exp_f32_e32 v24, v24
	v_exp_f32_e32 v25, v25
	v_exp_f32_e32 v26, v26
	v_exp_f32_e32 v27, v27
	v_mul_f32_e64 v28, v16, s50
	v_mul_f32_e64 v29, v17, s50
	v_mul_f32_e64 v30, v18, s50
	v_mul_f32_e64 v31, v19, s50
	v_exp_f32_e32 v28, v28
	v_exp_f32_e32 v29, v29
	v_exp_f32_e32 v30, v30
	v_exp_f32_e32 v31, v31
	v_add_f32_e64 v24, v24, 1.0
	v_add_f32_e64 v25, v25, 1.0
	v_add_f32_e64 v26, v26, 1.0
	v_add_f32_e64 v27, v27, 1.0
	v_rcp_f32_e32 v24, v24
	v_rcp_f32_e32 v25, v25
	v_rcp_f32_e32 v26, v26
	v_rcp_f32_e32 v27, v27
	v_add_f32_e64 v28, v28, 1.0
	v_add_f32_e64 v29, v29, 1.0
	v_add_f32_e64 v30, v30, 1.0
	v_add_f32_e64 v31, v31, 1.0
	v_rcp_f32_e32 v28, v28
	v_rcp_f32_e32 v29, v29
	v_rcp_f32_e32 v30, v30
	v_rcp_f32_e32 v31, v31
	v_lshlrev_b32_e32 v136, 1, v142
	v_mul_f32_e64 v24, v20, v24
	v_mul_f32_e64 v25, v21, v25
	v_mul_f32_e64 v26, v22, v26
	v_mul_f32_e64 v27, v23, v27
	v_lshl_add_u64 v[44:45], v[44:45], 0, v[136:137]
	v_mul_f32_e64 v28, v16, v28
	v_mul_f32_e64 v29, v17, v29
	v_mul_f32_e64 v30, v18, v30
	v_mul_f32_e64 v31, v19, v31
	v_cvt_pk_bf16_f32 v24, v24, v25
	v_cvt_pk_bf16_f32 v25, v26, v27
	v_cvt_pk_bf16_f32 v26, v28, v29
	s_nop 0
	v_cvt_pk_bf16_f32 v27, v30, v31
	global_store_dwordx4 v[44:45], v[24:27], off

; __device__ __forceinline__ f32x2 silu_pk(f32x2 x) { const f32x2 t = x * -1.4426950408889634f; f32x2 e; e.x = __builtin_amdgcn_exp2f(t.x); e.y = __builtin_amdgcn_exp2f(t.y); e = e + 1.0f; f32x2 r; r.x = __builtin_amdgcn_rcpf(e.x); r.y = __builtin_amdgcn_rcpf(e.y); return x * r; }
;     __device__ __forceinline__ void operator()(const pg8::f32x4 (&acc)[2][2][4][2], const pg8::Unit& u, int wr, int wc, int fr, int fq) const {
;     ...
;                     } else if (pn < 44) {
; #pragma unroll
;                         for (int e = 0; e < 8; e += 2) { const f32x2 g2 = silu_pk((f32x2){v[e], v[e + 1]}); v[e] = g2.x; v[e + 1] = g2.y; }
;                         st_bf16((bf16*)(ws + WS_ZB) + (size_t)r * 2048 + (pn - 36) * 256 + cl, v);
;                     } else if (pn < 48) {
;                         st_bf16((bf16*)(ws + WS_QC) + (size_t)r * 1024 + (pn - 44) * 256 + cl, v);
;                     } else if (pn < 50) {
;                         const bool isv = pn == 49;
;                         st_bf16((bf16*)(ws + (isv ? WS_VC : WS_KC)) + (size_t)r * 256 + cl, v);
;                         if (r < PT) st_f32(out + (isv ? O_PV : O_PK) + ((size_t)l * PT + r) * 256 + cl, v);
;                         else st_f32(out + (isv ? O_SV : O_SK) + ((size_t)l * ST + (r - PT)) * 256 + cl, v);
;                     } else if (pn < 54) {
; #pragma unroll
;                         for (int e = 0; e < 8; e += 2) { const f32x2 g2 = silu_pk((f32x2){v[e], v[e + 1]}); v[e] = g2.x; v[e + 1] = g2.y; }
;                         st_bf16((bf16*)(ws + WS_ZC) + (size_t)r * 1024 + (pn - 50) * 256 + cl, v);
.LBB0_2377:
	s_andn2_b64 vcc, exec, s[4:5]
	s_cbranch_vccnz .LBB0_2379
	v_mul_f32_e64 v24, v20, s50
	v_mul_f32_e64 v25, v21, s50
	v_mul_f32_e64 v26, v22, s50
	v_mul_f32_e64 v27, v23, s50
	v_exp_f32_e32 v24, v24
	v_exp_f32_e32 v25, v25
	v_exp_f32_e32 v26, v26
	v_exp_f32_e32 v27, v27
	v_mul_f32_e64 v28, v16, s50
	v_mul_f32_e64 v29, v17, s50
	v_mul_f32_e64 v30, v18, s50
	v_mul_f32_e64 v31, v19, s50
	v_exp_f32_e32 v28, v28
	v_exp_f32_e32 v29, v29
	v_exp_f32_e32 v30, v30
	v_exp_f32_e32 v31, v31
	v_add_f32_e64 v24, v24, 1.0
	v_add_f32_e64 v25, v25, 1.0
	v_add_f32_e64 v26, v26, 1.0
	v_add_f32_e64 v27, v27, 1.0
	v_rcp_f32_e32 v24, v24
	v_rcp_f32_e32 v25, v25
	v_rcp_f32_e32 v26, v26
	v_rcp_f32_e32 v27, v27
	v_add_f32_e64 v28, v28, 1.0
	v_add_f32_e64 v29, v29, 1.0
	v_add_f32_e64 v30, v30, 1.0
	v_add_f32_e64 v31, v31, 1.0
	v_rcp_f32_e32 v28, v28
	v_rcp_f32_e32 v29, v29
	v_rcp_f32_e32 v30, v30
	v_rcp_f32_e32 v31, v31
	v_lshlrev_b32_e32 v136, 1, v142
	v_mul_f32_e64 v24, v20, v24
	v_mul_f32_e64 v25, v21, v25
	v_mul_f32_e64 v26, v22, v26
	v_mul_f32_e64 v27, v23, v27
	v_lshl_add_u64 v[34:35], v[34:35], 0, v[136:137]
	v_mul_f32_e64 v28, v16, v28
	v_mul_f32_e64 v29, v17, v29
	v_mul_f32_e64 v30, v18, v30
	v_mul_f32_e64 v31, v19, v31
	v_cvt_pk_bf16_f32 v24, v24, v25
	v_cvt_pk_bf16_f32 v25, v26, v27
	v_cvt_pk_bf16_f32 v26, v28, v29
	s_nop 0
	v_cvt_pk_bf16_f32 v27, v30, v31
	global_store_dwordx4 v[34:35], v[24:27], off

; __device__ __forceinline__ f32x2 silu_pk(f32x2 x) { const f32x2 t = x * -1.4426950408889634f; f32x2 e; e.x = __builtin_amdgcn_exp2f(t.x); e.y = __builtin_amdgcn_exp2f(t.y); e = e + 1.0f; f32x2 r; r.x = __builtin_amdgcn_rcpf(e.x); r.y = __builtin_amdgcn_rcpf(e.y); return x * r; }
; __device__ __forceinline__ f32x2 gelu_pk(f32x2 x) { const f32x2 x2 = x * x; const f32x2 t = (x2 * 0.044715f + 1.0f) * (x * -2.302208198144325f); f32x2 e; e.x = __builtin_amdgcn_exp2f(t.x); e.y = __builtin_amdgcn_exp2f(t.y); e = e + 1.0f; f32x2 r; r.x = __builtin_amdgcn_rcpf(e.x); r.y = __builtin_amd ...
;     __device__ __forceinline__ void operator()(const pg8::f32x4 (&acc)[2][2][4][2], const pg8::Unit& u, int wr, int wc, int fr, int fq) const {
;     ...
;                     if (pn < 12) {
;                         const int seg = pn >> 2, cc = (pn & 3) * 256 + cl;
;                         if (seg < 2) {
; #pragma unroll
;                             for (int e = 0; e < 8; e += 2) { const f32x2 g2 = gelu_pk((f32x2){v[e], v[e + 1]}); v[e] = g2.x; v[e + 1] = g2.y; }
;                         } else {
; #pragma unroll
;                             for (int e = 0; e < 8; e += 2) { const f32x2 g2 = silu_pk((f32x2){v[e], v[e + 1]}); v[e] = g2.x; v[e + 1] = g2.y; }
;                         }
;                         bf16* base = (bf16*)(ws + (seg == 0 ? WS_UA : seg == 1 ? WS_VA : WS_ZA));
;                         st_bf16(base + (size_t)r * 1024 + cc, v);
.LBB0_2386:
	s_andn2_b64 vcc, exec, s[16:17]
	s_mov_b64 s[6:7], -1
	s_cbranch_vccnz .LBB0_2388
	v_mul_f32_e64 v52, v30, s50
	v_mul_f32_e64 v53, v31, s50
	v_mul_f32_e64 v50, v28, s50
	v_mul_f32_e64 v51, v29, s50
	v_exp_f32_e32 v52, v52
	v_exp_f32_e32 v53, v53
	v_mul_f32_e64 v54, v24, s50
	v_mul_f32_e64 v55, v25, s50
	v_exp_f32_e32 v50, v50
	v_exp_f32_e32 v51, v51
	v_exp_f32_e32 v54, v54
	v_exp_f32_e32 v55, v55
	v_add_f32_e64 v52, v52, 1.0
	v_add_f32_e64 v53, v53, 1.0
	v_add_f32_e64 v50, v50, 1.0
	v_add_f32_e64 v51, v51, 1.0
	v_rcp_f32_e32 v56, v52
	v_rcp_f32_e32 v57, v53
	v_add_f32_e64 v52, v54, 1.0
	v_add_f32_e64 v53, v55, 1.0
	v_rcp_f32_e32 v50, v50
	v_rcp_f32_e32 v51, v51
	v_rcp_f32_e32 v54, v52
	v_rcp_f32_e32 v55, v53
	s_mov_b64 s[6:7], 0
	v_mul_f32_e64 v52, v28, v50
	v_mul_f32_e64 v53, v29, v51
	v_mul_f32_e64 v50, v30, v56
	v_mul_f32_e64 v51, v31, v57
	v_mul_f32_e64 v54, v24, v54
	v_mul_f32_e64 v55, v25, v55
	v_mul_f32_e64 v56, v26, s50
	v_mul_f32_e64 v57, v27, s50
.LBB0_2388:
	s_andn2_b64 vcc, exec, s[6:7]
	s_cbranch_vccnz .LBB0_2390
	v_mul_f32_e64 v52, v28, v28
	v_mul_f32_e64 v53, v29, v29
	v_mul_f32_e64 v54, v28, s58
	v_mul_f32_e64 v55, v29, s58
	v_fma_f32 v52, v52, s56, 1.0
	v_fma_f32 v53, v53, s56, 1.0
	v_mul_f32_e64 v50, v30, v30
	v_mul_f32_e64 v51, v31, v31
	v_mul_f32_e64 v52, v54, v52
	v_mul_f32_e64 v53, v55, v53
	v_mul_f32_e64 v54, v24, s58
	v_mul_f32_e64 v55, v25, s58
	v_exp_f32_e32 v52, v52
	v_exp_f32_e32 v53, v53
	s_nop 0
	v_add_f32_e64 v52, v52, 1.0
	v_add_f32_e64 v53, v53, 1.0
	s_nop 0
	v_rcp_f32_e32 v52, v52
	v_rcp_f32_e32 v53, v53
	s_nop 0
	v_mul_f32_e64 v52, v28, v52
	v_mul_f32_e64 v53, v29, v53
	v_fma_f32 v28, v50, s56, 1.0
	v_fma_f32 v29, v51, s56, 1.0
	v_mul_f32_e64 v50, v30, s58
	v_mul_f32_e64 v51, v31, s58
	s_nop 0
	v_mul_f32_e64 v28, v50, v28
	v_mul_f32_e64 v29, v51, v29
	s_nop 0
	v_exp_f32_e32 v28, v28
	v_exp_f32_e32 v29, v29
	s_nop 0
	v_add_f32_e64 v28, v28, 1.0
	v_add_f32_e64 v29, v29, 1.0
	s_nop 0
	v_rcp_f32_e32 v28, v28
	v_rcp_f32_e32 v29, v29
	s_nop 0
	v_mul_f32_e64 v50, v30, v28
	v_mul_f32_e64 v51, v31, v29
	v_mul_f32_e64 v30, v24, v24
	v_mul_f32_e64 v31, v25, v25
	v_mul_f32_e64 v28, v26, v26
	v_mul_f32_e64 v29, v27, v27
	v_fma_f32 v30, v30, s56, 1.0
	v_fma_f32 v31, v31, s56, 1.0
	s_nop 0
	v_mul_f32_e64 v30, v54, v30
	v_mul_f32_e64 v31, v55, v31
	s_nop 0
	v_exp_f32_e32 v30, v30
	v_exp_f32_e32 v31, v31
	s_nop 0
	v_add_f32_e64 v30, v30, 1.0
	v_add_f32_e64 v31, v31, 1.0
	s_nop 0
	v_rcp_f32_e32 v30, v30
	v_rcp_f32_e32 v31, v31
	s_nop 0
	v_mul_f32_e64 v54, v24, v30
	v_mul_f32_e64 v55, v25, v31
	v_fma_f32 v24, v28, s56, 1.0
	v_fma_f32 v25, v29, s56, 1.0
	v_mul_f32_e64 v28, v26, s58
	v_mul_f32_e64 v29, v27, s58
	s_nop 0
	v_mul_f32_e64 v56, v28, v24
	v_mul_f32_e64 v57, v29, v25
.LBB0_2390:
	s_nop 0
	v_exp_f32_e32 v24, v56
	v_exp_f32_e32 v25, v57
	v_or_b32_e32 v30, s24, v140
	v_lshlrev_b32_e32 v136, 1, v30
	v_lshl_add_u64 v[30:31], v[46:47], 0, v[136:137]
	v_add_f32_e64 v24, v24, 1.0
	v_add_f32_e64 v25, v25, 1.0
	s_nop 0
	v_rcp_f32_e32 v24, v24
	v_rcp_f32_e32 v25, v25
	s_nop 0
	v_mul_f32_e64 v28, v26, v24
	v_mul_f32_e64 v29, v27, v25
	v_cvt_pk_bf16_f32 v24, v52, v53
	v_cvt_pk_bf16_f32 v25, v50, v51
	v_cvt_pk_bf16_f32 v26, v54, v55
	s_nop 0
	v_cvt_pk_bf16_f32 v27, v28, v29
	global_store_dwordx4 v[30:31], v[24:27], off
	s_and_b64 vcc, exec, s[10:11]
	s_mov_b64 s[4:5], -1
	s_cbranch_vccz .LBB0_2356

; __device__ __forceinline__ f32x2 silu_pk(f32x2 x) { const f32x2 t = x * -1.4426950408889634f; f32x2 e; e.x = __builtin_amdgcn_exp2f(t.x); e.y = __builtin_amdgcn_exp2f(t.y); e = e + 1.0f; f32x2 r; r.x = __builtin_amdgcn_rcpf(e.x); r.y = __builtin_amdgcn_rcpf(e.y); return x * r; }
; __device__ __forceinline__ f32x2 gelu_pk(f32x2 x) { const f32x2 x2 = x * x; const f32x2 t = (x2 * 0.044715f + 1.0f) * (x * -2.302208198144325f); f32x2 e; e.x = __builtin_amdgcn_exp2f(t.x); e.y = __builtin_amdgcn_exp2f(t.y); e = e + 1.0f; f32x2 r; r.x = __builtin_amdgcn_rcpf(e.x); r.y = __builtin_amd ...
;     __device__ __forceinline__ void operator()(const pg8::f32x4 (&acc)[2][2][4][2], const pg8::Unit& u, int wr, int wc, int fr, int fq) const {
;     ...
;                     if (pn < 12) {
;                         const int seg = pn >> 2, cc = (pn & 3) * 256 + cl;
;                         if (seg < 2) {
; #pragma unroll
;                             for (int e = 0; e < 8; e += 2) { const f32x2 g2 = gelu_pk((f32x2){v[e], v[e + 1]}); v[e] = g2.x; v[e + 1] = g2.y; }
;                         } else {
; #pragma unroll
;                             for (int e = 0; e < 8; e += 2) { const f32x2 g2 = silu_pk((f32x2){v[e], v[e + 1]}); v[e] = g2.x; v[e + 1] = g2.y; }
;                         }
;                         bf16* base = (bf16*)(ws + (seg == 0 ? WS_UA : seg == 1 ? WS_VA : WS_ZA));
;                         st_bf16(base + (size_t)r * 1024 + cc, v);
.LBB0_2392:
	s_andn2_b64 vcc, exec, s[16:17]
	s_mov_b64 s[0:1], -1
	s_cbranch_vccnz .LBB0_2394
	v_mul_f32_e64 v24, v20, s50
	v_mul_f32_e64 v25, v21, s50
	v_mul_f32_e64 v26, v22, s50
	v_mul_f32_e64 v27, v23, s50
	v_mul_f32_e64 v28, v16, s50
	v_mul_f32_e64 v29, v17, s50
	v_exp_f32_e32 v24, v24
	v_exp_f32_e32 v25, v25
	v_exp_f32_e32 v26, v26
	v_exp_f32_e32 v27, v27
	v_exp_f32_e32 v28, v28
	v_exp_f32_e32 v29, v29
	v_add_f32_e64 v24, v24, 1.0
	v_add_f32_e64 v25, v25, 1.0
	v_add_f32_e64 v26, v26, 1.0
	v_add_f32_e64 v27, v27, 1.0
	v_rcp_f32_e32 v24, v24
	v_add_f32_e64 v28, v28, 1.0
	v_add_f32_e64 v29, v29, 1.0
	v_rcp_f32_e32 v25, v25
	v_rcp_f32_e32 v26, v26
	v_rcp_f32_e32 v27, v27
	v_rcp_f32_e32 v28, v28
	v_rcp_f32_e32 v29, v29
	v_mul_f32_e64 v24, v20, v24
	v_mul_f32_e64 v25, v21, v25
	v_mul_f32_e64 v26, v22, v26
	v_mul_f32_e64 v27, v23, v27
	v_mul_f32_e64 v30, v18, s50
	v_mul_f32_e64 v31, v19, s50
	v_mul_f32_e64 v28, v16, v28
	v_mul_f32_e64 v29, v17, v29
	s_mov_b64 s[0:1], 0
.LBB0_2394:
	s_andn2_b64 vcc, exec, s[0:1]
	s_cbranch_vccnz .LBB0_2396
	v_mul_f32_e64 v24, v20, v20
	v_mul_f32_e64 v25, v21, v21
	v_mul_f32_e64 v28, v20, s58
	v_mul_f32_e64 v29, v21, s58
	v_fma_f32 v24, v24, s56, 1.0
	v_fma_f32 v25, v25, s56, 1.0
	v_mul_f32_e64 v26, v22, v22
	v_mul_f32_e64 v27, v23, v23
	v_mul_f32_e64 v24, v28, v24
	v_mul_f32_e64 v25, v29, v25
	v_mul_f32_e64 v28, v16, s58
	v_mul_f32_e64 v29, v17, s58
	v_exp_f32_e32 v24, v24
	v_exp_f32_e32 v25, v25
	s_nop 0
	v_add_f32_e64 v24, v24, 1.0
	v_add_f32_e64 v25, v25, 1.0
	s_nop 0
	v_rcp_f32_e32 v24, v24
	v_rcp_f32_e32 v25, v25
	s_nop 0
	v_mul_f32_e64 v24, v20, v24
	v_mul_f32_e64 v25, v21, v25
	v_fma_f32 v20, v26, s56, 1.0
	v_fma_f32 v21, v27, s56, 1.0
	v_mul_f32_e64 v26, v22, s58
	v_mul_f32_e64 v27, v23, s58
	s_nop 0
	v_mul_f32_e64 v20, v26, v20
	v_mul_f32_e64 v21, v27, v21
	s_nop 0
	v_exp_f32_e32 v20, v20
	v_exp_f32_e32 v21, v21
	s_nop 0
	v_add_f32_e64 v20, v20, 1.0
	v_add_f32_e64 v21, v21, 1.0
	s_nop 0
	v_rcp_f32_e32 v20, v20
	v_rcp_f32_e32 v21, v21
	s_nop 0
	v_mul_f32_e64 v26, v22, v20
	v_mul_f32_e64 v27, v23, v21
	v_mul_f32_e64 v22, v16, v16
	v_mul_f32_e64 v23, v17, v17
	v_mul_f32_e64 v20, v18, v18
	v_mul_f32_e64 v21, v19, v19
	v_fma_f32 v22, v22, s56, 1.0
	v_fma_f32 v23, v23, s56, 1.0
	s_nop 0
	v_mul_f32_e64 v22, v28, v22
	v_mul_f32_e64 v23, v29, v23
	s_nop 0
	v_exp_f32_e32 v22, v22
	v_exp_f32_e32 v23, v23
	s_nop 0
	v_add_f32_e64 v22, v22, 1.0
	v_add_f32_e64 v23, v23, 1.0
	s_nop 0
	v_rcp_f32_e32 v22, v22
	v_rcp_f32_e32 v23, v23
	s_nop 0
	v_mul_f32_e64 v28, v16, v22
	v_mul_f32_e64 v29, v17, v23
	v_fma_f32 v16, v20, s56, 1.0
	v_fma_f32 v17, v21, s56, 1.0
	v_mul_f32_e64 v20, v18, s58
	v_mul_f32_e64 v21, v19, s58
	s_nop 0
	v_mul_f32_e64 v30, v20, v16
	v_mul_f32_e64 v31, v21, v17
.LBB0_2396:
	s_nop 0
	v_exp_f32_e32 v16, v30
	v_exp_f32_e32 v17, v31
	v_add_lshl_u32 v136, s24, v140, 1
	v_lshl_add_u64 v[22:23], v[46:47], 0, v[136:137]
	v_add_f32_e64 v16, v16, 1.0
	v_add_f32_e64 v17, v17, 1.0
	s_nop 0
	v_rcp_f32_e32 v16, v16
	v_rcp_f32_e32 v17, v17
	s_nop 0
	v_mul_f32_e64 v20, v18, v16
	v_mul_f32_e64 v21, v19, v17
	v_cvt_pk_bf16_f32 v16, v24, v25
	v_cvt_pk_bf16_f32 v17, v26, v27
	v_cvt_pk_bf16_f32 v18, v28, v29
	s_nop 0
	v_cvt_pk_bf16_f32 v19, v20, v21
	global_store_dwordx4 v[22:23], v[16:19], off offset:256

; __device__ __forceinline__ f32x2 silu_pk(f32x2 x) { const f32x2 t = x * -1.4426950408889634f; f32x2 e; e.x = __builtin_amdgcn_exp2f(t.x); e.y = __builtin_amdgcn_exp2f(t.y); e = e + 1.0f; f32x2 r; r.x = __builtin_amdgcn_rcpf(e.x); r.y = __builtin_amdgcn_rcpf(e.y); return x * r; }
;     __device__ __forceinline__ void operator()(const pg8::f32x4 (&acc)[2][2][4][2], const pg8::Unit& u, int wr, int wc, int fr, int fq) const {
;     ...
;                     } else if (pn < 44) {
; #pragma unroll
;                         for (int e = 0; e < 8; e += 2) { const f32x2 g2 = silu_pk((f32x2){v[e], v[e + 1]}); v[e] = g2.x; v[e + 1] = g2.y; }
;                         st_bf16((bf16*)(ws + WS_ZB) + (size_t)r * 2048 + (pn - 36) * 256 + cl, v);
;                     } else if (pn < 48) {
;                         st_bf16((bf16*)(ws + WS_QC) + (size_t)r * 1024 + (pn - 44) * 256 + cl, v);
;                     } else if (pn < 50) {
;                         const bool isv = pn == 49;
;                         st_bf16((bf16*)(ws + (isv ? WS_VC : WS_KC)) + (size_t)r * 256 + cl, v);
;                         if (r < PT) st_f32(out + (isv ? O_PV : O_PK) + ((size_t)l * PT + r) * 256 + cl, v);
;                         else st_f32(out + (isv ? O_SV : O_SK) + ((size_t)l * ST + (r - PT)) * 256 + cl, v);
;                     } else if (pn < 54) {
; #pragma unroll
;                         for (int e = 0; e < 8; e += 2) { const f32x2 g2 = silu_pk((f32x2){v[e], v[e + 1]}); v[e] = g2.x; v[e + 1] = g2.y; }
;                         st_bf16((bf16*)(ws + WS_ZC) + (size_t)r * 1024 + (pn - 50) * 256 + cl, v);
.LBB0_2423:
	s_andn2_b64 vcc, exec, s[4:5]
	s_cbranch_vccnz .LBB0_2425
	v_mul_f32_e64 v36, v12, s50
	v_mul_f32_e64 v37, v13, s50
	v_mul_f32_e64 v38, v14, s50
	v_mul_f32_e64 v39, v15, s50
	v_exp_f32_e32 v36, v36
	v_exp_f32_e32 v37, v37
	v_exp_f32_e32 v38, v38
	v_exp_f32_e32 v39, v39
	v_mul_f32_e64 v40, v8, s50
	v_mul_f32_e64 v41, v9, s50
	v_mul_f32_e64 v42, v10, s50
	v_mul_f32_e64 v43, v11, s50
	v_exp_f32_e32 v40, v40
	v_exp_f32_e32 v41, v41
	v_exp_f32_e32 v42, v42
	v_exp_f32_e32 v43, v43
	v_add_f32_e64 v36, v36, 1.0
	v_add_f32_e64 v37, v37, 1.0
	v_add_f32_e64 v38, v38, 1.0
	v_add_f32_e64 v39, v39, 1.0
	v_rcp_f32_e32 v36, v36
	v_rcp_f32_e32 v37, v37
	v_rcp_f32_e32 v38, v38
	v_rcp_f32_e32 v39, v39
	v_add_f32_e64 v40, v40, 1.0
	v_add_f32_e64 v41, v41, 1.0
	v_add_f32_e64 v42, v42, 1.0
	v_add_f32_e64 v43, v43, 1.0
	v_rcp_f32_e32 v40, v40
	v_rcp_f32_e32 v41, v41
	v_rcp_f32_e32 v42, v42
	v_rcp_f32_e32 v43, v43
	v_lshlrev_b32_e32 v136, 1, v140
	v_mul_f32_e64 v36, v12, v36
	v_mul_f32_e64 v37, v13, v37
	v_mul_f32_e64 v38, v14, v38
	v_mul_f32_e64 v39, v15, v39
	v_lshl_add_u64 v[46:47], v[30:31], 0, v[136:137]
	v_mul_f32_e64 v40, v8, v40
	v_mul_f32_e64 v41, v9, v41
	v_mul_f32_e64 v42, v10, v42
	v_mul_f32_e64 v43, v11, v43
	v_cvt_pk_bf16_f32 v36, v36, v37
	v_cvt_pk_bf16_f32 v37, v38, v39
	v_cvt_pk_bf16_f32 v38, v40, v41
	s_nop 0
	v_cvt_pk_bf16_f32 v39, v42, v43
	global_store_dwordx4 v[46:47], v[36:39], off

; __device__ __forceinline__ f32x2 silu_pk(f32x2 x) { const f32x2 t = x * -1.4426950408889634f; f32x2 e; e.x = __builtin_amdgcn_exp2f(t.x); e.y = __builtin_amdgcn_exp2f(t.y); e = e + 1.0f; f32x2 r; r.x = __builtin_amdgcn_rcpf(e.x); r.y = __builtin_amdgcn_rcpf(e.y); return x * r; }
;     __device__ __forceinline__ void operator()(const pg8::f32x4 (&acc)[2][2][4][2], const pg8::Unit& u, int wr, int wc, int fr, int fq) const {
;     ...
;                     } else if (pn < 44) {
; #pragma unroll
;                         for (int e = 0; e < 8; e += 2) { const f32x2 g2 = silu_pk((f32x2){v[e], v[e + 1]}); v[e] = g2.x; v[e + 1] = g2.y; }
;                         st_bf16((bf16*)(ws + WS_ZB) + (size_t)r * 2048 + (pn - 36) * 256 + cl, v);
;                     } else if (pn < 48) {
;                         st_bf16((bf16*)(ws + WS_QC) + (size_t)r * 1024 + (pn - 44) * 256 + cl, v);
;                     } else if (pn < 50) {
;                         const bool isv = pn == 49;
;                         st_bf16((bf16*)(ws + (isv ? WS_VC : WS_KC)) + (size_t)r * 256 + cl, v);
;                         if (r < PT) st_f32(out + (isv ? O_PV : O_PK) + ((size_t)l * PT + r) * 256 + cl, v);
;                         else st_f32(out + (isv ? O_SV : O_SK) + ((size_t)l * ST + (r - PT)) * 256 + cl, v);
;                     } else if (pn < 54) {
; #pragma unroll
;                         for (int e = 0; e < 8; e += 2) { const f32x2 g2 = silu_pk((f32x2){v[e], v[e + 1]}); v[e] = g2.x; v[e + 1] = g2.y; }
;                         st_bf16((bf16*)(ws + WS_ZC) + (size_t)r * 1024 + (pn - 50) * 256 + cl, v);
.LBB0_2436:
	s_andn2_b64 vcc, exec, s[4:5]
	s_cbranch_vccnz .LBB0_2438
	v_mul_f32_e64 v36, v12, s50
	v_mul_f32_e64 v37, v13, s50
	v_mul_f32_e64 v38, v14, s50
	v_mul_f32_e64 v39, v15, s50
	v_exp_f32_e32 v36, v36
	v_exp_f32_e32 v37, v37
	v_exp_f32_e32 v38, v38
	v_exp_f32_e32 v39, v39
	v_mul_f32_e64 v40, v8, s50
	v_mul_f32_e64 v41, v9, s50
	v_mul_f32_e64 v42, v10, s50
	v_mul_f32_e64 v43, v11, s50
	v_exp_f32_e32 v40, v40
	v_exp_f32_e32 v41, v41
	v_exp_f32_e32 v42, v42
	v_exp_f32_e32 v43, v43
	v_add_f32_e64 v36, v36, 1.0
	v_add_f32_e64 v37, v37, 1.0
	v_add_f32_e64 v38, v38, 1.0
	v_add_f32_e64 v39, v39, 1.0
	v_rcp_f32_e32 v36, v36
	v_rcp_f32_e32 v37, v37
	v_rcp_f32_e32 v38, v38
	v_rcp_f32_e32 v39, v39
	v_add_f32_e64 v40, v40, 1.0
	v_add_f32_e64 v41, v41, 1.0
	v_add_f32_e64 v42, v42, 1.0
	v_add_f32_e64 v43, v43, 1.0
	v_rcp_f32_e32 v40, v40
	v_rcp_f32_e32 v41, v41
	v_rcp_f32_e32 v42, v42
	v_rcp_f32_e32 v43, v43
	v_lshlrev_b32_e32 v136, 1, v140
	v_mul_f32_e64 v36, v12, v36
	v_mul_f32_e64 v37, v13, v37
	v_mul_f32_e64 v38, v14, v38
	v_mul_f32_e64 v39, v15, v39
	v_lshl_add_u64 v[46:47], v[20:21], 0, v[136:137]
	v_mul_f32_e64 v40, v8, v40
	v_mul_f32_e64 v41, v9, v41
	v_mul_f32_e64 v42, v10, v42
	v_mul_f32_e64 v43, v11, v43
	v_cvt_pk_bf16_f32 v36, v36, v37
	v_cvt_pk_bf16_f32 v37, v38, v39
	v_cvt_pk_bf16_f32 v38, v40, v41
	s_nop 0
	v_cvt_pk_bf16_f32 v39, v42, v43
	global_store_dwordx4 v[46:47], v[36:39], off

; __device__ __forceinline__ f32x2 silu_pk(f32x2 x) { const f32x2 t = x * -1.4426950408889634f; f32x2 e; e.x = __builtin_amdgcn_exp2f(t.x); e.y = __builtin_amdgcn_exp2f(t.y); e = e + 1.0f; f32x2 r; r.x = __builtin_amdgcn_rcpf(e.x); r.y = __builtin_amdgcn_rcpf(e.y); return x * r; }
; __device__ __forceinline__ f32x2 gelu_pk(f32x2 x) { const f32x2 x2 = x * x; const f32x2 t = (x2 * 0.044715f + 1.0f) * (x * -2.302208198144325f); f32x2 e; e.x = __builtin_amdgcn_exp2f(t.x); e.y = __builtin_amdgcn_exp2f(t.y); e = e + 1.0f; f32x2 r; r.x = __builtin_amdgcn_rcpf(e.x); r.y = __builtin_amd ...
;     __device__ __forceinline__ void operator()(const pg8::f32x4 (&acc)[2][2][4][2], const pg8::Unit& u, int wr, int wc, int fr, int fq) const {
;     ...
;                     if (pn < 12) {
;                         const int seg = pn >> 2, cc = (pn & 3) * 256 + cl;
;                         if (seg < 2) {
; #pragma unroll
;                             for (int e = 0; e < 8; e += 2) { const f32x2 g2 = gelu_pk((f32x2){v[e], v[e + 1]}); v[e] = g2.x; v[e + 1] = g2.y; }
;                         } else {
; #pragma unroll
;                             for (int e = 0; e < 8; e += 2) { const f32x2 g2 = silu_pk((f32x2){v[e], v[e + 1]}); v[e] = g2.x; v[e + 1] = g2.y; }
;                         }
;                         bf16* base = (bf16*)(ws + (seg == 0 ? WS_UA : seg == 1 ? WS_VA : WS_ZA));
;                         st_bf16(base + (size_t)r * 1024 + cc, v);
.LBB0_2450:
	v_cndmask_b32_e64 v36, 0, 1, s[16:17]
	v_lshl_add_u64 v[34:35], s[80:81], 0, v[34:35]
	s_andn2_b64 vcc, exec, s[4:5]
	v_cmp_ne_u32_e64 s[16:17], 1, v36
	s_cbranch_vccnz .LBB0_2457
	s_and_b64 vcc, exec, s[16:17]
	s_mov_b64 s[6:7], -1
	s_cbranch_vccnz .LBB0_2453
	v_mul_f32_e64 v38, v14, s50
	v_mul_f32_e64 v39, v15, s50
	v_mul_f32_e64 v36, v12, s50
	v_mul_f32_e64 v37, v13, s50
	v_exp_f32_e32 v38, v38
	v_exp_f32_e32 v39, v39
	v_mul_f32_e64 v40, v8, s50
	v_mul_f32_e64 v41, v9, s50
	v_exp_f32_e32 v36, v36
	v_exp_f32_e32 v37, v37
	v_exp_f32_e32 v40, v40
	v_exp_f32_e32 v41, v41
	v_add_f32_e64 v38, v38, 1.0
	v_add_f32_e64 v39, v39, 1.0
	v_add_f32_e64 v36, v36, 1.0
	v_add_f32_e64 v37, v37, 1.0
	v_rcp_f32_e32 v42, v38
	v_rcp_f32_e32 v43, v39
	v_add_f32_e64 v38, v40, 1.0
	v_add_f32_e64 v39, v41, 1.0
	v_rcp_f32_e32 v36, v36
	v_rcp_f32_e32 v37, v37
	v_rcp_f32_e32 v40, v38
	v_rcp_f32_e32 v41, v39
	s_mov_b64 s[6:7], 0
	v_mul_f32_e64 v38, v12, v36
	v_mul_f32_e64 v39, v13, v37
	v_mul_f32_e64 v36, v14, v42
	v_mul_f32_e64 v37, v15, v43
	v_mul_f32_e64 v40, v8, v40
	v_mul_f32_e64 v41, v9, v41
	v_mul_f32_e64 v42, v10, s50
	v_mul_f32_e64 v43, v11, s50
.LBB0_2453:
	s_andn2_b64 vcc, exec, s[6:7]
	s_cbranch_vccnz .LBB0_2455
	v_mul_f32_e64 v38, v12, v12
	v_mul_f32_e64 v39, v13, v13
	v_mul_f32_e64 v40, v12, s58
	v_mul_f32_e64 v41, v13, s58
	v_fma_f32 v38, v38, s56, 1.0
	v_fma_f32 v39, v39, s56, 1.0
	v_mul_f32_e64 v36, v14, v14
	v_mul_f32_e64 v37, v15, v15
	v_mul_f32_e64 v38, v40, v38
	v_mul_f32_e64 v39, v41, v39
	v_mul_f32_e64 v40, v8, s58
	v_mul_f32_e64 v41, v9, s58
	v_exp_f32_e32 v38, v38
	v_exp_f32_e32 v39, v39
	s_nop 0
	v_add_f32_e64 v38, v38, 1.0
	v_add_f32_e64 v39, v39, 1.0
	s_nop 0
	v_rcp_f32_e32 v38, v38
	v_rcp_f32_e32 v39, v39
	s_nop 0
	v_mul_f32_e64 v38, v12, v38
	v_mul_f32_e64 v39, v13, v39
	v_fma_f32 v12, v36, s56, 1.0
	v_fma_f32 v13, v37, s56, 1.0
	v_mul_f32_e64 v36, v14, s58
	v_mul_f32_e64 v37, v15, s58
	s_nop 0
	v_mul_f32_e64 v12, v36, v12
	v_mul_f32_e64 v13, v37, v13
	s_nop 0
	v_exp_f32_e32 v12, v12
	v_exp_f32_e32 v13, v13
	s_nop 0
	v_add_f32_e64 v12, v12, 1.0
	v_add_f32_e64 v13, v13, 1.0
	s_nop 0
	v_rcp_f32_e32 v12, v12
	v_rcp_f32_e32 v13, v13
	s_nop 0
	v_mul_f32_e64 v36, v14, v12
	v_mul_f32_e64 v37, v15, v13
	v_mul_f32_e64 v14, v8, v8
	v_mul_f32_e64 v15, v9, v9
	v_mul_f32_e64 v12, v10, v10
	v_mul_f32_e64 v13, v11, v11
	v_fma_f32 v14, v14, s56, 1.0
	v_fma_f32 v15, v15, s56, 1.0
	s_nop 0
	v_mul_f32_e64 v14, v40, v14
	v_mul_f32_e64 v15, v41, v15
	s_nop 0
	v_exp_f32_e32 v14, v14
	v_exp_f32_e32 v15, v15
	s_nop 0
	v_add_f32_e64 v14, v14, 1.0
	v_add_f32_e64 v15, v15, 1.0
	s_nop 0
	v_rcp_f32_e32 v14, v14
	v_rcp_f32_e32 v15, v15
	s_nop 0
	v_mul_f32_e64 v40, v8, v14
	v_mul_f32_e64 v41, v9, v15
	v_fma_f32 v8, v12, s56, 1.0
	v_fma_f32 v9, v13, s56, 1.0
	v_mul_f32_e64 v12, v10, s58
	v_mul_f32_e64 v13, v11, s58
	s_nop 0
	v_mul_f32_e64 v42, v12, v8
	v_mul_f32_e64 v43, v13, v9
.LBB0_2455:
	s_nop 0
	v_exp_f32_e32 v8, v42
	v_exp_f32_e32 v9, v43
	v_or_b32_e32 v14, s24, v140
	v_lshlrev_b32_e32 v136, 1, v14
	v_lshl_add_u64 v[14:15], v[34:35], 0, v[136:137]
	v_add_f32_e64 v8, v8, 1.0
	v_add_f32_e64 v9, v9, 1.0
	s_nop 0
	v_rcp_f32_e32 v8, v8
	v_rcp_f32_e32 v9, v9
	s_nop 0
	v_mul_f32_e64 v12, v10, v8
	v_mul_f32_e64 v13, v11, v9
	v_cvt_pk_bf16_f32 v8, v38, v39
	v_cvt_pk_bf16_f32 v9, v36, v37
	v_cvt_pk_bf16_f32 v10, v40, v41
	s_nop 0
	v_cvt_pk_bf16_f32 v11, v12, v13
	global_store_dwordx4 v[14:15], v[8:11], off
	s_and_b64 vcc, exec, s[10:11]
	s_mov_b64 s[4:5], -1
	s_cbranch_vccz .LBB0_2458

; __device__ __forceinline__ f32x2 silu_pk(f32x2 x) { const f32x2 t = x * -1.4426950408889634f; f32x2 e; e.x = __builtin_amdgcn_exp2f(t.x); e.y = __builtin_amdgcn_exp2f(t.y); e = e + 1.0f; f32x2 r; r.x = __builtin_amdgcn_rcpf(e.x); r.y = __builtin_amdgcn_rcpf(e.y); return x * r; }
;     __device__ __forceinline__ void operator()(const pg8::f32x4 (&acc)[2][2][4][2], const pg8::Unit& u, int wr, int wc, int fr, int fq) const {
;     ...
;                     } else if (pn < 44) {
; #pragma unroll
;                         for (int e = 0; e < 8; e += 2) { const f32x2 g2 = silu_pk((f32x2){v[e], v[e + 1]}); v[e] = g2.x; v[e + 1] = g2.y; }
;                         st_bf16((bf16*)(ws + WS_ZB) + (size_t)r * 2048 + (pn - 36) * 256 + cl, v);
;                     } else if (pn < 48) {
;                         st_bf16((bf16*)(ws + WS_QC) + (size_t)r * 1024 + (pn - 44) * 256 + cl, v);
;                     } else if (pn < 50) {
;                         const bool isv = pn == 49;
;                         st_bf16((bf16*)(ws + (isv ? WS_VC : WS_KC)) + (size_t)r * 256 + cl, v);
;                         if (r < PT) st_f32(out + (isv ? O_PV : O_PK) + ((size_t)l * PT + r) * 256 + cl, v);
;                         else st_f32(out + (isv ? O_SV : O_SK) + ((size_t)l * ST + (r - PT)) * 256 + cl, v);
;                     } else if (pn < 54) {
; #pragma unroll
;                         for (int e = 0; e < 8; e += 2) { const f32x2 g2 = silu_pk((f32x2){v[e], v[e + 1]}); v[e] = g2.x; v[e + 1] = g2.y; }
;                         st_bf16((bf16*)(ws + WS_ZC) + (size_t)r * 1024 + (pn - 50) * 256 + cl, v);
.LBB0_2466:
	s_andn2_b64 vcc, exec, s[4:5]
	s_cbranch_vccnz .LBB0_2468
	v_mul_f32_e64 v8, v4, s50
	v_mul_f32_e64 v9, v5, s50
	v_mul_f32_e64 v10, v6, s50
	v_mul_f32_e64 v11, v7, s50
	v_exp_f32_e32 v8, v8
	v_exp_f32_e32 v9, v9
	v_exp_f32_e32 v10, v10
	v_exp_f32_e32 v11, v11
	v_mul_f32_e64 v12, v0, s50
	v_mul_f32_e64 v13, v1, s50
	v_mul_f32_e64 v14, v2, s50
	v_mul_f32_e64 v15, v3, s50
	v_exp_f32_e32 v12, v12
	v_exp_f32_e32 v13, v13
	v_exp_f32_e32 v14, v14
	v_exp_f32_e32 v15, v15
	v_add_f32_e64 v8, v8, 1.0
	v_add_f32_e64 v9, v9, 1.0
	v_add_f32_e64 v10, v10, 1.0
	v_add_f32_e64 v11, v11, 1.0
	v_rcp_f32_e32 v8, v8
	v_rcp_f32_e32 v9, v9
	v_rcp_f32_e32 v10, v10
	v_rcp_f32_e32 v11, v11
	v_add_f32_e64 v12, v12, 1.0
	v_add_f32_e64 v13, v13, 1.0
	v_add_f32_e64 v14, v14, 1.0
	v_add_f32_e64 v15, v15, 1.0
	v_rcp_f32_e32 v12, v12
	v_rcp_f32_e32 v13, v13
	v_rcp_f32_e32 v14, v14
	v_rcp_f32_e32 v15, v15
	v_lshlrev_b32_e32 v136, 1, v142
	v_mul_f32_e64 v8, v4, v8
	v_mul_f32_e64 v9, v5, v9
	v_mul_f32_e64 v10, v6, v10
	v_mul_f32_e64 v11, v7, v11
	v_lshl_add_u64 v[30:31], v[30:31], 0, v[136:137]
	v_mul_f32_e64 v12, v0, v12
	v_mul_f32_e64 v13, v1, v13
	v_mul_f32_e64 v14, v2, v14
	v_mul_f32_e64 v15, v3, v15
	v_cvt_pk_bf16_f32 v8, v8, v9
	v_cvt_pk_bf16_f32 v9, v10, v11
	v_cvt_pk_bf16_f32 v10, v12, v13
	s_nop 0
	v_cvt_pk_bf16_f32 v11, v14, v15
	global_store_dwordx4 v[30:31], v[8:11], off

; __device__ __forceinline__ f32x2 silu_pk(f32x2 x) { const f32x2 t = x * -1.4426950408889634f; f32x2 e; e.x = __builtin_amdgcn_exp2f(t.x); e.y = __builtin_amdgcn_exp2f(t.y); e = e + 1.0f; f32x2 r; r.x = __builtin_amdgcn_rcpf(e.x); r.y = __builtin_amdgcn_rcpf(e.y); return x * r; }
;     __device__ __forceinline__ void operator()(const pg8::f32x4 (&acc)[2][2][4][2], const pg8::Unit& u, int wr, int wc, int fr, int fq) const {
;     ...
;                     } else if (pn < 44) {
; #pragma unroll
;                         for (int e = 0; e < 8; e += 2) { const f32x2 g2 = silu_pk((f32x2){v[e], v[e + 1]}); v[e] = g2.x; v[e + 1] = g2.y; }
;                         st_bf16((bf16*)(ws + WS_ZB) + (size_t)r * 2048 + (pn - 36) * 256 + cl, v);
;                     } else if (pn < 48) {
;                         st_bf16((bf16*)(ws + WS_QC) + (size_t)r * 1024 + (pn - 44) * 256 + cl, v);
;                     } else if (pn < 50) {
;                         const bool isv = pn == 49;
;                         st_bf16((bf16*)(ws + (isv ? WS_VC : WS_KC)) + (size_t)r * 256 + cl, v);
;                         if (r < PT) st_f32(out + (isv ? O_PV : O_PK) + ((size_t)l * PT + r) * 256 + cl, v);
;                         else st_f32(out + (isv ? O_SV : O_SK) + ((size_t)l * ST + (r - PT)) * 256 + cl, v);
;                     } else if (pn < 54) {
; #pragma unroll
;                         for (int e = 0; e < 8; e += 2) { const f32x2 g2 = silu_pk((f32x2){v[e], v[e + 1]}); v[e] = g2.x; v[e + 1] = g2.y; }
;                         st_bf16((bf16*)(ws + WS_ZC) + (size_t)r * 1024 + (pn - 50) * 256 + cl, v);
.LBB0_2479:
	s_andn2_b64 vcc, exec, s[4:5]
	s_cbranch_vccnz .LBB0_2481
	v_mul_f32_e64 v8, v4, s50
	v_mul_f32_e64 v9, v5, s50
	v_mul_f32_e64 v10, v6, s50
	v_mul_f32_e64 v11, v7, s50
	v_exp_f32_e32 v8, v8
	v_exp_f32_e32 v9, v9
	v_exp_f32_e32 v10, v10
	v_exp_f32_e32 v11, v11
	v_mul_f32_e64 v12, v0, s50
	v_mul_f32_e64 v13, v1, s50
	v_mul_f32_e64 v14, v2, s50
	v_mul_f32_e64 v15, v3, s50
	v_exp_f32_e32 v12, v12
	v_exp_f32_e32 v13, v13
	v_exp_f32_e32 v14, v14
	v_exp_f32_e32 v15, v15
	v_add_f32_e64 v8, v8, 1.0
	v_add_f32_e64 v9, v9, 1.0
	v_add_f32_e64 v10, v10, 1.0
	v_add_f32_e64 v11, v11, 1.0
	v_rcp_f32_e32 v8, v8
	v_rcp_f32_e32 v9, v9
	v_rcp_f32_e32 v10, v10
	v_rcp_f32_e32 v11, v11
	v_add_f32_e64 v12, v12, 1.0
	v_add_f32_e64 v13, v13, 1.0
	v_add_f32_e64 v14, v14, 1.0
	v_add_f32_e64 v15, v15, 1.0
	v_rcp_f32_e32 v12, v12
	v_rcp_f32_e32 v13, v13
	v_rcp_f32_e32 v14, v14
	v_rcp_f32_e32 v15, v15
	v_lshlrev_b32_e32 v136, 1, v142
	v_mul_f32_e64 v8, v4, v8
	v_mul_f32_e64 v9, v5, v9
	v_mul_f32_e64 v10, v6, v10
	v_mul_f32_e64 v11, v7, v11
	v_lshl_add_u64 v[20:21], v[20:21], 0, v[136:137]
	v_mul_f32_e64 v12, v0, v12
	v_mul_f32_e64 v13, v1, v13
	v_mul_f32_e64 v14, v2, v14
	v_mul_f32_e64 v15, v3, v15
	v_cvt_pk_bf16_f32 v8, v8, v9
	v_cvt_pk_bf16_f32 v9, v10, v11
	v_cvt_pk_bf16_f32 v10, v12, v13
	s_nop 0
	v_cvt_pk_bf16_f32 v11, v14, v15
	global_store_dwordx4 v[20:21], v[8:11], off

; __device__ __forceinline__ f32x2 silu_pk(f32x2 x) { const f32x2 t = x * -1.4426950408889634f; f32x2 e; e.x = __builtin_amdgcn_exp2f(t.x); e.y = __builtin_amdgcn_exp2f(t.y); e = e + 1.0f; f32x2 r; r.x = __builtin_amdgcn_rcpf(e.x); r.y = __builtin_amdgcn_rcpf(e.y); return x * r; }
; __device__ __forceinline__ f32x2 gelu_pk(f32x2 x) { const f32x2 x2 = x * x; const f32x2 t = (x2 * 0.044715f + 1.0f) * (x * -2.302208198144325f); f32x2 e; e.x = __builtin_amdgcn_exp2f(t.x); e.y = __builtin_amdgcn_exp2f(t.y); e = e + 1.0f; f32x2 r; r.x = __builtin_amdgcn_rcpf(e.x); r.y = __builtin_amd ...
;     __device__ __forceinline__ void operator()(const pg8::f32x4 (&acc)[2][2][4][2], const pg8::Unit& u, int wr, int wc, int fr, int fq) const {
;     ...
;                     if (pn < 12) {
;                         const int seg = pn >> 2, cc = (pn & 3) * 256 + cl;
;                         if (seg < 2) {
; #pragma unroll
;                             for (int e = 0; e < 8; e += 2) { const f32x2 g2 = gelu_pk((f32x2){v[e], v[e + 1]}); v[e] = g2.x; v[e + 1] = g2.y; }
;                         } else {
; #pragma unroll
;                             for (int e = 0; e < 8; e += 2) { const f32x2 g2 = silu_pk((f32x2){v[e], v[e + 1]}); v[e] = g2.x; v[e + 1] = g2.y; }
;                         }
;                         bf16* base = (bf16*)(ws + (seg == 0 ? WS_UA : seg == 1 ? WS_VA : WS_ZA));
;                         st_bf16(base + (size_t)r * 1024 + cc, v);
.LBB0_2493:
	s_and_b64 vcc, exec, s[16:17]
	s_mov_b64 s[0:1], -1
	s_cbranch_vccnz .LBB0_2495
	v_mul_f32_e64 v8, v4, s50
	v_mul_f32_e64 v9, v5, s50
	v_mul_f32_e64 v10, v6, s50
	v_mul_f32_e64 v11, v7, s50
	v_mul_f32_e64 v12, v0, s50
	v_mul_f32_e64 v13, v1, s50
	v_exp_f32_e32 v8, v8
	v_exp_f32_e32 v9, v9
	v_exp_f32_e32 v10, v10
	v_exp_f32_e32 v11, v11
	v_exp_f32_e32 v12, v12
	v_exp_f32_e32 v13, v13
	v_add_f32_e64 v8, v8, 1.0
	v_add_f32_e64 v9, v9, 1.0
	v_add_f32_e64 v10, v10, 1.0
	v_add_f32_e64 v11, v11, 1.0
	v_rcp_f32_e32 v8, v8
	v_add_f32_e64 v12, v12, 1.0
	v_add_f32_e64 v13, v13, 1.0
	v_rcp_f32_e32 v9, v9
	v_rcp_f32_e32 v10, v10
	v_rcp_f32_e32 v11, v11
	v_rcp_f32_e32 v14, v12
	v_rcp_f32_e32 v15, v13
	v_mul_f32_e64 v12, v4, v8
	v_mul_f32_e64 v13, v5, v9
	v_mul_f32_e64 v10, v6, v10
	v_mul_f32_e64 v11, v7, v11
	s_mov_b64 s[0:1], 0
	v_mul_f32_e64 v8, v0, v14
	v_mul_f32_e64 v9, v1, v15
	v_mul_f32_e64 v14, v2, s50
	v_mul_f32_e64 v15, v3, s50
.LBB0_2495:
	s_andn2_b64 vcc, exec, s[0:1]
	s_cbranch_vccnz .LBB0_2497
	v_mul_f32_e64 v8, v4, v4
	v_mul_f32_e64 v9, v5, v5
	v_mul_f32_e64 v10, v4, s58
	v_mul_f32_e64 v11, v5, s58
	v_fma_f32 v8, v8, s56, 1.0
	v_fma_f32 v9, v9, s56, 1.0
	v_mul_f32_e64 v12, v6, s58
	v_mul_f32_e64 v13, v7, s58
	v_mul_f32_e64 v8, v10, v8
	v_mul_f32_e64 v9, v11, v9
	v_mul_f32_e64 v10, v6, v6
	v_mul_f32_e64 v11, v7, v7
	v_mul_f32_e64 v14, v0, s58
	v_mul_f32_e64 v15, v1, s58
	v_fma_f32 v10, v10, s56, 1.0
	v_fma_f32 v11, v11, s56, 1.0
	v_exp_f32_e32 v8, v8
	v_mul_f32_e64 v10, v12, v10
	v_mul_f32_e64 v11, v13, v11
	v_mul_f32_e64 v12, v0, v0
	v_mul_f32_e64 v13, v1, v1
	v_exp_f32_e32 v9, v9
	v_fma_f32 v12, v12, s56, 1.0
	v_fma_f32 v13, v13, s56, 1.0
	v_exp_f32_e32 v10, v10
	v_mul_f32_e64 v12, v14, v12
	v_mul_f32_e64 v13, v15, v13
	v_exp_f32_e32 v11, v11
	v_exp_f32_e32 v12, v12
	v_exp_f32_e32 v13, v13
	v_add_f32_e64 v8, v8, 1.0
	v_add_f32_e64 v9, v9, 1.0
	v_add_f32_e64 v10, v10, 1.0
	v_add_f32_e64 v11, v11, 1.0
	v_rcp_f32_e32 v8, v8
	v_rcp_f32_e32 v9, v9
	v_add_f32_e64 v12, v12, 1.0
	v_add_f32_e64 v13, v13, 1.0
	v_rcp_f32_e32 v10, v10
	v_rcp_f32_e32 v14, v12
	v_rcp_f32_e32 v15, v13
	v_rcp_f32_e32 v11, v11
	v_mul_f32_e64 v12, v4, v8
	v_mul_f32_e64 v13, v5, v9
	v_mul_f32_e64 v4, v2, v2
	v_mul_f32_e64 v5, v3, v3
	v_mul_f32_e64 v8, v0, v14
	v_mul_f32_e64 v9, v1, v15
	v_fma_f32 v0, v4, s56, 1.0
	v_fma_f32 v1, v5, s56, 1.0
	v_mul_f32_e64 v4, v2, s58
	v_mul_f32_e64 v5, v3, s58
	v_mul_f32_e64 v10, v6, v10
	v_mul_f32_e64 v11, v7, v11
	v_mul_f32_e64 v14, v4, v0
	v_mul_f32_e64 v15, v5, v1
.LBB0_2497:
	s_nop 0
	v_exp_f32_e32 v0, v14
	v_exp_f32_e32 v1, v15
	v_add_lshl_u32 v136, s24, v140, 1
	v_lshl_add_u64 v[6:7], v[34:35], 0, v[136:137]
	v_add_f32_e64 v0, v0, 1.0
	v_add_f32_e64 v1, v1, 1.0
	s_nop 0
	v_rcp_f32_e32 v4, v0
	v_rcp_f32_e32 v5, v1
	v_cvt_pk_bf16_f32 v0, v12, v13
	v_cvt_pk_bf16_f32 v1, v10, v11
	s_nop 0
	v_mul_f32_e64 v4, v2, v4
	v_mul_f32_e64 v5, v3, v5
	v_cvt_pk_bf16_f32 v2, v8, v9
	s_nop 0
	v_cvt_pk_bf16_f32 v3, v4, v5
	global_store_dwordx4 v[6:7], v[0:3], off offset:256
